# combined: v40 + hoisted LDS read addresses + MFMA segment-head rotation
# speedup vs baseline: 1.0202x; 1.0124x over previous
; #define PG8_STAGE(bufoff, gbase, voff) do { _Pragma("unroll") for (int _i = 0; _i < 2; ++_i) \
;         __builtin_amdgcn_global_load_lds((const unsigned*)((const char*)(gbase) + (voff)[_i]), (PG8_LAS unsigned*)(lds + (bufoff) + ldsw + _i * 8192), 16, 0, 0); } while (0)
; #define PG8_LDA(dst, b, h) do { _Pragma("unroll") for (int m = 0; m < 4; ++m) _Pragma("unroll") for (int k = 0; k < 2; ++k) dst[m][k] = *(const PG8_LAS bf16x8*)(lds + PG8_SA(b, h) + aoff + m * 2048 + k * 1024); } while (0)
; #define PG8_LDB(dst, b, h) do { _Pragma("unroll") for (int n = 0; n < 2; ++n) _Pragma("unroll") for (int k = 0; k < 2; ++k) dst[n][k] = *(const PG8_LAS bf16x8*)(lds + PG8_SB(b, h) + boff + n * 2048 + k * 1024); } while (0)
; #define PG8_SCHED __builtin_amdgcn_sched_barrier(0)
; template <class Epi, class Sched, bool ALIGN_EPI = false, bool SP2 = false>
; __device__ __forceinline__ void gemm_phase(PG8_LAS unsigned char* lds, const Gemm g, const Sched& S, const Epi& E) {
;     ...
;         for (int t = 0; t < nt; t += 2) {
;             const bool last = (t == nt - 2);
;             const char* a1 = cA + (size_t)(t + 1) * kstep;
;             const char* a2 = last ? nA : cA + (size_t)(t + 2) * kstep; const char* b2 = last ? nB : cB + (size_t)(t + 2) * kstep;
;             const char* a3 = a2 + kstep; const char* b3 = b2 + kstep;
;             if (last && has_next) S.a_ready(nxt);
;             if constexpr (SP2) {
;             PG8_LDB(B0, 0, 0); PG8_LDB(B1, 0, 1); PG8_SCHED; PG8_LDA(At, 0, 0); PG8_STAGE(PG8_SA(1, 1), a1 + hstep, voffA);
.LBB0_66:
	ds_read_b128 v[152:155], v149
	ds_read_b128 v[156:159], v149 offset:1024
	ds_read_b128 v[160:163], v149 offset:2048
	ds_read_b128 v[164:167], v149 offset:3072
	ds_read_b128 v[168:171], v150
	ds_read_b128 v[172:175], v150 offset:1024
	ds_read_b128 v[176:179], v150 offset:2048
	ds_read_b128 v[180:183], v150 offset:3072
	s_add_u32 s42, s40, 0xfff80080
	s_addc_u32 s43, s41, -1
	s_cmp_eq_u32 s68, 28
	s_cselect_b32 s45, s35, s43
	s_cselect_b32 s44, s63, s42
	s_cselect_b32 s43, s31, s67
	s_cselect_b32 s42, s64, s65

; #define PG8_STAGE(bufoff, gbase, voff) do { _Pragma("unroll") for (int _i = 0; _i < 2; ++_i) \
;         __builtin_amdgcn_global_load_lds((const unsigned*)((const char*)(gbase) + (voff)[_i]), (PG8_LAS unsigned*)(lds + (bufoff) + ldsw + _i * 8192), 16, 0, 0); } while (0)
; #define PG8_LDA(dst, b, h) do { _Pragma("unroll") for (int m = 0; m < 4; ++m) _Pragma("unroll") for (int k = 0; k < 2; ++k) dst[m][k] = *(const PG8_LAS bf16x8*)(lds + PG8_SA(b, h) + aoff + m * 2048 + k * 1024); } while (0)
; #define PG8_LDB(dst, b, h) do { _Pragma("unroll") for (int n = 0; n < 2; ++n) _Pragma("unroll") for (int k = 0; k < 2; ++k) dst[n][k] = *(const PG8_LAS bf16x8*)(lds + PG8_SB(b, h) + boff + n * 2048 + k * 1024); } while (0)
; #define PG8_SCHED __builtin_amdgcn_sched_barrier(0)
; template <class Epi, class Sched, bool ALIGN_EPI = false, bool SP2 = false>
; __device__ __forceinline__ void gemm_phase(PG8_LAS unsigned char* lds, const Gemm g, const Sched& S, const Epi& E) {
;     ...
;             PG8_LDB(B0, 0, 0); PG8_LDB(B1, 0, 1); PG8_SCHED; PG8_LDA(At, 0, 0); PG8_STAGE(PG8_SA(1, 1), a1 + hstep, voffA);
	s_add_i32 m0, s29, 0xc000
	ds_read_b128 v[184:187], v151
	ds_read_b128 v[188:191], v151 offset:1024
	ds_read_b128 v[192:195], v151 offset:2048
	ds_read_b128 v[196:199], v151 offset:3072
	ds_read_b128 v[200:203], v151 offset:4096
	ds_read_b128 v[204:207], v151 offset:5120
	ds_read_b128 v[208:211], v151 offset:6144
	ds_read_b128 v[212:215], v151 offset:7168
	global_load_lds_dwordx4 v136, s[40:41]

; #define PG8_STAGE(bufoff, gbase, voff) do { _Pragma("unroll") for (int _i = 0; _i < 2; ++_i) \
;         __builtin_amdgcn_global_load_lds((const unsigned*)((const char*)(gbase) + (voff)[_i]), (PG8_LAS unsigned*)(lds + (bufoff) + ldsw + _i * 8192), 16, 0, 0); } while (0)
; #define PG8_LDA(dst, b, h) do { _Pragma("unroll") for (int m = 0; m < 4; ++m) _Pragma("unroll") for (int k = 0; k < 2; ++k) dst[m][k] = *(const PG8_LAS bf16x8*)(lds + PG8_SA(b, h) + aoff + m * 2048 + k * 1024); } while (0)
; #define PG8_LDB(dst, b, h) do { _Pragma("unroll") for (int n = 0; n < 2; ++n) _Pragma("unroll") for (int k = 0; k < 2; ++k) dst[n][k] = *(const PG8_LAS bf16x8*)(lds + PG8_SB(b, h) + boff + n * 2048 + k * 1024); } while (0)
; #define PG8_MMA(ai, bj, At, Bt) do { __builtin_amdgcn_s_setprio(1); _Pragma("unroll") for (int m = 0; m < 4; ++m) _Pragma("unroll") for (int n = 0; n < 2; ++n) _Pragma("unroll") for (int k = 0; k < 2; ++k) \
;         acc[ai][bj][m][n] = __builtin_amdgcn_mfma_f32_16x16x32_bf16(Bt[n][k], At[m][k], acc[ai][bj][m][n], 0, 0, 0); __builtin_amdgcn_s_setprio(0); } while (0)
; #define PG8_WAIT_V(n) asm volatile("s_waitcnt vmcnt(" #n ")" ::: "memory")
; #define PG8_WAIT_L(n) asm volatile("s_waitcnt lgkmcnt(" #n ")" ::: "memory")
; #define PG8_BAR __builtin_amdgcn_s_barrier()
; #define PG8_SCHED __builtin_amdgcn_sched_barrier(0)
; template <class Epi, class Sched, bool ALIGN_EPI = false, bool SP2 = false>
; __device__ __forceinline__ void gemm_phase(PG8_LAS unsigned char* lds, const Gemm g, const Sched& S, const Epi& E) {
;     ...
;             PG8_LDB(B0, 0, 0); PG8_LDB(B1, 0, 1); PG8_SCHED; PG8_LDA(At, 0, 0); PG8_STAGE(PG8_SA(1, 1), a1 + hstep, voffA);
;             PG8_WAIT_V(8); PG8_WAIT_L(0); PG8_BAR; PG8_MMA(0, 0, At, B0); PG8_MMA(0, 1, At, B1); PG8_BAR; PG8_SCHED;
	s_add_i32 m0, s29, 0xe000
	s_nop 0
	global_load_lds_dwordx4 v138, s[40:41]
	s_waitcnt vmcnt(8)
	s_waitcnt lgkmcnt(0)
	s_setprio 1
	s_barrier

; #define PG8_MMA(ai, bj, At, Bt) do { __builtin_amdgcn_s_setprio(1); _Pragma("unroll") for (int m = 0; m < 4; ++m) _Pragma("unroll") for (int n = 0; n < 2; ++n) _Pragma("unroll") for (int k = 0; k < 2; ++k) \
;         acc[ai][bj][m][n] = __builtin_amdgcn_mfma_f32_16x16x32_bf16(Bt[n][k], At[m][k], acc[ai][bj][m][n], 0, 0, 0); __builtin_amdgcn_s_setprio(0); } while (0)
; #define PG8_WAIT_V(n) asm volatile("s_waitcnt vmcnt(" #n ")" ::: "memory")
; #define PG8_WAIT_L(n) asm volatile("s_waitcnt lgkmcnt(" #n ")" ::: "memory")
; #define PG8_BAR __builtin_amdgcn_s_barrier()
; #define PG8_SCHED __builtin_amdgcn_sched_barrier(0)
; template <class Epi, class Sched, bool ALIGN_EPI = false, bool SP2 = false>
; __device__ __forceinline__ void gemm_phase(PG8_LAS unsigned char* lds, const Gemm g, const Sched& S, const Epi& E) {
;     ...
;             PG8_WAIT_V(8); PG8_WAIT_L(0); PG8_BAR; PG8_MMA(0, 0, At, B0); PG8_MMA(0, 1, At, B1); PG8_BAR; PG8_SCHED;
	v_mfma_f32_16x16x32_bf16 v[124:127], v[152:155], v[184:187], v[124:127]
	v_mfma_f32_16x16x32_bf16 v[120:123], v[160:163], v[184:187], v[120:123]
	v_mfma_f32_16x16x32_bf16 v[116:119], v[152:155], v[192:195], v[116:119]
	v_mfma_f32_16x16x32_bf16 v[112:115], v[160:163], v[192:195], v[112:115]
	v_mfma_f32_16x16x32_bf16 v[100:103], v[152:155], v[200:203], v[100:103]
	v_mfma_f32_16x16x32_bf16 v[96:99], v[160:163], v[200:203], v[96:99]
	v_mfma_f32_16x16x32_bf16 v[84:87], v[152:155], v[208:211], v[84:87]
	v_mfma_f32_16x16x32_bf16 v[80:83], v[160:163], v[208:211], v[80:83]
	v_mfma_f32_16x16x32_bf16 v[124:127], v[156:159], v[188:191], v[124:127]
	v_mfma_f32_16x16x32_bf16 v[120:123], v[164:167], v[188:191], v[120:123]
	v_mfma_f32_16x16x32_bf16 v[116:119], v[156:159], v[196:199], v[116:119]
	v_mfma_f32_16x16x32_bf16 v[112:115], v[164:167], v[196:199], v[112:115]
	v_mfma_f32_16x16x32_bf16 v[100:103], v[156:159], v[204:207], v[100:103]
	v_mfma_f32_16x16x32_bf16 v[96:99], v[164:167], v[204:207], v[96:99]
	v_mfma_f32_16x16x32_bf16 v[84:87], v[156:159], v[212:215], v[84:87]
	v_mfma_f32_16x16x32_bf16 v[80:83], v[164:167], v[212:215], v[80:83]


; #define PG8_STAGE(bufoff, gbase, voff) do { _Pragma("unroll") for (int _i = 0; _i < 2; ++_i) \
;         __builtin_amdgcn_global_load_lds((const unsigned*)((const char*)(gbase) + (voff)[_i]), (PG8_LAS unsigned*)(lds + (bufoff) + ldsw + _i * 8192), 16, 0, 0); } while (0)
; #define PG8_LDA(dst, b, h) do { _Pragma("unroll") for (int m = 0; m < 4; ++m) _Pragma("unroll") for (int k = 0; k < 2; ++k) dst[m][k] = *(const PG8_LAS bf16x8*)(lds + PG8_SA(b, h) + aoff + m * 2048 + k * 1024); } while (0)
; #define PG8_MMA(ai, bj, At, Bt) do { __builtin_amdgcn_s_setprio(1); _Pragma("unroll") for (int m = 0; m < 4; ++m) _Pragma("unroll") for (int n = 0; n < 2; ++n) _Pragma("unroll") for (int k = 0; k < 2; ++k) \
;         acc[ai][bj][m][n] = __builtin_amdgcn_mfma_f32_16x16x32_bf16(Bt[n][k], At[m][k], acc[ai][bj][m][n], 0, 0, 0); __builtin_amdgcn_s_setprio(0); } while (0)
; #define PG8_WAIT_V(n) asm volatile("s_waitcnt vmcnt(" #n ")" ::: "memory")
; #define PG8_WAIT_L(n) asm volatile("s_waitcnt lgkmcnt(" #n ")" ::: "memory")
; #define PG8_BAR __builtin_amdgcn_s_barrier()
; #define PG8_SCHED __builtin_amdgcn_sched_barrier(0)
; template <class Epi, class Sched, bool ALIGN_EPI = false, bool SP2 = false>
; __device__ __forceinline__ void gemm_phase(PG8_LAS unsigned char* lds, const Gemm g, const Sched& S, const Epi& E) {
;     ...
;             PG8_WAIT_V(8); PG8_WAIT_L(0); PG8_BAR; PG8_MMA(0, 0, At, B0); PG8_MMA(0, 1, At, B1); PG8_BAR; PG8_SCHED;
;             PG8_LDA(At, 0, 1); PG8_STAGE(PG8_SB(0, 0), b2, voffB); PG8_STAGE(PG8_SB(0, 1), b2 + hstep, voffB); PG8_STAGE(PG8_SA(0, 0), a2, voffA);
	v_mfma_f32_16x16x32_bf16 v[108:111], v[168:171], v[184:187], v[108:111]
	v_mfma_f32_16x16x32_bf16 v[104:107], v[176:179], v[184:187], v[104:107]
	v_mfma_f32_16x16x32_bf16 v[92:95], v[168:171], v[192:195], v[92:95]
	v_mfma_f32_16x16x32_bf16 v[88:91], v[176:179], v[192:195], v[88:91]
	v_mfma_f32_16x16x32_bf16 v[76:79], v[168:171], v[200:203], v[76:79]
	v_mfma_f32_16x16x32_bf16 v[72:75], v[176:179], v[200:203], v[72:75]
	v_mfma_f32_16x16x32_bf16 v[68:71], v[168:171], v[208:211], v[68:71]
	v_mfma_f32_16x16x32_bf16 v[64:67], v[176:179], v[208:211], v[64:67]
	v_mfma_f32_16x16x32_bf16 v[108:111], v[172:175], v[188:191], v[108:111]
	v_mfma_f32_16x16x32_bf16 v[104:107], v[180:183], v[188:191], v[104:107]
	v_mfma_f32_16x16x32_bf16 v[92:95], v[172:175], v[196:199], v[92:95]
	v_mfma_f32_16x16x32_bf16 v[88:91], v[180:183], v[196:199], v[88:91]
	v_mfma_f32_16x16x32_bf16 v[76:79], v[172:175], v[204:207], v[76:79]
	v_mfma_f32_16x16x32_bf16 v[72:75], v[180:183], v[204:207], v[72:75]
	v_mfma_f32_16x16x32_bf16 v[68:71], v[172:175], v[212:215], v[68:71]
	v_mfma_f32_16x16x32_bf16 v[64:67], v[180:183], v[212:215], v[64:67]
	s_setprio 0
	s_barrier
	s_add_i32 s69, s59, s48
	s_mov_b64 s[96:97], s[42:43]

; #define PG8_STAGE(bufoff, gbase, voff) do { _Pragma("unroll") for (int _i = 0; _i < 2; ++_i) \
;         __builtin_amdgcn_global_load_lds((const unsigned*)((const char*)(gbase) + (voff)[_i]), (PG8_LAS unsigned*)(lds + (bufoff) + ldsw + _i * 8192), 16, 0, 0); } while (0)
; #define PG8_LDA(dst, b, h) do { _Pragma("unroll") for (int m = 0; m < 4; ++m) _Pragma("unroll") for (int k = 0; k < 2; ++k) dst[m][k] = *(const PG8_LAS bf16x8*)(lds + PG8_SA(b, h) + aoff + m * 2048 + k * 1024); } while (0)
; template <class Epi, class Sched, bool ALIGN_EPI = false, bool SP2 = false>
; __device__ __forceinline__ void gemm_phase(PG8_LAS unsigned char* lds, const Gemm g, const Sched& S, const Epi& E) {
;     ...
;             PG8_LDA(At, 0, 1); PG8_STAGE(PG8_SB(0, 0), b2, voffB); PG8_STAGE(PG8_SB(0, 1), b2 + hstep, voffB); PG8_STAGE(PG8_SA(0, 0), a2, voffA);
	s_mov_b32 m0, s69
	ds_read_b128 v[184:187], v151 offset:16384
	ds_read_b128 v[188:191], v151 offset:17408
	ds_read_b128 v[192:195], v151 offset:18432
	ds_read_b128 v[196:199], v151 offset:19456
	ds_read_b128 v[200:203], v151 offset:20480
	ds_read_b128 v[204:207], v151 offset:21504
	ds_read_b128 v[208:211], v151 offset:22528
	ds_read_b128 v[212:215], v151 offset:23552
	global_load_lds_dwordx4 v132, s[42:43]
	s_add_i32 m0, s69, 0x2000
	s_add_u32 s70, s42, 0x80000

; #define PG8_STAGE(bufoff, gbase, voff) do { _Pragma("unroll") for (int _i = 0; _i < 2; ++_i) \
;         __builtin_amdgcn_global_load_lds((const unsigned*)((const char*)(gbase) + (voff)[_i]), (PG8_LAS unsigned*)(lds + (bufoff) + ldsw + _i * 8192), 16, 0, 0); } while (0)
; #define PG8_LDA(dst, b, h) do { _Pragma("unroll") for (int m = 0; m < 4; ++m) _Pragma("unroll") for (int k = 0; k < 2; ++k) dst[m][k] = *(const PG8_LAS bf16x8*)(lds + PG8_SA(b, h) + aoff + m * 2048 + k * 1024); } while (0)
; template <class Epi, class Sched, bool ALIGN_EPI = false, bool SP2 = false>
; __device__ __forceinline__ void gemm_phase(PG8_LAS unsigned char* lds, const Gemm g, const Sched& S, const Epi& E) {
;     ...
;             PG8_LDA(At, 0, 1); PG8_STAGE(PG8_SB(0, 0), b2, voffB); PG8_STAGE(PG8_SB(0, 1), b2 + hstep, voffB); PG8_STAGE(PG8_SA(0, 0), a2, voffA);
	s_addc_u32 s71, s43, 0
	s_add_i32 s69, s60, s48
	global_load_lds_dwordx4 v128, s[42:43]

; #define PG8_STAGE(bufoff, gbase, voff) do { _Pragma("unroll") for (int _i = 0; _i < 2; ++_i) \
;         __builtin_amdgcn_global_load_lds((const unsigned*)((const char*)(gbase) + (voff)[_i]), (PG8_LAS unsigned*)(lds + (bufoff) + ldsw + _i * 8192), 16, 0, 0); } while (0)
; #define PG8_LDA(dst, b, h) do { _Pragma("unroll") for (int m = 0; m < 4; ++m) _Pragma("unroll") for (int k = 0; k < 2; ++k) dst[m][k] = *(const PG8_LAS bf16x8*)(lds + PG8_SA(b, h) + aoff + m * 2048 + k * 1024); } while (0)
; template <class Epi, class Sched, bool ALIGN_EPI = false, bool SP2 = false>
; __device__ __forceinline__ void gemm_phase(PG8_LAS unsigned char* lds, const Gemm g, const Sched& S, const Epi& E) {
;     ...
;             PG8_LDA(At, 0, 1); PG8_STAGE(PG8_SB(0, 0), b2, voffB); PG8_STAGE(PG8_SB(0, 1), b2 + hstep, voffB); PG8_STAGE(PG8_SA(0, 0), a2, voffA);
	s_mov_b32 m0, s69
	s_nop 0
	global_load_lds_dwordx4 v132, s[70:71]

; #define PG8_STAGE(bufoff, gbase, voff) do { _Pragma("unroll") for (int _i = 0; _i < 2; ++_i) \
;         __builtin_amdgcn_global_load_lds((const unsigned*)((const char*)(gbase) + (voff)[_i]), (PG8_LAS unsigned*)(lds + (bufoff) + ldsw + _i * 8192), 16, 0, 0); } while (0)
; #define PG8_LDA(dst, b, h) do { _Pragma("unroll") for (int m = 0; m < 4; ++m) _Pragma("unroll") for (int k = 0; k < 2; ++k) dst[m][k] = *(const PG8_LAS bf16x8*)(lds + PG8_SA(b, h) + aoff + m * 2048 + k * 1024); } while (0)
; template <class Epi, class Sched, bool ALIGN_EPI = false, bool SP2 = false>
; __device__ __forceinline__ void gemm_phase(PG8_LAS unsigned char* lds, const Gemm g, const Sched& S, const Epi& E) {
;     ...
;             PG8_LDA(At, 0, 1); PG8_STAGE(PG8_SB(0, 0), b2, voffB); PG8_STAGE(PG8_SB(0, 1), b2 + hstep, voffB); PG8_STAGE(PG8_SA(0, 0), a2, voffA);
	s_add_i32 m0, s69, 0x2000
	s_nop 0
	global_load_lds_dwordx4 v128, s[70:71]
	s_mov_b64 s[98:99], s[44:45]

; #define PG8_STAGE(bufoff, gbase, voff) do { _Pragma("unroll") for (int _i = 0; _i < 2; ++_i) \
;         __builtin_amdgcn_global_load_lds((const unsigned*)((const char*)(gbase) + (voff)[_i]), (PG8_LAS unsigned*)(lds + (bufoff) + ldsw + _i * 8192), 16, 0, 0); } while (0)
; #define PG8_LDA(dst, b, h) do { _Pragma("unroll") for (int m = 0; m < 4; ++m) _Pragma("unroll") for (int k = 0; k < 2; ++k) dst[m][k] = *(const PG8_LAS bf16x8*)(lds + PG8_SA(b, h) + aoff + m * 2048 + k * 1024); } while (0)
; #define PG8_MMA(ai, bj, At, Bt) do { __builtin_amdgcn_s_setprio(1); _Pragma("unroll") for (int m = 0; m < 4; ++m) _Pragma("unroll") for (int n = 0; n < 2; ++n) _Pragma("unroll") for (int k = 0; k < 2; ++k) \
;         acc[ai][bj][m][n] = __builtin_amdgcn_mfma_f32_16x16x32_bf16(Bt[n][k], At[m][k], acc[ai][bj][m][n], 0, 0, 0); __builtin_amdgcn_s_setprio(0); } while (0)
; #define PG8_WAIT_V(n) asm volatile("s_waitcnt vmcnt(" #n ")" ::: "memory")
; #define PG8_WAIT_L(n) asm volatile("s_waitcnt lgkmcnt(" #n ")" ::: "memory")
; #define PG8_BAR __builtin_amdgcn_s_barrier()
; #define PG8_SCHED __builtin_amdgcn_sched_barrier(0)
; template <class Epi, class Sched, bool ALIGN_EPI = false, bool SP2 = false>
; __device__ __forceinline__ void gemm_phase(PG8_LAS unsigned char* lds, const Gemm g, const Sched& S, const Epi& E) {
;     ...
;             PG8_LDA(At, 0, 1); PG8_STAGE(PG8_SB(0, 0), b2, voffB); PG8_STAGE(PG8_SB(0, 1), b2 + hstep, voffB); PG8_STAGE(PG8_SA(0, 0), a2, voffA);
;             PG8_WAIT_V(8); PG8_WAIT_L(0); PG8_BAR; PG8_MMA(1, 0, At, B0); PG8_MMA(1, 1, At, B1); PG8_BAR; PG8_SCHED;
	s_mov_b32 m0, s29
	s_nop 0
	global_load_lds_dwordx4 v134, s[44:45]
	s_mov_b32 m0, s51
	s_nop 0
	global_load_lds_dwordx4 v130, s[44:45]
	s_waitcnt vmcnt(8)
	s_waitcnt lgkmcnt(0)
	s_setprio 1
	s_barrier

; #define PG8_MMA(ai, bj, At, Bt) do { __builtin_amdgcn_s_setprio(1); _Pragma("unroll") for (int m = 0; m < 4; ++m) _Pragma("unroll") for (int n = 0; n < 2; ++n) _Pragma("unroll") for (int k = 0; k < 2; ++k) \
;         acc[ai][bj][m][n] = __builtin_amdgcn_mfma_f32_16x16x32_bf16(Bt[n][k], At[m][k], acc[ai][bj][m][n], 0, 0, 0); __builtin_amdgcn_s_setprio(0); } while (0)
; #define PG8_WAIT_V(n) asm volatile("s_waitcnt vmcnt(" #n ")" ::: "memory")
; #define PG8_WAIT_L(n) asm volatile("s_waitcnt lgkmcnt(" #n ")" ::: "memory")
; #define PG8_BAR __builtin_amdgcn_s_barrier()
; #define PG8_SCHED __builtin_amdgcn_sched_barrier(0)
; template <class Epi, class Sched, bool ALIGN_EPI = false, bool SP2 = false>
; __device__ __forceinline__ void gemm_phase(PG8_LAS unsigned char* lds, const Gemm g, const Sched& S, const Epi& E) {
;     ...
;             PG8_WAIT_V(8); PG8_WAIT_L(0); PG8_BAR; PG8_MMA(1, 0, At, B0); PG8_MMA(1, 1, At, B1); PG8_BAR; PG8_SCHED;
	v_mfma_f32_16x16x32_bf16 v[60:63], v[152:155], v[184:187], v[60:63]
	v_mfma_f32_16x16x32_bf16 v[56:59], v[160:163], v[184:187], v[56:59]
	v_mfma_f32_16x16x32_bf16 v[52:55], v[152:155], v[192:195], v[52:55]
	v_mfma_f32_16x16x32_bf16 v[48:51], v[160:163], v[192:195], v[48:51]
	v_mfma_f32_16x16x32_bf16 v[36:39], v[152:155], v[200:203], v[36:39]
	v_mfma_f32_16x16x32_bf16 v[32:35], v[160:163], v[200:203], v[32:35]
	v_mfma_f32_16x16x32_bf16 v[20:23], v[152:155], v[208:211], v[20:23]
	v_mfma_f32_16x16x32_bf16 v[16:19], v[160:163], v[208:211], v[16:19]
	v_mfma_f32_16x16x32_bf16 v[60:63], v[156:159], v[188:191], v[60:63]
	v_mfma_f32_16x16x32_bf16 v[56:59], v[164:167], v[188:191], v[56:59]
	v_mfma_f32_16x16x32_bf16 v[52:55], v[156:159], v[196:199], v[52:55]
	v_mfma_f32_16x16x32_bf16 v[48:51], v[164:167], v[196:199], v[48:51]
	v_mfma_f32_16x16x32_bf16 v[36:39], v[156:159], v[204:207], v[36:39]
	v_mfma_f32_16x16x32_bf16 v[32:35], v[164:167], v[204:207], v[32:35]
	v_mfma_f32_16x16x32_bf16 v[20:23], v[156:159], v[212:215], v[20:23]
	v_mfma_f32_16x16x32_bf16 v[16:19], v[164:167], v[212:215], v[16:19]


; #define PG8_STAGE(bufoff, gbase, voff) do { _Pragma("unroll") for (int _i = 0; _i < 2; ++_i) \
;         __builtin_amdgcn_global_load_lds((const unsigned*)((const char*)(gbase) + (voff)[_i]), (PG8_LAS unsigned*)(lds + (bufoff) + ldsw + _i * 8192), 16, 0, 0); } while (0)
; #define PG8_LDA(dst, b, h) do { _Pragma("unroll") for (int m = 0; m < 4; ++m) _Pragma("unroll") for (int k = 0; k < 2; ++k) dst[m][k] = *(const PG8_LAS bf16x8*)(lds + PG8_SA(b, h) + aoff + m * 2048 + k * 1024); } while (0)
; #define PG8_LDB(dst, b, h) do { _Pragma("unroll") for (int n = 0; n < 2; ++n) _Pragma("unroll") for (int k = 0; k < 2; ++k) dst[n][k] = *(const PG8_LAS bf16x8*)(lds + PG8_SB(b, h) + boff + n * 2048 + k * 1024); } while (0)
; #define PG8_MMA(ai, bj, At, Bt) do { __builtin_amdgcn_s_setprio(1); _Pragma("unroll") for (int m = 0; m < 4; ++m) _Pragma("unroll") for (int n = 0; n < 2; ++n) _Pragma("unroll") for (int k = 0; k < 2; ++k) \
;         acc[ai][bj][m][n] = __builtin_amdgcn_mfma_f32_16x16x32_bf16(Bt[n][k], At[m][k], acc[ai][bj][m][n], 0, 0, 0); __builtin_amdgcn_s_setprio(0); } while (0)
; #define PG8_WAIT_V(n) asm volatile("s_waitcnt vmcnt(" #n ")" ::: "memory")
; #define PG8_WAIT_L(n) asm volatile("s_waitcnt lgkmcnt(" #n ")" ::: "memory")
; #define PG8_BAR __builtin_amdgcn_s_barrier()
; #define PG8_SCHED __builtin_amdgcn_sched_barrier(0)
; template <class Epi, class Sched, bool ALIGN_EPI = false, bool SP2 = false>
; __device__ __forceinline__ void gemm_phase(PG8_LAS unsigned char* lds, const Gemm g, const Sched& S, const Epi& E) {
;     ...
;             PG8_WAIT_V(8); PG8_WAIT_L(0); PG8_BAR; PG8_MMA(1, 0, At, B0); PG8_MMA(1, 1, At, B1); PG8_BAR; PG8_SCHED;
;             PG8_LDB(B0, 1, 0); PG8_LDB(B1, 1, 1); PG8_SCHED; PG8_LDA(At, 1, 0); PG8_STAGE(PG8_SA(0, 1), a2 + hstep, voffA);
	v_mfma_f32_16x16x32_bf16 v[44:47], v[168:171], v[184:187], v[44:47]
	v_mfma_f32_16x16x32_bf16 v[40:43], v[176:179], v[184:187], v[40:43]
	v_mfma_f32_16x16x32_bf16 v[28:31], v[168:171], v[192:195], v[28:31]
	v_mfma_f32_16x16x32_bf16 v[24:27], v[176:179], v[192:195], v[24:27]
	v_mfma_f32_16x16x32_bf16 v[12:15], v[168:171], v[200:203], v[12:15]
	v_mfma_f32_16x16x32_bf16 v[8:11], v[176:179], v[200:203], v[8:11]
	v_mfma_f32_16x16x32_bf16 v[4:7], v[168:171], v[208:211], v[4:7]
	v_mfma_f32_16x16x32_bf16 v[0:3], v[176:179], v[208:211], v[0:3]
	v_mfma_f32_16x16x32_bf16 v[44:47], v[172:175], v[188:191], v[44:47]
	v_mfma_f32_16x16x32_bf16 v[40:43], v[180:183], v[188:191], v[40:43]
	v_mfma_f32_16x16x32_bf16 v[28:31], v[172:175], v[196:199], v[28:31]
	v_mfma_f32_16x16x32_bf16 v[24:27], v[180:183], v[196:199], v[24:27]
	v_mfma_f32_16x16x32_bf16 v[12:15], v[172:175], v[204:207], v[12:15]
	v_mfma_f32_16x16x32_bf16 v[8:11], v[180:183], v[204:207], v[8:11]
	v_mfma_f32_16x16x32_bf16 v[4:7], v[172:175], v[212:215], v[4:7]
	v_mfma_f32_16x16x32_bf16 v[0:3], v[180:183], v[212:215], v[0:3]
	s_setprio 0
	s_barrier
	s_add_i32 s69, 0, 0x18000
	s_add_i32 s70, 0, 0x1c000


; #define PG8_STAGE(bufoff, gbase, voff) do { _Pragma("unroll") for (int _i = 0; _i < 2; ++_i) \
;         __builtin_amdgcn_global_load_lds((const unsigned*)((const char*)(gbase) + (voff)[_i]), (PG8_LAS unsigned*)(lds + (bufoff) + ldsw + _i * 8192), 16, 0, 0); } while (0)
; #define PG8_LDA(dst, b, h) do { _Pragma("unroll") for (int m = 0; m < 4; ++m) _Pragma("unroll") for (int k = 0; k < 2; ++k) dst[m][k] = *(const PG8_LAS bf16x8*)(lds + PG8_SA(b, h) + aoff + m * 2048 + k * 1024); } while (0)
; #define PG8_LDB(dst, b, h) do { _Pragma("unroll") for (int n = 0; n < 2; ++n) _Pragma("unroll") for (int k = 0; k < 2; ++k) dst[n][k] = *(const PG8_LAS bf16x8*)(lds + PG8_SB(b, h) + boff + n * 2048 + k * 1024); } while (0)
; #define PG8_SCHED __builtin_amdgcn_sched_barrier(0)
; template <class Epi, class Sched, bool ALIGN_EPI = false, bool SP2 = false>
; __device__ __forceinline__ void gemm_phase(PG8_LAS unsigned char* lds, const Gemm g, const Sched& S, const Epi& E) {
;     ...
;             PG8_LDB(B0, 1, 0); PG8_LDB(B1, 1, 1); PG8_SCHED; PG8_LDA(At, 1, 0); PG8_STAGE(PG8_SA(0, 1), a2 + hstep, voffA);
	ds_read_b128 v[152:155], v254
	ds_read_b128 v[156:159], v254 offset:1024
	ds_read_b128 v[160:163], v254 offset:2048
	ds_read_b128 v[164:167], v254 offset:3072
	ds_read_b128 v[168:171], v255
	ds_read_b128 v[172:175], v255 offset:1024
	ds_read_b128 v[176:179], v255 offset:2048
	ds_read_b128 v[180:183], v255 offset:3072
	s_add_u32 s44, s44, 0x80000
	s_addc_u32 s45, s45, 0
	s_mov_b32 m0, s52

; #define PG8_STAGE(bufoff, gbase, voff) do { _Pragma("unroll") for (int _i = 0; _i < 2; ++_i) \
;         __builtin_amdgcn_global_load_lds((const unsigned*)((const char*)(gbase) + (voff)[_i]), (PG8_LAS unsigned*)(lds + (bufoff) + ldsw + _i * 8192), 16, 0, 0); } while (0)
; #define PG8_LDA(dst, b, h) do { _Pragma("unroll") for (int m = 0; m < 4; ++m) _Pragma("unroll") for (int k = 0; k < 2; ++k) dst[m][k] = *(const PG8_LAS bf16x8*)(lds + PG8_SA(b, h) + aoff + m * 2048 + k * 1024); } while (0)
; #define PG8_LDB(dst, b, h) do { _Pragma("unroll") for (int n = 0; n < 2; ++n) _Pragma("unroll") for (int k = 0; k < 2; ++k) dst[n][k] = *(const PG8_LAS bf16x8*)(lds + PG8_SB(b, h) + boff + n * 2048 + k * 1024); } while (0)
; #define PG8_SCHED __builtin_amdgcn_sched_barrier(0)
; template <class Epi, class Sched, bool ALIGN_EPI = false, bool SP2 = false>
; __device__ __forceinline__ void gemm_phase(PG8_LAS unsigned char* lds, const Gemm g, const Sched& S, const Epi& E) {
;     ...
;             PG8_LDB(B0, 1, 0); PG8_LDB(B1, 1, 1); PG8_SCHED; PG8_LDA(At, 1, 0); PG8_STAGE(PG8_SA(0, 1), a2 + hstep, voffA);
	ds_read_b128 v[184:187], v151 offset:32768
	ds_read_b128 v[188:191], v151 offset:33792
	ds_read_b128 v[192:195], v151 offset:34816
	ds_read_b128 v[196:199], v151 offset:35840
	ds_read_b128 v[200:203], v151 offset:36864
	ds_read_b128 v[204:207], v151 offset:37888
	ds_read_b128 v[208:211], v151 offset:38912
	ds_read_b128 v[212:215], v151 offset:39936
	global_load_lds_dwordx4 v134, s[44:45]

; #define PG8_STAGE(bufoff, gbase, voff) do { _Pragma("unroll") for (int _i = 0; _i < 2; ++_i) \
;         __builtin_amdgcn_global_load_lds((const unsigned*)((const char*)(gbase) + (voff)[_i]), (PG8_LAS unsigned*)(lds + (bufoff) + ldsw + _i * 8192), 16, 0, 0); } while (0)
; #define PG8_LDA(dst, b, h) do { _Pragma("unroll") for (int m = 0; m < 4; ++m) _Pragma("unroll") for (int k = 0; k < 2; ++k) dst[m][k] = *(const PG8_LAS bf16x8*)(lds + PG8_SA(b, h) + aoff + m * 2048 + k * 1024); } while (0)
; #define PG8_LDB(dst, b, h) do { _Pragma("unroll") for (int n = 0; n < 2; ++n) _Pragma("unroll") for (int k = 0; k < 2; ++k) dst[n][k] = *(const PG8_LAS bf16x8*)(lds + PG8_SB(b, h) + boff + n * 2048 + k * 1024); } while (0)
; #define PG8_MMA(ai, bj, At, Bt) do { __builtin_amdgcn_s_setprio(1); _Pragma("unroll") for (int m = 0; m < 4; ++m) _Pragma("unroll") for (int n = 0; n < 2; ++n) _Pragma("unroll") for (int k = 0; k < 2; ++k) \
;         acc[ai][bj][m][n] = __builtin_amdgcn_mfma_f32_16x16x32_bf16(Bt[n][k], At[m][k], acc[ai][bj][m][n], 0, 0, 0); __builtin_amdgcn_s_setprio(0); } while (0)
; #define PG8_WAIT_V(n) asm volatile("s_waitcnt vmcnt(" #n ")" ::: "memory")
; #define PG8_WAIT_L(n) asm volatile("s_waitcnt lgkmcnt(" #n ")" ::: "memory")
; #define PG8_BAR __builtin_amdgcn_s_barrier()
; #define PG8_SCHED __builtin_amdgcn_sched_barrier(0)
; template <class Epi, class Sched, bool ALIGN_EPI = false, bool SP2 = false>
; __device__ __forceinline__ void gemm_phase(PG8_LAS unsigned char* lds, const Gemm g, const Sched& S, const Epi& E) {
;     ...
;             PG8_LDB(B0, 1, 0); PG8_LDB(B1, 1, 1); PG8_SCHED; PG8_LDA(At, 1, 0); PG8_STAGE(PG8_SA(0, 1), a2 + hstep, voffA);
;             PG8_WAIT_V(8); PG8_WAIT_L(0); PG8_BAR; PG8_MMA(0, 0, At, B0); PG8_MMA(0, 1, At, B1); PG8_BAR; PG8_SCHED;
	s_mov_b32 m0, s53
	s_nop 0
	global_load_lds_dwordx4 v130, s[44:45]
	s_waitcnt vmcnt(8)
	s_waitcnt lgkmcnt(0)
	s_setprio 1
	s_barrier

; #define PG8_MMA(ai, bj, At, Bt) do { __builtin_amdgcn_s_setprio(1); _Pragma("unroll") for (int m = 0; m < 4; ++m) _Pragma("unroll") for (int n = 0; n < 2; ++n) _Pragma("unroll") for (int k = 0; k < 2; ++k) \
;         acc[ai][bj][m][n] = __builtin_amdgcn_mfma_f32_16x16x32_bf16(Bt[n][k], At[m][k], acc[ai][bj][m][n], 0, 0, 0); __builtin_amdgcn_s_setprio(0); } while (0)
; #define PG8_WAIT_V(n) asm volatile("s_waitcnt vmcnt(" #n ")" ::: "memory")
; #define PG8_WAIT_L(n) asm volatile("s_waitcnt lgkmcnt(" #n ")" ::: "memory")
; #define PG8_BAR __builtin_amdgcn_s_barrier()
; #define PG8_SCHED __builtin_amdgcn_sched_barrier(0)
; template <class Epi, class Sched, bool ALIGN_EPI = false, bool SP2 = false>
; __device__ __forceinline__ void gemm_phase(PG8_LAS unsigned char* lds, const Gemm g, const Sched& S, const Epi& E) {
;     ...
;             PG8_WAIT_V(8); PG8_WAIT_L(0); PG8_BAR; PG8_MMA(0, 0, At, B0); PG8_MMA(0, 1, At, B1); PG8_BAR; PG8_SCHED;
	v_mfma_f32_16x16x32_bf16 v[124:127], v[152:155], v[184:187], v[124:127]
	v_mfma_f32_16x16x32_bf16 v[120:123], v[160:163], v[184:187], v[120:123]
	v_mfma_f32_16x16x32_bf16 v[116:119], v[152:155], v[192:195], v[116:119]
	v_mfma_f32_16x16x32_bf16 v[112:115], v[160:163], v[192:195], v[112:115]
	v_mfma_f32_16x16x32_bf16 v[100:103], v[152:155], v[200:203], v[100:103]
	v_mfma_f32_16x16x32_bf16 v[96:99], v[160:163], v[200:203], v[96:99]
	v_mfma_f32_16x16x32_bf16 v[84:87], v[152:155], v[208:211], v[84:87]
	v_mfma_f32_16x16x32_bf16 v[80:83], v[160:163], v[208:211], v[80:83]
	v_mfma_f32_16x16x32_bf16 v[124:127], v[156:159], v[188:191], v[124:127]
	v_mfma_f32_16x16x32_bf16 v[120:123], v[164:167], v[188:191], v[120:123]
	v_mfma_f32_16x16x32_bf16 v[116:119], v[156:159], v[196:199], v[116:119]
	v_mfma_f32_16x16x32_bf16 v[112:115], v[164:167], v[196:199], v[112:115]
	v_mfma_f32_16x16x32_bf16 v[100:103], v[156:159], v[204:207], v[100:103]
	v_mfma_f32_16x16x32_bf16 v[96:99], v[164:167], v[204:207], v[96:99]
	v_mfma_f32_16x16x32_bf16 v[84:87], v[156:159], v[212:215], v[84:87]
	v_mfma_f32_16x16x32_bf16 v[80:83], v[164:167], v[212:215], v[80:83]


; #define PG8_STAGE(bufoff, gbase, voff) do { _Pragma("unroll") for (int _i = 0; _i < 2; ++_i) \
;         __builtin_amdgcn_global_load_lds((const unsigned*)((const char*)(gbase) + (voff)[_i]), (PG8_LAS unsigned*)(lds + (bufoff) + ldsw + _i * 8192), 16, 0, 0); } while (0)
; #define PG8_LDA(dst, b, h) do { _Pragma("unroll") for (int m = 0; m < 4; ++m) _Pragma("unroll") for (int k = 0; k < 2; ++k) dst[m][k] = *(const PG8_LAS bf16x8*)(lds + PG8_SA(b, h) + aoff + m * 2048 + k * 1024); } while (0)
; #define PG8_MMA(ai, bj, At, Bt) do { __builtin_amdgcn_s_setprio(1); _Pragma("unroll") for (int m = 0; m < 4; ++m) _Pragma("unroll") for (int n = 0; n < 2; ++n) _Pragma("unroll") for (int k = 0; k < 2; ++k) \
;         acc[ai][bj][m][n] = __builtin_amdgcn_mfma_f32_16x16x32_bf16(Bt[n][k], At[m][k], acc[ai][bj][m][n], 0, 0, 0); __builtin_amdgcn_s_setprio(0); } while (0)
; #define PG8_WAIT_V(n) asm volatile("s_waitcnt vmcnt(" #n ")" ::: "memory")
; #define PG8_WAIT_L(n) asm volatile("s_waitcnt lgkmcnt(" #n ")" ::: "memory")
; #define PG8_BAR __builtin_amdgcn_s_barrier()
; #define PG8_SCHED __builtin_amdgcn_sched_barrier(0)
; template <class Epi, class Sched, bool ALIGN_EPI = false, bool SP2 = false>
; __device__ __forceinline__ void gemm_phase(PG8_LAS unsigned char* lds, const Gemm g, const Sched& S, const Epi& E) {
;     ...
;             PG8_WAIT_V(8); PG8_WAIT_L(0); PG8_BAR; PG8_MMA(0, 0, At, B0); PG8_MMA(0, 1, At, B1); PG8_BAR; PG8_SCHED;
;             PG8_LDA(At, 1, 1); PG8_STAGE(PG8_SB(1, 0), b3, voffB); PG8_STAGE(PG8_SB(1, 1), b3 + hstep, voffB); PG8_STAGE(PG8_SA(1, 0), a3, voffA);
	v_mfma_f32_16x16x32_bf16 v[108:111], v[168:171], v[184:187], v[108:111]
	v_mfma_f32_16x16x32_bf16 v[104:107], v[176:179], v[184:187], v[104:107]
	v_mfma_f32_16x16x32_bf16 v[92:95], v[168:171], v[192:195], v[92:95]
	v_mfma_f32_16x16x32_bf16 v[88:91], v[176:179], v[192:195], v[88:91]
	v_mfma_f32_16x16x32_bf16 v[76:79], v[168:171], v[200:203], v[76:79]
	v_mfma_f32_16x16x32_bf16 v[72:75], v[176:179], v[200:203], v[72:75]
	v_mfma_f32_16x16x32_bf16 v[68:71], v[168:171], v[208:211], v[68:71]
	v_mfma_f32_16x16x32_bf16 v[64:67], v[176:179], v[208:211], v[64:67]
	v_mfma_f32_16x16x32_bf16 v[108:111], v[172:175], v[188:191], v[108:111]
	v_mfma_f32_16x16x32_bf16 v[104:107], v[180:183], v[188:191], v[104:107]
	v_mfma_f32_16x16x32_bf16 v[92:95], v[172:175], v[196:199], v[92:95]
	v_mfma_f32_16x16x32_bf16 v[88:91], v[180:183], v[196:199], v[88:91]
	v_mfma_f32_16x16x32_bf16 v[76:79], v[172:175], v[204:207], v[76:79]
	v_mfma_f32_16x16x32_bf16 v[72:75], v[180:183], v[204:207], v[72:75]
	v_mfma_f32_16x16x32_bf16 v[68:71], v[172:175], v[212:215], v[68:71]
	v_mfma_f32_16x16x32_bf16 v[64:67], v[180:183], v[212:215], v[64:67]
	s_setprio 0
	s_barrier
	s_add_i32 s44, s69, s48

; #define PG8_STAGE(bufoff, gbase, voff) do { _Pragma("unroll") for (int _i = 0; _i < 2; ++_i) \
;         __builtin_amdgcn_global_load_lds((const unsigned*)((const char*)(gbase) + (voff)[_i]), (PG8_LAS unsigned*)(lds + (bufoff) + ldsw + _i * 8192), 16, 0, 0); } while (0)
; #define PG8_LDA(dst, b, h) do { _Pragma("unroll") for (int m = 0; m < 4; ++m) _Pragma("unroll") for (int k = 0; k < 2; ++k) dst[m][k] = *(const PG8_LAS bf16x8*)(lds + PG8_SA(b, h) + aoff + m * 2048 + k * 1024); } while (0)
; template <class Epi, class Sched, bool ALIGN_EPI = false, bool SP2 = false>
; __device__ __forceinline__ void gemm_phase(PG8_LAS unsigned char* lds, const Gemm g, const Sched& S, const Epi& E) {
;     ...
;             PG8_LDA(At, 1, 1); PG8_STAGE(PG8_SB(1, 0), b3, voffB); PG8_STAGE(PG8_SB(1, 1), b3 + hstep, voffB); PG8_STAGE(PG8_SA(1, 0), a3, voffA);
	s_mov_b32 m0, s44
	ds_read_b128 v[184:187], v151 offset:49152
	ds_read_b128 v[188:191], v151 offset:50176
	ds_read_b128 v[192:195], v151 offset:51200
	ds_read_b128 v[196:199], v151 offset:52224
	ds_read_b128 v[200:203], v151 offset:53248
	ds_read_b128 v[204:207], v151 offset:54272
	ds_read_b128 v[208:211], v151 offset:55296
	ds_read_b128 v[212:215], v151 offset:56320
	global_load_lds_dwordx4 v250, s[96:97]
	s_add_i32 m0, s44, 0x2000
	s_add_u32 s42, s42, 0x80080

; #define PG8_STAGE(bufoff, gbase, voff) do { _Pragma("unroll") for (int _i = 0; _i < 2; ++_i) \
;         __builtin_amdgcn_global_load_lds((const unsigned*)((const char*)(gbase) + (voff)[_i]), (PG8_LAS unsigned*)(lds + (bufoff) + ldsw + _i * 8192), 16, 0, 0); } while (0)
; #define PG8_LDA(dst, b, h) do { _Pragma("unroll") for (int m = 0; m < 4; ++m) _Pragma("unroll") for (int k = 0; k < 2; ++k) dst[m][k] = *(const PG8_LAS bf16x8*)(lds + PG8_SA(b, h) + aoff + m * 2048 + k * 1024); } while (0)
; template <class Epi, class Sched, bool ALIGN_EPI = false, bool SP2 = false>
; __device__ __forceinline__ void gemm_phase(PG8_LAS unsigned char* lds, const Gemm g, const Sched& S, const Epi& E) {
;     ...
;             PG8_LDA(At, 1, 1); PG8_STAGE(PG8_SB(1, 0), b3, voffB); PG8_STAGE(PG8_SB(1, 1), b3 + hstep, voffB); PG8_STAGE(PG8_SA(1, 0), a3, voffA);
	s_addc_u32 s43, s43, 0
	s_add_i32 s44, s70, s48
	global_load_lds_dwordx4 v251, s[96:97]

; #define PG8_STAGE(bufoff, gbase, voff) do { _Pragma("unroll") for (int _i = 0; _i < 2; ++_i) \
;         __builtin_amdgcn_global_load_lds((const unsigned*)((const char*)(gbase) + (voff)[_i]), (PG8_LAS unsigned*)(lds + (bufoff) + ldsw + _i * 8192), 16, 0, 0); } while (0)
; #define PG8_LDA(dst, b, h) do { _Pragma("unroll") for (int m = 0; m < 4; ++m) _Pragma("unroll") for (int k = 0; k < 2; ++k) dst[m][k] = *(const PG8_LAS bf16x8*)(lds + PG8_SA(b, h) + aoff + m * 2048 + k * 1024); } while (0)
; template <class Epi, class Sched, bool ALIGN_EPI = false, bool SP2 = false>
; __device__ __forceinline__ void gemm_phase(PG8_LAS unsigned char* lds, const Gemm g, const Sched& S, const Epi& E) {
;     ...
;             PG8_LDA(At, 1, 1); PG8_STAGE(PG8_SB(1, 0), b3, voffB); PG8_STAGE(PG8_SB(1, 1), b3 + hstep, voffB); PG8_STAGE(PG8_SA(1, 0), a3, voffA);
	s_mov_b32 m0, s44
	s_nop 0
	global_load_lds_dwordx4 v132, s[42:43]

; #define PG8_STAGE(bufoff, gbase, voff) do { _Pragma("unroll") for (int _i = 0; _i < 2; ++_i) \
;         __builtin_amdgcn_global_load_lds((const unsigned*)((const char*)(gbase) + (voff)[_i]), (PG8_LAS unsigned*)(lds + (bufoff) + ldsw + _i * 8192), 16, 0, 0); } while (0)
; #define PG8_LDA(dst, b, h) do { _Pragma("unroll") for (int m = 0; m < 4; ++m) _Pragma("unroll") for (int k = 0; k < 2; ++k) dst[m][k] = *(const PG8_LAS bf16x8*)(lds + PG8_SA(b, h) + aoff + m * 2048 + k * 1024); } while (0)
; template <class Epi, class Sched, bool ALIGN_EPI = false, bool SP2 = false>
; __device__ __forceinline__ void gemm_phase(PG8_LAS unsigned char* lds, const Gemm g, const Sched& S, const Epi& E) {
;     ...
;             PG8_LDA(At, 1, 1); PG8_STAGE(PG8_SB(1, 0), b3, voffB); PG8_STAGE(PG8_SB(1, 1), b3 + hstep, voffB); PG8_STAGE(PG8_SA(1, 0), a3, voffA);
	s_add_i32 m0, s44, 0x2000
	s_nop 0
	global_load_lds_dwordx4 v128, s[42:43]

; #define PG8_STAGE(bufoff, gbase, voff) do { _Pragma("unroll") for (int _i = 0; _i < 2; ++_i) \
;         __builtin_amdgcn_global_load_lds((const unsigned*)((const char*)(gbase) + (voff)[_i]), (PG8_LAS unsigned*)(lds + (bufoff) + ldsw + _i * 8192), 16, 0, 0); } while (0)
; #define PG8_LDA(dst, b, h) do { _Pragma("unroll") for (int m = 0; m < 4; ++m) _Pragma("unroll") for (int k = 0; k < 2; ++k) dst[m][k] = *(const PG8_LAS bf16x8*)(lds + PG8_SA(b, h) + aoff + m * 2048 + k * 1024); } while (0)
; template <class Epi, class Sched, bool ALIGN_EPI = false, bool SP2 = false>
; __device__ __forceinline__ void gemm_phase(PG8_LAS unsigned char* lds, const Gemm g, const Sched& S, const Epi& E) {
;     ...
;             PG8_LDA(At, 1, 1); PG8_STAGE(PG8_SB(1, 0), b3, voffB); PG8_STAGE(PG8_SB(1, 1), b3 + hstep, voffB); PG8_STAGE(PG8_SA(1, 0), a3, voffA);
	s_mov_b32 m0, s55
	s_nop 0
	global_load_lds_dwordx4 v252, s[98:99]

; #define PG8_STAGE(bufoff, gbase, voff) do { _Pragma("unroll") for (int _i = 0; _i < 2; ++_i) \
;         __builtin_amdgcn_global_load_lds((const unsigned*)((const char*)(gbase) + (voff)[_i]), (PG8_LAS unsigned*)(lds + (bufoff) + ldsw + _i * 8192), 16, 0, 0); } while (0)
; #define PG8_LDA(dst, b, h) do { _Pragma("unroll") for (int m = 0; m < 4; ++m) _Pragma("unroll") for (int k = 0; k < 2; ++k) dst[m][k] = *(const PG8_LAS bf16x8*)(lds + PG8_SA(b, h) + aoff + m * 2048 + k * 1024); } while (0)
; #define PG8_MMA(ai, bj, At, Bt) do { __builtin_amdgcn_s_setprio(1); _Pragma("unroll") for (int m = 0; m < 4; ++m) _Pragma("unroll") for (int n = 0; n < 2; ++n) _Pragma("unroll") for (int k = 0; k < 2; ++k) \
;         acc[ai][bj][m][n] = __builtin_amdgcn_mfma_f32_16x16x32_bf16(Bt[n][k], At[m][k], acc[ai][bj][m][n], 0, 0, 0); __builtin_amdgcn_s_setprio(0); } while (0)
; #define PG8_WAIT_V(n) asm volatile("s_waitcnt vmcnt(" #n ")" ::: "memory")
; #define PG8_WAIT_L(n) asm volatile("s_waitcnt lgkmcnt(" #n ")" ::: "memory")
; #define PG8_BAR __builtin_amdgcn_s_barrier()
; #define PG8_SCHED __builtin_amdgcn_sched_barrier(0)
; template <class Epi, class Sched, bool ALIGN_EPI = false, bool SP2 = false>
; __device__ __forceinline__ void gemm_phase(PG8_LAS unsigned char* lds, const Gemm g, const Sched& S, const Epi& E) {
;     ...
;             PG8_LDA(At, 1, 1); PG8_STAGE(PG8_SB(1, 0), b3, voffB); PG8_STAGE(PG8_SB(1, 1), b3 + hstep, voffB); PG8_STAGE(PG8_SA(1, 0), a3, voffA);
;             PG8_WAIT_V(8); PG8_WAIT_L(0); PG8_BAR; PG8_MMA(1, 0, At, B0); PG8_MMA(1, 1, At, B1); PG8_BAR; PG8_SCHED;
	s_mov_b32 m0, s56
	s_nop 0
	global_load_lds_dwordx4 v253, s[98:99]
	s_waitcnt vmcnt(8)
	s_waitcnt lgkmcnt(0)
	s_setprio 1
	s_barrier

; #define PG8_MMA(ai, bj, At, Bt) do { __builtin_amdgcn_s_setprio(1); _Pragma("unroll") for (int m = 0; m < 4; ++m) _Pragma("unroll") for (int n = 0; n < 2; ++n) _Pragma("unroll") for (int k = 0; k < 2; ++k) \
;         acc[ai][bj][m][n] = __builtin_amdgcn_mfma_f32_16x16x32_bf16(Bt[n][k], At[m][k], acc[ai][bj][m][n], 0, 0, 0); __builtin_amdgcn_s_setprio(0); } while (0)
; #define PG8_WAIT_V(n) asm volatile("s_waitcnt vmcnt(" #n ")" ::: "memory")
; #define PG8_WAIT_L(n) asm volatile("s_waitcnt lgkmcnt(" #n ")" ::: "memory")
; #define PG8_BAR __builtin_amdgcn_s_barrier()
; #define PG8_SCHED __builtin_amdgcn_sched_barrier(0)
; template <class Epi, class Sched, bool ALIGN_EPI = false, bool SP2 = false>
; __device__ __forceinline__ void gemm_phase(PG8_LAS unsigned char* lds, const Gemm g, const Sched& S, const Epi& E) {
;     ...
;             PG8_WAIT_V(8); PG8_WAIT_L(0); PG8_BAR; PG8_MMA(1, 0, At, B0); PG8_MMA(1, 1, At, B1); PG8_BAR; PG8_SCHED;
	v_mfma_f32_16x16x32_bf16 v[60:63], v[152:155], v[184:187], v[60:63]
	v_mfma_f32_16x16x32_bf16 v[56:59], v[160:163], v[184:187], v[56:59]
	v_mfma_f32_16x16x32_bf16 v[52:55], v[152:155], v[192:195], v[52:55]
	v_mfma_f32_16x16x32_bf16 v[48:51], v[160:163], v[192:195], v[48:51]
	v_mfma_f32_16x16x32_bf16 v[36:39], v[152:155], v[200:203], v[36:39]
	v_mfma_f32_16x16x32_bf16 v[32:35], v[160:163], v[200:203], v[32:35]
	v_mfma_f32_16x16x32_bf16 v[20:23], v[152:155], v[208:211], v[20:23]
	v_mfma_f32_16x16x32_bf16 v[16:19], v[160:163], v[208:211], v[16:19]
	v_mfma_f32_16x16x32_bf16 v[60:63], v[156:159], v[188:191], v[60:63]
	v_mfma_f32_16x16x32_bf16 v[56:59], v[164:167], v[188:191], v[56:59]
	v_mfma_f32_16x16x32_bf16 v[52:55], v[156:159], v[196:199], v[52:55]
	v_mfma_f32_16x16x32_bf16 v[48:51], v[164:167], v[196:199], v[48:51]
	v_mfma_f32_16x16x32_bf16 v[36:39], v[156:159], v[204:207], v[36:39]
	v_mfma_f32_16x16x32_bf16 v[32:35], v[164:167], v[204:207], v[32:35]
	v_mfma_f32_16x16x32_bf16 v[20:23], v[156:159], v[212:215], v[20:23]
	v_mfma_f32_16x16x32_bf16 v[16:19], v[164:167], v[212:215], v[16:19]


; #define PG8_STAGE(bufoff, gbase, voff) do { _Pragma("unroll") for (int _i = 0; _i < 2; ++_i) \
;         __builtin_amdgcn_global_load_lds((const unsigned*)((const char*)(gbase) + (voff)[_i]), (PG8_LAS unsigned*)(lds + (bufoff) + ldsw + _i * 8192), 16, 0, 0); } while (0)
; #define PG8_LDA(dst, b, h) do { _Pragma("unroll") for (int m = 0; m < 4; ++m) _Pragma("unroll") for (int k = 0; k < 2; ++k) dst[m][k] = *(const PG8_LAS bf16x8*)(lds + PG8_SA(b, h) + aoff + m * 2048 + k * 1024); } while (0)
; #define PG8_LDB(dst, b, h) do { _Pragma("unroll") for (int n = 0; n < 2; ++n) _Pragma("unroll") for (int k = 0; k < 2; ++k) dst[n][k] = *(const PG8_LAS bf16x8*)(lds + PG8_SB(b, h) + boff + n * 2048 + k * 1024); } while (0)
; template <class Epi, class Sched, bool ALIGN_EPI = false, bool SP2 = false>
; __device__ __forceinline__ void gemm_phase(PG8_LAS unsigned char* lds, const Gemm g, const Sched& S, const Epi& E) {
;     ...
;             PG8_WAIT_V(8); PG8_WAIT_L(0); PG8_BAR; PG8_MMA(1, 0, At, B0); PG8_MMA(1, 1, At, B1); PG8_BAR; PG8_SCHED;
;             } else {
;             PG8_LDB(B0, 0, 0); PG8_SCHED; PG8_LDA(At, 0, 0); PG8_STAGE(PG8_SA(1, 1), a1 + hstep, voffA);
;             PG8_WAIT_L(8); PG8_BAR; PG8_WAIT_L(0); PG8_MMA(0, 0, At, B0); PG8_BAR; PG8_SCHED;
;             PG8_LDB(B1, 0, 1); PG8_STAGE(PG8_SB(0, 0), b2, voffB);
;             PG8_BAR; PG8_WAIT_L(0); PG8_MMA(0, 1, At, B1); PG8_BAR;
;             PG8_LDA(At, 0, 1); PG8_STAGE(PG8_SA(0, 0), a2, voffA);
;             PG8_BAR; PG8_WAIT_L(0); PG8_MMA(1, 0, At, B0); PG8_BAR; PG8_SCHED;
;             PG8_STAGE(PG8_SB(0, 1), b2 + hstep, voffB);
;             PG8_WAIT_V(6); PG8_BAR; PG8_MMA(1, 1, At, B1); PG8_BAR;
;             PG8_LDB(B0, 1, 0); PG8_SCHED; PG8_LDA(At, 1, 0); PG8_STAGE(PG8_SA(0, 1), a2 + hstep, voffA);
;             PG8_WAIT_L(8); PG8_BAR; PG8_WAIT_L(0); PG8_MMA(0, 0, At, B0); PG8_BAR; PG8_SCHED;
;             PG8_LDB(B1, 1, 1); PG8_STAGE(PG8_SB(1, 0), b3, voffB);
;             PG8_BAR; PG8_WAIT_L(0); PG8_MMA(0, 1, At, B1); PG8_BAR;
;             PG8_LDA(At, 1, 1); PG8_STAGE(PG8_SA(1, 0), a3, voffA);
;             PG8_BAR; PG8_WAIT_L(0); PG8_MMA(1, 0, At, B0); PG8_BAR; PG8_SCHED;
;             PG8_STAGE(PG8_SB(1, 1), b3 + hstep, voffB);
;             PG8_WAIT_V(6); PG8_BAR; PG8_MMA(1, 1, At, B1); PG8_BAR;
;             }
;         }
;         if constexpr (ALIGN_EPI) { if (wr == 0) PG8_BAR; }
	v_mfma_f32_16x16x32_bf16 v[44:47], v[168:171], v[184:187], v[44:47]
	v_mfma_f32_16x16x32_bf16 v[40:43], v[176:179], v[184:187], v[40:43]
	v_mfma_f32_16x16x32_bf16 v[28:31], v[168:171], v[192:195], v[28:31]
	v_mfma_f32_16x16x32_bf16 v[24:27], v[176:179], v[192:195], v[24:27]
	v_mfma_f32_16x16x32_bf16 v[12:15], v[168:171], v[200:203], v[12:15]
	v_mfma_f32_16x16x32_bf16 v[8:11], v[176:179], v[200:203], v[8:11]
	v_mfma_f32_16x16x32_bf16 v[4:7], v[168:171], v[208:211], v[4:7]
	v_mfma_f32_16x16x32_bf16 v[0:3], v[176:179], v[208:211], v[0:3]
	v_mfma_f32_16x16x32_bf16 v[44:47], v[172:175], v[188:191], v[44:47]
	v_mfma_f32_16x16x32_bf16 v[40:43], v[180:183], v[188:191], v[40:43]
	v_mfma_f32_16x16x32_bf16 v[28:31], v[172:175], v[196:199], v[28:31]
	v_mfma_f32_16x16x32_bf16 v[24:27], v[180:183], v[196:199], v[24:27]
	v_mfma_f32_16x16x32_bf16 v[12:15], v[172:175], v[204:207], v[12:15]
	v_mfma_f32_16x16x32_bf16 v[8:11], v[180:183], v[204:207], v[8:11]
	v_mfma_f32_16x16x32_bf16 v[4:7], v[172:175], v[212:215], v[4:7]
	v_mfma_f32_16x16x32_bf16 v[0:3], v[180:183], v[212:215], v[0:3]
	s_setprio 0
	s_barrier
	s_add_i32 s68, s68, 2
	s_add_u32 s40, s40, 0x100
	s_addc_u32 s41, s41, 0
	s_add_u32 s65, s65, 0x100
	s_addc_u32 s67, s67, 0
	s_cmp_gt_u32 s68, 29
	s_cbranch_scc0 .LBB0_66
	s_and_b64 vcc, exec, s[26:27]
	s_cbranch_vccz .LBB0_69
	s_barrier

; #define PG8_STAGE(bufoff, gbase, voff) do { _Pragma("unroll") for (int _i = 0; _i < 2; ++_i) \
;         __builtin_amdgcn_global_load_lds((const unsigned*)((const char*)(gbase) + (voff)[_i]), (PG8_LAS unsigned*)(lds + (bufoff) + ldsw + _i * 8192), 16, 0, 0); } while (0)
; #define PG8_LDA(dst, b, h) do { _Pragma("unroll") for (int m = 0; m < 4; ++m) _Pragma("unroll") for (int k = 0; k < 2; ++k) dst[m][k] = *(const PG8_LAS bf16x8*)(lds + PG8_SA(b, h) + aoff + m * 2048 + k * 1024); } while (0)
; #define PG8_LDB(dst, b, h) do { _Pragma("unroll") for (int n = 0; n < 2; ++n) _Pragma("unroll") for (int k = 0; k < 2; ++k) dst[n][k] = *(const PG8_LAS bf16x8*)(lds + PG8_SB(b, h) + boff + n * 2048 + k * 1024); } while (0)
; #define PG8_SCHED __builtin_amdgcn_sched_barrier(0)
; template <class Epi, class Sched, bool ALIGN_EPI = false, bool SP2 = false>
; __device__ __forceinline__ void gemm_phase(PG8_LAS unsigned char* lds, const Gemm g, const Sched& S, const Epi& E) {
;     ...
;         for (int t = 0; t < nt; t += 2) {
;             const bool last = (t == nt - 2);
;             const char* a1 = cA + (size_t)(t + 1) * kstep;
;             const char* a2 = last ? nA : cA + (size_t)(t + 2) * kstep; const char* b2 = last ? nB : cB + (size_t)(t + 2) * kstep;
;             const char* a3 = a2 + kstep; const char* b3 = b2 + kstep;
;             if (last && has_next) S.a_ready(nxt);
;             if constexpr (SP2) {
;             PG8_LDB(B0, 0, 0); PG8_LDB(B1, 0, 1); PG8_SCHED; PG8_LDA(At, 0, 0); PG8_STAGE(PG8_SA(1, 1), a1 + hstep, voffA);
.LBB0_333:
	ds_read_b128 v[64:67], v211
	ds_read_b128 v[68:71], v211 offset:1024
	ds_read_b128 v[72:75], v211 offset:2048
	ds_read_b128 v[76:79], v211 offset:3072
	ds_read_b128 v[144:147], v212
	ds_read_b128 v[148:151], v212 offset:1024
	ds_read_b128 v[152:155], v212 offset:2048
	ds_read_b128 v[156:159], v212 offset:3072
	s_add_u32 s60, s58, 0xfff80080
	s_addc_u32 s61, s59, -1
	s_cmp_eq_u32 s81, 28
	s_cselect_b32 s63, s11, s61
	s_cselect_b32 s62, s51, s60
	s_cselect_b32 s61, s49, s80
	s_cselect_b32 s60, s78, s79

; #define PG8_STAGE(bufoff, gbase, voff) do { _Pragma("unroll") for (int _i = 0; _i < 2; ++_i) \
;         __builtin_amdgcn_global_load_lds((const unsigned*)((const char*)(gbase) + (voff)[_i]), (PG8_LAS unsigned*)(lds + (bufoff) + ldsw + _i * 8192), 16, 0, 0); } while (0)
; #define PG8_LDA(dst, b, h) do { _Pragma("unroll") for (int m = 0; m < 4; ++m) _Pragma("unroll") for (int k = 0; k < 2; ++k) dst[m][k] = *(const PG8_LAS bf16x8*)(lds + PG8_SA(b, h) + aoff + m * 2048 + k * 1024); } while (0)
; #define PG8_LDB(dst, b, h) do { _Pragma("unroll") for (int n = 0; n < 2; ++n) _Pragma("unroll") for (int k = 0; k < 2; ++k) dst[n][k] = *(const PG8_LAS bf16x8*)(lds + PG8_SB(b, h) + boff + n * 2048 + k * 1024); } while (0)
; #define PG8_SCHED __builtin_amdgcn_sched_barrier(0)
; template <class Epi, class Sched, bool ALIGN_EPI = false, bool SP2 = false>
; __device__ __forceinline__ void gemm_phase(PG8_LAS unsigned char* lds, const Gemm g, const Sched& S, const Epi& E) {
;     ...
;             PG8_LDB(B0, 0, 0); PG8_LDB(B1, 0, 1); PG8_SCHED; PG8_LDA(At, 0, 0); PG8_STAGE(PG8_SA(1, 1), a1 + hstep, voffA);
	s_add_i32 m0, s57, 0xc000
	ds_read_b128 v[176:179], v213
	ds_read_b128 v[180:183], v213 offset:1024
	ds_read_b128 v[184:187], v213 offset:2048
	ds_read_b128 v[188:191], v213 offset:3072
	ds_read_b128 v[192:195], v213 offset:4096
	ds_read_b128 v[196:199], v213 offset:5120
	ds_read_b128 v[200:203], v213 offset:6144
	ds_read_b128 v[204:207], v213 offset:7168
	global_load_lds_dwordx4 v168, s[58:59]

; #define PG8_STAGE(bufoff, gbase, voff) do { _Pragma("unroll") for (int _i = 0; _i < 2; ++_i) \
;         __builtin_amdgcn_global_load_lds((const unsigned*)((const char*)(gbase) + (voff)[_i]), (PG8_LAS unsigned*)(lds + (bufoff) + ldsw + _i * 8192), 16, 0, 0); } while (0)
; #define PG8_LDA(dst, b, h) do { _Pragma("unroll") for (int m = 0; m < 4; ++m) _Pragma("unroll") for (int k = 0; k < 2; ++k) dst[m][k] = *(const PG8_LAS bf16x8*)(lds + PG8_SA(b, h) + aoff + m * 2048 + k * 1024); } while (0)
; #define PG8_LDB(dst, b, h) do { _Pragma("unroll") for (int n = 0; n < 2; ++n) _Pragma("unroll") for (int k = 0; k < 2; ++k) dst[n][k] = *(const PG8_LAS bf16x8*)(lds + PG8_SB(b, h) + boff + n * 2048 + k * 1024); } while (0)
; #define PG8_MMA(ai, bj, At, Bt) do { __builtin_amdgcn_s_setprio(1); _Pragma("unroll") for (int m = 0; m < 4; ++m) _Pragma("unroll") for (int n = 0; n < 2; ++n) _Pragma("unroll") for (int k = 0; k < 2; ++k) \
;         acc[ai][bj][m][n] = __builtin_amdgcn_mfma_f32_16x16x32_bf16(Bt[n][k], At[m][k], acc[ai][bj][m][n], 0, 0, 0); __builtin_amdgcn_s_setprio(0); } while (0)
; #define PG8_WAIT_V(n) asm volatile("s_waitcnt vmcnt(" #n ")" ::: "memory")
; #define PG8_WAIT_L(n) asm volatile("s_waitcnt lgkmcnt(" #n ")" ::: "memory")
; #define PG8_BAR __builtin_amdgcn_s_barrier()
; #define PG8_SCHED __builtin_amdgcn_sched_barrier(0)
; template <class Epi, class Sched, bool ALIGN_EPI = false, bool SP2 = false>
; __device__ __forceinline__ void gemm_phase(PG8_LAS unsigned char* lds, const Gemm g, const Sched& S, const Epi& E) {
;     ...
;             PG8_LDB(B0, 0, 0); PG8_LDB(B1, 0, 1); PG8_SCHED; PG8_LDA(At, 0, 0); PG8_STAGE(PG8_SA(1, 1), a1 + hstep, voffA);
;             PG8_WAIT_V(8); PG8_WAIT_L(0); PG8_BAR; PG8_MMA(0, 0, At, B0); PG8_MMA(0, 1, At, B1); PG8_BAR; PG8_SCHED;
	s_add_i32 m0, s57, 0xe000
	s_nop 0
	global_load_lds_dwordx4 v170, s[58:59]
	s_waitcnt vmcnt(8)
	s_waitcnt lgkmcnt(0)
	s_setprio 1
	s_barrier

; #define PG8_MMA(ai, bj, At, Bt) do { __builtin_amdgcn_s_setprio(1); _Pragma("unroll") for (int m = 0; m < 4; ++m) _Pragma("unroll") for (int n = 0; n < 2; ++n) _Pragma("unroll") for (int k = 0; k < 2; ++k) \
;         acc[ai][bj][m][n] = __builtin_amdgcn_mfma_f32_16x16x32_bf16(Bt[n][k], At[m][k], acc[ai][bj][m][n], 0, 0, 0); __builtin_amdgcn_s_setprio(0); } while (0)
; #define PG8_WAIT_V(n) asm volatile("s_waitcnt vmcnt(" #n ")" ::: "memory")
; #define PG8_WAIT_L(n) asm volatile("s_waitcnt lgkmcnt(" #n ")" ::: "memory")
; #define PG8_BAR __builtin_amdgcn_s_barrier()
; #define PG8_SCHED __builtin_amdgcn_sched_barrier(0)
; template <class Epi, class Sched, bool ALIGN_EPI = false, bool SP2 = false>
; __device__ __forceinline__ void gemm_phase(PG8_LAS unsigned char* lds, const Gemm g, const Sched& S, const Epi& E) {
;     ...
;             PG8_WAIT_V(8); PG8_WAIT_L(0); PG8_BAR; PG8_MMA(0, 0, At, B0); PG8_MMA(0, 1, At, B1); PG8_BAR; PG8_SCHED;
	v_mfma_f32_16x16x32_bf16 v[140:143], v[64:67], v[176:179], v[140:143]
	v_mfma_f32_16x16x32_bf16 v[136:139], v[72:75], v[176:179], v[136:139]
	v_mfma_f32_16x16x32_bf16 v[124:127], v[64:67], v[184:187], v[124:127]
	v_mfma_f32_16x16x32_bf16 v[120:123], v[72:75], v[184:187], v[120:123]
	v_mfma_f32_16x16x32_bf16 v[108:111], v[64:67], v[192:195], v[108:111]
	v_mfma_f32_16x16x32_bf16 v[104:107], v[72:75], v[192:195], v[104:107]
	v_mfma_f32_16x16x32_bf16 v[92:95], v[64:67], v[200:203], v[92:95]
	v_mfma_f32_16x16x32_bf16 v[88:91], v[72:75], v[200:203], v[88:91]
	v_mfma_f32_16x16x32_bf16 v[140:143], v[68:71], v[180:183], v[140:143]
	v_mfma_f32_16x16x32_bf16 v[136:139], v[76:79], v[180:183], v[136:139]
	v_mfma_f32_16x16x32_bf16 v[124:127], v[68:71], v[188:191], v[124:127]
	v_mfma_f32_16x16x32_bf16 v[120:123], v[76:79], v[188:191], v[120:123]
	v_mfma_f32_16x16x32_bf16 v[108:111], v[68:71], v[196:199], v[108:111]
	v_mfma_f32_16x16x32_bf16 v[104:107], v[76:79], v[196:199], v[104:107]
	v_mfma_f32_16x16x32_bf16 v[92:95], v[68:71], v[204:207], v[92:95]
	v_mfma_f32_16x16x32_bf16 v[88:91], v[76:79], v[204:207], v[88:91]


; #define PG8_STAGE(bufoff, gbase, voff) do { _Pragma("unroll") for (int _i = 0; _i < 2; ++_i) \
;         __builtin_amdgcn_global_load_lds((const unsigned*)((const char*)(gbase) + (voff)[_i]), (PG8_LAS unsigned*)(lds + (bufoff) + ldsw + _i * 8192), 16, 0, 0); } while (0)
; #define PG8_LDA(dst, b, h) do { _Pragma("unroll") for (int m = 0; m < 4; ++m) _Pragma("unroll") for (int k = 0; k < 2; ++k) dst[m][k] = *(const PG8_LAS bf16x8*)(lds + PG8_SA(b, h) + aoff + m * 2048 + k * 1024); } while (0)
; #define PG8_MMA(ai, bj, At, Bt) do { __builtin_amdgcn_s_setprio(1); _Pragma("unroll") for (int m = 0; m < 4; ++m) _Pragma("unroll") for (int n = 0; n < 2; ++n) _Pragma("unroll") for (int k = 0; k < 2; ++k) \
;         acc[ai][bj][m][n] = __builtin_amdgcn_mfma_f32_16x16x32_bf16(Bt[n][k], At[m][k], acc[ai][bj][m][n], 0, 0, 0); __builtin_amdgcn_s_setprio(0); } while (0)
; #define PG8_WAIT_V(n) asm volatile("s_waitcnt vmcnt(" #n ")" ::: "memory")
; #define PG8_WAIT_L(n) asm volatile("s_waitcnt lgkmcnt(" #n ")" ::: "memory")
; #define PG8_BAR __builtin_amdgcn_s_barrier()
; #define PG8_SCHED __builtin_amdgcn_sched_barrier(0)
; template <class Epi, class Sched, bool ALIGN_EPI = false, bool SP2 = false>
; __device__ __forceinline__ void gemm_phase(PG8_LAS unsigned char* lds, const Gemm g, const Sched& S, const Epi& E) {
;     ...
;             PG8_WAIT_V(8); PG8_WAIT_L(0); PG8_BAR; PG8_MMA(0, 0, At, B0); PG8_MMA(0, 1, At, B1); PG8_BAR; PG8_SCHED;
;             PG8_LDA(At, 0, 1); PG8_STAGE(PG8_SB(0, 0), b2, voffB); PG8_STAGE(PG8_SB(0, 1), b2 + hstep, voffB); PG8_STAGE(PG8_SA(0, 0), a2, voffA);
	v_mfma_f32_16x16x32_bf16 v[132:135], v[144:147], v[176:179], v[132:135]
	v_mfma_f32_16x16x32_bf16 v[128:131], v[152:155], v[176:179], v[128:131]
	v_mfma_f32_16x16x32_bf16 v[116:119], v[144:147], v[184:187], v[116:119]
	v_mfma_f32_16x16x32_bf16 v[112:115], v[152:155], v[184:187], v[112:115]
	v_mfma_f32_16x16x32_bf16 v[100:103], v[144:147], v[192:195], v[100:103]
	v_mfma_f32_16x16x32_bf16 v[96:99], v[152:155], v[192:195], v[96:99]
	v_mfma_f32_16x16x32_bf16 v[84:87], v[144:147], v[200:203], v[84:87]
	v_mfma_f32_16x16x32_bf16 v[80:83], v[152:155], v[200:203], v[80:83]
	v_mfma_f32_16x16x32_bf16 v[132:135], v[148:151], v[180:183], v[132:135]
	v_mfma_f32_16x16x32_bf16 v[128:131], v[156:159], v[180:183], v[128:131]
	v_mfma_f32_16x16x32_bf16 v[116:119], v[148:151], v[188:191], v[116:119]
	v_mfma_f32_16x16x32_bf16 v[112:115], v[156:159], v[188:191], v[112:115]
	v_mfma_f32_16x16x32_bf16 v[100:103], v[148:151], v[196:199], v[100:103]
	v_mfma_f32_16x16x32_bf16 v[96:99], v[156:159], v[196:199], v[96:99]
	v_mfma_f32_16x16x32_bf16 v[84:87], v[148:151], v[204:207], v[84:87]
	v_mfma_f32_16x16x32_bf16 v[80:83], v[156:159], v[204:207], v[80:83]
	s_setprio 0
	s_barrier
	s_add_i32 s82, s75, s64
	s_mov_b64 s[96:97], s[60:61]

; #define PG8_STAGE(bufoff, gbase, voff) do { _Pragma("unroll") for (int _i = 0; _i < 2; ++_i) \
;         __builtin_amdgcn_global_load_lds((const unsigned*)((const char*)(gbase) + (voff)[_i]), (PG8_LAS unsigned*)(lds + (bufoff) + ldsw + _i * 8192), 16, 0, 0); } while (0)
; #define PG8_LDA(dst, b, h) do { _Pragma("unroll") for (int m = 0; m < 4; ++m) _Pragma("unroll") for (int k = 0; k < 2; ++k) dst[m][k] = *(const PG8_LAS bf16x8*)(lds + PG8_SA(b, h) + aoff + m * 2048 + k * 1024); } while (0)
; template <class Epi, class Sched, bool ALIGN_EPI = false, bool SP2 = false>
; __device__ __forceinline__ void gemm_phase(PG8_LAS unsigned char* lds, const Gemm g, const Sched& S, const Epi& E) {
;     ...
;             PG8_LDA(At, 0, 1); PG8_STAGE(PG8_SB(0, 0), b2, voffB); PG8_STAGE(PG8_SB(0, 1), b2 + hstep, voffB); PG8_STAGE(PG8_SA(0, 0), a2, voffA);
	s_mov_b32 m0, s82
	ds_read_b128 v[176:179], v213 offset:16384
	ds_read_b128 v[180:183], v213 offset:17408
	ds_read_b128 v[184:187], v213 offset:18432
	ds_read_b128 v[188:191], v213 offset:19456
	ds_read_b128 v[192:195], v213 offset:20480
	ds_read_b128 v[196:199], v213 offset:21504
	ds_read_b128 v[200:203], v213 offset:22528
	ds_read_b128 v[204:207], v213 offset:23552
	global_load_lds_dwordx4 v162, s[60:61]
	s_add_i32 m0, s82, 0x2000
	s_add_u32 s82, s60, 0x80000

; #define PG8_STAGE(bufoff, gbase, voff) do { _Pragma("unroll") for (int _i = 0; _i < 2; ++_i) \
;         __builtin_amdgcn_global_load_lds((const unsigned*)((const char*)(gbase) + (voff)[_i]), (PG8_LAS unsigned*)(lds + (bufoff) + ldsw + _i * 8192), 16, 0, 0); } while (0)
; #define PG8_LDA(dst, b, h) do { _Pragma("unroll") for (int m = 0; m < 4; ++m) _Pragma("unroll") for (int k = 0; k < 2; ++k) dst[m][k] = *(const PG8_LAS bf16x8*)(lds + PG8_SA(b, h) + aoff + m * 2048 + k * 1024); } while (0)
; template <class Epi, class Sched, bool ALIGN_EPI = false, bool SP2 = false>
; __device__ __forceinline__ void gemm_phase(PG8_LAS unsigned char* lds, const Gemm g, const Sched& S, const Epi& E) {
;     ...
;             PG8_LDA(At, 0, 1); PG8_STAGE(PG8_SB(0, 0), b2, voffB); PG8_STAGE(PG8_SB(0, 1), b2 + hstep, voffB); PG8_STAGE(PG8_SA(0, 0), a2, voffA);
	s_addc_u32 s83, s61, 0
	s_add_i32 s84, s76, s64
	global_load_lds_dwordx4 v166, s[60:61]

; #define PG8_STAGE(bufoff, gbase, voff) do { _Pragma("unroll") for (int _i = 0; _i < 2; ++_i) \
;         __builtin_amdgcn_global_load_lds((const unsigned*)((const char*)(gbase) + (voff)[_i]), (PG8_LAS unsigned*)(lds + (bufoff) + ldsw + _i * 8192), 16, 0, 0); } while (0)
; #define PG8_LDA(dst, b, h) do { _Pragma("unroll") for (int m = 0; m < 4; ++m) _Pragma("unroll") for (int k = 0; k < 2; ++k) dst[m][k] = *(const PG8_LAS bf16x8*)(lds + PG8_SA(b, h) + aoff + m * 2048 + k * 1024); } while (0)
; template <class Epi, class Sched, bool ALIGN_EPI = false, bool SP2 = false>
; __device__ __forceinline__ void gemm_phase(PG8_LAS unsigned char* lds, const Gemm g, const Sched& S, const Epi& E) {
;     ...
;             PG8_LDA(At, 0, 1); PG8_STAGE(PG8_SB(0, 0), b2, voffB); PG8_STAGE(PG8_SB(0, 1), b2 + hstep, voffB); PG8_STAGE(PG8_SA(0, 0), a2, voffA);
	s_mov_b32 m0, s84
	s_nop 0
	global_load_lds_dwordx4 v162, s[82:83]

; #define PG8_STAGE(bufoff, gbase, voff) do { _Pragma("unroll") for (int _i = 0; _i < 2; ++_i) \
;         __builtin_amdgcn_global_load_lds((const unsigned*)((const char*)(gbase) + (voff)[_i]), (PG8_LAS unsigned*)(lds + (bufoff) + ldsw + _i * 8192), 16, 0, 0); } while (0)
; #define PG8_LDA(dst, b, h) do { _Pragma("unroll") for (int m = 0; m < 4; ++m) _Pragma("unroll") for (int k = 0; k < 2; ++k) dst[m][k] = *(const PG8_LAS bf16x8*)(lds + PG8_SA(b, h) + aoff + m * 2048 + k * 1024); } while (0)
; template <class Epi, class Sched, bool ALIGN_EPI = false, bool SP2 = false>
; __device__ __forceinline__ void gemm_phase(PG8_LAS unsigned char* lds, const Gemm g, const Sched& S, const Epi& E) {
;     ...
;             PG8_LDA(At, 0, 1); PG8_STAGE(PG8_SB(0, 0), b2, voffB); PG8_STAGE(PG8_SB(0, 1), b2 + hstep, voffB); PG8_STAGE(PG8_SA(0, 0), a2, voffA);
	s_add_i32 m0, s84, 0x2000
	s_nop 0
	global_load_lds_dwordx4 v166, s[82:83]
	s_mov_b64 s[98:99], s[62:63]

; #define PG8_STAGE(bufoff, gbase, voff) do { _Pragma("unroll") for (int _i = 0; _i < 2; ++_i) \
;         __builtin_amdgcn_global_load_lds((const unsigned*)((const char*)(gbase) + (voff)[_i]), (PG8_LAS unsigned*)(lds + (bufoff) + ldsw + _i * 8192), 16, 0, 0); } while (0)
; #define PG8_LDA(dst, b, h) do { _Pragma("unroll") for (int m = 0; m < 4; ++m) _Pragma("unroll") for (int k = 0; k < 2; ++k) dst[m][k] = *(const PG8_LAS bf16x8*)(lds + PG8_SA(b, h) + aoff + m * 2048 + k * 1024); } while (0)
; #define PG8_MMA(ai, bj, At, Bt) do { __builtin_amdgcn_s_setprio(1); _Pragma("unroll") for (int m = 0; m < 4; ++m) _Pragma("unroll") for (int n = 0; n < 2; ++n) _Pragma("unroll") for (int k = 0; k < 2; ++k) \
;         acc[ai][bj][m][n] = __builtin_amdgcn_mfma_f32_16x16x32_bf16(Bt[n][k], At[m][k], acc[ai][bj][m][n], 0, 0, 0); __builtin_amdgcn_s_setprio(0); } while (0)
; #define PG8_WAIT_V(n) asm volatile("s_waitcnt vmcnt(" #n ")" ::: "memory")
; #define PG8_WAIT_L(n) asm volatile("s_waitcnt lgkmcnt(" #n ")" ::: "memory")
; #define PG8_BAR __builtin_amdgcn_s_barrier()
; #define PG8_SCHED __builtin_amdgcn_sched_barrier(0)
; template <class Epi, class Sched, bool ALIGN_EPI = false, bool SP2 = false>
; __device__ __forceinline__ void gemm_phase(PG8_LAS unsigned char* lds, const Gemm g, const Sched& S, const Epi& E) {
;     ...
;             PG8_LDA(At, 0, 1); PG8_STAGE(PG8_SB(0, 0), b2, voffB); PG8_STAGE(PG8_SB(0, 1), b2 + hstep, voffB); PG8_STAGE(PG8_SA(0, 0), a2, voffA);
;             PG8_WAIT_V(8); PG8_WAIT_L(0); PG8_BAR; PG8_MMA(1, 0, At, B0); PG8_MMA(1, 1, At, B1); PG8_BAR; PG8_SCHED;
	s_mov_b32 m0, s57
	s_nop 0
	global_load_lds_dwordx4 v160, s[62:63]
	s_mov_b32 m0, s65
	s_nop 0
	global_load_lds_dwordx4 v164, s[62:63]
	s_waitcnt vmcnt(8)
	s_waitcnt lgkmcnt(0)
	s_setprio 1
	s_barrier

; #define PG8_MMA(ai, bj, At, Bt) do { __builtin_amdgcn_s_setprio(1); _Pragma("unroll") for (int m = 0; m < 4; ++m) _Pragma("unroll") for (int n = 0; n < 2; ++n) _Pragma("unroll") for (int k = 0; k < 2; ++k) \
;         acc[ai][bj][m][n] = __builtin_amdgcn_mfma_f32_16x16x32_bf16(Bt[n][k], At[m][k], acc[ai][bj][m][n], 0, 0, 0); __builtin_amdgcn_s_setprio(0); } while (0)
; #define PG8_WAIT_V(n) asm volatile("s_waitcnt vmcnt(" #n ")" ::: "memory")
; #define PG8_WAIT_L(n) asm volatile("s_waitcnt lgkmcnt(" #n ")" ::: "memory")
; #define PG8_BAR __builtin_amdgcn_s_barrier()
; #define PG8_SCHED __builtin_amdgcn_sched_barrier(0)
; template <class Epi, class Sched, bool ALIGN_EPI = false, bool SP2 = false>
; __device__ __forceinline__ void gemm_phase(PG8_LAS unsigned char* lds, const Gemm g, const Sched& S, const Epi& E) {
;     ...
;             PG8_WAIT_V(8); PG8_WAIT_L(0); PG8_BAR; PG8_MMA(1, 0, At, B0); PG8_MMA(1, 1, At, B1); PG8_BAR; PG8_SCHED;
	v_mfma_f32_16x16x32_bf16 v[60:63], v[64:67], v[176:179], v[60:63]
	v_mfma_f32_16x16x32_bf16 v[56:59], v[72:75], v[176:179], v[56:59]
	v_mfma_f32_16x16x32_bf16 v[44:47], v[64:67], v[184:187], v[44:47]
	v_mfma_f32_16x16x32_bf16 v[40:43], v[72:75], v[184:187], v[40:43]
	v_mfma_f32_16x16x32_bf16 v[28:31], v[64:67], v[192:195], v[28:31]
	v_mfma_f32_16x16x32_bf16 v[24:27], v[72:75], v[192:195], v[24:27]
	v_mfma_f32_16x16x32_bf16 v[12:15], v[64:67], v[200:203], v[12:15]
	v_mfma_f32_16x16x32_bf16 v[8:11], v[72:75], v[200:203], v[8:11]
	v_mfma_f32_16x16x32_bf16 v[60:63], v[68:71], v[180:183], v[60:63]
	v_mfma_f32_16x16x32_bf16 v[56:59], v[76:79], v[180:183], v[56:59]
	v_mfma_f32_16x16x32_bf16 v[44:47], v[68:71], v[188:191], v[44:47]
	v_mfma_f32_16x16x32_bf16 v[40:43], v[76:79], v[188:191], v[40:43]
	v_mfma_f32_16x16x32_bf16 v[28:31], v[68:71], v[196:199], v[28:31]
	v_mfma_f32_16x16x32_bf16 v[24:27], v[76:79], v[196:199], v[24:27]
	v_mfma_f32_16x16x32_bf16 v[12:15], v[68:71], v[204:207], v[12:15]
	v_mfma_f32_16x16x32_bf16 v[8:11], v[76:79], v[204:207], v[8:11]


; #define PG8_STAGE(bufoff, gbase, voff) do { _Pragma("unroll") for (int _i = 0; _i < 2; ++_i) \
;         __builtin_amdgcn_global_load_lds((const unsigned*)((const char*)(gbase) + (voff)[_i]), (PG8_LAS unsigned*)(lds + (bufoff) + ldsw + _i * 8192), 16, 0, 0); } while (0)
; #define PG8_LDA(dst, b, h) do { _Pragma("unroll") for (int m = 0; m < 4; ++m) _Pragma("unroll") for (int k = 0; k < 2; ++k) dst[m][k] = *(const PG8_LAS bf16x8*)(lds + PG8_SA(b, h) + aoff + m * 2048 + k * 1024); } while (0)
; #define PG8_LDB(dst, b, h) do { _Pragma("unroll") for (int n = 0; n < 2; ++n) _Pragma("unroll") for (int k = 0; k < 2; ++k) dst[n][k] = *(const PG8_LAS bf16x8*)(lds + PG8_SB(b, h) + boff + n * 2048 + k * 1024); } while (0)
; #define PG8_MMA(ai, bj, At, Bt) do { __builtin_amdgcn_s_setprio(1); _Pragma("unroll") for (int m = 0; m < 4; ++m) _Pragma("unroll") for (int n = 0; n < 2; ++n) _Pragma("unroll") for (int k = 0; k < 2; ++k) \
;         acc[ai][bj][m][n] = __builtin_amdgcn_mfma_f32_16x16x32_bf16(Bt[n][k], At[m][k], acc[ai][bj][m][n], 0, 0, 0); __builtin_amdgcn_s_setprio(0); } while (0)
; #define PG8_WAIT_V(n) asm volatile("s_waitcnt vmcnt(" #n ")" ::: "memory")
; #define PG8_WAIT_L(n) asm volatile("s_waitcnt lgkmcnt(" #n ")" ::: "memory")
; #define PG8_BAR __builtin_amdgcn_s_barrier()
; #define PG8_SCHED __builtin_amdgcn_sched_barrier(0)
; template <class Epi, class Sched, bool ALIGN_EPI = false, bool SP2 = false>
; __device__ __forceinline__ void gemm_phase(PG8_LAS unsigned char* lds, const Gemm g, const Sched& S, const Epi& E) {
;     ...
;             PG8_WAIT_V(8); PG8_WAIT_L(0); PG8_BAR; PG8_MMA(1, 0, At, B0); PG8_MMA(1, 1, At, B1); PG8_BAR; PG8_SCHED;
;             PG8_LDB(B0, 1, 0); PG8_LDB(B1, 1, 1); PG8_SCHED; PG8_LDA(At, 1, 0); PG8_STAGE(PG8_SA(0, 1), a2 + hstep, voffA);
	v_mfma_f32_16x16x32_bf16 v[52:55], v[144:147], v[176:179], v[52:55]
	v_mfma_f32_16x16x32_bf16 v[48:51], v[152:155], v[176:179], v[48:51]
	v_mfma_f32_16x16x32_bf16 v[36:39], v[144:147], v[184:187], v[36:39]
	v_mfma_f32_16x16x32_bf16 v[32:35], v[152:155], v[184:187], v[32:35]
	v_mfma_f32_16x16x32_bf16 v[20:23], v[144:147], v[192:195], v[20:23]
	v_mfma_f32_16x16x32_bf16 v[16:19], v[152:155], v[192:195], v[16:19]
	v_mfma_f32_16x16x32_bf16 v[4:7], v[144:147], v[200:203], v[4:7]
	v_mfma_f32_16x16x32_bf16 v[0:3], v[152:155], v[200:203], v[0:3]
	v_mfma_f32_16x16x32_bf16 v[52:55], v[148:151], v[180:183], v[52:55]
	v_mfma_f32_16x16x32_bf16 v[48:51], v[156:159], v[180:183], v[48:51]
	v_mfma_f32_16x16x32_bf16 v[36:39], v[148:151], v[188:191], v[36:39]
	v_mfma_f32_16x16x32_bf16 v[32:35], v[156:159], v[188:191], v[32:35]
	v_mfma_f32_16x16x32_bf16 v[20:23], v[148:151], v[196:199], v[20:23]
	v_mfma_f32_16x16x32_bf16 v[16:19], v[156:159], v[196:199], v[16:19]
	v_mfma_f32_16x16x32_bf16 v[4:7], v[148:151], v[204:207], v[4:7]
	v_mfma_f32_16x16x32_bf16 v[0:3], v[156:159], v[204:207], v[0:3]
	s_setprio 0
	s_barrier
	s_add_i32 s82, 0, 0x18000
	s_add_i32 s83, 0, 0x1c000


; #define PG8_STAGE(bufoff, gbase, voff) do { _Pragma("unroll") for (int _i = 0; _i < 2; ++_i) \
;         __builtin_amdgcn_global_load_lds((const unsigned*)((const char*)(gbase) + (voff)[_i]), (PG8_LAS unsigned*)(lds + (bufoff) + ldsw + _i * 8192), 16, 0, 0); } while (0)
; #define PG8_LDA(dst, b, h) do { _Pragma("unroll") for (int m = 0; m < 4; ++m) _Pragma("unroll") for (int k = 0; k < 2; ++k) dst[m][k] = *(const PG8_LAS bf16x8*)(lds + PG8_SA(b, h) + aoff + m * 2048 + k * 1024); } while (0)
; #define PG8_LDB(dst, b, h) do { _Pragma("unroll") for (int n = 0; n < 2; ++n) _Pragma("unroll") for (int k = 0; k < 2; ++k) dst[n][k] = *(const PG8_LAS bf16x8*)(lds + PG8_SB(b, h) + boff + n * 2048 + k * 1024); } while (0)
; #define PG8_SCHED __builtin_amdgcn_sched_barrier(0)
; template <class Epi, class Sched, bool ALIGN_EPI = false, bool SP2 = false>
; __device__ __forceinline__ void gemm_phase(PG8_LAS unsigned char* lds, const Gemm g, const Sched& S, const Epi& E) {
;     ...
;             PG8_LDB(B0, 1, 0); PG8_LDB(B1, 1, 1); PG8_SCHED; PG8_LDA(At, 1, 0); PG8_STAGE(PG8_SA(0, 1), a2 + hstep, voffA);
	ds_read_b128 v[64:67], v254
	ds_read_b128 v[68:71], v254 offset:1024
	ds_read_b128 v[72:75], v254 offset:2048
	ds_read_b128 v[76:79], v254 offset:3072
	ds_read_b128 v[144:147], v255
	ds_read_b128 v[148:151], v255 offset:1024
	ds_read_b128 v[152:155], v255 offset:2048
	ds_read_b128 v[156:159], v255 offset:3072
	s_add_u32 s62, s62, 0x80000
	s_addc_u32 s63, s63, 0
	s_mov_b32 m0, s67

; #define PG8_STAGE(bufoff, gbase, voff) do { _Pragma("unroll") for (int _i = 0; _i < 2; ++_i) \
;         __builtin_amdgcn_global_load_lds((const unsigned*)((const char*)(gbase) + (voff)[_i]), (PG8_LAS unsigned*)(lds + (bufoff) + ldsw + _i * 8192), 16, 0, 0); } while (0)
; #define PG8_LDA(dst, b, h) do { _Pragma("unroll") for (int m = 0; m < 4; ++m) _Pragma("unroll") for (int k = 0; k < 2; ++k) dst[m][k] = *(const PG8_LAS bf16x8*)(lds + PG8_SA(b, h) + aoff + m * 2048 + k * 1024); } while (0)
; #define PG8_LDB(dst, b, h) do { _Pragma("unroll") for (int n = 0; n < 2; ++n) _Pragma("unroll") for (int k = 0; k < 2; ++k) dst[n][k] = *(const PG8_LAS bf16x8*)(lds + PG8_SB(b, h) + boff + n * 2048 + k * 1024); } while (0)
; #define PG8_SCHED __builtin_amdgcn_sched_barrier(0)
; template <class Epi, class Sched, bool ALIGN_EPI = false, bool SP2 = false>
; __device__ __forceinline__ void gemm_phase(PG8_LAS unsigned char* lds, const Gemm g, const Sched& S, const Epi& E) {
;     ...
;             PG8_LDB(B0, 1, 0); PG8_LDB(B1, 1, 1); PG8_SCHED; PG8_LDA(At, 1, 0); PG8_STAGE(PG8_SA(0, 1), a2 + hstep, voffA);
	ds_read_b128 v[176:179], v213 offset:32768
	ds_read_b128 v[180:183], v213 offset:33792
	ds_read_b128 v[184:187], v213 offset:34816
	ds_read_b128 v[188:191], v213 offset:35840
	ds_read_b128 v[192:195], v213 offset:36864
	ds_read_b128 v[196:199], v213 offset:37888
	ds_read_b128 v[200:203], v213 offset:38912
	ds_read_b128 v[204:207], v213 offset:39936
	global_load_lds_dwordx4 v160, s[62:63]

; #define PG8_STAGE(bufoff, gbase, voff) do { _Pragma("unroll") for (int _i = 0; _i < 2; ++_i) \
;         __builtin_amdgcn_global_load_lds((const unsigned*)((const char*)(gbase) + (voff)[_i]), (PG8_LAS unsigned*)(lds + (bufoff) + ldsw + _i * 8192), 16, 0, 0); } while (0)
; #define PG8_LDA(dst, b, h) do { _Pragma("unroll") for (int m = 0; m < 4; ++m) _Pragma("unroll") for (int k = 0; k < 2; ++k) dst[m][k] = *(const PG8_LAS bf16x8*)(lds + PG8_SA(b, h) + aoff + m * 2048 + k * 1024); } while (0)
; #define PG8_LDB(dst, b, h) do { _Pragma("unroll") for (int n = 0; n < 2; ++n) _Pragma("unroll") for (int k = 0; k < 2; ++k) dst[n][k] = *(const PG8_LAS bf16x8*)(lds + PG8_SB(b, h) + boff + n * 2048 + k * 1024); } while (0)
; #define PG8_MMA(ai, bj, At, Bt) do { __builtin_amdgcn_s_setprio(1); _Pragma("unroll") for (int m = 0; m < 4; ++m) _Pragma("unroll") for (int n = 0; n < 2; ++n) _Pragma("unroll") for (int k = 0; k < 2; ++k) \
;         acc[ai][bj][m][n] = __builtin_amdgcn_mfma_f32_16x16x32_bf16(Bt[n][k], At[m][k], acc[ai][bj][m][n], 0, 0, 0); __builtin_amdgcn_s_setprio(0); } while (0)
; #define PG8_WAIT_V(n) asm volatile("s_waitcnt vmcnt(" #n ")" ::: "memory")
; #define PG8_WAIT_L(n) asm volatile("s_waitcnt lgkmcnt(" #n ")" ::: "memory")
; #define PG8_BAR __builtin_amdgcn_s_barrier()
; #define PG8_SCHED __builtin_amdgcn_sched_barrier(0)
; template <class Epi, class Sched, bool ALIGN_EPI = false, bool SP2 = false>
; __device__ __forceinline__ void gemm_phase(PG8_LAS unsigned char* lds, const Gemm g, const Sched& S, const Epi& E) {
;     ...
;             PG8_LDB(B0, 1, 0); PG8_LDB(B1, 1, 1); PG8_SCHED; PG8_LDA(At, 1, 0); PG8_STAGE(PG8_SA(0, 1), a2 + hstep, voffA);
;             PG8_WAIT_V(8); PG8_WAIT_L(0); PG8_BAR; PG8_MMA(0, 0, At, B0); PG8_MMA(0, 1, At, B1); PG8_BAR; PG8_SCHED;
	s_mov_b32 m0, s68
	s_nop 0
	global_load_lds_dwordx4 v164, s[62:63]
	s_waitcnt vmcnt(8)
	s_waitcnt lgkmcnt(0)
	s_setprio 1
	s_barrier

; #define PG8_MMA(ai, bj, At, Bt) do { __builtin_amdgcn_s_setprio(1); _Pragma("unroll") for (int m = 0; m < 4; ++m) _Pragma("unroll") for (int n = 0; n < 2; ++n) _Pragma("unroll") for (int k = 0; k < 2; ++k) \
;         acc[ai][bj][m][n] = __builtin_amdgcn_mfma_f32_16x16x32_bf16(Bt[n][k], At[m][k], acc[ai][bj][m][n], 0, 0, 0); __builtin_amdgcn_s_setprio(0); } while (0)
; #define PG8_WAIT_V(n) asm volatile("s_waitcnt vmcnt(" #n ")" ::: "memory")
; #define PG8_WAIT_L(n) asm volatile("s_waitcnt lgkmcnt(" #n ")" ::: "memory")
; #define PG8_BAR __builtin_amdgcn_s_barrier()
; #define PG8_SCHED __builtin_amdgcn_sched_barrier(0)
; template <class Epi, class Sched, bool ALIGN_EPI = false, bool SP2 = false>
; __device__ __forceinline__ void gemm_phase(PG8_LAS unsigned char* lds, const Gemm g, const Sched& S, const Epi& E) {
;     ...
;             PG8_WAIT_V(8); PG8_WAIT_L(0); PG8_BAR; PG8_MMA(0, 0, At, B0); PG8_MMA(0, 1, At, B1); PG8_BAR; PG8_SCHED;
	v_mfma_f32_16x16x32_bf16 v[140:143], v[64:67], v[176:179], v[140:143]
	v_mfma_f32_16x16x32_bf16 v[136:139], v[72:75], v[176:179], v[136:139]
	v_mfma_f32_16x16x32_bf16 v[124:127], v[64:67], v[184:187], v[124:127]
	v_mfma_f32_16x16x32_bf16 v[120:123], v[72:75], v[184:187], v[120:123]
	v_mfma_f32_16x16x32_bf16 v[108:111], v[64:67], v[192:195], v[108:111]
	v_mfma_f32_16x16x32_bf16 v[104:107], v[72:75], v[192:195], v[104:107]
	v_mfma_f32_16x16x32_bf16 v[92:95], v[64:67], v[200:203], v[92:95]
	v_mfma_f32_16x16x32_bf16 v[88:91], v[72:75], v[200:203], v[88:91]
	v_mfma_f32_16x16x32_bf16 v[140:143], v[68:71], v[180:183], v[140:143]
	v_mfma_f32_16x16x32_bf16 v[136:139], v[76:79], v[180:183], v[136:139]
	v_mfma_f32_16x16x32_bf16 v[124:127], v[68:71], v[188:191], v[124:127]
	v_mfma_f32_16x16x32_bf16 v[120:123], v[76:79], v[188:191], v[120:123]
	v_mfma_f32_16x16x32_bf16 v[108:111], v[68:71], v[196:199], v[108:111]
	v_mfma_f32_16x16x32_bf16 v[104:107], v[76:79], v[196:199], v[104:107]
	v_mfma_f32_16x16x32_bf16 v[92:95], v[68:71], v[204:207], v[92:95]
	v_mfma_f32_16x16x32_bf16 v[88:91], v[76:79], v[204:207], v[88:91]


; #define PG8_STAGE(bufoff, gbase, voff) do { _Pragma("unroll") for (int _i = 0; _i < 2; ++_i) \
;         __builtin_amdgcn_global_load_lds((const unsigned*)((const char*)(gbase) + (voff)[_i]), (PG8_LAS unsigned*)(lds + (bufoff) + ldsw + _i * 8192), 16, 0, 0); } while (0)
; #define PG8_LDA(dst, b, h) do { _Pragma("unroll") for (int m = 0; m < 4; ++m) _Pragma("unroll") for (int k = 0; k < 2; ++k) dst[m][k] = *(const PG8_LAS bf16x8*)(lds + PG8_SA(b, h) + aoff + m * 2048 + k * 1024); } while (0)
; #define PG8_MMA(ai, bj, At, Bt) do { __builtin_amdgcn_s_setprio(1); _Pragma("unroll") for (int m = 0; m < 4; ++m) _Pragma("unroll") for (int n = 0; n < 2; ++n) _Pragma("unroll") for (int k = 0; k < 2; ++k) \
;         acc[ai][bj][m][n] = __builtin_amdgcn_mfma_f32_16x16x32_bf16(Bt[n][k], At[m][k], acc[ai][bj][m][n], 0, 0, 0); __builtin_amdgcn_s_setprio(0); } while (0)
; #define PG8_WAIT_V(n) asm volatile("s_waitcnt vmcnt(" #n ")" ::: "memory")
; #define PG8_WAIT_L(n) asm volatile("s_waitcnt lgkmcnt(" #n ")" ::: "memory")
; #define PG8_BAR __builtin_amdgcn_s_barrier()
; #define PG8_SCHED __builtin_amdgcn_sched_barrier(0)
; template <class Epi, class Sched, bool ALIGN_EPI = false, bool SP2 = false>
; __device__ __forceinline__ void gemm_phase(PG8_LAS unsigned char* lds, const Gemm g, const Sched& S, const Epi& E) {
;     ...
;             PG8_WAIT_V(8); PG8_WAIT_L(0); PG8_BAR; PG8_MMA(0, 0, At, B0); PG8_MMA(0, 1, At, B1); PG8_BAR; PG8_SCHED;
;             PG8_LDA(At, 1, 1); PG8_STAGE(PG8_SB(1, 0), b3, voffB); PG8_STAGE(PG8_SB(1, 1), b3 + hstep, voffB); PG8_STAGE(PG8_SA(1, 0), a3, voffA);
	v_mfma_f32_16x16x32_bf16 v[132:135], v[144:147], v[176:179], v[132:135]
	v_mfma_f32_16x16x32_bf16 v[128:131], v[152:155], v[176:179], v[128:131]
	v_mfma_f32_16x16x32_bf16 v[116:119], v[144:147], v[184:187], v[116:119]
	v_mfma_f32_16x16x32_bf16 v[112:115], v[152:155], v[184:187], v[112:115]
	v_mfma_f32_16x16x32_bf16 v[100:103], v[144:147], v[192:195], v[100:103]
	v_mfma_f32_16x16x32_bf16 v[96:99], v[152:155], v[192:195], v[96:99]
	v_mfma_f32_16x16x32_bf16 v[84:87], v[144:147], v[200:203], v[84:87]
	v_mfma_f32_16x16x32_bf16 v[80:83], v[152:155], v[200:203], v[80:83]
	v_mfma_f32_16x16x32_bf16 v[132:135], v[148:151], v[180:183], v[132:135]
	v_mfma_f32_16x16x32_bf16 v[128:131], v[156:159], v[180:183], v[128:131]
	v_mfma_f32_16x16x32_bf16 v[116:119], v[148:151], v[188:191], v[116:119]
	v_mfma_f32_16x16x32_bf16 v[112:115], v[156:159], v[188:191], v[112:115]
	v_mfma_f32_16x16x32_bf16 v[100:103], v[148:151], v[196:199], v[100:103]
	v_mfma_f32_16x16x32_bf16 v[96:99], v[156:159], v[196:199], v[96:99]
	v_mfma_f32_16x16x32_bf16 v[84:87], v[148:151], v[204:207], v[84:87]
	v_mfma_f32_16x16x32_bf16 v[80:83], v[156:159], v[204:207], v[80:83]
	s_setprio 0
	s_barrier
	s_add_i32 s62, s82, s64

; #define PG8_STAGE(bufoff, gbase, voff) do { _Pragma("unroll") for (int _i = 0; _i < 2; ++_i) \
;         __builtin_amdgcn_global_load_lds((const unsigned*)((const char*)(gbase) + (voff)[_i]), (PG8_LAS unsigned*)(lds + (bufoff) + ldsw + _i * 8192), 16, 0, 0); } while (0)
; #define PG8_LDA(dst, b, h) do { _Pragma("unroll") for (int m = 0; m < 4; ++m) _Pragma("unroll") for (int k = 0; k < 2; ++k) dst[m][k] = *(const PG8_LAS bf16x8*)(lds + PG8_SA(b, h) + aoff + m * 2048 + k * 1024); } while (0)
; template <class Epi, class Sched, bool ALIGN_EPI = false, bool SP2 = false>
; __device__ __forceinline__ void gemm_phase(PG8_LAS unsigned char* lds, const Gemm g, const Sched& S, const Epi& E) {
;     ...
;             PG8_LDA(At, 1, 1); PG8_STAGE(PG8_SB(1, 0), b3, voffB); PG8_STAGE(PG8_SB(1, 1), b3 + hstep, voffB); PG8_STAGE(PG8_SA(1, 0), a3, voffA);
	s_mov_b32 m0, s62
	ds_read_b128 v[176:179], v213 offset:49152
	ds_read_b128 v[180:183], v213 offset:50176
	ds_read_b128 v[184:187], v213 offset:51200
	ds_read_b128 v[188:191], v213 offset:52224
	ds_read_b128 v[192:195], v213 offset:53248
	ds_read_b128 v[196:199], v213 offset:54272
	ds_read_b128 v[200:203], v213 offset:55296
	ds_read_b128 v[204:207], v213 offset:56320
	global_load_lds_dwordx4 v250, s[96:97]
	s_add_i32 m0, s62, 0x2000
	s_add_u32 s60, s60, 0x80080

; #define PG8_STAGE(bufoff, gbase, voff) do { _Pragma("unroll") for (int _i = 0; _i < 2; ++_i) \
;         __builtin_amdgcn_global_load_lds((const unsigned*)((const char*)(gbase) + (voff)[_i]), (PG8_LAS unsigned*)(lds + (bufoff) + ldsw + _i * 8192), 16, 0, 0); } while (0)
; #define PG8_LDA(dst, b, h) do { _Pragma("unroll") for (int m = 0; m < 4; ++m) _Pragma("unroll") for (int k = 0; k < 2; ++k) dst[m][k] = *(const PG8_LAS bf16x8*)(lds + PG8_SA(b, h) + aoff + m * 2048 + k * 1024); } while (0)
; template <class Epi, class Sched, bool ALIGN_EPI = false, bool SP2 = false>
; __device__ __forceinline__ void gemm_phase(PG8_LAS unsigned char* lds, const Gemm g, const Sched& S, const Epi& E) {
;     ...
;             PG8_LDA(At, 1, 1); PG8_STAGE(PG8_SB(1, 0), b3, voffB); PG8_STAGE(PG8_SB(1, 1), b3 + hstep, voffB); PG8_STAGE(PG8_SA(1, 0), a3, voffA);
	s_addc_u32 s61, s61, 0
	s_add_i32 s62, s83, s64
	global_load_lds_dwordx4 v251, s[96:97]

; #define PG8_STAGE(bufoff, gbase, voff) do { _Pragma("unroll") for (int _i = 0; _i < 2; ++_i) \
;         __builtin_amdgcn_global_load_lds((const unsigned*)((const char*)(gbase) + (voff)[_i]), (PG8_LAS unsigned*)(lds + (bufoff) + ldsw + _i * 8192), 16, 0, 0); } while (0)
; #define PG8_LDA(dst, b, h) do { _Pragma("unroll") for (int m = 0; m < 4; ++m) _Pragma("unroll") for (int k = 0; k < 2; ++k) dst[m][k] = *(const PG8_LAS bf16x8*)(lds + PG8_SA(b, h) + aoff + m * 2048 + k * 1024); } while (0)
; template <class Epi, class Sched, bool ALIGN_EPI = false, bool SP2 = false>
; __device__ __forceinline__ void gemm_phase(PG8_LAS unsigned char* lds, const Gemm g, const Sched& S, const Epi& E) {
;     ...
;             PG8_LDA(At, 1, 1); PG8_STAGE(PG8_SB(1, 0), b3, voffB); PG8_STAGE(PG8_SB(1, 1), b3 + hstep, voffB); PG8_STAGE(PG8_SA(1, 0), a3, voffA);
	s_mov_b32 m0, s62
	s_nop 0
	global_load_lds_dwordx4 v162, s[60:61]

; #define PG8_STAGE(bufoff, gbase, voff) do { _Pragma("unroll") for (int _i = 0; _i < 2; ++_i) \
;         __builtin_amdgcn_global_load_lds((const unsigned*)((const char*)(gbase) + (voff)[_i]), (PG8_LAS unsigned*)(lds + (bufoff) + ldsw + _i * 8192), 16, 0, 0); } while (0)
; #define PG8_LDA(dst, b, h) do { _Pragma("unroll") for (int m = 0; m < 4; ++m) _Pragma("unroll") for (int k = 0; k < 2; ++k) dst[m][k] = *(const PG8_LAS bf16x8*)(lds + PG8_SA(b, h) + aoff + m * 2048 + k * 1024); } while (0)
; template <class Epi, class Sched, bool ALIGN_EPI = false, bool SP2 = false>
; __device__ __forceinline__ void gemm_phase(PG8_LAS unsigned char* lds, const Gemm g, const Sched& S, const Epi& E) {
;     ...
;             PG8_LDA(At, 1, 1); PG8_STAGE(PG8_SB(1, 0), b3, voffB); PG8_STAGE(PG8_SB(1, 1), b3 + hstep, voffB); PG8_STAGE(PG8_SA(1, 0), a3, voffA);
	s_add_i32 m0, s62, 0x2000
	s_nop 0
	global_load_lds_dwordx4 v166, s[60:61]

; #define PG8_STAGE(bufoff, gbase, voff) do { _Pragma("unroll") for (int _i = 0; _i < 2; ++_i) \
;         __builtin_amdgcn_global_load_lds((const unsigned*)((const char*)(gbase) + (voff)[_i]), (PG8_LAS unsigned*)(lds + (bufoff) + ldsw + _i * 8192), 16, 0, 0); } while (0)
; #define PG8_LDA(dst, b, h) do { _Pragma("unroll") for (int m = 0; m < 4; ++m) _Pragma("unroll") for (int k = 0; k < 2; ++k) dst[m][k] = *(const PG8_LAS bf16x8*)(lds + PG8_SA(b, h) + aoff + m * 2048 + k * 1024); } while (0)
; template <class Epi, class Sched, bool ALIGN_EPI = false, bool SP2 = false>
; __device__ __forceinline__ void gemm_phase(PG8_LAS unsigned char* lds, const Gemm g, const Sched& S, const Epi& E) {
;     ...
;             PG8_LDA(At, 1, 1); PG8_STAGE(PG8_SB(1, 0), b3, voffB); PG8_STAGE(PG8_SB(1, 1), b3 + hstep, voffB); PG8_STAGE(PG8_SA(1, 0), a3, voffA);
	s_mov_b32 m0, s70
	s_nop 0
	global_load_lds_dwordx4 v252, s[98:99]

; #define PG8_STAGE(bufoff, gbase, voff) do { _Pragma("unroll") for (int _i = 0; _i < 2; ++_i) \
;         __builtin_amdgcn_global_load_lds((const unsigned*)((const char*)(gbase) + (voff)[_i]), (PG8_LAS unsigned*)(lds + (bufoff) + ldsw + _i * 8192), 16, 0, 0); } while (0)
; #define PG8_LDA(dst, b, h) do { _Pragma("unroll") for (int m = 0; m < 4; ++m) _Pragma("unroll") for (int k = 0; k < 2; ++k) dst[m][k] = *(const PG8_LAS bf16x8*)(lds + PG8_SA(b, h) + aoff + m * 2048 + k * 1024); } while (0)
; #define PG8_MMA(ai, bj, At, Bt) do { __builtin_amdgcn_s_setprio(1); _Pragma("unroll") for (int m = 0; m < 4; ++m) _Pragma("unroll") for (int n = 0; n < 2; ++n) _Pragma("unroll") for (int k = 0; k < 2; ++k) \
;         acc[ai][bj][m][n] = __builtin_amdgcn_mfma_f32_16x16x32_bf16(Bt[n][k], At[m][k], acc[ai][bj][m][n], 0, 0, 0); __builtin_amdgcn_s_setprio(0); } while (0)
; #define PG8_WAIT_V(n) asm volatile("s_waitcnt vmcnt(" #n ")" ::: "memory")
; #define PG8_WAIT_L(n) asm volatile("s_waitcnt lgkmcnt(" #n ")" ::: "memory")
; #define PG8_BAR __builtin_amdgcn_s_barrier()
; #define PG8_SCHED __builtin_amdgcn_sched_barrier(0)
; template <class Epi, class Sched, bool ALIGN_EPI = false, bool SP2 = false>
; __device__ __forceinline__ void gemm_phase(PG8_LAS unsigned char* lds, const Gemm g, const Sched& S, const Epi& E) {
;     ...
;             PG8_LDA(At, 1, 1); PG8_STAGE(PG8_SB(1, 0), b3, voffB); PG8_STAGE(PG8_SB(1, 1), b3 + hstep, voffB); PG8_STAGE(PG8_SA(1, 0), a3, voffA);
;             PG8_WAIT_V(8); PG8_WAIT_L(0); PG8_BAR; PG8_MMA(1, 0, At, B0); PG8_MMA(1, 1, At, B1); PG8_BAR; PG8_SCHED;
	s_mov_b32 m0, s71
	s_nop 0
	global_load_lds_dwordx4 v253, s[98:99]
	s_waitcnt vmcnt(8)
	s_waitcnt lgkmcnt(0)
	s_setprio 1
	s_barrier

; #define PG8_MMA(ai, bj, At, Bt) do { __builtin_amdgcn_s_setprio(1); _Pragma("unroll") for (int m = 0; m < 4; ++m) _Pragma("unroll") for (int n = 0; n < 2; ++n) _Pragma("unroll") for (int k = 0; k < 2; ++k) \
;         acc[ai][bj][m][n] = __builtin_amdgcn_mfma_f32_16x16x32_bf16(Bt[n][k], At[m][k], acc[ai][bj][m][n], 0, 0, 0); __builtin_amdgcn_s_setprio(0); } while (0)
; #define PG8_WAIT_V(n) asm volatile("s_waitcnt vmcnt(" #n ")" ::: "memory")
; #define PG8_WAIT_L(n) asm volatile("s_waitcnt lgkmcnt(" #n ")" ::: "memory")
; #define PG8_BAR __builtin_amdgcn_s_barrier()
; #define PG8_SCHED __builtin_amdgcn_sched_barrier(0)
; template <class Epi, class Sched, bool ALIGN_EPI = false, bool SP2 = false>
; __device__ __forceinline__ void gemm_phase(PG8_LAS unsigned char* lds, const Gemm g, const Sched& S, const Epi& E) {
;     ...
;             PG8_WAIT_V(8); PG8_WAIT_L(0); PG8_BAR; PG8_MMA(1, 0, At, B0); PG8_MMA(1, 1, At, B1); PG8_BAR; PG8_SCHED;
	v_mfma_f32_16x16x32_bf16 v[60:63], v[64:67], v[176:179], v[60:63]
	v_mfma_f32_16x16x32_bf16 v[56:59], v[72:75], v[176:179], v[56:59]
	v_mfma_f32_16x16x32_bf16 v[44:47], v[64:67], v[184:187], v[44:47]
	v_mfma_f32_16x16x32_bf16 v[40:43], v[72:75], v[184:187], v[40:43]
	v_mfma_f32_16x16x32_bf16 v[28:31], v[64:67], v[192:195], v[28:31]
	v_mfma_f32_16x16x32_bf16 v[24:27], v[72:75], v[192:195], v[24:27]
	v_mfma_f32_16x16x32_bf16 v[12:15], v[64:67], v[200:203], v[12:15]
	v_mfma_f32_16x16x32_bf16 v[8:11], v[72:75], v[200:203], v[8:11]
	v_mfma_f32_16x16x32_bf16 v[60:63], v[68:71], v[180:183], v[60:63]
	v_mfma_f32_16x16x32_bf16 v[56:59], v[76:79], v[180:183], v[56:59]
	v_mfma_f32_16x16x32_bf16 v[44:47], v[68:71], v[188:191], v[44:47]
	v_mfma_f32_16x16x32_bf16 v[40:43], v[76:79], v[188:191], v[40:43]
	v_mfma_f32_16x16x32_bf16 v[28:31], v[68:71], v[196:199], v[28:31]
	v_mfma_f32_16x16x32_bf16 v[24:27], v[76:79], v[196:199], v[24:27]
	v_mfma_f32_16x16x32_bf16 v[12:15], v[68:71], v[204:207], v[12:15]
	v_mfma_f32_16x16x32_bf16 v[8:11], v[76:79], v[204:207], v[8:11]


; #define PG8_STAGE(bufoff, gbase, voff) do { _Pragma("unroll") for (int _i = 0; _i < 2; ++_i) \
;         __builtin_amdgcn_global_load_lds((const unsigned*)((const char*)(gbase) + (voff)[_i]), (PG8_LAS unsigned*)(lds + (bufoff) + ldsw + _i * 8192), 16, 0, 0); } while (0)
; #define PG8_LDA(dst, b, h) do { _Pragma("unroll") for (int m = 0; m < 4; ++m) _Pragma("unroll") for (int k = 0; k < 2; ++k) dst[m][k] = *(const PG8_LAS bf16x8*)(lds + PG8_SA(b, h) + aoff + m * 2048 + k * 1024); } while (0)
; #define PG8_LDB(dst, b, h) do { _Pragma("unroll") for (int n = 0; n < 2; ++n) _Pragma("unroll") for (int k = 0; k < 2; ++k) dst[n][k] = *(const PG8_LAS bf16x8*)(lds + PG8_SB(b, h) + boff + n * 2048 + k * 1024); } while (0)
; template <class Epi, class Sched, bool ALIGN_EPI = false, bool SP2 = false>
; __device__ __forceinline__ void gemm_phase(PG8_LAS unsigned char* lds, const Gemm g, const Sched& S, const Epi& E) {
;     ...
;             PG8_WAIT_V(8); PG8_WAIT_L(0); PG8_BAR; PG8_MMA(1, 0, At, B0); PG8_MMA(1, 1, At, B1); PG8_BAR; PG8_SCHED;
;             } else {
;             PG8_LDB(B0, 0, 0); PG8_SCHED; PG8_LDA(At, 0, 0); PG8_STAGE(PG8_SA(1, 1), a1 + hstep, voffA);
;             PG8_WAIT_L(8); PG8_BAR; PG8_WAIT_L(0); PG8_MMA(0, 0, At, B0); PG8_BAR; PG8_SCHED;
;             PG8_LDB(B1, 0, 1); PG8_STAGE(PG8_SB(0, 0), b2, voffB);
;             PG8_BAR; PG8_WAIT_L(0); PG8_MMA(0, 1, At, B1); PG8_BAR;
;             PG8_LDA(At, 0, 1); PG8_STAGE(PG8_SA(0, 0), a2, voffA);
;             PG8_BAR; PG8_WAIT_L(0); PG8_MMA(1, 0, At, B0); PG8_BAR; PG8_SCHED;
;             PG8_STAGE(PG8_SB(0, 1), b2 + hstep, voffB);
;             PG8_WAIT_V(6); PG8_BAR; PG8_MMA(1, 1, At, B1); PG8_BAR;
;             PG8_LDB(B0, 1, 0); PG8_SCHED; PG8_LDA(At, 1, 0); PG8_STAGE(PG8_SA(0, 1), a2 + hstep, voffA);
;             PG8_WAIT_L(8); PG8_BAR; PG8_WAIT_L(0); PG8_MMA(0, 0, At, B0); PG8_BAR; PG8_SCHED;
;             PG8_LDB(B1, 1, 1); PG8_STAGE(PG8_SB(1, 0), b3, voffB);
;             PG8_BAR; PG8_WAIT_L(0); PG8_MMA(0, 1, At, B1); PG8_BAR;
;             PG8_LDA(At, 1, 1); PG8_STAGE(PG8_SA(1, 0), a3, voffA);
;             PG8_BAR; PG8_WAIT_L(0); PG8_MMA(1, 0, At, B0); PG8_BAR; PG8_SCHED;
;             PG8_STAGE(PG8_SB(1, 1), b3 + hstep, voffB);
;             PG8_WAIT_V(6); PG8_BAR; PG8_MMA(1, 1, At, B1); PG8_BAR;
;             }
;         }
;         if constexpr (ALIGN_EPI) { if (wr == 0) PG8_BAR; }
	v_mfma_f32_16x16x32_bf16 v[52:55], v[144:147], v[176:179], v[52:55]
	v_mfma_f32_16x16x32_bf16 v[48:51], v[152:155], v[176:179], v[48:51]
	v_mfma_f32_16x16x32_bf16 v[36:39], v[144:147], v[184:187], v[36:39]
	v_mfma_f32_16x16x32_bf16 v[32:35], v[152:155], v[184:187], v[32:35]
	v_mfma_f32_16x16x32_bf16 v[20:23], v[144:147], v[192:195], v[20:23]
	v_mfma_f32_16x16x32_bf16 v[16:19], v[152:155], v[192:195], v[16:19]
	v_mfma_f32_16x16x32_bf16 v[4:7], v[144:147], v[200:203], v[4:7]
	v_mfma_f32_16x16x32_bf16 v[0:3], v[152:155], v[200:203], v[0:3]
	v_mfma_f32_16x16x32_bf16 v[52:55], v[148:151], v[180:183], v[52:55]
	v_mfma_f32_16x16x32_bf16 v[48:51], v[156:159], v[180:183], v[48:51]
	v_mfma_f32_16x16x32_bf16 v[36:39], v[148:151], v[188:191], v[36:39]
	v_mfma_f32_16x16x32_bf16 v[32:35], v[156:159], v[188:191], v[32:35]
	v_mfma_f32_16x16x32_bf16 v[20:23], v[148:151], v[196:199], v[20:23]
	v_mfma_f32_16x16x32_bf16 v[16:19], v[156:159], v[196:199], v[16:19]
	v_mfma_f32_16x16x32_bf16 v[4:7], v[148:151], v[204:207], v[4:7]
	v_mfma_f32_16x16x32_bf16 v[0:3], v[156:159], v[204:207], v[0:3]
	s_setprio 0
	s_barrier
	s_add_i32 s81, s81, 2
	s_add_u32 s58, s58, 0x100
	s_addc_u32 s59, s59, 0
	s_add_u32 s79, s79, 0x100
	s_addc_u32 s80, s80, 0
	s_cmp_gt_u32 s81, 29
	s_cbranch_scc0 .LBB0_333
	s_and_b64 vcc, exec, s[42:43]
	s_cbranch_vccz .LBB0_336
	s_barrier

; #define PG8_STAGE(bufoff, gbase, voff) do { _Pragma("unroll") for (int _i = 0; _i < 2; ++_i) \
;         __builtin_amdgcn_global_load_lds((const unsigned*)((const char*)(gbase) + (voff)[_i]), (PG8_LAS unsigned*)(lds + (bufoff) + ldsw + _i * 8192), 16, 0, 0); } while (0)
; #define PG8_LDA(dst, b, h) do { _Pragma("unroll") for (int m = 0; m < 4; ++m) _Pragma("unroll") for (int k = 0; k < 2; ++k) dst[m][k] = *(const PG8_LAS bf16x8*)(lds + PG8_SA(b, h) + aoff + m * 2048 + k * 1024); } while (0)
; #define PG8_LDB(dst, b, h) do { _Pragma("unroll") for (int n = 0; n < 2; ++n) _Pragma("unroll") for (int k = 0; k < 2; ++k) dst[n][k] = *(const PG8_LAS bf16x8*)(lds + PG8_SB(b, h) + boff + n * 2048 + k * 1024); } while (0)
; #define PG8_SCHED __builtin_amdgcn_sched_barrier(0)
; template <class Epi, class Sched, bool ALIGN_EPI = false, bool SP2 = false>
; __device__ __forceinline__ void gemm_phase(PG8_LAS unsigned char* lds, const Gemm g, const Sched& S, const Epi& E) {
;     ...
;             const char* a2 = last ? nA : cA + (size_t)(t + 2) * kstep; const char* b2 = last ? nB : cB + (size_t)(t + 2) * kstep;
;             const char* a3 = a2 + kstep; const char* b3 = b2 + kstep;
;             if (last && has_next) S.a_ready(nxt);
;             if constexpr (SP2) {
;             PG8_LDB(B0, 0, 0); PG8_LDB(B1, 0, 1); PG8_SCHED; PG8_LDA(At, 0, 0); PG8_STAGE(PG8_SA(1, 1), a1 + hstep, voffA);
.LBB0_428:
	ds_read_b128 v[128:131], v201
	ds_read_b128 v[132:135], v201 offset:1024
	ds_read_b128 v[136:139], v201 offset:2048
	ds_read_b128 v[140:143], v201 offset:3072
	ds_read_b128 v[144:147], v205
	ds_read_b128 v[148:151], v205 offset:1024
	ds_read_b128 v[152:155], v205 offset:2048
	ds_read_b128 v[156:159], v205 offset:3072
	s_add_u32 s12, s10, 0xfff80080
	s_addc_u32 s13, s11, -1
	s_cmp_eq_u32 s85, 28
	s_cselect_b32 s61, s55, s13
	s_cselect_b32 s60, s81, s12
	s_cselect_b32 s13, s53, s84
	s_cselect_b32 s12, s82, s83

; #define PG8_STAGE(bufoff, gbase, voff) do { _Pragma("unroll") for (int _i = 0; _i < 2; ++_i) \
;         __builtin_amdgcn_global_load_lds((const unsigned*)((const char*)(gbase) + (voff)[_i]), (PG8_LAS unsigned*)(lds + (bufoff) + ldsw + _i * 8192), 16, 0, 0); } while (0)
; #define PG8_LDA(dst, b, h) do { _Pragma("unroll") for (int m = 0; m < 4; ++m) _Pragma("unroll") for (int k = 0; k < 2; ++k) dst[m][k] = *(const PG8_LAS bf16x8*)(lds + PG8_SA(b, h) + aoff + m * 2048 + k * 1024); } while (0)
; #define PG8_LDB(dst, b, h) do { _Pragma("unroll") for (int n = 0; n < 2; ++n) _Pragma("unroll") for (int k = 0; k < 2; ++k) dst[n][k] = *(const PG8_LAS bf16x8*)(lds + PG8_SB(b, h) + boff + n * 2048 + k * 1024); } while (0)
; #define PG8_SCHED __builtin_amdgcn_sched_barrier(0)
; template <class Epi, class Sched, bool ALIGN_EPI = false, bool SP2 = false>
; __device__ __forceinline__ void gemm_phase(PG8_LAS unsigned char* lds, const Gemm g, const Sched& S, const Epi& E) {
;     ...
;             PG8_LDB(B0, 0, 0); PG8_LDB(B1, 0, 1); PG8_SCHED; PG8_LDA(At, 0, 0); PG8_STAGE(PG8_SA(1, 1), a1 + hstep, voffA);
	s_add_i32 m0, s65, 0xc000
	ds_read_b128 v[176:179], v207
	ds_read_b128 v[184:187], v207 offset:1024
	ds_read_b128 v[190:193], v207 offset:2048
	ds_read_b128 v[210:213], v207 offset:3072
	ds_read_b128 v[214:217], v207 offset:4096
	ds_read_b128 v[218:221], v207 offset:5120
	ds_read_b128 v[222:225], v207 offset:6144
	ds_read_b128 v[226:229], v207 offset:7168
	global_load_lds_dwordx4 v168, s[10:11]

; #define PG8_STAGE(bufoff, gbase, voff) do { _Pragma("unroll") for (int _i = 0; _i < 2; ++_i) \
;         __builtin_amdgcn_global_load_lds((const unsigned*)((const char*)(gbase) + (voff)[_i]), (PG8_LAS unsigned*)(lds + (bufoff) + ldsw + _i * 8192), 16, 0, 0); } while (0)
; #define PG8_LDA(dst, b, h) do { _Pragma("unroll") for (int m = 0; m < 4; ++m) _Pragma("unroll") for (int k = 0; k < 2; ++k) dst[m][k] = *(const PG8_LAS bf16x8*)(lds + PG8_SA(b, h) + aoff + m * 2048 + k * 1024); } while (0)
; #define PG8_LDB(dst, b, h) do { _Pragma("unroll") for (int n = 0; n < 2; ++n) _Pragma("unroll") for (int k = 0; k < 2; ++k) dst[n][k] = *(const PG8_LAS bf16x8*)(lds + PG8_SB(b, h) + boff + n * 2048 + k * 1024); } while (0)
; #define PG8_MMA(ai, bj, At, Bt) do { __builtin_amdgcn_s_setprio(1); _Pragma("unroll") for (int m = 0; m < 4; ++m) _Pragma("unroll") for (int n = 0; n < 2; ++n) _Pragma("unroll") for (int k = 0; k < 2; ++k) \
;         acc[ai][bj][m][n] = __builtin_amdgcn_mfma_f32_16x16x32_bf16(Bt[n][k], At[m][k], acc[ai][bj][m][n], 0, 0, 0); __builtin_amdgcn_s_setprio(0); } while (0)
; #define PG8_WAIT_V(n) asm volatile("s_waitcnt vmcnt(" #n ")" ::: "memory")
; #define PG8_WAIT_L(n) asm volatile("s_waitcnt lgkmcnt(" #n ")" ::: "memory")
; #define PG8_BAR __builtin_amdgcn_s_barrier()
; #define PG8_SCHED __builtin_amdgcn_sched_barrier(0)
; template <class Epi, class Sched, bool ALIGN_EPI = false, bool SP2 = false>
; __device__ __forceinline__ void gemm_phase(PG8_LAS unsigned char* lds, const Gemm g, const Sched& S, const Epi& E) {
;     ...
;             PG8_LDB(B0, 0, 0); PG8_LDB(B1, 0, 1); PG8_SCHED; PG8_LDA(At, 0, 0); PG8_STAGE(PG8_SA(1, 1), a1 + hstep, voffA);
;             PG8_WAIT_V(8); PG8_WAIT_L(0); PG8_BAR; PG8_MMA(0, 0, At, B0); PG8_MMA(0, 1, At, B1); PG8_BAR; PG8_SCHED;
	s_add_i32 m0, s65, 0xe000
	s_nop 0
	global_load_lds_dwordx4 v170, s[10:11]
	s_waitcnt vmcnt(8)
	s_waitcnt lgkmcnt(0)
	s_setprio 1
	s_barrier

; #define PG8_MMA(ai, bj, At, Bt) do { __builtin_amdgcn_s_setprio(1); _Pragma("unroll") for (int m = 0; m < 4; ++m) _Pragma("unroll") for (int n = 0; n < 2; ++n) _Pragma("unroll") for (int k = 0; k < 2; ++k) \
;         acc[ai][bj][m][n] = __builtin_amdgcn_mfma_f32_16x16x32_bf16(Bt[n][k], At[m][k], acc[ai][bj][m][n], 0, 0, 0); __builtin_amdgcn_s_setprio(0); } while (0)
; #define PG8_WAIT_V(n) asm volatile("s_waitcnt vmcnt(" #n ")" ::: "memory")
; #define PG8_WAIT_L(n) asm volatile("s_waitcnt lgkmcnt(" #n ")" ::: "memory")
; #define PG8_BAR __builtin_amdgcn_s_barrier()
; #define PG8_SCHED __builtin_amdgcn_sched_barrier(0)
; template <class Epi, class Sched, bool ALIGN_EPI = false, bool SP2 = false>
; __device__ __forceinline__ void gemm_phase(PG8_LAS unsigned char* lds, const Gemm g, const Sched& S, const Epi& E) {
;     ...
;             PG8_WAIT_V(8); PG8_WAIT_L(0); PG8_BAR; PG8_MMA(0, 0, At, B0); PG8_MMA(0, 1, At, B1); PG8_BAR; PG8_SCHED;
	v_mfma_f32_16x16x32_bf16 v[124:127], v[128:131], v[176:179], v[124:127]
	v_mfma_f32_16x16x32_bf16 v[120:123], v[136:139], v[176:179], v[120:123]
	v_mfma_f32_16x16x32_bf16 v[108:111], v[128:131], v[190:193], v[108:111]
	v_mfma_f32_16x16x32_bf16 v[104:107], v[136:139], v[190:193], v[104:107]
	v_mfma_f32_16x16x32_bf16 v[92:95], v[128:131], v[214:217], v[92:95]
	v_mfma_f32_16x16x32_bf16 v[88:91], v[136:139], v[214:217], v[88:91]
	v_mfma_f32_16x16x32_bf16 v[76:79], v[128:131], v[222:225], v[76:79]
	v_mfma_f32_16x16x32_bf16 v[72:75], v[136:139], v[222:225], v[72:75]
	v_mfma_f32_16x16x32_bf16 v[124:127], v[132:135], v[184:187], v[124:127]
	v_mfma_f32_16x16x32_bf16 v[120:123], v[140:143], v[184:187], v[120:123]
	v_mfma_f32_16x16x32_bf16 v[108:111], v[132:135], v[210:213], v[108:111]
	v_mfma_f32_16x16x32_bf16 v[104:107], v[140:143], v[210:213], v[104:107]
	v_mfma_f32_16x16x32_bf16 v[92:95], v[132:135], v[218:221], v[92:95]
	v_mfma_f32_16x16x32_bf16 v[88:91], v[140:143], v[218:221], v[88:91]
	v_mfma_f32_16x16x32_bf16 v[76:79], v[132:135], v[226:229], v[76:79]
	v_mfma_f32_16x16x32_bf16 v[72:75], v[140:143], v[226:229], v[72:75]


; #define PG8_STAGE(bufoff, gbase, voff) do { _Pragma("unroll") for (int _i = 0; _i < 2; ++_i) \
;         __builtin_amdgcn_global_load_lds((const unsigned*)((const char*)(gbase) + (voff)[_i]), (PG8_LAS unsigned*)(lds + (bufoff) + ldsw + _i * 8192), 16, 0, 0); } while (0)
; #define PG8_LDA(dst, b, h) do { _Pragma("unroll") for (int m = 0; m < 4; ++m) _Pragma("unroll") for (int k = 0; k < 2; ++k) dst[m][k] = *(const PG8_LAS bf16x8*)(lds + PG8_SA(b, h) + aoff + m * 2048 + k * 1024); } while (0)
; #define PG8_MMA(ai, bj, At, Bt) do { __builtin_amdgcn_s_setprio(1); _Pragma("unroll") for (int m = 0; m < 4; ++m) _Pragma("unroll") for (int n = 0; n < 2; ++n) _Pragma("unroll") for (int k = 0; k < 2; ++k) \
;         acc[ai][bj][m][n] = __builtin_amdgcn_mfma_f32_16x16x32_bf16(Bt[n][k], At[m][k], acc[ai][bj][m][n], 0, 0, 0); __builtin_amdgcn_s_setprio(0); } while (0)
; #define PG8_WAIT_V(n) asm volatile("s_waitcnt vmcnt(" #n ")" ::: "memory")
; #define PG8_WAIT_L(n) asm volatile("s_waitcnt lgkmcnt(" #n ")" ::: "memory")
; #define PG8_BAR __builtin_amdgcn_s_barrier()
; #define PG8_SCHED __builtin_amdgcn_sched_barrier(0)
; template <class Epi, class Sched, bool ALIGN_EPI = false, bool SP2 = false>
; __device__ __forceinline__ void gemm_phase(PG8_LAS unsigned char* lds, const Gemm g, const Sched& S, const Epi& E) {
;     ...
;             PG8_WAIT_V(8); PG8_WAIT_L(0); PG8_BAR; PG8_MMA(0, 0, At, B0); PG8_MMA(0, 1, At, B1); PG8_BAR; PG8_SCHED;
;             PG8_LDA(At, 0, 1); PG8_STAGE(PG8_SB(0, 0), b2, voffB); PG8_STAGE(PG8_SB(0, 1), b2 + hstep, voffB); PG8_STAGE(PG8_SA(0, 0), a2, voffA);
	v_mfma_f32_16x16x32_bf16 v[116:119], v[144:147], v[176:179], v[116:119]
	v_mfma_f32_16x16x32_bf16 v[112:115], v[152:155], v[176:179], v[112:115]
	v_mfma_f32_16x16x32_bf16 v[100:103], v[144:147], v[190:193], v[100:103]
	v_mfma_f32_16x16x32_bf16 v[96:99], v[152:155], v[190:193], v[96:99]
	v_mfma_f32_16x16x32_bf16 v[84:87], v[144:147], v[214:217], v[84:87]
	v_mfma_f32_16x16x32_bf16 v[80:83], v[152:155], v[214:217], v[80:83]
	v_mfma_f32_16x16x32_bf16 v[68:71], v[144:147], v[222:225], v[68:71]
	v_mfma_f32_16x16x32_bf16 v[64:67], v[152:155], v[222:225], v[64:67]
	v_mfma_f32_16x16x32_bf16 v[116:119], v[148:151], v[184:187], v[116:119]
	v_mfma_f32_16x16x32_bf16 v[112:115], v[156:159], v[184:187], v[112:115]
	v_mfma_f32_16x16x32_bf16 v[100:103], v[148:151], v[210:213], v[100:103]
	v_mfma_f32_16x16x32_bf16 v[96:99], v[156:159], v[210:213], v[96:99]
	v_mfma_f32_16x16x32_bf16 v[84:87], v[148:151], v[218:221], v[84:87]
	v_mfma_f32_16x16x32_bf16 v[80:83], v[156:159], v[218:221], v[80:83]
	v_mfma_f32_16x16x32_bf16 v[68:71], v[148:151], v[226:229], v[68:71]
	v_mfma_f32_16x16x32_bf16 v[64:67], v[156:159], v[226:229], v[64:67]
	s_setprio 0
	s_barrier
	s_add_i32 s86, s75, s64
	s_mov_b64 s[96:97], s[12:13]

; #define PG8_STAGE(bufoff, gbase, voff) do { _Pragma("unroll") for (int _i = 0; _i < 2; ++_i) \
;         __builtin_amdgcn_global_load_lds((const unsigned*)((const char*)(gbase) + (voff)[_i]), (PG8_LAS unsigned*)(lds + (bufoff) + ldsw + _i * 8192), 16, 0, 0); } while (0)
; #define PG8_LDA(dst, b, h) do { _Pragma("unroll") for (int m = 0; m < 4; ++m) _Pragma("unroll") for (int k = 0; k < 2; ++k) dst[m][k] = *(const PG8_LAS bf16x8*)(lds + PG8_SA(b, h) + aoff + m * 2048 + k * 1024); } while (0)
; template <class Epi, class Sched, bool ALIGN_EPI = false, bool SP2 = false>
; __device__ __forceinline__ void gemm_phase(PG8_LAS unsigned char* lds, const Gemm g, const Sched& S, const Epi& E) {
;     ...
;             PG8_LDA(At, 0, 1); PG8_STAGE(PG8_SB(0, 0), b2, voffB); PG8_STAGE(PG8_SB(0, 1), b2 + hstep, voffB); PG8_STAGE(PG8_SA(0, 0), a2, voffA);
	s_mov_b32 m0, s86
	ds_read_b128 v[176:179], v207 offset:16384
	ds_read_b128 v[184:187], v207 offset:17408
	ds_read_b128 v[190:193], v207 offset:18432
	ds_read_b128 v[210:213], v207 offset:19456
	ds_read_b128 v[214:217], v207 offset:20480
	ds_read_b128 v[218:221], v207 offset:21504
	ds_read_b128 v[222:225], v207 offset:22528
	ds_read_b128 v[226:229], v207 offset:23552
	global_load_lds_dwordx4 v162, s[12:13]
	s_add_i32 m0, s86, 0x2000
	s_add_u32 s86, s12, 0x80000

; #define PG8_STAGE(bufoff, gbase, voff) do { _Pragma("unroll") for (int _i = 0; _i < 2; ++_i) \
;         __builtin_amdgcn_global_load_lds((const unsigned*)((const char*)(gbase) + (voff)[_i]), (PG8_LAS unsigned*)(lds + (bufoff) + ldsw + _i * 8192), 16, 0, 0); } while (0)
; #define PG8_LDA(dst, b, h) do { _Pragma("unroll") for (int m = 0; m < 4; ++m) _Pragma("unroll") for (int k = 0; k < 2; ++k) dst[m][k] = *(const PG8_LAS bf16x8*)(lds + PG8_SA(b, h) + aoff + m * 2048 + k * 1024); } while (0)
; template <class Epi, class Sched, bool ALIGN_EPI = false, bool SP2 = false>
; __device__ __forceinline__ void gemm_phase(PG8_LAS unsigned char* lds, const Gemm g, const Sched& S, const Epi& E) {
;     ...
;             PG8_LDA(At, 0, 1); PG8_STAGE(PG8_SB(0, 0), b2, voffB); PG8_STAGE(PG8_SB(0, 1), b2 + hstep, voffB); PG8_STAGE(PG8_SA(0, 0), a2, voffA);
	s_addc_u32 s87, s13, 0
	s_add_i32 s88, s76, s64
	global_load_lds_dwordx4 v166, s[12:13]

; #define PG8_STAGE(bufoff, gbase, voff) do { _Pragma("unroll") for (int _i = 0; _i < 2; ++_i) \
;         __builtin_amdgcn_global_load_lds((const unsigned*)((const char*)(gbase) + (voff)[_i]), (PG8_LAS unsigned*)(lds + (bufoff) + ldsw + _i * 8192), 16, 0, 0); } while (0)
; #define PG8_LDA(dst, b, h) do { _Pragma("unroll") for (int m = 0; m < 4; ++m) _Pragma("unroll") for (int k = 0; k < 2; ++k) dst[m][k] = *(const PG8_LAS bf16x8*)(lds + PG8_SA(b, h) + aoff + m * 2048 + k * 1024); } while (0)
; template <class Epi, class Sched, bool ALIGN_EPI = false, bool SP2 = false>
; __device__ __forceinline__ void gemm_phase(PG8_LAS unsigned char* lds, const Gemm g, const Sched& S, const Epi& E) {
;     ...
;             PG8_LDA(At, 0, 1); PG8_STAGE(PG8_SB(0, 0), b2, voffB); PG8_STAGE(PG8_SB(0, 1), b2 + hstep, voffB); PG8_STAGE(PG8_SA(0, 0), a2, voffA);
	s_mov_b32 m0, s88
	s_nop 0
	global_load_lds_dwordx4 v162, s[86:87]

; #define PG8_STAGE(bufoff, gbase, voff) do { _Pragma("unroll") for (int _i = 0; _i < 2; ++_i) \
;         __builtin_amdgcn_global_load_lds((const unsigned*)((const char*)(gbase) + (voff)[_i]), (PG8_LAS unsigned*)(lds + (bufoff) + ldsw + _i * 8192), 16, 0, 0); } while (0)
; #define PG8_LDA(dst, b, h) do { _Pragma("unroll") for (int m = 0; m < 4; ++m) _Pragma("unroll") for (int k = 0; k < 2; ++k) dst[m][k] = *(const PG8_LAS bf16x8*)(lds + PG8_SA(b, h) + aoff + m * 2048 + k * 1024); } while (0)
; template <class Epi, class Sched, bool ALIGN_EPI = false, bool SP2 = false>
; __device__ __forceinline__ void gemm_phase(PG8_LAS unsigned char* lds, const Gemm g, const Sched& S, const Epi& E) {
;     ...
;             PG8_LDA(At, 0, 1); PG8_STAGE(PG8_SB(0, 0), b2, voffB); PG8_STAGE(PG8_SB(0, 1), b2 + hstep, voffB); PG8_STAGE(PG8_SA(0, 0), a2, voffA);
	s_add_i32 m0, s88, 0x2000
	s_nop 0
	global_load_lds_dwordx4 v166, s[86:87]
	s_mov_b64 s[98:99], s[60:61]

; #define PG8_STAGE(bufoff, gbase, voff) do { _Pragma("unroll") for (int _i = 0; _i < 2; ++_i) \
;         __builtin_amdgcn_global_load_lds((const unsigned*)((const char*)(gbase) + (voff)[_i]), (PG8_LAS unsigned*)(lds + (bufoff) + ldsw + _i * 8192), 16, 0, 0); } while (0)
; #define PG8_LDA(dst, b, h) do { _Pragma("unroll") for (int m = 0; m < 4; ++m) _Pragma("unroll") for (int k = 0; k < 2; ++k) dst[m][k] = *(const PG8_LAS bf16x8*)(lds + PG8_SA(b, h) + aoff + m * 2048 + k * 1024); } while (0)
; #define PG8_MMA(ai, bj, At, Bt) do { __builtin_amdgcn_s_setprio(1); _Pragma("unroll") for (int m = 0; m < 4; ++m) _Pragma("unroll") for (int n = 0; n < 2; ++n) _Pragma("unroll") for (int k = 0; k < 2; ++k) \
;         acc[ai][bj][m][n] = __builtin_amdgcn_mfma_f32_16x16x32_bf16(Bt[n][k], At[m][k], acc[ai][bj][m][n], 0, 0, 0); __builtin_amdgcn_s_setprio(0); } while (0)
; #define PG8_WAIT_V(n) asm volatile("s_waitcnt vmcnt(" #n ")" ::: "memory")
; #define PG8_WAIT_L(n) asm volatile("s_waitcnt lgkmcnt(" #n ")" ::: "memory")
; #define PG8_BAR __builtin_amdgcn_s_barrier()
; #define PG8_SCHED __builtin_amdgcn_sched_barrier(0)
; template <class Epi, class Sched, bool ALIGN_EPI = false, bool SP2 = false>
; __device__ __forceinline__ void gemm_phase(PG8_LAS unsigned char* lds, const Gemm g, const Sched& S, const Epi& E) {
;     ...
;             PG8_LDA(At, 0, 1); PG8_STAGE(PG8_SB(0, 0), b2, voffB); PG8_STAGE(PG8_SB(0, 1), b2 + hstep, voffB); PG8_STAGE(PG8_SA(0, 0), a2, voffA);
;             PG8_WAIT_V(8); PG8_WAIT_L(0); PG8_BAR; PG8_MMA(1, 0, At, B0); PG8_MMA(1, 1, At, B1); PG8_BAR; PG8_SCHED;
	s_mov_b32 m0, s65
	s_nop 0
	global_load_lds_dwordx4 v160, s[60:61]
	s_mov_b32 m0, s67
	s_nop 0
	global_load_lds_dwordx4 v164, s[60:61]
	s_waitcnt vmcnt(8)
	s_waitcnt lgkmcnt(0)
	s_setprio 1
	s_barrier

; #define PG8_MMA(ai, bj, At, Bt) do { __builtin_amdgcn_s_setprio(1); _Pragma("unroll") for (int m = 0; m < 4; ++m) _Pragma("unroll") for (int n = 0; n < 2; ++n) _Pragma("unroll") for (int k = 0; k < 2; ++k) \
;         acc[ai][bj][m][n] = __builtin_amdgcn_mfma_f32_16x16x32_bf16(Bt[n][k], At[m][k], acc[ai][bj][m][n], 0, 0, 0); __builtin_amdgcn_s_setprio(0); } while (0)
; #define PG8_WAIT_V(n) asm volatile("s_waitcnt vmcnt(" #n ")" ::: "memory")
; #define PG8_WAIT_L(n) asm volatile("s_waitcnt lgkmcnt(" #n ")" ::: "memory")
; #define PG8_BAR __builtin_amdgcn_s_barrier()
; #define PG8_SCHED __builtin_amdgcn_sched_barrier(0)
; template <class Epi, class Sched, bool ALIGN_EPI = false, bool SP2 = false>
; __device__ __forceinline__ void gemm_phase(PG8_LAS unsigned char* lds, const Gemm g, const Sched& S, const Epi& E) {
;     ...
;             PG8_WAIT_V(8); PG8_WAIT_L(0); PG8_BAR; PG8_MMA(1, 0, At, B0); PG8_MMA(1, 1, At, B1); PG8_BAR; PG8_SCHED;
	v_mfma_f32_16x16x32_bf16 v[60:63], v[128:131], v[176:179], v[60:63]
	v_mfma_f32_16x16x32_bf16 v[56:59], v[136:139], v[176:179], v[56:59]
	v_mfma_f32_16x16x32_bf16 v[44:47], v[128:131], v[190:193], v[44:47]
	v_mfma_f32_16x16x32_bf16 v[40:43], v[136:139], v[190:193], v[40:43]
	v_mfma_f32_16x16x32_bf16 v[28:31], v[128:131], v[214:217], v[28:31]
	v_mfma_f32_16x16x32_bf16 v[24:27], v[136:139], v[214:217], v[24:27]
	v_mfma_f32_16x16x32_bf16 v[12:15], v[128:131], v[222:225], v[12:15]
	v_mfma_f32_16x16x32_bf16 v[8:11], v[136:139], v[222:225], v[8:11]
	v_mfma_f32_16x16x32_bf16 v[60:63], v[132:135], v[184:187], v[60:63]
	v_mfma_f32_16x16x32_bf16 v[56:59], v[140:143], v[184:187], v[56:59]
	v_mfma_f32_16x16x32_bf16 v[44:47], v[132:135], v[210:213], v[44:47]
	v_mfma_f32_16x16x32_bf16 v[40:43], v[140:143], v[210:213], v[40:43]
	v_mfma_f32_16x16x32_bf16 v[28:31], v[132:135], v[218:221], v[28:31]
	v_mfma_f32_16x16x32_bf16 v[24:27], v[140:143], v[218:221], v[24:27]
	v_mfma_f32_16x16x32_bf16 v[12:15], v[132:135], v[226:229], v[12:15]
	v_mfma_f32_16x16x32_bf16 v[8:11], v[140:143], v[226:229], v[8:11]


; #define PG8_STAGE(bufoff, gbase, voff) do { _Pragma("unroll") for (int _i = 0; _i < 2; ++_i) \
;         __builtin_amdgcn_global_load_lds((const unsigned*)((const char*)(gbase) + (voff)[_i]), (PG8_LAS unsigned*)(lds + (bufoff) + ldsw + _i * 8192), 16, 0, 0); } while (0)
; #define PG8_LDA(dst, b, h) do { _Pragma("unroll") for (int m = 0; m < 4; ++m) _Pragma("unroll") for (int k = 0; k < 2; ++k) dst[m][k] = *(const PG8_LAS bf16x8*)(lds + PG8_SA(b, h) + aoff + m * 2048 + k * 1024); } while (0)
; #define PG8_LDB(dst, b, h) do { _Pragma("unroll") for (int n = 0; n < 2; ++n) _Pragma("unroll") for (int k = 0; k < 2; ++k) dst[n][k] = *(const PG8_LAS bf16x8*)(lds + PG8_SB(b, h) + boff + n * 2048 + k * 1024); } while (0)
; #define PG8_MMA(ai, bj, At, Bt) do { __builtin_amdgcn_s_setprio(1); _Pragma("unroll") for (int m = 0; m < 4; ++m) _Pragma("unroll") for (int n = 0; n < 2; ++n) _Pragma("unroll") for (int k = 0; k < 2; ++k) \
;         acc[ai][bj][m][n] = __builtin_amdgcn_mfma_f32_16x16x32_bf16(Bt[n][k], At[m][k], acc[ai][bj][m][n], 0, 0, 0); __builtin_amdgcn_s_setprio(0); } while (0)
; #define PG8_WAIT_V(n) asm volatile("s_waitcnt vmcnt(" #n ")" ::: "memory")
; #define PG8_WAIT_L(n) asm volatile("s_waitcnt lgkmcnt(" #n ")" ::: "memory")
; #define PG8_BAR __builtin_amdgcn_s_barrier()
; #define PG8_SCHED __builtin_amdgcn_sched_barrier(0)
; template <class Epi, class Sched, bool ALIGN_EPI = false, bool SP2 = false>
; __device__ __forceinline__ void gemm_phase(PG8_LAS unsigned char* lds, const Gemm g, const Sched& S, const Epi& E) {
;     ...
;             PG8_WAIT_V(8); PG8_WAIT_L(0); PG8_BAR; PG8_MMA(1, 0, At, B0); PG8_MMA(1, 1, At, B1); PG8_BAR; PG8_SCHED;
;             PG8_LDB(B0, 1, 0); PG8_LDB(B1, 1, 1); PG8_SCHED; PG8_LDA(At, 1, 0); PG8_STAGE(PG8_SA(0, 1), a2 + hstep, voffA);
	v_mfma_f32_16x16x32_bf16 v[52:55], v[144:147], v[176:179], v[52:55]
	v_mfma_f32_16x16x32_bf16 v[48:51], v[152:155], v[176:179], v[48:51]
	v_mfma_f32_16x16x32_bf16 v[36:39], v[144:147], v[190:193], v[36:39]
	v_mfma_f32_16x16x32_bf16 v[32:35], v[152:155], v[190:193], v[32:35]
	v_mfma_f32_16x16x32_bf16 v[20:23], v[144:147], v[214:217], v[20:23]
	v_mfma_f32_16x16x32_bf16 v[16:19], v[152:155], v[214:217], v[16:19]
	v_mfma_f32_16x16x32_bf16 v[4:7], v[144:147], v[222:225], v[4:7]
	v_mfma_f32_16x16x32_bf16 v[0:3], v[152:155], v[222:225], v[0:3]
	v_mfma_f32_16x16x32_bf16 v[52:55], v[148:151], v[184:187], v[52:55]
	v_mfma_f32_16x16x32_bf16 v[48:51], v[156:159], v[184:187], v[48:51]
	v_mfma_f32_16x16x32_bf16 v[36:39], v[148:151], v[210:213], v[36:39]
	v_mfma_f32_16x16x32_bf16 v[32:35], v[156:159], v[210:213], v[32:35]
	v_mfma_f32_16x16x32_bf16 v[20:23], v[148:151], v[218:221], v[20:23]
	v_mfma_f32_16x16x32_bf16 v[16:19], v[156:159], v[218:221], v[16:19]
	v_mfma_f32_16x16x32_bf16 v[4:7], v[148:151], v[226:229], v[4:7]
	v_mfma_f32_16x16x32_bf16 v[0:3], v[156:159], v[226:229], v[0:3]
	s_setprio 0
	s_barrier
	s_add_i32 s86, 0, 0x18000
	s_add_i32 s87, 0, 0x1c000


; #define PG8_STAGE(bufoff, gbase, voff) do { _Pragma("unroll") for (int _i = 0; _i < 2; ++_i) \
;         __builtin_amdgcn_global_load_lds((const unsigned*)((const char*)(gbase) + (voff)[_i]), (PG8_LAS unsigned*)(lds + (bufoff) + ldsw + _i * 8192), 16, 0, 0); } while (0)
; #define PG8_LDA(dst, b, h) do { _Pragma("unroll") for (int m = 0; m < 4; ++m) _Pragma("unroll") for (int k = 0; k < 2; ++k) dst[m][k] = *(const PG8_LAS bf16x8*)(lds + PG8_SA(b, h) + aoff + m * 2048 + k * 1024); } while (0)
; #define PG8_LDB(dst, b, h) do { _Pragma("unroll") for (int n = 0; n < 2; ++n) _Pragma("unroll") for (int k = 0; k < 2; ++k) dst[n][k] = *(const PG8_LAS bf16x8*)(lds + PG8_SB(b, h) + boff + n * 2048 + k * 1024); } while (0)
; #define PG8_SCHED __builtin_amdgcn_sched_barrier(0)
; template <class Epi, class Sched, bool ALIGN_EPI = false, bool SP2 = false>
; __device__ __forceinline__ void gemm_phase(PG8_LAS unsigned char* lds, const Gemm g, const Sched& S, const Epi& E) {
;     ...
;             PG8_LDB(B0, 1, 0); PG8_LDB(B1, 1, 1); PG8_SCHED; PG8_LDA(At, 1, 0); PG8_STAGE(PG8_SA(0, 1), a2 + hstep, voffA);
	ds_read_b128 v[128:131], v254
	ds_read_b128 v[132:135], v254 offset:1024
	ds_read_b128 v[136:139], v254 offset:2048
	ds_read_b128 v[140:143], v254 offset:3072
	ds_read_b128 v[144:147], v255
	ds_read_b128 v[148:151], v255 offset:1024
	ds_read_b128 v[152:155], v255 offset:2048
	ds_read_b128 v[156:159], v255 offset:3072
	s_add_u32 s60, s60, 0x80000
	s_addc_u32 s61, s61, 0
	s_mov_b32 m0, s68

; #define PG8_STAGE(bufoff, gbase, voff) do { _Pragma("unroll") for (int _i = 0; _i < 2; ++_i) \
;         __builtin_amdgcn_global_load_lds((const unsigned*)((const char*)(gbase) + (voff)[_i]), (PG8_LAS unsigned*)(lds + (bufoff) + ldsw + _i * 8192), 16, 0, 0); } while (0)
; #define PG8_LDA(dst, b, h) do { _Pragma("unroll") for (int m = 0; m < 4; ++m) _Pragma("unroll") for (int k = 0; k < 2; ++k) dst[m][k] = *(const PG8_LAS bf16x8*)(lds + PG8_SA(b, h) + aoff + m * 2048 + k * 1024); } while (0)
; #define PG8_LDB(dst, b, h) do { _Pragma("unroll") for (int n = 0; n < 2; ++n) _Pragma("unroll") for (int k = 0; k < 2; ++k) dst[n][k] = *(const PG8_LAS bf16x8*)(lds + PG8_SB(b, h) + boff + n * 2048 + k * 1024); } while (0)
; #define PG8_SCHED __builtin_amdgcn_sched_barrier(0)
; template <class Epi, class Sched, bool ALIGN_EPI = false, bool SP2 = false>
; __device__ __forceinline__ void gemm_phase(PG8_LAS unsigned char* lds, const Gemm g, const Sched& S, const Epi& E) {
;     ...
;             PG8_LDB(B0, 1, 0); PG8_LDB(B1, 1, 1); PG8_SCHED; PG8_LDA(At, 1, 0); PG8_STAGE(PG8_SA(0, 1), a2 + hstep, voffA);
	ds_read_b128 v[176:179], v207 offset:32768
	ds_read_b128 v[184:187], v207 offset:33792
	ds_read_b128 v[190:193], v207 offset:34816
	ds_read_b128 v[210:213], v207 offset:35840
	ds_read_b128 v[214:217], v207 offset:36864
	ds_read_b128 v[218:221], v207 offset:37888
	ds_read_b128 v[222:225], v207 offset:38912
	ds_read_b128 v[226:229], v207 offset:39936
	global_load_lds_dwordx4 v160, s[60:61]

; #define PG8_STAGE(bufoff, gbase, voff) do { _Pragma("unroll") for (int _i = 0; _i < 2; ++_i) \
;         __builtin_amdgcn_global_load_lds((const unsigned*)((const char*)(gbase) + (voff)[_i]), (PG8_LAS unsigned*)(lds + (bufoff) + ldsw + _i * 8192), 16, 0, 0); } while (0)
; #define PG8_LDA(dst, b, h) do { _Pragma("unroll") for (int m = 0; m < 4; ++m) _Pragma("unroll") for (int k = 0; k < 2; ++k) dst[m][k] = *(const PG8_LAS bf16x8*)(lds + PG8_SA(b, h) + aoff + m * 2048 + k * 1024); } while (0)
; #define PG8_LDB(dst, b, h) do { _Pragma("unroll") for (int n = 0; n < 2; ++n) _Pragma("unroll") for (int k = 0; k < 2; ++k) dst[n][k] = *(const PG8_LAS bf16x8*)(lds + PG8_SB(b, h) + boff + n * 2048 + k * 1024); } while (0)
; #define PG8_MMA(ai, bj, At, Bt) do { __builtin_amdgcn_s_setprio(1); _Pragma("unroll") for (int m = 0; m < 4; ++m) _Pragma("unroll") for (int n = 0; n < 2; ++n) _Pragma("unroll") for (int k = 0; k < 2; ++k) \
;         acc[ai][bj][m][n] = __builtin_amdgcn_mfma_f32_16x16x32_bf16(Bt[n][k], At[m][k], acc[ai][bj][m][n], 0, 0, 0); __builtin_amdgcn_s_setprio(0); } while (0)
; #define PG8_WAIT_V(n) asm volatile("s_waitcnt vmcnt(" #n ")" ::: "memory")
; #define PG8_WAIT_L(n) asm volatile("s_waitcnt lgkmcnt(" #n ")" ::: "memory")
; #define PG8_BAR __builtin_amdgcn_s_barrier()
; #define PG8_SCHED __builtin_amdgcn_sched_barrier(0)
; template <class Epi, class Sched, bool ALIGN_EPI = false, bool SP2 = false>
; __device__ __forceinline__ void gemm_phase(PG8_LAS unsigned char* lds, const Gemm g, const Sched& S, const Epi& E) {
;     ...
;             PG8_LDB(B0, 1, 0); PG8_LDB(B1, 1, 1); PG8_SCHED; PG8_LDA(At, 1, 0); PG8_STAGE(PG8_SA(0, 1), a2 + hstep, voffA);
;             PG8_WAIT_V(8); PG8_WAIT_L(0); PG8_BAR; PG8_MMA(0, 0, At, B0); PG8_MMA(0, 1, At, B1); PG8_BAR; PG8_SCHED;
	s_mov_b32 m0, s69
	s_nop 0
	global_load_lds_dwordx4 v164, s[60:61]
	s_waitcnt vmcnt(8)
	s_waitcnt lgkmcnt(0)
	s_setprio 1
	s_barrier

; #define PG8_MMA(ai, bj, At, Bt) do { __builtin_amdgcn_s_setprio(1); _Pragma("unroll") for (int m = 0; m < 4; ++m) _Pragma("unroll") for (int n = 0; n < 2; ++n) _Pragma("unroll") for (int k = 0; k < 2; ++k) \
;         acc[ai][bj][m][n] = __builtin_amdgcn_mfma_f32_16x16x32_bf16(Bt[n][k], At[m][k], acc[ai][bj][m][n], 0, 0, 0); __builtin_amdgcn_s_setprio(0); } while (0)
; #define PG8_WAIT_V(n) asm volatile("s_waitcnt vmcnt(" #n ")" ::: "memory")
; #define PG8_WAIT_L(n) asm volatile("s_waitcnt lgkmcnt(" #n ")" ::: "memory")
; #define PG8_BAR __builtin_amdgcn_s_barrier()
; #define PG8_SCHED __builtin_amdgcn_sched_barrier(0)
; template <class Epi, class Sched, bool ALIGN_EPI = false, bool SP2 = false>
; __device__ __forceinline__ void gemm_phase(PG8_LAS unsigned char* lds, const Gemm g, const Sched& S, const Epi& E) {
;     ...
;             PG8_WAIT_V(8); PG8_WAIT_L(0); PG8_BAR; PG8_MMA(0, 0, At, B0); PG8_MMA(0, 1, At, B1); PG8_BAR; PG8_SCHED;
	v_mfma_f32_16x16x32_bf16 v[124:127], v[128:131], v[176:179], v[124:127]
	v_mfma_f32_16x16x32_bf16 v[120:123], v[136:139], v[176:179], v[120:123]
	v_mfma_f32_16x16x32_bf16 v[108:111], v[128:131], v[190:193], v[108:111]
	v_mfma_f32_16x16x32_bf16 v[104:107], v[136:139], v[190:193], v[104:107]
	v_mfma_f32_16x16x32_bf16 v[92:95], v[128:131], v[214:217], v[92:95]
	v_mfma_f32_16x16x32_bf16 v[88:91], v[136:139], v[214:217], v[88:91]
	v_mfma_f32_16x16x32_bf16 v[76:79], v[128:131], v[222:225], v[76:79]
	v_mfma_f32_16x16x32_bf16 v[72:75], v[136:139], v[222:225], v[72:75]
	v_mfma_f32_16x16x32_bf16 v[124:127], v[132:135], v[184:187], v[124:127]
	v_mfma_f32_16x16x32_bf16 v[120:123], v[140:143], v[184:187], v[120:123]
	v_mfma_f32_16x16x32_bf16 v[108:111], v[132:135], v[210:213], v[108:111]
	v_mfma_f32_16x16x32_bf16 v[104:107], v[140:143], v[210:213], v[104:107]
	v_mfma_f32_16x16x32_bf16 v[92:95], v[132:135], v[218:221], v[92:95]
	v_mfma_f32_16x16x32_bf16 v[88:91], v[140:143], v[218:221], v[88:91]
	v_mfma_f32_16x16x32_bf16 v[76:79], v[132:135], v[226:229], v[76:79]
	v_mfma_f32_16x16x32_bf16 v[72:75], v[140:143], v[226:229], v[72:75]


; #define PG8_STAGE(bufoff, gbase, voff) do { _Pragma("unroll") for (int _i = 0; _i < 2; ++_i) \
;         __builtin_amdgcn_global_load_lds((const unsigned*)((const char*)(gbase) + (voff)[_i]), (PG8_LAS unsigned*)(lds + (bufoff) + ldsw + _i * 8192), 16, 0, 0); } while (0)
; #define PG8_LDA(dst, b, h) do { _Pragma("unroll") for (int m = 0; m < 4; ++m) _Pragma("unroll") for (int k = 0; k < 2; ++k) dst[m][k] = *(const PG8_LAS bf16x8*)(lds + PG8_SA(b, h) + aoff + m * 2048 + k * 1024); } while (0)
; #define PG8_MMA(ai, bj, At, Bt) do { __builtin_amdgcn_s_setprio(1); _Pragma("unroll") for (int m = 0; m < 4; ++m) _Pragma("unroll") for (int n = 0; n < 2; ++n) _Pragma("unroll") for (int k = 0; k < 2; ++k) \
;         acc[ai][bj][m][n] = __builtin_amdgcn_mfma_f32_16x16x32_bf16(Bt[n][k], At[m][k], acc[ai][bj][m][n], 0, 0, 0); __builtin_amdgcn_s_setprio(0); } while (0)
; #define PG8_WAIT_V(n) asm volatile("s_waitcnt vmcnt(" #n ")" ::: "memory")
; #define PG8_WAIT_L(n) asm volatile("s_waitcnt lgkmcnt(" #n ")" ::: "memory")
; #define PG8_BAR __builtin_amdgcn_s_barrier()
; #define PG8_SCHED __builtin_amdgcn_sched_barrier(0)
; template <class Epi, class Sched, bool ALIGN_EPI = false, bool SP2 = false>
; __device__ __forceinline__ void gemm_phase(PG8_LAS unsigned char* lds, const Gemm g, const Sched& S, const Epi& E) {
;     ...
;             PG8_WAIT_V(8); PG8_WAIT_L(0); PG8_BAR; PG8_MMA(0, 0, At, B0); PG8_MMA(0, 1, At, B1); PG8_BAR; PG8_SCHED;
;             PG8_LDA(At, 1, 1); PG8_STAGE(PG8_SB(1, 0), b3, voffB); PG8_STAGE(PG8_SB(1, 1), b3 + hstep, voffB); PG8_STAGE(PG8_SA(1, 0), a3, voffA);
	v_mfma_f32_16x16x32_bf16 v[116:119], v[144:147], v[176:179], v[116:119]
	v_mfma_f32_16x16x32_bf16 v[112:115], v[152:155], v[176:179], v[112:115]
	v_mfma_f32_16x16x32_bf16 v[100:103], v[144:147], v[190:193], v[100:103]
	v_mfma_f32_16x16x32_bf16 v[96:99], v[152:155], v[190:193], v[96:99]
	v_mfma_f32_16x16x32_bf16 v[84:87], v[144:147], v[214:217], v[84:87]
	v_mfma_f32_16x16x32_bf16 v[80:83], v[152:155], v[214:217], v[80:83]
	v_mfma_f32_16x16x32_bf16 v[68:71], v[144:147], v[222:225], v[68:71]
	v_mfma_f32_16x16x32_bf16 v[64:67], v[152:155], v[222:225], v[64:67]
	v_mfma_f32_16x16x32_bf16 v[116:119], v[148:151], v[184:187], v[116:119]
	v_mfma_f32_16x16x32_bf16 v[112:115], v[156:159], v[184:187], v[112:115]
	v_mfma_f32_16x16x32_bf16 v[100:103], v[148:151], v[210:213], v[100:103]
	v_mfma_f32_16x16x32_bf16 v[96:99], v[156:159], v[210:213], v[96:99]
	v_mfma_f32_16x16x32_bf16 v[84:87], v[148:151], v[218:221], v[84:87]
	v_mfma_f32_16x16x32_bf16 v[80:83], v[156:159], v[218:221], v[80:83]
	v_mfma_f32_16x16x32_bf16 v[68:71], v[148:151], v[226:229], v[68:71]
	v_mfma_f32_16x16x32_bf16 v[64:67], v[156:159], v[226:229], v[64:67]
	s_setprio 0
	s_barrier
	s_add_i32 s60, s86, s64

; #define PG8_STAGE(bufoff, gbase, voff) do { _Pragma("unroll") for (int _i = 0; _i < 2; ++_i) \
;         __builtin_amdgcn_global_load_lds((const unsigned*)((const char*)(gbase) + (voff)[_i]), (PG8_LAS unsigned*)(lds + (bufoff) + ldsw + _i * 8192), 16, 0, 0); } while (0)
; #define PG8_LDA(dst, b, h) do { _Pragma("unroll") for (int m = 0; m < 4; ++m) _Pragma("unroll") for (int k = 0; k < 2; ++k) dst[m][k] = *(const PG8_LAS bf16x8*)(lds + PG8_SA(b, h) + aoff + m * 2048 + k * 1024); } while (0)
; template <class Epi, class Sched, bool ALIGN_EPI = false, bool SP2 = false>
; __device__ __forceinline__ void gemm_phase(PG8_LAS unsigned char* lds, const Gemm g, const Sched& S, const Epi& E) {
;     ...
;             PG8_LDA(At, 1, 1); PG8_STAGE(PG8_SB(1, 0), b3, voffB); PG8_STAGE(PG8_SB(1, 1), b3 + hstep, voffB); PG8_STAGE(PG8_SA(1, 0), a3, voffA);
	s_mov_b32 m0, s60
	ds_read_b128 v[176:179], v207 offset:49152
	ds_read_b128 v[184:187], v207 offset:50176
	ds_read_b128 v[190:193], v207 offset:51200
	ds_read_b128 v[210:213], v207 offset:52224
	ds_read_b128 v[214:217], v207 offset:53248
	ds_read_b128 v[218:221], v207 offset:54272
	ds_read_b128 v[222:225], v207 offset:55296
	ds_read_b128 v[226:229], v207 offset:56320
	global_load_lds_dwordx4 v250, s[96:97]
	s_add_i32 m0, s60, 0x2000
	s_add_u32 s12, s12, 0x80080

; #define PG8_STAGE(bufoff, gbase, voff) do { _Pragma("unroll") for (int _i = 0; _i < 2; ++_i) \
;         __builtin_amdgcn_global_load_lds((const unsigned*)((const char*)(gbase) + (voff)[_i]), (PG8_LAS unsigned*)(lds + (bufoff) + ldsw + _i * 8192), 16, 0, 0); } while (0)
; #define PG8_LDA(dst, b, h) do { _Pragma("unroll") for (int m = 0; m < 4; ++m) _Pragma("unroll") for (int k = 0; k < 2; ++k) dst[m][k] = *(const PG8_LAS bf16x8*)(lds + PG8_SA(b, h) + aoff + m * 2048 + k * 1024); } while (0)
; template <class Epi, class Sched, bool ALIGN_EPI = false, bool SP2 = false>
; __device__ __forceinline__ void gemm_phase(PG8_LAS unsigned char* lds, const Gemm g, const Sched& S, const Epi& E) {
;     ...
;             PG8_LDA(At, 1, 1); PG8_STAGE(PG8_SB(1, 0), b3, voffB); PG8_STAGE(PG8_SB(1, 1), b3 + hstep, voffB); PG8_STAGE(PG8_SA(1, 0), a3, voffA);
	s_addc_u32 s13, s13, 0
	s_add_i32 s60, s87, s64
	global_load_lds_dwordx4 v251, s[96:97]

; #define PG8_STAGE(bufoff, gbase, voff) do { _Pragma("unroll") for (int _i = 0; _i < 2; ++_i) \
;         __builtin_amdgcn_global_load_lds((const unsigned*)((const char*)(gbase) + (voff)[_i]), (PG8_LAS unsigned*)(lds + (bufoff) + ldsw + _i * 8192), 16, 0, 0); } while (0)
; #define PG8_LDA(dst, b, h) do { _Pragma("unroll") for (int m = 0; m < 4; ++m) _Pragma("unroll") for (int k = 0; k < 2; ++k) dst[m][k] = *(const PG8_LAS bf16x8*)(lds + PG8_SA(b, h) + aoff + m * 2048 + k * 1024); } while (0)
; template <class Epi, class Sched, bool ALIGN_EPI = false, bool SP2 = false>
; __device__ __forceinline__ void gemm_phase(PG8_LAS unsigned char* lds, const Gemm g, const Sched& S, const Epi& E) {
;     ...
;             PG8_LDA(At, 1, 1); PG8_STAGE(PG8_SB(1, 0), b3, voffB); PG8_STAGE(PG8_SB(1, 1), b3 + hstep, voffB); PG8_STAGE(PG8_SA(1, 0), a3, voffA);
	s_mov_b32 m0, s60
	s_nop 0
	global_load_lds_dwordx4 v162, s[12:13]

; #define PG8_STAGE(bufoff, gbase, voff) do { _Pragma("unroll") for (int _i = 0; _i < 2; ++_i) \
;         __builtin_amdgcn_global_load_lds((const unsigned*)((const char*)(gbase) + (voff)[_i]), (PG8_LAS unsigned*)(lds + (bufoff) + ldsw + _i * 8192), 16, 0, 0); } while (0)
; #define PG8_LDA(dst, b, h) do { _Pragma("unroll") for (int m = 0; m < 4; ++m) _Pragma("unroll") for (int k = 0; k < 2; ++k) dst[m][k] = *(const PG8_LAS bf16x8*)(lds + PG8_SA(b, h) + aoff + m * 2048 + k * 1024); } while (0)
; template <class Epi, class Sched, bool ALIGN_EPI = false, bool SP2 = false>
; __device__ __forceinline__ void gemm_phase(PG8_LAS unsigned char* lds, const Gemm g, const Sched& S, const Epi& E) {
;     ...
;             PG8_LDA(At, 1, 1); PG8_STAGE(PG8_SB(1, 0), b3, voffB); PG8_STAGE(PG8_SB(1, 1), b3 + hstep, voffB); PG8_STAGE(PG8_SA(1, 0), a3, voffA);
	s_add_i32 m0, s60, 0x2000
	s_nop 0
	global_load_lds_dwordx4 v166, s[12:13]

; #define PG8_STAGE(bufoff, gbase, voff) do { _Pragma("unroll") for (int _i = 0; _i < 2; ++_i) \
;         __builtin_amdgcn_global_load_lds((const unsigned*)((const char*)(gbase) + (voff)[_i]), (PG8_LAS unsigned*)(lds + (bufoff) + ldsw + _i * 8192), 16, 0, 0); } while (0)
; #define PG8_LDA(dst, b, h) do { _Pragma("unroll") for (int m = 0; m < 4; ++m) _Pragma("unroll") for (int k = 0; k < 2; ++k) dst[m][k] = *(const PG8_LAS bf16x8*)(lds + PG8_SA(b, h) + aoff + m * 2048 + k * 1024); } while (0)
; template <class Epi, class Sched, bool ALIGN_EPI = false, bool SP2 = false>
; __device__ __forceinline__ void gemm_phase(PG8_LAS unsigned char* lds, const Gemm g, const Sched& S, const Epi& E) {
;     ...
;             PG8_LDA(At, 1, 1); PG8_STAGE(PG8_SB(1, 0), b3, voffB); PG8_STAGE(PG8_SB(1, 1), b3 + hstep, voffB); PG8_STAGE(PG8_SA(1, 0), a3, voffA);
	s_mov_b32 m0, s71
	s_nop 0
	global_load_lds_dwordx4 v252, s[98:99]

; #define PG8_STAGE(bufoff, gbase, voff) do { _Pragma("unroll") for (int _i = 0; _i < 2; ++_i) \
;         __builtin_amdgcn_global_load_lds((const unsigned*)((const char*)(gbase) + (voff)[_i]), (PG8_LAS unsigned*)(lds + (bufoff) + ldsw + _i * 8192), 16, 0, 0); } while (0)
; #define PG8_LDA(dst, b, h) do { _Pragma("unroll") for (int m = 0; m < 4; ++m) _Pragma("unroll") for (int k = 0; k < 2; ++k) dst[m][k] = *(const PG8_LAS bf16x8*)(lds + PG8_SA(b, h) + aoff + m * 2048 + k * 1024); } while (0)
; #define PG8_MMA(ai, bj, At, Bt) do { __builtin_amdgcn_s_setprio(1); _Pragma("unroll") for (int m = 0; m < 4; ++m) _Pragma("unroll") for (int n = 0; n < 2; ++n) _Pragma("unroll") for (int k = 0; k < 2; ++k) \
;         acc[ai][bj][m][n] = __builtin_amdgcn_mfma_f32_16x16x32_bf16(Bt[n][k], At[m][k], acc[ai][bj][m][n], 0, 0, 0); __builtin_amdgcn_s_setprio(0); } while (0)
; #define PG8_WAIT_V(n) asm volatile("s_waitcnt vmcnt(" #n ")" ::: "memory")
; #define PG8_WAIT_L(n) asm volatile("s_waitcnt lgkmcnt(" #n ")" ::: "memory")
; #define PG8_BAR __builtin_amdgcn_s_barrier()
; #define PG8_SCHED __builtin_amdgcn_sched_barrier(0)
; template <class Epi, class Sched, bool ALIGN_EPI = false, bool SP2 = false>
; __device__ __forceinline__ void gemm_phase(PG8_LAS unsigned char* lds, const Gemm g, const Sched& S, const Epi& E) {
;     ...
;             PG8_LDA(At, 1, 1); PG8_STAGE(PG8_SB(1, 0), b3, voffB); PG8_STAGE(PG8_SB(1, 1), b3 + hstep, voffB); PG8_STAGE(PG8_SA(1, 0), a3, voffA);
;             PG8_WAIT_V(8); PG8_WAIT_L(0); PG8_BAR; PG8_MMA(1, 0, At, B0); PG8_MMA(1, 1, At, B1); PG8_BAR; PG8_SCHED;
	s_mov_b32 m0, s72
	s_nop 0
	global_load_lds_dwordx4 v253, s[98:99]
	s_waitcnt vmcnt(8)
	s_waitcnt lgkmcnt(0)
	s_setprio 1
	s_barrier

; #define PG8_MMA(ai, bj, At, Bt) do { __builtin_amdgcn_s_setprio(1); _Pragma("unroll") for (int m = 0; m < 4; ++m) _Pragma("unroll") for (int n = 0; n < 2; ++n) _Pragma("unroll") for (int k = 0; k < 2; ++k) \
;         acc[ai][bj][m][n] = __builtin_amdgcn_mfma_f32_16x16x32_bf16(Bt[n][k], At[m][k], acc[ai][bj][m][n], 0, 0, 0); __builtin_amdgcn_s_setprio(0); } while (0)
; #define PG8_WAIT_V(n) asm volatile("s_waitcnt vmcnt(" #n ")" ::: "memory")
; #define PG8_WAIT_L(n) asm volatile("s_waitcnt lgkmcnt(" #n ")" ::: "memory")
; #define PG8_BAR __builtin_amdgcn_s_barrier()
; #define PG8_SCHED __builtin_amdgcn_sched_barrier(0)
; template <class Epi, class Sched, bool ALIGN_EPI = false, bool SP2 = false>
; __device__ __forceinline__ void gemm_phase(PG8_LAS unsigned char* lds, const Gemm g, const Sched& S, const Epi& E) {
;     ...
;             PG8_WAIT_V(8); PG8_WAIT_L(0); PG8_BAR; PG8_MMA(1, 0, At, B0); PG8_MMA(1, 1, At, B1); PG8_BAR; PG8_SCHED;
	v_mfma_f32_16x16x32_bf16 v[60:63], v[128:131], v[176:179], v[60:63]
	v_mfma_f32_16x16x32_bf16 v[56:59], v[136:139], v[176:179], v[56:59]
	v_mfma_f32_16x16x32_bf16 v[44:47], v[128:131], v[190:193], v[44:47]
	v_mfma_f32_16x16x32_bf16 v[40:43], v[136:139], v[190:193], v[40:43]
	v_mfma_f32_16x16x32_bf16 v[28:31], v[128:131], v[214:217], v[28:31]
	v_mfma_f32_16x16x32_bf16 v[24:27], v[136:139], v[214:217], v[24:27]
	v_mfma_f32_16x16x32_bf16 v[12:15], v[128:131], v[222:225], v[12:15]
	v_mfma_f32_16x16x32_bf16 v[8:11], v[136:139], v[222:225], v[8:11]
	v_mfma_f32_16x16x32_bf16 v[60:63], v[132:135], v[184:187], v[60:63]
	v_mfma_f32_16x16x32_bf16 v[56:59], v[140:143], v[184:187], v[56:59]
	v_mfma_f32_16x16x32_bf16 v[44:47], v[132:135], v[210:213], v[44:47]
	v_mfma_f32_16x16x32_bf16 v[40:43], v[140:143], v[210:213], v[40:43]
	v_mfma_f32_16x16x32_bf16 v[28:31], v[132:135], v[218:221], v[28:31]
	v_mfma_f32_16x16x32_bf16 v[24:27], v[140:143], v[218:221], v[24:27]
	v_mfma_f32_16x16x32_bf16 v[12:15], v[132:135], v[226:229], v[12:15]
	v_mfma_f32_16x16x32_bf16 v[8:11], v[140:143], v[226:229], v[8:11]


; #define PG8_STAGE(bufoff, gbase, voff) do { _Pragma("unroll") for (int _i = 0; _i < 2; ++_i) \
;         __builtin_amdgcn_global_load_lds((const unsigned*)((const char*)(gbase) + (voff)[_i]), (PG8_LAS unsigned*)(lds + (bufoff) + ldsw + _i * 8192), 16, 0, 0); } while (0)
; #define PG8_LDA(dst, b, h) do { _Pragma("unroll") for (int m = 0; m < 4; ++m) _Pragma("unroll") for (int k = 0; k < 2; ++k) dst[m][k] = *(const PG8_LAS bf16x8*)(lds + PG8_SA(b, h) + aoff + m * 2048 + k * 1024); } while (0)
; #define PG8_WAIT_V(n) asm volatile("s_waitcnt vmcnt(" #n ")" ::: "memory")
; #define PG8_WAIT_L(n) asm volatile("s_waitcnt lgkmcnt(" #n ")" ::: "memory")
; template <class Epi, class Sched, bool ALIGN_EPI = false, bool SP2 = false>
; __device__ __forceinline__ void gemm_phase(PG8_LAS unsigned char* lds, const Gemm g, const Sched& S, const Epi& E) {
;     ...
;         for (int t = 0; t < nt; t += 2) {
;             const bool last = (t == nt - 2);
;             const char* a1 = cA + (size_t)(t + 1) * kstep;
;             const char* a2 = last ? nA : cA + (size_t)(t + 2) * kstep; const char* b2 = last ? nB : cB + (size_t)(t + 2) * kstep;
;             const char* a3 = a2 + kstep; const char* b3 = b2 + kstep;
;             if (last && has_next) S.a_ready(nxt);
;             if constexpr (SP2) {
;             PG8_LDB(B0, 0, 0); PG8_LDB(B1, 0, 1); PG8_SCHED; PG8_LDA(At, 0, 0); PG8_STAGE(PG8_SA(1, 1), a1 + hstep, voffA);
;             PG8_WAIT_V(8); PG8_WAIT_L(0); PG8_BAR; PG8_MMA(0, 0, At, B0); PG8_MMA(0, 1, At, B1); PG8_BAR; PG8_SCHED;
;             PG8_LDA(At, 0, 1); PG8_STAGE(PG8_SB(0, 0), b2, voffB); PG8_STAGE(PG8_SB(0, 1), b2 + hstep, voffB); PG8_STAGE(PG8_SA(0, 0), a2, voffA);
;             PG8_WAIT_V(8); PG8_WAIT_L(0); PG8_BAR; PG8_MMA(1, 0, At, B0); PG8_MMA(1, 1, At, B1); PG8_BAR; PG8_SCHED;
;             PG8_LDB(B0, 1, 0); PG8_LDB(B1, 1, 1); PG8_SCHED; PG8_LDA(At, 1, 0); PG8_STAGE(PG8_SA(0, 1), a2 + hstep, voffA);
;             PG8_WAIT_V(8); PG8_WAIT_L(0); PG8_BAR; PG8_MMA(0, 0, At, B0); PG8_MMA(0, 1, At, B1); PG8_BAR; PG8_SCHED;
;             PG8_LDA(At, 1, 1); PG8_STAGE(PG8_SB(1, 0), b3, voffB); PG8_STAGE(PG8_SB(1, 1), b3 + hstep, voffB); PG8_STAGE(PG8_SA(1, 0), a3, voffA);
;             PG8_WAIT_V(8); PG8_WAIT_L(0); PG8_BAR; PG8_MMA(1, 0, At, B0); PG8_MMA(1, 1, At, B1); PG8_BAR; PG8_SCHED;
;     ...
;         if constexpr (ALIGN_EPI) { if (wr == 0) PG8_BAR; }
	v_mfma_f32_16x16x32_bf16 v[52:55], v[144:147], v[176:179], v[52:55]
	v_mfma_f32_16x16x32_bf16 v[48:51], v[152:155], v[176:179], v[48:51]
	v_mfma_f32_16x16x32_bf16 v[36:39], v[144:147], v[190:193], v[36:39]
	v_mfma_f32_16x16x32_bf16 v[32:35], v[152:155], v[190:193], v[32:35]
	v_mfma_f32_16x16x32_bf16 v[20:23], v[144:147], v[214:217], v[20:23]
	v_mfma_f32_16x16x32_bf16 v[16:19], v[152:155], v[214:217], v[16:19]
	v_mfma_f32_16x16x32_bf16 v[4:7], v[144:147], v[222:225], v[4:7]
	v_mfma_f32_16x16x32_bf16 v[0:3], v[152:155], v[222:225], v[0:3]
	v_mfma_f32_16x16x32_bf16 v[52:55], v[148:151], v[184:187], v[52:55]
	v_mfma_f32_16x16x32_bf16 v[48:51], v[156:159], v[184:187], v[48:51]
	v_mfma_f32_16x16x32_bf16 v[36:39], v[148:151], v[210:213], v[36:39]
	v_mfma_f32_16x16x32_bf16 v[32:35], v[156:159], v[210:213], v[32:35]
	v_mfma_f32_16x16x32_bf16 v[20:23], v[148:151], v[218:221], v[20:23]
	v_mfma_f32_16x16x32_bf16 v[16:19], v[156:159], v[218:221], v[16:19]
	v_mfma_f32_16x16x32_bf16 v[4:7], v[148:151], v[226:229], v[4:7]
	v_mfma_f32_16x16x32_bf16 v[0:3], v[156:159], v[226:229], v[0:3]
	s_setprio 0
	s_barrier
	s_add_i32 s85, s85, 2
	s_add_u32 s10, s10, 0x100
	s_addc_u32 s11, s11, 0
	s_add_u32 s83, s83, 0x100
	s_addc_u32 s84, s84, 0
	s_cmp_gt_u32 s85, 29
	s_cbranch_scc0 .LBB0_428
	s_and_b64 vcc, exec, s[42:43]
	s_cbranch_vccz .LBB0_431
	s_barrier

; #define PG8_STAGE(bufoff, gbase, voff) do { _Pragma("unroll") for (int _i = 0; _i < 2; ++_i) \
;         __builtin_amdgcn_global_load_lds((const unsigned*)((const char*)(gbase) + (voff)[_i]), (PG8_LAS unsigned*)(lds + (bufoff) + ldsw + _i * 8192), 16, 0, 0); } while (0)
; #define PG8_LDA(dst, b, h) do { _Pragma("unroll") for (int m = 0; m < 4; ++m) _Pragma("unroll") for (int k = 0; k < 2; ++k) dst[m][k] = *(const PG8_LAS bf16x8*)(lds + PG8_SA(b, h) + aoff + m * 2048 + k * 1024); } while (0)
; #define PG8_LDB(dst, b, h) do { _Pragma("unroll") for (int n = 0; n < 2; ++n) _Pragma("unroll") for (int k = 0; k < 2; ++k) dst[n][k] = *(const PG8_LAS bf16x8*)(lds + PG8_SB(b, h) + boff + n * 2048 + k * 1024); } while (0)
; #define PG8_SCHED __builtin_amdgcn_sched_barrier(0)
; template <class Epi, class Sched, bool ALIGN_EPI = false, bool SP2 = false>
; __device__ __forceinline__ void gemm_phase(PG8_LAS unsigned char* lds, const Gemm g, const Sched& S, const Epi& E) {
;     ...
;             const char* a2 = last ? nA : cA + (size_t)(t + 2) * kstep; const char* b2 = last ? nB : cB + (size_t)(t + 2) * kstep;
;             const char* a3 = a2 + kstep; const char* b3 = b2 + kstep;
;             if (last && has_next) S.a_ready(nxt);
;             if constexpr (SP2) {
;             PG8_LDB(B0, 0, 0); PG8_LDB(B1, 0, 1); PG8_SCHED; PG8_LDA(At, 0, 0); PG8_STAGE(PG8_SA(1, 1), a1 + hstep, voffA);
.LBB0_509:
	ds_read_b128 v[64:67], v213
	ds_read_b128 v[68:71], v213 offset:1024
	ds_read_b128 v[72:75], v213 offset:2048
	ds_read_b128 v[76:79], v213 offset:3072
	ds_read_b128 v[144:147], v214
	ds_read_b128 v[148:151], v214 offset:1024
	ds_read_b128 v[152:155], v214 offset:2048
	ds_read_b128 v[156:159], v214 offset:3072
	s_add_u32 s60, s58, 0xffe00080
	s_addc_u32 s61, s59, -1
	s_cmpk_eq_i32 s81, 0x7c
	s_cselect_b32 s63, s11, s61
	s_cselect_b32 s62, s51, s60
	s_cselect_b32 s61, s49, s80
	s_cselect_b32 s60, s78, s79

; #define PG8_STAGE(bufoff, gbase, voff) do { _Pragma("unroll") for (int _i = 0; _i < 2; ++_i) \
;         __builtin_amdgcn_global_load_lds((const unsigned*)((const char*)(gbase) + (voff)[_i]), (PG8_LAS unsigned*)(lds + (bufoff) + ldsw + _i * 8192), 16, 0, 0); } while (0)
; #define PG8_LDA(dst, b, h) do { _Pragma("unroll") for (int m = 0; m < 4; ++m) _Pragma("unroll") for (int k = 0; k < 2; ++k) dst[m][k] = *(const PG8_LAS bf16x8*)(lds + PG8_SA(b, h) + aoff + m * 2048 + k * 1024); } while (0)
; #define PG8_LDB(dst, b, h) do { _Pragma("unroll") for (int n = 0; n < 2; ++n) _Pragma("unroll") for (int k = 0; k < 2; ++k) dst[n][k] = *(const PG8_LAS bf16x8*)(lds + PG8_SB(b, h) + boff + n * 2048 + k * 1024); } while (0)
; #define PG8_SCHED __builtin_amdgcn_sched_barrier(0)
; template <class Epi, class Sched, bool ALIGN_EPI = false, bool SP2 = false>
; __device__ __forceinline__ void gemm_phase(PG8_LAS unsigned char* lds, const Gemm g, const Sched& S, const Epi& E) {
;     ...
;             PG8_LDB(B0, 0, 0); PG8_LDB(B1, 0, 1); PG8_SCHED; PG8_LDA(At, 0, 0); PG8_STAGE(PG8_SA(1, 1), a1 + hstep, voffA);
	s_add_i32 m0, s57, 0xc000
	ds_read_b128 v[176:179], v215
	ds_read_b128 v[180:183], v215 offset:1024
	ds_read_b128 v[184:187], v215 offset:2048
	ds_read_b128 v[188:191], v215 offset:3072
	ds_read_b128 v[192:195], v215 offset:4096
	ds_read_b128 v[196:199], v215 offset:5120
	ds_read_b128 v[200:203], v215 offset:6144
	ds_read_b128 v[204:207], v215 offset:7168
	global_load_lds_dwordx4 v168, s[58:59]

; #define PG8_STAGE(bufoff, gbase, voff) do { _Pragma("unroll") for (int _i = 0; _i < 2; ++_i) \
;         __builtin_amdgcn_global_load_lds((const unsigned*)((const char*)(gbase) + (voff)[_i]), (PG8_LAS unsigned*)(lds + (bufoff) + ldsw + _i * 8192), 16, 0, 0); } while (0)
; #define PG8_LDA(dst, b, h) do { _Pragma("unroll") for (int m = 0; m < 4; ++m) _Pragma("unroll") for (int k = 0; k < 2; ++k) dst[m][k] = *(const PG8_LAS bf16x8*)(lds + PG8_SA(b, h) + aoff + m * 2048 + k * 1024); } while (0)
; #define PG8_LDB(dst, b, h) do { _Pragma("unroll") for (int n = 0; n < 2; ++n) _Pragma("unroll") for (int k = 0; k < 2; ++k) dst[n][k] = *(const PG8_LAS bf16x8*)(lds + PG8_SB(b, h) + boff + n * 2048 + k * 1024); } while (0)
; #define PG8_MMA(ai, bj, At, Bt) do { __builtin_amdgcn_s_setprio(1); _Pragma("unroll") for (int m = 0; m < 4; ++m) _Pragma("unroll") for (int n = 0; n < 2; ++n) _Pragma("unroll") for (int k = 0; k < 2; ++k) \
;         acc[ai][bj][m][n] = __builtin_amdgcn_mfma_f32_16x16x32_bf16(Bt[n][k], At[m][k], acc[ai][bj][m][n], 0, 0, 0); __builtin_amdgcn_s_setprio(0); } while (0)
; #define PG8_WAIT_V(n) asm volatile("s_waitcnt vmcnt(" #n ")" ::: "memory")
; #define PG8_WAIT_L(n) asm volatile("s_waitcnt lgkmcnt(" #n ")" ::: "memory")
; #define PG8_BAR __builtin_amdgcn_s_barrier()
; #define PG8_SCHED __builtin_amdgcn_sched_barrier(0)
; template <class Epi, class Sched, bool ALIGN_EPI = false, bool SP2 = false>
; __device__ __forceinline__ void gemm_phase(PG8_LAS unsigned char* lds, const Gemm g, const Sched& S, const Epi& E) {
;     ...
;             PG8_LDB(B0, 0, 0); PG8_LDB(B1, 0, 1); PG8_SCHED; PG8_LDA(At, 0, 0); PG8_STAGE(PG8_SA(1, 1), a1 + hstep, voffA);
;             PG8_WAIT_V(8); PG8_WAIT_L(0); PG8_BAR; PG8_MMA(0, 0, At, B0); PG8_MMA(0, 1, At, B1); PG8_BAR; PG8_SCHED;
	s_add_i32 m0, s57, 0xe000
	s_nop 0
	global_load_lds_dwordx4 v170, s[58:59]
	s_waitcnt vmcnt(8)
	s_waitcnt lgkmcnt(0)
	s_setprio 1
	s_barrier

; #define PG8_MMA(ai, bj, At, Bt) do { __builtin_amdgcn_s_setprio(1); _Pragma("unroll") for (int m = 0; m < 4; ++m) _Pragma("unroll") for (int n = 0; n < 2; ++n) _Pragma("unroll") for (int k = 0; k < 2; ++k) \
;         acc[ai][bj][m][n] = __builtin_amdgcn_mfma_f32_16x16x32_bf16(Bt[n][k], At[m][k], acc[ai][bj][m][n], 0, 0, 0); __builtin_amdgcn_s_setprio(0); } while (0)
; #define PG8_WAIT_V(n) asm volatile("s_waitcnt vmcnt(" #n ")" ::: "memory")
; #define PG8_WAIT_L(n) asm volatile("s_waitcnt lgkmcnt(" #n ")" ::: "memory")
; #define PG8_BAR __builtin_amdgcn_s_barrier()
; #define PG8_SCHED __builtin_amdgcn_sched_barrier(0)
; template <class Epi, class Sched, bool ALIGN_EPI = false, bool SP2 = false>
; __device__ __forceinline__ void gemm_phase(PG8_LAS unsigned char* lds, const Gemm g, const Sched& S, const Epi& E) {
;     ...
;             PG8_WAIT_V(8); PG8_WAIT_L(0); PG8_BAR; PG8_MMA(0, 0, At, B0); PG8_MMA(0, 1, At, B1); PG8_BAR; PG8_SCHED;
	v_mfma_f32_16x16x32_bf16 v[140:143], v[64:67], v[176:179], v[140:143]
	v_mfma_f32_16x16x32_bf16 v[136:139], v[72:75], v[176:179], v[136:139]
	v_mfma_f32_16x16x32_bf16 v[124:127], v[64:67], v[184:187], v[124:127]
	v_mfma_f32_16x16x32_bf16 v[120:123], v[72:75], v[184:187], v[120:123]
	v_mfma_f32_16x16x32_bf16 v[108:111], v[64:67], v[192:195], v[108:111]
	v_mfma_f32_16x16x32_bf16 v[104:107], v[72:75], v[192:195], v[104:107]
	v_mfma_f32_16x16x32_bf16 v[92:95], v[64:67], v[200:203], v[92:95]
	v_mfma_f32_16x16x32_bf16 v[88:91], v[72:75], v[200:203], v[88:91]
	v_mfma_f32_16x16x32_bf16 v[140:143], v[68:71], v[180:183], v[140:143]
	v_mfma_f32_16x16x32_bf16 v[136:139], v[76:79], v[180:183], v[136:139]
	v_mfma_f32_16x16x32_bf16 v[124:127], v[68:71], v[188:191], v[124:127]
	v_mfma_f32_16x16x32_bf16 v[120:123], v[76:79], v[188:191], v[120:123]
	v_mfma_f32_16x16x32_bf16 v[108:111], v[68:71], v[196:199], v[108:111]
	v_mfma_f32_16x16x32_bf16 v[104:107], v[76:79], v[196:199], v[104:107]
	v_mfma_f32_16x16x32_bf16 v[92:95], v[68:71], v[204:207], v[92:95]
	v_mfma_f32_16x16x32_bf16 v[88:91], v[76:79], v[204:207], v[88:91]


; #define PG8_STAGE(bufoff, gbase, voff) do { _Pragma("unroll") for (int _i = 0; _i < 2; ++_i) \
;         __builtin_amdgcn_global_load_lds((const unsigned*)((const char*)(gbase) + (voff)[_i]), (PG8_LAS unsigned*)(lds + (bufoff) + ldsw + _i * 8192), 16, 0, 0); } while (0)
; #define PG8_LDA(dst, b, h) do { _Pragma("unroll") for (int m = 0; m < 4; ++m) _Pragma("unroll") for (int k = 0; k < 2; ++k) dst[m][k] = *(const PG8_LAS bf16x8*)(lds + PG8_SA(b, h) + aoff + m * 2048 + k * 1024); } while (0)
; #define PG8_MMA(ai, bj, At, Bt) do { __builtin_amdgcn_s_setprio(1); _Pragma("unroll") for (int m = 0; m < 4; ++m) _Pragma("unroll") for (int n = 0; n < 2; ++n) _Pragma("unroll") for (int k = 0; k < 2; ++k) \
;         acc[ai][bj][m][n] = __builtin_amdgcn_mfma_f32_16x16x32_bf16(Bt[n][k], At[m][k], acc[ai][bj][m][n], 0, 0, 0); __builtin_amdgcn_s_setprio(0); } while (0)
; #define PG8_WAIT_V(n) asm volatile("s_waitcnt vmcnt(" #n ")" ::: "memory")
; #define PG8_WAIT_L(n) asm volatile("s_waitcnt lgkmcnt(" #n ")" ::: "memory")
; #define PG8_BAR __builtin_amdgcn_s_barrier()
; #define PG8_SCHED __builtin_amdgcn_sched_barrier(0)
; template <class Epi, class Sched, bool ALIGN_EPI = false, bool SP2 = false>
; __device__ __forceinline__ void gemm_phase(PG8_LAS unsigned char* lds, const Gemm g, const Sched& S, const Epi& E) {
;     ...
;             PG8_WAIT_V(8); PG8_WAIT_L(0); PG8_BAR; PG8_MMA(0, 0, At, B0); PG8_MMA(0, 1, At, B1); PG8_BAR; PG8_SCHED;
;             PG8_LDA(At, 0, 1); PG8_STAGE(PG8_SB(0, 0), b2, voffB); PG8_STAGE(PG8_SB(0, 1), b2 + hstep, voffB); PG8_STAGE(PG8_SA(0, 0), a2, voffA);
	v_mfma_f32_16x16x32_bf16 v[132:135], v[144:147], v[176:179], v[132:135]
	v_mfma_f32_16x16x32_bf16 v[128:131], v[152:155], v[176:179], v[128:131]
	v_mfma_f32_16x16x32_bf16 v[116:119], v[144:147], v[184:187], v[116:119]
	v_mfma_f32_16x16x32_bf16 v[112:115], v[152:155], v[184:187], v[112:115]
	v_mfma_f32_16x16x32_bf16 v[100:103], v[144:147], v[192:195], v[100:103]
	v_mfma_f32_16x16x32_bf16 v[96:99], v[152:155], v[192:195], v[96:99]
	v_mfma_f32_16x16x32_bf16 v[84:87], v[144:147], v[200:203], v[84:87]
	v_mfma_f32_16x16x32_bf16 v[80:83], v[152:155], v[200:203], v[80:83]
	v_mfma_f32_16x16x32_bf16 v[132:135], v[148:151], v[180:183], v[132:135]
	v_mfma_f32_16x16x32_bf16 v[128:131], v[156:159], v[180:183], v[128:131]
	v_mfma_f32_16x16x32_bf16 v[116:119], v[148:151], v[188:191], v[116:119]
	v_mfma_f32_16x16x32_bf16 v[112:115], v[156:159], v[188:191], v[112:115]
	v_mfma_f32_16x16x32_bf16 v[100:103], v[148:151], v[196:199], v[100:103]
	v_mfma_f32_16x16x32_bf16 v[96:99], v[156:159], v[196:199], v[96:99]
	v_mfma_f32_16x16x32_bf16 v[84:87], v[148:151], v[204:207], v[84:87]
	v_mfma_f32_16x16x32_bf16 v[80:83], v[156:159], v[204:207], v[80:83]
	s_setprio 0
	s_barrier
	s_add_i32 s82, s75, s64
	s_mov_b64 s[96:97], s[60:61]

; #define PG8_STAGE(bufoff, gbase, voff) do { _Pragma("unroll") for (int _i = 0; _i < 2; ++_i) \
;         __builtin_amdgcn_global_load_lds((const unsigned*)((const char*)(gbase) + (voff)[_i]), (PG8_LAS unsigned*)(lds + (bufoff) + ldsw + _i * 8192), 16, 0, 0); } while (0)
; #define PG8_LDA(dst, b, h) do { _Pragma("unroll") for (int m = 0; m < 4; ++m) _Pragma("unroll") for (int k = 0; k < 2; ++k) dst[m][k] = *(const PG8_LAS bf16x8*)(lds + PG8_SA(b, h) + aoff + m * 2048 + k * 1024); } while (0)
; template <class Epi, class Sched, bool ALIGN_EPI = false, bool SP2 = false>
; __device__ __forceinline__ void gemm_phase(PG8_LAS unsigned char* lds, const Gemm g, const Sched& S, const Epi& E) {
;     ...
;             PG8_LDA(At, 0, 1); PG8_STAGE(PG8_SB(0, 0), b2, voffB); PG8_STAGE(PG8_SB(0, 1), b2 + hstep, voffB); PG8_STAGE(PG8_SA(0, 0), a2, voffA);
	s_mov_b32 m0, s82
	ds_read_b128 v[176:179], v215 offset:16384
	ds_read_b128 v[180:183], v215 offset:17408
	ds_read_b128 v[184:187], v215 offset:18432
	ds_read_b128 v[188:191], v215 offset:19456
	ds_read_b128 v[192:195], v215 offset:20480
	ds_read_b128 v[196:199], v215 offset:21504
	ds_read_b128 v[200:203], v215 offset:22528
	ds_read_b128 v[204:207], v215 offset:23552
	global_load_lds_dwordx4 v162, s[60:61]
	s_add_i32 m0, s82, 0x2000
	s_add_u32 s82, s60, 0x200000

; #define PG8_STAGE(bufoff, gbase, voff) do { _Pragma("unroll") for (int _i = 0; _i < 2; ++_i) \
;         __builtin_amdgcn_global_load_lds((const unsigned*)((const char*)(gbase) + (voff)[_i]), (PG8_LAS unsigned*)(lds + (bufoff) + ldsw + _i * 8192), 16, 0, 0); } while (0)
; #define PG8_LDA(dst, b, h) do { _Pragma("unroll") for (int m = 0; m < 4; ++m) _Pragma("unroll") for (int k = 0; k < 2; ++k) dst[m][k] = *(const PG8_LAS bf16x8*)(lds + PG8_SA(b, h) + aoff + m * 2048 + k * 1024); } while (0)
; template <class Epi, class Sched, bool ALIGN_EPI = false, bool SP2 = false>
; __device__ __forceinline__ void gemm_phase(PG8_LAS unsigned char* lds, const Gemm g, const Sched& S, const Epi& E) {
;     ...
;             PG8_LDA(At, 0, 1); PG8_STAGE(PG8_SB(0, 0), b2, voffB); PG8_STAGE(PG8_SB(0, 1), b2 + hstep, voffB); PG8_STAGE(PG8_SA(0, 0), a2, voffA);
	s_addc_u32 s83, s61, 0
	s_add_i32 s84, s76, s64
	global_load_lds_dwordx4 v166, s[60:61]

; #define PG8_STAGE(bufoff, gbase, voff) do { _Pragma("unroll") for (int _i = 0; _i < 2; ++_i) \
;         __builtin_amdgcn_global_load_lds((const unsigned*)((const char*)(gbase) + (voff)[_i]), (PG8_LAS unsigned*)(lds + (bufoff) + ldsw + _i * 8192), 16, 0, 0); } while (0)
; #define PG8_LDA(dst, b, h) do { _Pragma("unroll") for (int m = 0; m < 4; ++m) _Pragma("unroll") for (int k = 0; k < 2; ++k) dst[m][k] = *(const PG8_LAS bf16x8*)(lds + PG8_SA(b, h) + aoff + m * 2048 + k * 1024); } while (0)
; template <class Epi, class Sched, bool ALIGN_EPI = false, bool SP2 = false>
; __device__ __forceinline__ void gemm_phase(PG8_LAS unsigned char* lds, const Gemm g, const Sched& S, const Epi& E) {
;     ...
;             PG8_LDA(At, 0, 1); PG8_STAGE(PG8_SB(0, 0), b2, voffB); PG8_STAGE(PG8_SB(0, 1), b2 + hstep, voffB); PG8_STAGE(PG8_SA(0, 0), a2, voffA);
	s_mov_b32 m0, s84
	s_nop 0
	global_load_lds_dwordx4 v162, s[82:83]

; #define PG8_STAGE(bufoff, gbase, voff) do { _Pragma("unroll") for (int _i = 0; _i < 2; ++_i) \
;         __builtin_amdgcn_global_load_lds((const unsigned*)((const char*)(gbase) + (voff)[_i]), (PG8_LAS unsigned*)(lds + (bufoff) + ldsw + _i * 8192), 16, 0, 0); } while (0)
; #define PG8_LDA(dst, b, h) do { _Pragma("unroll") for (int m = 0; m < 4; ++m) _Pragma("unroll") for (int k = 0; k < 2; ++k) dst[m][k] = *(const PG8_LAS bf16x8*)(lds + PG8_SA(b, h) + aoff + m * 2048 + k * 1024); } while (0)
; template <class Epi, class Sched, bool ALIGN_EPI = false, bool SP2 = false>
; __device__ __forceinline__ void gemm_phase(PG8_LAS unsigned char* lds, const Gemm g, const Sched& S, const Epi& E) {
;     ...
;             PG8_LDA(At, 0, 1); PG8_STAGE(PG8_SB(0, 0), b2, voffB); PG8_STAGE(PG8_SB(0, 1), b2 + hstep, voffB); PG8_STAGE(PG8_SA(0, 0), a2, voffA);
	s_add_i32 m0, s84, 0x2000
	s_nop 0
	global_load_lds_dwordx4 v166, s[82:83]
	s_mov_b64 s[98:99], s[62:63]

; #define PG8_STAGE(bufoff, gbase, voff) do { _Pragma("unroll") for (int _i = 0; _i < 2; ++_i) \
;         __builtin_amdgcn_global_load_lds((const unsigned*)((const char*)(gbase) + (voff)[_i]), (PG8_LAS unsigned*)(lds + (bufoff) + ldsw + _i * 8192), 16, 0, 0); } while (0)
; #define PG8_LDA(dst, b, h) do { _Pragma("unroll") for (int m = 0; m < 4; ++m) _Pragma("unroll") for (int k = 0; k < 2; ++k) dst[m][k] = *(const PG8_LAS bf16x8*)(lds + PG8_SA(b, h) + aoff + m * 2048 + k * 1024); } while (0)
; #define PG8_MMA(ai, bj, At, Bt) do { __builtin_amdgcn_s_setprio(1); _Pragma("unroll") for (int m = 0; m < 4; ++m) _Pragma("unroll") for (int n = 0; n < 2; ++n) _Pragma("unroll") for (int k = 0; k < 2; ++k) \
;         acc[ai][bj][m][n] = __builtin_amdgcn_mfma_f32_16x16x32_bf16(Bt[n][k], At[m][k], acc[ai][bj][m][n], 0, 0, 0); __builtin_amdgcn_s_setprio(0); } while (0)
; #define PG8_WAIT_V(n) asm volatile("s_waitcnt vmcnt(" #n ")" ::: "memory")
; #define PG8_WAIT_L(n) asm volatile("s_waitcnt lgkmcnt(" #n ")" ::: "memory")
; #define PG8_BAR __builtin_amdgcn_s_barrier()
; #define PG8_SCHED __builtin_amdgcn_sched_barrier(0)
; template <class Epi, class Sched, bool ALIGN_EPI = false, bool SP2 = false>
; __device__ __forceinline__ void gemm_phase(PG8_LAS unsigned char* lds, const Gemm g, const Sched& S, const Epi& E) {
;     ...
;             PG8_LDA(At, 0, 1); PG8_STAGE(PG8_SB(0, 0), b2, voffB); PG8_STAGE(PG8_SB(0, 1), b2 + hstep, voffB); PG8_STAGE(PG8_SA(0, 0), a2, voffA);
;             PG8_WAIT_V(8); PG8_WAIT_L(0); PG8_BAR; PG8_MMA(1, 0, At, B0); PG8_MMA(1, 1, At, B1); PG8_BAR; PG8_SCHED;
	s_mov_b32 m0, s57
	s_nop 0
	global_load_lds_dwordx4 v160, s[62:63]
	s_mov_b32 m0, s65
	s_nop 0
	global_load_lds_dwordx4 v164, s[62:63]
	s_waitcnt vmcnt(8)
	s_waitcnt lgkmcnt(0)
	s_setprio 1
	s_barrier

; #define PG8_MMA(ai, bj, At, Bt) do { __builtin_amdgcn_s_setprio(1); _Pragma("unroll") for (int m = 0; m < 4; ++m) _Pragma("unroll") for (int n = 0; n < 2; ++n) _Pragma("unroll") for (int k = 0; k < 2; ++k) \
;         acc[ai][bj][m][n] = __builtin_amdgcn_mfma_f32_16x16x32_bf16(Bt[n][k], At[m][k], acc[ai][bj][m][n], 0, 0, 0); __builtin_amdgcn_s_setprio(0); } while (0)
; #define PG8_WAIT_V(n) asm volatile("s_waitcnt vmcnt(" #n ")" ::: "memory")
; #define PG8_WAIT_L(n) asm volatile("s_waitcnt lgkmcnt(" #n ")" ::: "memory")
; #define PG8_BAR __builtin_amdgcn_s_barrier()
; #define PG8_SCHED __builtin_amdgcn_sched_barrier(0)
; template <class Epi, class Sched, bool ALIGN_EPI = false, bool SP2 = false>
; __device__ __forceinline__ void gemm_phase(PG8_LAS unsigned char* lds, const Gemm g, const Sched& S, const Epi& E) {
;     ...
;             PG8_WAIT_V(8); PG8_WAIT_L(0); PG8_BAR; PG8_MMA(1, 0, At, B0); PG8_MMA(1, 1, At, B1); PG8_BAR; PG8_SCHED;
	v_mfma_f32_16x16x32_bf16 v[60:63], v[64:67], v[176:179], v[60:63]
	v_mfma_f32_16x16x32_bf16 v[56:59], v[72:75], v[176:179], v[56:59]
	v_mfma_f32_16x16x32_bf16 v[44:47], v[64:67], v[184:187], v[44:47]
	v_mfma_f32_16x16x32_bf16 v[40:43], v[72:75], v[184:187], v[40:43]
	v_mfma_f32_16x16x32_bf16 v[28:31], v[64:67], v[192:195], v[28:31]
	v_mfma_f32_16x16x32_bf16 v[24:27], v[72:75], v[192:195], v[24:27]
	v_mfma_f32_16x16x32_bf16 v[12:15], v[64:67], v[200:203], v[12:15]
	v_mfma_f32_16x16x32_bf16 v[8:11], v[72:75], v[200:203], v[8:11]
	v_mfma_f32_16x16x32_bf16 v[60:63], v[68:71], v[180:183], v[60:63]
	v_mfma_f32_16x16x32_bf16 v[56:59], v[76:79], v[180:183], v[56:59]
	v_mfma_f32_16x16x32_bf16 v[44:47], v[68:71], v[188:191], v[44:47]
	v_mfma_f32_16x16x32_bf16 v[40:43], v[76:79], v[188:191], v[40:43]
	v_mfma_f32_16x16x32_bf16 v[28:31], v[68:71], v[196:199], v[28:31]
	v_mfma_f32_16x16x32_bf16 v[24:27], v[76:79], v[196:199], v[24:27]
	v_mfma_f32_16x16x32_bf16 v[12:15], v[68:71], v[204:207], v[12:15]
	v_mfma_f32_16x16x32_bf16 v[8:11], v[76:79], v[204:207], v[8:11]


; #define PG8_STAGE(bufoff, gbase, voff) do { _Pragma("unroll") for (int _i = 0; _i < 2; ++_i) \
;         __builtin_amdgcn_global_load_lds((const unsigned*)((const char*)(gbase) + (voff)[_i]), (PG8_LAS unsigned*)(lds + (bufoff) + ldsw + _i * 8192), 16, 0, 0); } while (0)
; #define PG8_LDA(dst, b, h) do { _Pragma("unroll") for (int m = 0; m < 4; ++m) _Pragma("unroll") for (int k = 0; k < 2; ++k) dst[m][k] = *(const PG8_LAS bf16x8*)(lds + PG8_SA(b, h) + aoff + m * 2048 + k * 1024); } while (0)
; #define PG8_LDB(dst, b, h) do { _Pragma("unroll") for (int n = 0; n < 2; ++n) _Pragma("unroll") for (int k = 0; k < 2; ++k) dst[n][k] = *(const PG8_LAS bf16x8*)(lds + PG8_SB(b, h) + boff + n * 2048 + k * 1024); } while (0)
; #define PG8_MMA(ai, bj, At, Bt) do { __builtin_amdgcn_s_setprio(1); _Pragma("unroll") for (int m = 0; m < 4; ++m) _Pragma("unroll") for (int n = 0; n < 2; ++n) _Pragma("unroll") for (int k = 0; k < 2; ++k) \
;         acc[ai][bj][m][n] = __builtin_amdgcn_mfma_f32_16x16x32_bf16(Bt[n][k], At[m][k], acc[ai][bj][m][n], 0, 0, 0); __builtin_amdgcn_s_setprio(0); } while (0)
; #define PG8_WAIT_V(n) asm volatile("s_waitcnt vmcnt(" #n ")" ::: "memory")
; #define PG8_WAIT_L(n) asm volatile("s_waitcnt lgkmcnt(" #n ")" ::: "memory")
; #define PG8_BAR __builtin_amdgcn_s_barrier()
; #define PG8_SCHED __builtin_amdgcn_sched_barrier(0)
; template <class Epi, class Sched, bool ALIGN_EPI = false, bool SP2 = false>
; __device__ __forceinline__ void gemm_phase(PG8_LAS unsigned char* lds, const Gemm g, const Sched& S, const Epi& E) {
;     ...
;             PG8_WAIT_V(8); PG8_WAIT_L(0); PG8_BAR; PG8_MMA(1, 0, At, B0); PG8_MMA(1, 1, At, B1); PG8_BAR; PG8_SCHED;
;             PG8_LDB(B0, 1, 0); PG8_LDB(B1, 1, 1); PG8_SCHED; PG8_LDA(At, 1, 0); PG8_STAGE(PG8_SA(0, 1), a2 + hstep, voffA);
	v_mfma_f32_16x16x32_bf16 v[52:55], v[144:147], v[176:179], v[52:55]
	v_mfma_f32_16x16x32_bf16 v[48:51], v[152:155], v[176:179], v[48:51]
	v_mfma_f32_16x16x32_bf16 v[36:39], v[144:147], v[184:187], v[36:39]
	v_mfma_f32_16x16x32_bf16 v[32:35], v[152:155], v[184:187], v[32:35]
	v_mfma_f32_16x16x32_bf16 v[20:23], v[144:147], v[192:195], v[20:23]
	v_mfma_f32_16x16x32_bf16 v[16:19], v[152:155], v[192:195], v[16:19]
	v_mfma_f32_16x16x32_bf16 v[4:7], v[144:147], v[200:203], v[4:7]
	v_mfma_f32_16x16x32_bf16 v[0:3], v[152:155], v[200:203], v[0:3]
	v_mfma_f32_16x16x32_bf16 v[52:55], v[148:151], v[180:183], v[52:55]
	v_mfma_f32_16x16x32_bf16 v[48:51], v[156:159], v[180:183], v[48:51]
	v_mfma_f32_16x16x32_bf16 v[36:39], v[148:151], v[188:191], v[36:39]
	v_mfma_f32_16x16x32_bf16 v[32:35], v[156:159], v[188:191], v[32:35]
	v_mfma_f32_16x16x32_bf16 v[20:23], v[148:151], v[196:199], v[20:23]
	v_mfma_f32_16x16x32_bf16 v[16:19], v[156:159], v[196:199], v[16:19]
	v_mfma_f32_16x16x32_bf16 v[4:7], v[148:151], v[204:207], v[4:7]
	v_mfma_f32_16x16x32_bf16 v[0:3], v[156:159], v[204:207], v[0:3]
	s_setprio 0
	s_barrier
	s_add_i32 s82, 0, 0x18000
	s_add_i32 s83, 0, 0x1c000


; #define PG8_STAGE(bufoff, gbase, voff) do { _Pragma("unroll") for (int _i = 0; _i < 2; ++_i) \
;         __builtin_amdgcn_global_load_lds((const unsigned*)((const char*)(gbase) + (voff)[_i]), (PG8_LAS unsigned*)(lds + (bufoff) + ldsw + _i * 8192), 16, 0, 0); } while (0)
; #define PG8_LDA(dst, b, h) do { _Pragma("unroll") for (int m = 0; m < 4; ++m) _Pragma("unroll") for (int k = 0; k < 2; ++k) dst[m][k] = *(const PG8_LAS bf16x8*)(lds + PG8_SA(b, h) + aoff + m * 2048 + k * 1024); } while (0)
; #define PG8_LDB(dst, b, h) do { _Pragma("unroll") for (int n = 0; n < 2; ++n) _Pragma("unroll") for (int k = 0; k < 2; ++k) dst[n][k] = *(const PG8_LAS bf16x8*)(lds + PG8_SB(b, h) + boff + n * 2048 + k * 1024); } while (0)
; #define PG8_SCHED __builtin_amdgcn_sched_barrier(0)
; template <class Epi, class Sched, bool ALIGN_EPI = false, bool SP2 = false>
; __device__ __forceinline__ void gemm_phase(PG8_LAS unsigned char* lds, const Gemm g, const Sched& S, const Epi& E) {
;     ...
;             PG8_LDB(B0, 1, 0); PG8_LDB(B1, 1, 1); PG8_SCHED; PG8_LDA(At, 1, 0); PG8_STAGE(PG8_SA(0, 1), a2 + hstep, voffA);
	ds_read_b128 v[64:67], v254
	ds_read_b128 v[68:71], v254 offset:1024
	ds_read_b128 v[72:75], v254 offset:2048
	ds_read_b128 v[76:79], v254 offset:3072
	ds_read_b128 v[144:147], v255
	ds_read_b128 v[148:151], v255 offset:1024
	ds_read_b128 v[152:155], v255 offset:2048
	ds_read_b128 v[156:159], v255 offset:3072
	s_add_u32 s62, s62, 0x200000
	s_addc_u32 s63, s63, 0
	s_mov_b32 m0, s67

; #define PG8_STAGE(bufoff, gbase, voff) do { _Pragma("unroll") for (int _i = 0; _i < 2; ++_i) \
;         __builtin_amdgcn_global_load_lds((const unsigned*)((const char*)(gbase) + (voff)[_i]), (PG8_LAS unsigned*)(lds + (bufoff) + ldsw + _i * 8192), 16, 0, 0); } while (0)
; #define PG8_LDA(dst, b, h) do { _Pragma("unroll") for (int m = 0; m < 4; ++m) _Pragma("unroll") for (int k = 0; k < 2; ++k) dst[m][k] = *(const PG8_LAS bf16x8*)(lds + PG8_SA(b, h) + aoff + m * 2048 + k * 1024); } while (0)
; #define PG8_LDB(dst, b, h) do { _Pragma("unroll") for (int n = 0; n < 2; ++n) _Pragma("unroll") for (int k = 0; k < 2; ++k) dst[n][k] = *(const PG8_LAS bf16x8*)(lds + PG8_SB(b, h) + boff + n * 2048 + k * 1024); } while (0)
; #define PG8_SCHED __builtin_amdgcn_sched_barrier(0)
; template <class Epi, class Sched, bool ALIGN_EPI = false, bool SP2 = false>
; __device__ __forceinline__ void gemm_phase(PG8_LAS unsigned char* lds, const Gemm g, const Sched& S, const Epi& E) {
;     ...
;             PG8_LDB(B0, 1, 0); PG8_LDB(B1, 1, 1); PG8_SCHED; PG8_LDA(At, 1, 0); PG8_STAGE(PG8_SA(0, 1), a2 + hstep, voffA);
	ds_read_b128 v[176:179], v215 offset:32768
	ds_read_b128 v[180:183], v215 offset:33792
	ds_read_b128 v[184:187], v215 offset:34816
	ds_read_b128 v[188:191], v215 offset:35840
	ds_read_b128 v[192:195], v215 offset:36864
	ds_read_b128 v[196:199], v215 offset:37888
	ds_read_b128 v[200:203], v215 offset:38912
	ds_read_b128 v[204:207], v215 offset:39936
	global_load_lds_dwordx4 v160, s[62:63]

; #define PG8_STAGE(bufoff, gbase, voff) do { _Pragma("unroll") for (int _i = 0; _i < 2; ++_i) \
;         __builtin_amdgcn_global_load_lds((const unsigned*)((const char*)(gbase) + (voff)[_i]), (PG8_LAS unsigned*)(lds + (bufoff) + ldsw + _i * 8192), 16, 0, 0); } while (0)
; #define PG8_LDA(dst, b, h) do { _Pragma("unroll") for (int m = 0; m < 4; ++m) _Pragma("unroll") for (int k = 0; k < 2; ++k) dst[m][k] = *(const PG8_LAS bf16x8*)(lds + PG8_SA(b, h) + aoff + m * 2048 + k * 1024); } while (0)
; #define PG8_LDB(dst, b, h) do { _Pragma("unroll") for (int n = 0; n < 2; ++n) _Pragma("unroll") for (int k = 0; k < 2; ++k) dst[n][k] = *(const PG8_LAS bf16x8*)(lds + PG8_SB(b, h) + boff + n * 2048 + k * 1024); } while (0)
; #define PG8_MMA(ai, bj, At, Bt) do { __builtin_amdgcn_s_setprio(1); _Pragma("unroll") for (int m = 0; m < 4; ++m) _Pragma("unroll") for (int n = 0; n < 2; ++n) _Pragma("unroll") for (int k = 0; k < 2; ++k) \
;         acc[ai][bj][m][n] = __builtin_amdgcn_mfma_f32_16x16x32_bf16(Bt[n][k], At[m][k], acc[ai][bj][m][n], 0, 0, 0); __builtin_amdgcn_s_setprio(0); } while (0)
; #define PG8_WAIT_V(n) asm volatile("s_waitcnt vmcnt(" #n ")" ::: "memory")
; #define PG8_WAIT_L(n) asm volatile("s_waitcnt lgkmcnt(" #n ")" ::: "memory")
; #define PG8_BAR __builtin_amdgcn_s_barrier()
; #define PG8_SCHED __builtin_amdgcn_sched_barrier(0)
; template <class Epi, class Sched, bool ALIGN_EPI = false, bool SP2 = false>
; __device__ __forceinline__ void gemm_phase(PG8_LAS unsigned char* lds, const Gemm g, const Sched& S, const Epi& E) {
;     ...
;             PG8_LDB(B0, 1, 0); PG8_LDB(B1, 1, 1); PG8_SCHED; PG8_LDA(At, 1, 0); PG8_STAGE(PG8_SA(0, 1), a2 + hstep, voffA);
;             PG8_WAIT_V(8); PG8_WAIT_L(0); PG8_BAR; PG8_MMA(0, 0, At, B0); PG8_MMA(0, 1, At, B1); PG8_BAR; PG8_SCHED;
	s_mov_b32 m0, s68
	s_nop 0
	global_load_lds_dwordx4 v164, s[62:63]
	s_waitcnt vmcnt(8)
	s_waitcnt lgkmcnt(0)
	s_setprio 1
	s_barrier

; #define PG8_MMA(ai, bj, At, Bt) do { __builtin_amdgcn_s_setprio(1); _Pragma("unroll") for (int m = 0; m < 4; ++m) _Pragma("unroll") for (int n = 0; n < 2; ++n) _Pragma("unroll") for (int k = 0; k < 2; ++k) \
;         acc[ai][bj][m][n] = __builtin_amdgcn_mfma_f32_16x16x32_bf16(Bt[n][k], At[m][k], acc[ai][bj][m][n], 0, 0, 0); __builtin_amdgcn_s_setprio(0); } while (0)
; #define PG8_WAIT_V(n) asm volatile("s_waitcnt vmcnt(" #n ")" ::: "memory")
; #define PG8_WAIT_L(n) asm volatile("s_waitcnt lgkmcnt(" #n ")" ::: "memory")
; #define PG8_BAR __builtin_amdgcn_s_barrier()
; #define PG8_SCHED __builtin_amdgcn_sched_barrier(0)
; template <class Epi, class Sched, bool ALIGN_EPI = false, bool SP2 = false>
; __device__ __forceinline__ void gemm_phase(PG8_LAS unsigned char* lds, const Gemm g, const Sched& S, const Epi& E) {
;     ...
;             PG8_WAIT_V(8); PG8_WAIT_L(0); PG8_BAR; PG8_MMA(0, 0, At, B0); PG8_MMA(0, 1, At, B1); PG8_BAR; PG8_SCHED;
	v_mfma_f32_16x16x32_bf16 v[140:143], v[64:67], v[176:179], v[140:143]
	v_mfma_f32_16x16x32_bf16 v[136:139], v[72:75], v[176:179], v[136:139]
	v_mfma_f32_16x16x32_bf16 v[124:127], v[64:67], v[184:187], v[124:127]
	v_mfma_f32_16x16x32_bf16 v[120:123], v[72:75], v[184:187], v[120:123]
	v_mfma_f32_16x16x32_bf16 v[108:111], v[64:67], v[192:195], v[108:111]
	v_mfma_f32_16x16x32_bf16 v[104:107], v[72:75], v[192:195], v[104:107]
	v_mfma_f32_16x16x32_bf16 v[92:95], v[64:67], v[200:203], v[92:95]
	v_mfma_f32_16x16x32_bf16 v[88:91], v[72:75], v[200:203], v[88:91]
	v_mfma_f32_16x16x32_bf16 v[140:143], v[68:71], v[180:183], v[140:143]
	v_mfma_f32_16x16x32_bf16 v[136:139], v[76:79], v[180:183], v[136:139]
	v_mfma_f32_16x16x32_bf16 v[124:127], v[68:71], v[188:191], v[124:127]
	v_mfma_f32_16x16x32_bf16 v[120:123], v[76:79], v[188:191], v[120:123]
	v_mfma_f32_16x16x32_bf16 v[108:111], v[68:71], v[196:199], v[108:111]
	v_mfma_f32_16x16x32_bf16 v[104:107], v[76:79], v[196:199], v[104:107]
	v_mfma_f32_16x16x32_bf16 v[92:95], v[68:71], v[204:207], v[92:95]
	v_mfma_f32_16x16x32_bf16 v[88:91], v[76:79], v[204:207], v[88:91]


; #define PG8_STAGE(bufoff, gbase, voff) do { _Pragma("unroll") for (int _i = 0; _i < 2; ++_i) \
;         __builtin_amdgcn_global_load_lds((const unsigned*)((const char*)(gbase) + (voff)[_i]), (PG8_LAS unsigned*)(lds + (bufoff) + ldsw + _i * 8192), 16, 0, 0); } while (0)
; #define PG8_LDA(dst, b, h) do { _Pragma("unroll") for (int m = 0; m < 4; ++m) _Pragma("unroll") for (int k = 0; k < 2; ++k) dst[m][k] = *(const PG8_LAS bf16x8*)(lds + PG8_SA(b, h) + aoff + m * 2048 + k * 1024); } while (0)
; #define PG8_MMA(ai, bj, At, Bt) do { __builtin_amdgcn_s_setprio(1); _Pragma("unroll") for (int m = 0; m < 4; ++m) _Pragma("unroll") for (int n = 0; n < 2; ++n) _Pragma("unroll") for (int k = 0; k < 2; ++k) \
;         acc[ai][bj][m][n] = __builtin_amdgcn_mfma_f32_16x16x32_bf16(Bt[n][k], At[m][k], acc[ai][bj][m][n], 0, 0, 0); __builtin_amdgcn_s_setprio(0); } while (0)
; #define PG8_WAIT_V(n) asm volatile("s_waitcnt vmcnt(" #n ")" ::: "memory")
; #define PG8_WAIT_L(n) asm volatile("s_waitcnt lgkmcnt(" #n ")" ::: "memory")
; #define PG8_BAR __builtin_amdgcn_s_barrier()
; #define PG8_SCHED __builtin_amdgcn_sched_barrier(0)
; template <class Epi, class Sched, bool ALIGN_EPI = false, bool SP2 = false>
; __device__ __forceinline__ void gemm_phase(PG8_LAS unsigned char* lds, const Gemm g, const Sched& S, const Epi& E) {
;     ...
;             PG8_WAIT_V(8); PG8_WAIT_L(0); PG8_BAR; PG8_MMA(0, 0, At, B0); PG8_MMA(0, 1, At, B1); PG8_BAR; PG8_SCHED;
;             PG8_LDA(At, 1, 1); PG8_STAGE(PG8_SB(1, 0), b3, voffB); PG8_STAGE(PG8_SB(1, 1), b3 + hstep, voffB); PG8_STAGE(PG8_SA(1, 0), a3, voffA);
	v_mfma_f32_16x16x32_bf16 v[132:135], v[144:147], v[176:179], v[132:135]
	v_mfma_f32_16x16x32_bf16 v[128:131], v[152:155], v[176:179], v[128:131]
	v_mfma_f32_16x16x32_bf16 v[116:119], v[144:147], v[184:187], v[116:119]
	v_mfma_f32_16x16x32_bf16 v[112:115], v[152:155], v[184:187], v[112:115]
	v_mfma_f32_16x16x32_bf16 v[100:103], v[144:147], v[192:195], v[100:103]
	v_mfma_f32_16x16x32_bf16 v[96:99], v[152:155], v[192:195], v[96:99]
	v_mfma_f32_16x16x32_bf16 v[84:87], v[144:147], v[200:203], v[84:87]
	v_mfma_f32_16x16x32_bf16 v[80:83], v[152:155], v[200:203], v[80:83]
	v_mfma_f32_16x16x32_bf16 v[132:135], v[148:151], v[180:183], v[132:135]
	v_mfma_f32_16x16x32_bf16 v[128:131], v[156:159], v[180:183], v[128:131]
	v_mfma_f32_16x16x32_bf16 v[116:119], v[148:151], v[188:191], v[116:119]
	v_mfma_f32_16x16x32_bf16 v[112:115], v[156:159], v[188:191], v[112:115]
	v_mfma_f32_16x16x32_bf16 v[100:103], v[148:151], v[196:199], v[100:103]
	v_mfma_f32_16x16x32_bf16 v[96:99], v[156:159], v[196:199], v[96:99]
	v_mfma_f32_16x16x32_bf16 v[84:87], v[148:151], v[204:207], v[84:87]
	v_mfma_f32_16x16x32_bf16 v[80:83], v[156:159], v[204:207], v[80:83]
	s_setprio 0
	s_barrier
	s_add_i32 s62, s82, s64

; #define PG8_STAGE(bufoff, gbase, voff) do { _Pragma("unroll") for (int _i = 0; _i < 2; ++_i) \
;         __builtin_amdgcn_global_load_lds((const unsigned*)((const char*)(gbase) + (voff)[_i]), (PG8_LAS unsigned*)(lds + (bufoff) + ldsw + _i * 8192), 16, 0, 0); } while (0)
; #define PG8_LDA(dst, b, h) do { _Pragma("unroll") for (int m = 0; m < 4; ++m) _Pragma("unroll") for (int k = 0; k < 2; ++k) dst[m][k] = *(const PG8_LAS bf16x8*)(lds + PG8_SA(b, h) + aoff + m * 2048 + k * 1024); } while (0)
; template <class Epi, class Sched, bool ALIGN_EPI = false, bool SP2 = false>
; __device__ __forceinline__ void gemm_phase(PG8_LAS unsigned char* lds, const Gemm g, const Sched& S, const Epi& E) {
;     ...
;             PG8_LDA(At, 1, 1); PG8_STAGE(PG8_SB(1, 0), b3, voffB); PG8_STAGE(PG8_SB(1, 1), b3 + hstep, voffB); PG8_STAGE(PG8_SA(1, 0), a3, voffA);
	s_mov_b32 m0, s62
	ds_read_b128 v[176:179], v215 offset:49152
	ds_read_b128 v[180:183], v215 offset:50176
	ds_read_b128 v[184:187], v215 offset:51200
	ds_read_b128 v[188:191], v215 offset:52224
	ds_read_b128 v[192:195], v215 offset:53248
	ds_read_b128 v[196:199], v215 offset:54272
	ds_read_b128 v[200:203], v215 offset:55296
	ds_read_b128 v[204:207], v215 offset:56320
	global_load_lds_dwordx4 v250, s[96:97]
	s_add_i32 m0, s62, 0x2000
	s_add_u32 s60, s60, 0x200080

; #define PG8_STAGE(bufoff, gbase, voff) do { _Pragma("unroll") for (int _i = 0; _i < 2; ++_i) \
;         __builtin_amdgcn_global_load_lds((const unsigned*)((const char*)(gbase) + (voff)[_i]), (PG8_LAS unsigned*)(lds + (bufoff) + ldsw + _i * 8192), 16, 0, 0); } while (0)
; #define PG8_LDA(dst, b, h) do { _Pragma("unroll") for (int m = 0; m < 4; ++m) _Pragma("unroll") for (int k = 0; k < 2; ++k) dst[m][k] = *(const PG8_LAS bf16x8*)(lds + PG8_SA(b, h) + aoff + m * 2048 + k * 1024); } while (0)
; template <class Epi, class Sched, bool ALIGN_EPI = false, bool SP2 = false>
; __device__ __forceinline__ void gemm_phase(PG8_LAS unsigned char* lds, const Gemm g, const Sched& S, const Epi& E) {
;     ...
;             PG8_LDA(At, 1, 1); PG8_STAGE(PG8_SB(1, 0), b3, voffB); PG8_STAGE(PG8_SB(1, 1), b3 + hstep, voffB); PG8_STAGE(PG8_SA(1, 0), a3, voffA);
	s_addc_u32 s61, s61, 0
	s_add_i32 s62, s83, s64
	global_load_lds_dwordx4 v251, s[96:97]

; #define PG8_STAGE(bufoff, gbase, voff) do { _Pragma("unroll") for (int _i = 0; _i < 2; ++_i) \
;         __builtin_amdgcn_global_load_lds((const unsigned*)((const char*)(gbase) + (voff)[_i]), (PG8_LAS unsigned*)(lds + (bufoff) + ldsw + _i * 8192), 16, 0, 0); } while (0)
; #define PG8_LDA(dst, b, h) do { _Pragma("unroll") for (int m = 0; m < 4; ++m) _Pragma("unroll") for (int k = 0; k < 2; ++k) dst[m][k] = *(const PG8_LAS bf16x8*)(lds + PG8_SA(b, h) + aoff + m * 2048 + k * 1024); } while (0)
; template <class Epi, class Sched, bool ALIGN_EPI = false, bool SP2 = false>
; __device__ __forceinline__ void gemm_phase(PG8_LAS unsigned char* lds, const Gemm g, const Sched& S, const Epi& E) {
;     ...
;             PG8_LDA(At, 1, 1); PG8_STAGE(PG8_SB(1, 0), b3, voffB); PG8_STAGE(PG8_SB(1, 1), b3 + hstep, voffB); PG8_STAGE(PG8_SA(1, 0), a3, voffA);
	s_mov_b32 m0, s62
	s_nop 0
	global_load_lds_dwordx4 v162, s[60:61]

; #define PG8_STAGE(bufoff, gbase, voff) do { _Pragma("unroll") for (int _i = 0; _i < 2; ++_i) \
;         __builtin_amdgcn_global_load_lds((const unsigned*)((const char*)(gbase) + (voff)[_i]), (PG8_LAS unsigned*)(lds + (bufoff) + ldsw + _i * 8192), 16, 0, 0); } while (0)
; #define PG8_LDA(dst, b, h) do { _Pragma("unroll") for (int m = 0; m < 4; ++m) _Pragma("unroll") for (int k = 0; k < 2; ++k) dst[m][k] = *(const PG8_LAS bf16x8*)(lds + PG8_SA(b, h) + aoff + m * 2048 + k * 1024); } while (0)
; template <class Epi, class Sched, bool ALIGN_EPI = false, bool SP2 = false>
; __device__ __forceinline__ void gemm_phase(PG8_LAS unsigned char* lds, const Gemm g, const Sched& S, const Epi& E) {
;     ...
;             PG8_LDA(At, 1, 1); PG8_STAGE(PG8_SB(1, 0), b3, voffB); PG8_STAGE(PG8_SB(1, 1), b3 + hstep, voffB); PG8_STAGE(PG8_SA(1, 0), a3, voffA);
	s_add_i32 m0, s62, 0x2000
	s_nop 0
	global_load_lds_dwordx4 v166, s[60:61]

; #define PG8_STAGE(bufoff, gbase, voff) do { _Pragma("unroll") for (int _i = 0; _i < 2; ++_i) \
;         __builtin_amdgcn_global_load_lds((const unsigned*)((const char*)(gbase) + (voff)[_i]), (PG8_LAS unsigned*)(lds + (bufoff) + ldsw + _i * 8192), 16, 0, 0); } while (0)
; #define PG8_LDA(dst, b, h) do { _Pragma("unroll") for (int m = 0; m < 4; ++m) _Pragma("unroll") for (int k = 0; k < 2; ++k) dst[m][k] = *(const PG8_LAS bf16x8*)(lds + PG8_SA(b, h) + aoff + m * 2048 + k * 1024); } while (0)
; template <class Epi, class Sched, bool ALIGN_EPI = false, bool SP2 = false>
; __device__ __forceinline__ void gemm_phase(PG8_LAS unsigned char* lds, const Gemm g, const Sched& S, const Epi& E) {
;     ...
;             PG8_LDA(At, 1, 1); PG8_STAGE(PG8_SB(1, 0), b3, voffB); PG8_STAGE(PG8_SB(1, 1), b3 + hstep, voffB); PG8_STAGE(PG8_SA(1, 0), a3, voffA);
	s_mov_b32 m0, s70
	s_nop 0
	global_load_lds_dwordx4 v252, s[98:99]

; #define PG8_STAGE(bufoff, gbase, voff) do { _Pragma("unroll") for (int _i = 0; _i < 2; ++_i) \
;         __builtin_amdgcn_global_load_lds((const unsigned*)((const char*)(gbase) + (voff)[_i]), (PG8_LAS unsigned*)(lds + (bufoff) + ldsw + _i * 8192), 16, 0, 0); } while (0)
; #define PG8_LDA(dst, b, h) do { _Pragma("unroll") for (int m = 0; m < 4; ++m) _Pragma("unroll") for (int k = 0; k < 2; ++k) dst[m][k] = *(const PG8_LAS bf16x8*)(lds + PG8_SA(b, h) + aoff + m * 2048 + k * 1024); } while (0)
; #define PG8_MMA(ai, bj, At, Bt) do { __builtin_amdgcn_s_setprio(1); _Pragma("unroll") for (int m = 0; m < 4; ++m) _Pragma("unroll") for (int n = 0; n < 2; ++n) _Pragma("unroll") for (int k = 0; k < 2; ++k) \
;         acc[ai][bj][m][n] = __builtin_amdgcn_mfma_f32_16x16x32_bf16(Bt[n][k], At[m][k], acc[ai][bj][m][n], 0, 0, 0); __builtin_amdgcn_s_setprio(0); } while (0)
; #define PG8_WAIT_V(n) asm volatile("s_waitcnt vmcnt(" #n ")" ::: "memory")
; #define PG8_WAIT_L(n) asm volatile("s_waitcnt lgkmcnt(" #n ")" ::: "memory")
; #define PG8_BAR __builtin_amdgcn_s_barrier()
; #define PG8_SCHED __builtin_amdgcn_sched_barrier(0)
; template <class Epi, class Sched, bool ALIGN_EPI = false, bool SP2 = false>
; __device__ __forceinline__ void gemm_phase(PG8_LAS unsigned char* lds, const Gemm g, const Sched& S, const Epi& E) {
;     ...
;             PG8_LDA(At, 1, 1); PG8_STAGE(PG8_SB(1, 0), b3, voffB); PG8_STAGE(PG8_SB(1, 1), b3 + hstep, voffB); PG8_STAGE(PG8_SA(1, 0), a3, voffA);
;             PG8_WAIT_V(8); PG8_WAIT_L(0); PG8_BAR; PG8_MMA(1, 0, At, B0); PG8_MMA(1, 1, At, B1); PG8_BAR; PG8_SCHED;
	s_mov_b32 m0, s71
	s_nop 0
	global_load_lds_dwordx4 v253, s[98:99]
	s_waitcnt vmcnt(8)
	s_waitcnt lgkmcnt(0)
	s_setprio 1
	s_barrier

; #define PG8_MMA(ai, bj, At, Bt) do { __builtin_amdgcn_s_setprio(1); _Pragma("unroll") for (int m = 0; m < 4; ++m) _Pragma("unroll") for (int n = 0; n < 2; ++n) _Pragma("unroll") for (int k = 0; k < 2; ++k) \
;         acc[ai][bj][m][n] = __builtin_amdgcn_mfma_f32_16x16x32_bf16(Bt[n][k], At[m][k], acc[ai][bj][m][n], 0, 0, 0); __builtin_amdgcn_s_setprio(0); } while (0)
; #define PG8_WAIT_V(n) asm volatile("s_waitcnt vmcnt(" #n ")" ::: "memory")
; #define PG8_WAIT_L(n) asm volatile("s_waitcnt lgkmcnt(" #n ")" ::: "memory")
; #define PG8_BAR __builtin_amdgcn_s_barrier()
; #define PG8_SCHED __builtin_amdgcn_sched_barrier(0)
; template <class Epi, class Sched, bool ALIGN_EPI = false, bool SP2 = false>
; __device__ __forceinline__ void gemm_phase(PG8_LAS unsigned char* lds, const Gemm g, const Sched& S, const Epi& E) {
;     ...
;             PG8_WAIT_V(8); PG8_WAIT_L(0); PG8_BAR; PG8_MMA(1, 0, At, B0); PG8_MMA(1, 1, At, B1); PG8_BAR; PG8_SCHED;
	v_mfma_f32_16x16x32_bf16 v[60:63], v[64:67], v[176:179], v[60:63]
	v_mfma_f32_16x16x32_bf16 v[56:59], v[72:75], v[176:179], v[56:59]
	v_mfma_f32_16x16x32_bf16 v[44:47], v[64:67], v[184:187], v[44:47]
	v_mfma_f32_16x16x32_bf16 v[40:43], v[72:75], v[184:187], v[40:43]
	v_mfma_f32_16x16x32_bf16 v[28:31], v[64:67], v[192:195], v[28:31]
	v_mfma_f32_16x16x32_bf16 v[24:27], v[72:75], v[192:195], v[24:27]
	v_mfma_f32_16x16x32_bf16 v[12:15], v[64:67], v[200:203], v[12:15]
	v_mfma_f32_16x16x32_bf16 v[8:11], v[72:75], v[200:203], v[8:11]
	v_mfma_f32_16x16x32_bf16 v[60:63], v[68:71], v[180:183], v[60:63]
	v_mfma_f32_16x16x32_bf16 v[56:59], v[76:79], v[180:183], v[56:59]
	v_mfma_f32_16x16x32_bf16 v[44:47], v[68:71], v[188:191], v[44:47]
	v_mfma_f32_16x16x32_bf16 v[40:43], v[76:79], v[188:191], v[40:43]
	v_mfma_f32_16x16x32_bf16 v[28:31], v[68:71], v[196:199], v[28:31]
	v_mfma_f32_16x16x32_bf16 v[24:27], v[76:79], v[196:199], v[24:27]
	v_mfma_f32_16x16x32_bf16 v[12:15], v[68:71], v[204:207], v[12:15]
	v_mfma_f32_16x16x32_bf16 v[8:11], v[76:79], v[204:207], v[8:11]


; #define PG8_STAGE(bufoff, gbase, voff) do { _Pragma("unroll") for (int _i = 0; _i < 2; ++_i) \
;         __builtin_amdgcn_global_load_lds((const unsigned*)((const char*)(gbase) + (voff)[_i]), (PG8_LAS unsigned*)(lds + (bufoff) + ldsw + _i * 8192), 16, 0, 0); } while (0)
; #define PG8_LDA(dst, b, h) do { _Pragma("unroll") for (int m = 0; m < 4; ++m) _Pragma("unroll") for (int k = 0; k < 2; ++k) dst[m][k] = *(const PG8_LAS bf16x8*)(lds + PG8_SA(b, h) + aoff + m * 2048 + k * 1024); } while (0)
; #define PG8_WAIT_V(n) asm volatile("s_waitcnt vmcnt(" #n ")" ::: "memory")
; #define PG8_WAIT_L(n) asm volatile("s_waitcnt lgkmcnt(" #n ")" ::: "memory")
; template <class Epi, class Sched, bool ALIGN_EPI = false, bool SP2 = false>
; __device__ __forceinline__ void gemm_phase(PG8_LAS unsigned char* lds, const Gemm g, const Sched& S, const Epi& E) {
;     ...
;         for (int t = 0; t < nt; t += 2) {
;             const bool last = (t == nt - 2);
;             const char* a1 = cA + (size_t)(t + 1) * kstep;
;             const char* a2 = last ? nA : cA + (size_t)(t + 2) * kstep; const char* b2 = last ? nB : cB + (size_t)(t + 2) * kstep;
;             const char* a3 = a2 + kstep; const char* b3 = b2 + kstep;
;             if (last && has_next) S.a_ready(nxt);
;             if constexpr (SP2) {
;             PG8_LDB(B0, 0, 0); PG8_LDB(B1, 0, 1); PG8_SCHED; PG8_LDA(At, 0, 0); PG8_STAGE(PG8_SA(1, 1), a1 + hstep, voffA);
;             PG8_WAIT_V(8); PG8_WAIT_L(0); PG8_BAR; PG8_MMA(0, 0, At, B0); PG8_MMA(0, 1, At, B1); PG8_BAR; PG8_SCHED;
;             PG8_LDA(At, 0, 1); PG8_STAGE(PG8_SB(0, 0), b2, voffB); PG8_STAGE(PG8_SB(0, 1), b2 + hstep, voffB); PG8_STAGE(PG8_SA(0, 0), a2, voffA);
;             PG8_WAIT_V(8); PG8_WAIT_L(0); PG8_BAR; PG8_MMA(1, 0, At, B0); PG8_MMA(1, 1, At, B1); PG8_BAR; PG8_SCHED;
;             PG8_LDB(B0, 1, 0); PG8_LDB(B1, 1, 1); PG8_SCHED; PG8_LDA(At, 1, 0); PG8_STAGE(PG8_SA(0, 1), a2 + hstep, voffA);
;             PG8_WAIT_V(8); PG8_WAIT_L(0); PG8_BAR; PG8_MMA(0, 0, At, B0); PG8_MMA(0, 1, At, B1); PG8_BAR; PG8_SCHED;
;             PG8_LDA(At, 1, 1); PG8_STAGE(PG8_SB(1, 0), b3, voffB); PG8_STAGE(PG8_SB(1, 1), b3 + hstep, voffB); PG8_STAGE(PG8_SA(1, 0), a3, voffA);
;             PG8_WAIT_V(8); PG8_WAIT_L(0); PG8_BAR; PG8_MMA(1, 0, At, B0); PG8_MMA(1, 1, At, B1); PG8_BAR; PG8_SCHED;
;     ...
;         if constexpr (ALIGN_EPI) { if (wr == 0) PG8_BAR; }
	v_mfma_f32_16x16x32_bf16 v[52:55], v[144:147], v[176:179], v[52:55]
	v_mfma_f32_16x16x32_bf16 v[48:51], v[152:155], v[176:179], v[48:51]
	v_mfma_f32_16x16x32_bf16 v[36:39], v[144:147], v[184:187], v[36:39]
	v_mfma_f32_16x16x32_bf16 v[32:35], v[152:155], v[184:187], v[32:35]
	v_mfma_f32_16x16x32_bf16 v[20:23], v[144:147], v[192:195], v[20:23]
	v_mfma_f32_16x16x32_bf16 v[16:19], v[152:155], v[192:195], v[16:19]
	v_mfma_f32_16x16x32_bf16 v[4:7], v[144:147], v[200:203], v[4:7]
	v_mfma_f32_16x16x32_bf16 v[0:3], v[152:155], v[200:203], v[0:3]
	v_mfma_f32_16x16x32_bf16 v[52:55], v[148:151], v[180:183], v[52:55]
	v_mfma_f32_16x16x32_bf16 v[48:51], v[156:159], v[180:183], v[48:51]
	v_mfma_f32_16x16x32_bf16 v[36:39], v[148:151], v[188:191], v[36:39]
	v_mfma_f32_16x16x32_bf16 v[32:35], v[156:159], v[188:191], v[32:35]
	v_mfma_f32_16x16x32_bf16 v[20:23], v[148:151], v[196:199], v[20:23]
	v_mfma_f32_16x16x32_bf16 v[16:19], v[156:159], v[196:199], v[16:19]
	v_mfma_f32_16x16x32_bf16 v[4:7], v[148:151], v[204:207], v[4:7]
	v_mfma_f32_16x16x32_bf16 v[0:3], v[156:159], v[204:207], v[0:3]
	s_setprio 0
	s_barrier
	s_add_i32 s81, s81, 2
	s_add_u32 s58, s58, 0x100
	s_addc_u32 s59, s59, 0
	s_add_u32 s79, s79, 0x100
	s_addc_u32 s80, s80, 0
	s_cmpk_gt_u32 s81, 0x7d
	s_cbranch_scc0 .LBB0_509
	s_and_b64 vcc, exec, s[42:43]
	s_cbranch_vccz .LBB0_512
	s_barrier

; #define PG8_STAGE(bufoff, gbase, voff) do { _Pragma("unroll") for (int _i = 0; _i < 2; ++_i) \
;         __builtin_amdgcn_global_load_lds((const unsigned*)((const char*)(gbase) + (voff)[_i]), (PG8_LAS unsigned*)(lds + (bufoff) + ldsw + _i * 8192), 16, 0, 0); } while (0)
; #define PG8_LDA(dst, b, h) do { _Pragma("unroll") for (int m = 0; m < 4; ++m) _Pragma("unroll") for (int k = 0; k < 2; ++k) dst[m][k] = *(const PG8_LAS bf16x8*)(lds + PG8_SA(b, h) + aoff + m * 2048 + k * 1024); } while (0)
; #define PG8_LDB(dst, b, h) do { _Pragma("unroll") for (int n = 0; n < 2; ++n) _Pragma("unroll") for (int k = 0; k < 2; ++k) dst[n][k] = *(const PG8_LAS bf16x8*)(lds + PG8_SB(b, h) + boff + n * 2048 + k * 1024); } while (0)
; #define PG8_SCHED __builtin_amdgcn_sched_barrier(0)
; template <class Epi, class Sched, bool ALIGN_EPI = false, bool SP2 = false>
; __device__ __forceinline__ void gemm_phase(PG8_LAS unsigned char* lds, const Gemm g, const Sched& S, const Epi& E) {
;     ...
;             const char* a2 = last ? nA : cA + (size_t)(t + 2) * kstep; const char* b2 = last ? nB : cB + (size_t)(t + 2) * kstep;
;             const char* a3 = a2 + kstep; const char* b3 = b2 + kstep;
;             if (last && has_next) S.a_ready(nxt);
;             if constexpr (SP2) {
;             PG8_LDB(B0, 0, 0); PG8_LDB(B1, 0, 1); PG8_SCHED; PG8_LDA(At, 0, 0); PG8_STAGE(PG8_SA(1, 1), a1 + hstep, voffA);
.LBB0_679:
	ds_read_b128 v[128:131], v203
	ds_read_b128 v[132:135], v203 offset:1024
	ds_read_b128 v[136:139], v203 offset:2048
	ds_read_b128 v[140:143], v203 offset:3072
	ds_read_b128 v[144:147], v205
	ds_read_b128 v[148:151], v205 offset:1024
	ds_read_b128 v[152:155], v205 offset:2048
	ds_read_b128 v[156:159], v205 offset:3072
	s_add_u32 s12, s10, 0xfff80080
	s_addc_u32 s13, s11, -1
	s_cmp_eq_u32 s78, 28
	s_cselect_b32 s55, s49, s13
	s_cselect_b32 s54, s74, s12
	s_cselect_b32 s13, s47, s77
	s_cselect_b32 s12, s75, s76

; #define PG8_STAGE(bufoff, gbase, voff) do { _Pragma("unroll") for (int _i = 0; _i < 2; ++_i) \
;         __builtin_amdgcn_global_load_lds((const unsigned*)((const char*)(gbase) + (voff)[_i]), (PG8_LAS unsigned*)(lds + (bufoff) + ldsw + _i * 8192), 16, 0, 0); } while (0)
; #define PG8_LDA(dst, b, h) do { _Pragma("unroll") for (int m = 0; m < 4; ++m) _Pragma("unroll") for (int k = 0; k < 2; ++k) dst[m][k] = *(const PG8_LAS bf16x8*)(lds + PG8_SA(b, h) + aoff + m * 2048 + k * 1024); } while (0)
; #define PG8_LDB(dst, b, h) do { _Pragma("unroll") for (int n = 0; n < 2; ++n) _Pragma("unroll") for (int k = 0; k < 2; ++k) dst[n][k] = *(const PG8_LAS bf16x8*)(lds + PG8_SB(b, h) + boff + n * 2048 + k * 1024); } while (0)
; #define PG8_SCHED __builtin_amdgcn_sched_barrier(0)
; template <class Epi, class Sched, bool ALIGN_EPI = false, bool SP2 = false>
; __device__ __forceinline__ void gemm_phase(PG8_LAS unsigned char* lds, const Gemm g, const Sched& S, const Epi& E) {
;     ...
;             PG8_LDB(B0, 0, 0); PG8_LDB(B1, 0, 1); PG8_SCHED; PG8_LDA(At, 0, 0); PG8_STAGE(PG8_SA(1, 1), a1 + hstep, voffA);
	s_add_i32 m0, s60, 0xc000
	ds_read_b128 v[176:179], v207
	ds_read_b128 v[180:183], v207 offset:1024
	ds_read_b128 v[184:187], v207 offset:2048
	ds_read_b128 v[192:195], v207 offset:3072
	ds_read_b128 v[210:213], v207 offset:4096
	ds_read_b128 v[214:217], v207 offset:5120
	ds_read_b128 v[218:221], v207 offset:6144
	ds_read_b128 v[222:225], v207 offset:7168
	global_load_lds_dwordx4 v168, s[10:11]

; #define PG8_STAGE(bufoff, gbase, voff) do { _Pragma("unroll") for (int _i = 0; _i < 2; ++_i) \
;         __builtin_amdgcn_global_load_lds((const unsigned*)((const char*)(gbase) + (voff)[_i]), (PG8_LAS unsigned*)(lds + (bufoff) + ldsw + _i * 8192), 16, 0, 0); } while (0)
; #define PG8_LDA(dst, b, h) do { _Pragma("unroll") for (int m = 0; m < 4; ++m) _Pragma("unroll") for (int k = 0; k < 2; ++k) dst[m][k] = *(const PG8_LAS bf16x8*)(lds + PG8_SA(b, h) + aoff + m * 2048 + k * 1024); } while (0)
; #define PG8_LDB(dst, b, h) do { _Pragma("unroll") for (int n = 0; n < 2; ++n) _Pragma("unroll") for (int k = 0; k < 2; ++k) dst[n][k] = *(const PG8_LAS bf16x8*)(lds + PG8_SB(b, h) + boff + n * 2048 + k * 1024); } while (0)
; #define PG8_MMA(ai, bj, At, Bt) do { __builtin_amdgcn_s_setprio(1); _Pragma("unroll") for (int m = 0; m < 4; ++m) _Pragma("unroll") for (int n = 0; n < 2; ++n) _Pragma("unroll") for (int k = 0; k < 2; ++k) \
;         acc[ai][bj][m][n] = __builtin_amdgcn_mfma_f32_16x16x32_bf16(Bt[n][k], At[m][k], acc[ai][bj][m][n], 0, 0, 0); __builtin_amdgcn_s_setprio(0); } while (0)
; #define PG8_WAIT_V(n) asm volatile("s_waitcnt vmcnt(" #n ")" ::: "memory")
; #define PG8_WAIT_L(n) asm volatile("s_waitcnt lgkmcnt(" #n ")" ::: "memory")
; #define PG8_BAR __builtin_amdgcn_s_barrier()
; #define PG8_SCHED __builtin_amdgcn_sched_barrier(0)
; template <class Epi, class Sched, bool ALIGN_EPI = false, bool SP2 = false>
; __device__ __forceinline__ void gemm_phase(PG8_LAS unsigned char* lds, const Gemm g, const Sched& S, const Epi& E) {
;     ...
;             PG8_LDB(B0, 0, 0); PG8_LDB(B1, 0, 1); PG8_SCHED; PG8_LDA(At, 0, 0); PG8_STAGE(PG8_SA(1, 1), a1 + hstep, voffA);
;             PG8_WAIT_V(8); PG8_WAIT_L(0); PG8_BAR; PG8_MMA(0, 0, At, B0); PG8_MMA(0, 1, At, B1); PG8_BAR; PG8_SCHED;
	s_add_i32 m0, s60, 0xe000
	s_nop 0
	global_load_lds_dwordx4 v170, s[10:11]
	s_waitcnt vmcnt(8)
	s_waitcnt lgkmcnt(0)
	s_setprio 1
	s_barrier

; #define PG8_MMA(ai, bj, At, Bt) do { __builtin_amdgcn_s_setprio(1); _Pragma("unroll") for (int m = 0; m < 4; ++m) _Pragma("unroll") for (int n = 0; n < 2; ++n) _Pragma("unroll") for (int k = 0; k < 2; ++k) \
;         acc[ai][bj][m][n] = __builtin_amdgcn_mfma_f32_16x16x32_bf16(Bt[n][k], At[m][k], acc[ai][bj][m][n], 0, 0, 0); __builtin_amdgcn_s_setprio(0); } while (0)
; #define PG8_WAIT_V(n) asm volatile("s_waitcnt vmcnt(" #n ")" ::: "memory")
; #define PG8_WAIT_L(n) asm volatile("s_waitcnt lgkmcnt(" #n ")" ::: "memory")
; #define PG8_BAR __builtin_amdgcn_s_barrier()
; #define PG8_SCHED __builtin_amdgcn_sched_barrier(0)
; template <class Epi, class Sched, bool ALIGN_EPI = false, bool SP2 = false>
; __device__ __forceinline__ void gemm_phase(PG8_LAS unsigned char* lds, const Gemm g, const Sched& S, const Epi& E) {
;     ...
;             PG8_WAIT_V(8); PG8_WAIT_L(0); PG8_BAR; PG8_MMA(0, 0, At, B0); PG8_MMA(0, 1, At, B1); PG8_BAR; PG8_SCHED;
	v_mfma_f32_16x16x32_bf16 v[124:127], v[128:131], v[176:179], v[124:127]
	v_mfma_f32_16x16x32_bf16 v[120:123], v[136:139], v[176:179], v[120:123]
	v_mfma_f32_16x16x32_bf16 v[112:115], v[128:131], v[184:187], v[112:115]
	v_mfma_f32_16x16x32_bf16 v[104:107], v[136:139], v[184:187], v[104:107]
	v_mfma_f32_16x16x32_bf16 v[100:103], v[128:131], v[210:213], v[100:103]
	v_mfma_f32_16x16x32_bf16 v[88:91], v[136:139], v[210:213], v[88:91]
	v_mfma_f32_16x16x32_bf16 v[84:87], v[128:131], v[218:221], v[84:87]
	v_mfma_f32_16x16x32_bf16 v[72:75], v[136:139], v[218:221], v[72:75]
	v_mfma_f32_16x16x32_bf16 v[124:127], v[132:135], v[180:183], v[124:127]
	v_mfma_f32_16x16x32_bf16 v[120:123], v[140:143], v[180:183], v[120:123]
	v_mfma_f32_16x16x32_bf16 v[112:115], v[132:135], v[192:195], v[112:115]
	v_mfma_f32_16x16x32_bf16 v[104:107], v[140:143], v[192:195], v[104:107]
	v_mfma_f32_16x16x32_bf16 v[100:103], v[132:135], v[214:217], v[100:103]
	v_mfma_f32_16x16x32_bf16 v[88:91], v[140:143], v[214:217], v[88:91]
	v_mfma_f32_16x16x32_bf16 v[84:87], v[132:135], v[222:225], v[84:87]
	v_mfma_f32_16x16x32_bf16 v[72:75], v[140:143], v[222:225], v[72:75]


; #define PG8_STAGE(bufoff, gbase, voff) do { _Pragma("unroll") for (int _i = 0; _i < 2; ++_i) \
;         __builtin_amdgcn_global_load_lds((const unsigned*)((const char*)(gbase) + (voff)[_i]), (PG8_LAS unsigned*)(lds + (bufoff) + ldsw + _i * 8192), 16, 0, 0); } while (0)
; #define PG8_LDA(dst, b, h) do { _Pragma("unroll") for (int m = 0; m < 4; ++m) _Pragma("unroll") for (int k = 0; k < 2; ++k) dst[m][k] = *(const PG8_LAS bf16x8*)(lds + PG8_SA(b, h) + aoff + m * 2048 + k * 1024); } while (0)
; #define PG8_MMA(ai, bj, At, Bt) do { __builtin_amdgcn_s_setprio(1); _Pragma("unroll") for (int m = 0; m < 4; ++m) _Pragma("unroll") for (int n = 0; n < 2; ++n) _Pragma("unroll") for (int k = 0; k < 2; ++k) \
;         acc[ai][bj][m][n] = __builtin_amdgcn_mfma_f32_16x16x32_bf16(Bt[n][k], At[m][k], acc[ai][bj][m][n], 0, 0, 0); __builtin_amdgcn_s_setprio(0); } while (0)
; #define PG8_WAIT_V(n) asm volatile("s_waitcnt vmcnt(" #n ")" ::: "memory")
; #define PG8_WAIT_L(n) asm volatile("s_waitcnt lgkmcnt(" #n ")" ::: "memory")
; #define PG8_BAR __builtin_amdgcn_s_barrier()
; #define PG8_SCHED __builtin_amdgcn_sched_barrier(0)
; template <class Epi, class Sched, bool ALIGN_EPI = false, bool SP2 = false>
; __device__ __forceinline__ void gemm_phase(PG8_LAS unsigned char* lds, const Gemm g, const Sched& S, const Epi& E) {
;     ...
;             PG8_WAIT_V(8); PG8_WAIT_L(0); PG8_BAR; PG8_MMA(0, 0, At, B0); PG8_MMA(0, 1, At, B1); PG8_BAR; PG8_SCHED;
;             PG8_LDA(At, 0, 1); PG8_STAGE(PG8_SB(0, 0), b2, voffB); PG8_STAGE(PG8_SB(0, 1), b2 + hstep, voffB); PG8_STAGE(PG8_SA(0, 0), a2, voffA);
	v_mfma_f32_16x16x32_bf16 v[116:119], v[144:147], v[176:179], v[116:119]
	v_mfma_f32_16x16x32_bf16 v[108:111], v[152:155], v[176:179], v[108:111]
	v_mfma_f32_16x16x32_bf16 v[96:99], v[144:147], v[184:187], v[96:99]
	v_mfma_f32_16x16x32_bf16 v[92:95], v[152:155], v[184:187], v[92:95]
	v_mfma_f32_16x16x32_bf16 v[80:83], v[144:147], v[210:213], v[80:83]
	v_mfma_f32_16x16x32_bf16 v[76:79], v[152:155], v[210:213], v[76:79]
	v_mfma_f32_16x16x32_bf16 v[68:71], v[144:147], v[218:221], v[68:71]
	v_mfma_f32_16x16x32_bf16 v[64:67], v[152:155], v[218:221], v[64:67]
	v_mfma_f32_16x16x32_bf16 v[116:119], v[148:151], v[180:183], v[116:119]
	v_mfma_f32_16x16x32_bf16 v[108:111], v[156:159], v[180:183], v[108:111]
	v_mfma_f32_16x16x32_bf16 v[96:99], v[148:151], v[192:195], v[96:99]
	v_mfma_f32_16x16x32_bf16 v[92:95], v[156:159], v[192:195], v[92:95]
	v_mfma_f32_16x16x32_bf16 v[80:83], v[148:151], v[214:217], v[80:83]
	v_mfma_f32_16x16x32_bf16 v[76:79], v[156:159], v[214:217], v[76:79]
	v_mfma_f32_16x16x32_bf16 v[68:71], v[148:151], v[222:225], v[68:71]
	v_mfma_f32_16x16x32_bf16 v[64:67], v[156:159], v[222:225], v[64:67]
	s_setprio 0
	s_barrier
	s_add_i32 s79, s70, s57
	s_mov_b64 s[96:97], s[12:13]

; #define PG8_STAGE(bufoff, gbase, voff) do { _Pragma("unroll") for (int _i = 0; _i < 2; ++_i) \
;         __builtin_amdgcn_global_load_lds((const unsigned*)((const char*)(gbase) + (voff)[_i]), (PG8_LAS unsigned*)(lds + (bufoff) + ldsw + _i * 8192), 16, 0, 0); } while (0)
; #define PG8_LDA(dst, b, h) do { _Pragma("unroll") for (int m = 0; m < 4; ++m) _Pragma("unroll") for (int k = 0; k < 2; ++k) dst[m][k] = *(const PG8_LAS bf16x8*)(lds + PG8_SA(b, h) + aoff + m * 2048 + k * 1024); } while (0)
; template <class Epi, class Sched, bool ALIGN_EPI = false, bool SP2 = false>
; __device__ __forceinline__ void gemm_phase(PG8_LAS unsigned char* lds, const Gemm g, const Sched& S, const Epi& E) {
;     ...
;             PG8_LDA(At, 0, 1); PG8_STAGE(PG8_SB(0, 0), b2, voffB); PG8_STAGE(PG8_SB(0, 1), b2 + hstep, voffB); PG8_STAGE(PG8_SA(0, 0), a2, voffA);
	s_mov_b32 m0, s79
	ds_read_b128 v[176:179], v207 offset:16384
	ds_read_b128 v[180:183], v207 offset:17408
	ds_read_b128 v[184:187], v207 offset:18432
	ds_read_b128 v[192:195], v207 offset:19456
	ds_read_b128 v[210:213], v207 offset:20480
	ds_read_b128 v[214:217], v207 offset:21504
	ds_read_b128 v[218:221], v207 offset:22528
	ds_read_b128 v[222:225], v207 offset:23552
	global_load_lds_dwordx4 v164, s[12:13]
	s_add_i32 m0, s79, 0x2000
	s_add_u32 s80, s12, 0x80000

; #define PG8_STAGE(bufoff, gbase, voff) do { _Pragma("unroll") for (int _i = 0; _i < 2; ++_i) \
;         __builtin_amdgcn_global_load_lds((const unsigned*)((const char*)(gbase) + (voff)[_i]), (PG8_LAS unsigned*)(lds + (bufoff) + ldsw + _i * 8192), 16, 0, 0); } while (0)
; #define PG8_LDA(dst, b, h) do { _Pragma("unroll") for (int m = 0; m < 4; ++m) _Pragma("unroll") for (int k = 0; k < 2; ++k) dst[m][k] = *(const PG8_LAS bf16x8*)(lds + PG8_SA(b, h) + aoff + m * 2048 + k * 1024); } while (0)
; template <class Epi, class Sched, bool ALIGN_EPI = false, bool SP2 = false>
; __device__ __forceinline__ void gemm_phase(PG8_LAS unsigned char* lds, const Gemm g, const Sched& S, const Epi& E) {
;     ...
;             PG8_LDA(At, 0, 1); PG8_STAGE(PG8_SB(0, 0), b2, voffB); PG8_STAGE(PG8_SB(0, 1), b2 + hstep, voffB); PG8_STAGE(PG8_SA(0, 0), a2, voffA);
	s_addc_u32 s81, s13, 0
	s_add_i32 s79, s71, s57
	global_load_lds_dwordx4 v160, s[12:13]

; #define PG8_STAGE(bufoff, gbase, voff) do { _Pragma("unroll") for (int _i = 0; _i < 2; ++_i) \
;         __builtin_amdgcn_global_load_lds((const unsigned*)((const char*)(gbase) + (voff)[_i]), (PG8_LAS unsigned*)(lds + (bufoff) + ldsw + _i * 8192), 16, 0, 0); } while (0)
; #define PG8_LDA(dst, b, h) do { _Pragma("unroll") for (int m = 0; m < 4; ++m) _Pragma("unroll") for (int k = 0; k < 2; ++k) dst[m][k] = *(const PG8_LAS bf16x8*)(lds + PG8_SA(b, h) + aoff + m * 2048 + k * 1024); } while (0)
; template <class Epi, class Sched, bool ALIGN_EPI = false, bool SP2 = false>
; __device__ __forceinline__ void gemm_phase(PG8_LAS unsigned char* lds, const Gemm g, const Sched& S, const Epi& E) {
;     ...
;             PG8_LDA(At, 0, 1); PG8_STAGE(PG8_SB(0, 0), b2, voffB); PG8_STAGE(PG8_SB(0, 1), b2 + hstep, voffB); PG8_STAGE(PG8_SA(0, 0), a2, voffA);
	s_mov_b32 m0, s79
	s_nop 0
	global_load_lds_dwordx4 v164, s[80:81]

; #define PG8_STAGE(bufoff, gbase, voff) do { _Pragma("unroll") for (int _i = 0; _i < 2; ++_i) \
;         __builtin_amdgcn_global_load_lds((const unsigned*)((const char*)(gbase) + (voff)[_i]), (PG8_LAS unsigned*)(lds + (bufoff) + ldsw + _i * 8192), 16, 0, 0); } while (0)
; #define PG8_LDA(dst, b, h) do { _Pragma("unroll") for (int m = 0; m < 4; ++m) _Pragma("unroll") for (int k = 0; k < 2; ++k) dst[m][k] = *(const PG8_LAS bf16x8*)(lds + PG8_SA(b, h) + aoff + m * 2048 + k * 1024); } while (0)
; template <class Epi, class Sched, bool ALIGN_EPI = false, bool SP2 = false>
; __device__ __forceinline__ void gemm_phase(PG8_LAS unsigned char* lds, const Gemm g, const Sched& S, const Epi& E) {
;     ...
;             PG8_LDA(At, 0, 1); PG8_STAGE(PG8_SB(0, 0), b2, voffB); PG8_STAGE(PG8_SB(0, 1), b2 + hstep, voffB); PG8_STAGE(PG8_SA(0, 0), a2, voffA);
	s_add_i32 m0, s79, 0x2000
	s_nop 0
	global_load_lds_dwordx4 v160, s[80:81]
	s_mov_b64 s[98:99], s[54:55]

; #define PG8_STAGE(bufoff, gbase, voff) do { _Pragma("unroll") for (int _i = 0; _i < 2; ++_i) \
;         __builtin_amdgcn_global_load_lds((const unsigned*)((const char*)(gbase) + (voff)[_i]), (PG8_LAS unsigned*)(lds + (bufoff) + ldsw + _i * 8192), 16, 0, 0); } while (0)
; #define PG8_LDA(dst, b, h) do { _Pragma("unroll") for (int m = 0; m < 4; ++m) _Pragma("unroll") for (int k = 0; k < 2; ++k) dst[m][k] = *(const PG8_LAS bf16x8*)(lds + PG8_SA(b, h) + aoff + m * 2048 + k * 1024); } while (0)
; #define PG8_MMA(ai, bj, At, Bt) do { __builtin_amdgcn_s_setprio(1); _Pragma("unroll") for (int m = 0; m < 4; ++m) _Pragma("unroll") for (int n = 0; n < 2; ++n) _Pragma("unroll") for (int k = 0; k < 2; ++k) \
;         acc[ai][bj][m][n] = __builtin_amdgcn_mfma_f32_16x16x32_bf16(Bt[n][k], At[m][k], acc[ai][bj][m][n], 0, 0, 0); __builtin_amdgcn_s_setprio(0); } while (0)
; #define PG8_WAIT_V(n) asm volatile("s_waitcnt vmcnt(" #n ")" ::: "memory")
; #define PG8_WAIT_L(n) asm volatile("s_waitcnt lgkmcnt(" #n ")" ::: "memory")
; #define PG8_BAR __builtin_amdgcn_s_barrier()
; #define PG8_SCHED __builtin_amdgcn_sched_barrier(0)
; template <class Epi, class Sched, bool ALIGN_EPI = false, bool SP2 = false>
; __device__ __forceinline__ void gemm_phase(PG8_LAS unsigned char* lds, const Gemm g, const Sched& S, const Epi& E) {
;     ...
;             PG8_LDA(At, 0, 1); PG8_STAGE(PG8_SB(0, 0), b2, voffB); PG8_STAGE(PG8_SB(0, 1), b2 + hstep, voffB); PG8_STAGE(PG8_SA(0, 0), a2, voffA);
;             PG8_WAIT_V(8); PG8_WAIT_L(0); PG8_BAR; PG8_MMA(1, 0, At, B0); PG8_MMA(1, 1, At, B1); PG8_BAR; PG8_SCHED;
	s_mov_b32 m0, s60
	s_nop 0
	global_load_lds_dwordx4 v166, s[54:55]
	s_mov_b32 m0, s61
	s_nop 0
	global_load_lds_dwordx4 v162, s[54:55]
	s_waitcnt vmcnt(8)
	s_waitcnt lgkmcnt(0)
	s_setprio 1
	s_barrier

; #define PG8_MMA(ai, bj, At, Bt) do { __builtin_amdgcn_s_setprio(1); _Pragma("unroll") for (int m = 0; m < 4; ++m) _Pragma("unroll") for (int n = 0; n < 2; ++n) _Pragma("unroll") for (int k = 0; k < 2; ++k) \
;         acc[ai][bj][m][n] = __builtin_amdgcn_mfma_f32_16x16x32_bf16(Bt[n][k], At[m][k], acc[ai][bj][m][n], 0, 0, 0); __builtin_amdgcn_s_setprio(0); } while (0)
; #define PG8_WAIT_V(n) asm volatile("s_waitcnt vmcnt(" #n ")" ::: "memory")
; #define PG8_WAIT_L(n) asm volatile("s_waitcnt lgkmcnt(" #n ")" ::: "memory")
; #define PG8_BAR __builtin_amdgcn_s_barrier()
; #define PG8_SCHED __builtin_amdgcn_sched_barrier(0)
; template <class Epi, class Sched, bool ALIGN_EPI = false, bool SP2 = false>
; __device__ __forceinline__ void gemm_phase(PG8_LAS unsigned char* lds, const Gemm g, const Sched& S, const Epi& E) {
;     ...
;             PG8_WAIT_V(8); PG8_WAIT_L(0); PG8_BAR; PG8_MMA(1, 0, At, B0); PG8_MMA(1, 1, At, B1); PG8_BAR; PG8_SCHED;
	v_mfma_f32_16x16x32_bf16 v[60:63], v[128:131], v[176:179], v[60:63]
	v_mfma_f32_16x16x32_bf16 v[56:59], v[136:139], v[176:179], v[56:59]
	v_mfma_f32_16x16x32_bf16 v[52:55], v[128:131], v[184:187], v[52:55]
	v_mfma_f32_16x16x32_bf16 v[40:43], v[136:139], v[184:187], v[40:43]
	v_mfma_f32_16x16x32_bf16 v[36:39], v[128:131], v[210:213], v[36:39]
	v_mfma_f32_16x16x32_bf16 v[24:27], v[136:139], v[210:213], v[24:27]
	v_mfma_f32_16x16x32_bf16 v[20:23], v[128:131], v[218:221], v[20:23]
	v_mfma_f32_16x16x32_bf16 v[8:11], v[136:139], v[218:221], v[8:11]
	v_mfma_f32_16x16x32_bf16 v[60:63], v[132:135], v[180:183], v[60:63]
	v_mfma_f32_16x16x32_bf16 v[56:59], v[140:143], v[180:183], v[56:59]
	v_mfma_f32_16x16x32_bf16 v[52:55], v[132:135], v[192:195], v[52:55]
	v_mfma_f32_16x16x32_bf16 v[40:43], v[140:143], v[192:195], v[40:43]
	v_mfma_f32_16x16x32_bf16 v[36:39], v[132:135], v[214:217], v[36:39]
	v_mfma_f32_16x16x32_bf16 v[24:27], v[140:143], v[214:217], v[24:27]
	v_mfma_f32_16x16x32_bf16 v[20:23], v[132:135], v[222:225], v[20:23]
	v_mfma_f32_16x16x32_bf16 v[8:11], v[140:143], v[222:225], v[8:11]


; #define PG8_STAGE(bufoff, gbase, voff) do { _Pragma("unroll") for (int _i = 0; _i < 2; ++_i) \
;         __builtin_amdgcn_global_load_lds((const unsigned*)((const char*)(gbase) + (voff)[_i]), (PG8_LAS unsigned*)(lds + (bufoff) + ldsw + _i * 8192), 16, 0, 0); } while (0)
; #define PG8_LDA(dst, b, h) do { _Pragma("unroll") for (int m = 0; m < 4; ++m) _Pragma("unroll") for (int k = 0; k < 2; ++k) dst[m][k] = *(const PG8_LAS bf16x8*)(lds + PG8_SA(b, h) + aoff + m * 2048 + k * 1024); } while (0)
; #define PG8_LDB(dst, b, h) do { _Pragma("unroll") for (int n = 0; n < 2; ++n) _Pragma("unroll") for (int k = 0; k < 2; ++k) dst[n][k] = *(const PG8_LAS bf16x8*)(lds + PG8_SB(b, h) + boff + n * 2048 + k * 1024); } while (0)
; #define PG8_MMA(ai, bj, At, Bt) do { __builtin_amdgcn_s_setprio(1); _Pragma("unroll") for (int m = 0; m < 4; ++m) _Pragma("unroll") for (int n = 0; n < 2; ++n) _Pragma("unroll") for (int k = 0; k < 2; ++k) \
;         acc[ai][bj][m][n] = __builtin_amdgcn_mfma_f32_16x16x32_bf16(Bt[n][k], At[m][k], acc[ai][bj][m][n], 0, 0, 0); __builtin_amdgcn_s_setprio(0); } while (0)
; #define PG8_WAIT_V(n) asm volatile("s_waitcnt vmcnt(" #n ")" ::: "memory")
; #define PG8_WAIT_L(n) asm volatile("s_waitcnt lgkmcnt(" #n ")" ::: "memory")
; #define PG8_BAR __builtin_amdgcn_s_barrier()
; #define PG8_SCHED __builtin_amdgcn_sched_barrier(0)
; template <class Epi, class Sched, bool ALIGN_EPI = false, bool SP2 = false>
; __device__ __forceinline__ void gemm_phase(PG8_LAS unsigned char* lds, const Gemm g, const Sched& S, const Epi& E) {
;     ...
;             PG8_WAIT_V(8); PG8_WAIT_L(0); PG8_BAR; PG8_MMA(1, 0, At, B0); PG8_MMA(1, 1, At, B1); PG8_BAR; PG8_SCHED;
;             PG8_LDB(B0, 1, 0); PG8_LDB(B1, 1, 1); PG8_SCHED; PG8_LDA(At, 1, 0); PG8_STAGE(PG8_SA(0, 1), a2 + hstep, voffA);
	v_mfma_f32_16x16x32_bf16 v[48:51], v[144:147], v[176:179], v[48:51]
	v_mfma_f32_16x16x32_bf16 v[44:47], v[152:155], v[176:179], v[44:47]
	v_mfma_f32_16x16x32_bf16 v[32:35], v[144:147], v[184:187], v[32:35]
	v_mfma_f32_16x16x32_bf16 v[28:31], v[152:155], v[184:187], v[28:31]
	v_mfma_f32_16x16x32_bf16 v[16:19], v[144:147], v[210:213], v[16:19]
	v_mfma_f32_16x16x32_bf16 v[12:15], v[152:155], v[210:213], v[12:15]
	v_mfma_f32_16x16x32_bf16 v[4:7], v[144:147], v[218:221], v[4:7]
	v_mfma_f32_16x16x32_bf16 v[0:3], v[152:155], v[218:221], v[0:3]
	v_mfma_f32_16x16x32_bf16 v[48:51], v[148:151], v[180:183], v[48:51]
	v_mfma_f32_16x16x32_bf16 v[44:47], v[156:159], v[180:183], v[44:47]
	v_mfma_f32_16x16x32_bf16 v[32:35], v[148:151], v[192:195], v[32:35]
	v_mfma_f32_16x16x32_bf16 v[28:31], v[156:159], v[192:195], v[28:31]
	v_mfma_f32_16x16x32_bf16 v[16:19], v[148:151], v[214:217], v[16:19]
	v_mfma_f32_16x16x32_bf16 v[12:15], v[156:159], v[214:217], v[12:15]
	v_mfma_f32_16x16x32_bf16 v[4:7], v[148:151], v[222:225], v[4:7]
	v_mfma_f32_16x16x32_bf16 v[0:3], v[156:159], v[222:225], v[0:3]
	s_setprio 0
	s_barrier
	s_add_i32 s79, 0, 0x18000
	s_add_i32 s80, 0, 0x1c000


; #define PG8_STAGE(bufoff, gbase, voff) do { _Pragma("unroll") for (int _i = 0; _i < 2; ++_i) \
;         __builtin_amdgcn_global_load_lds((const unsigned*)((const char*)(gbase) + (voff)[_i]), (PG8_LAS unsigned*)(lds + (bufoff) + ldsw + _i * 8192), 16, 0, 0); } while (0)
; #define PG8_LDA(dst, b, h) do { _Pragma("unroll") for (int m = 0; m < 4; ++m) _Pragma("unroll") for (int k = 0; k < 2; ++k) dst[m][k] = *(const PG8_LAS bf16x8*)(lds + PG8_SA(b, h) + aoff + m * 2048 + k * 1024); } while (0)
; #define PG8_LDB(dst, b, h) do { _Pragma("unroll") for (int n = 0; n < 2; ++n) _Pragma("unroll") for (int k = 0; k < 2; ++k) dst[n][k] = *(const PG8_LAS bf16x8*)(lds + PG8_SB(b, h) + boff + n * 2048 + k * 1024); } while (0)
; #define PG8_SCHED __builtin_amdgcn_sched_barrier(0)
; template <class Epi, class Sched, bool ALIGN_EPI = false, bool SP2 = false>
; __device__ __forceinline__ void gemm_phase(PG8_LAS unsigned char* lds, const Gemm g, const Sched& S, const Epi& E) {
;     ...
;             PG8_LDB(B0, 1, 0); PG8_LDB(B1, 1, 1); PG8_SCHED; PG8_LDA(At, 1, 0); PG8_STAGE(PG8_SA(0, 1), a2 + hstep, voffA);
	ds_read_b128 v[128:131], v254
	ds_read_b128 v[132:135], v254 offset:1024
	ds_read_b128 v[136:139], v254 offset:2048
	ds_read_b128 v[140:143], v254 offset:3072
	ds_read_b128 v[144:147], v255
	ds_read_b128 v[148:151], v255 offset:1024
	ds_read_b128 v[152:155], v255 offset:2048
	ds_read_b128 v[156:159], v255 offset:3072
	s_add_u32 s54, s54, 0x80000
	s_addc_u32 s55, s55, 0
	s_mov_b32 m0, s62

; #define PG8_STAGE(bufoff, gbase, voff) do { _Pragma("unroll") for (int _i = 0; _i < 2; ++_i) \
;         __builtin_amdgcn_global_load_lds((const unsigned*)((const char*)(gbase) + (voff)[_i]), (PG8_LAS unsigned*)(lds + (bufoff) + ldsw + _i * 8192), 16, 0, 0); } while (0)
; #define PG8_LDA(dst, b, h) do { _Pragma("unroll") for (int m = 0; m < 4; ++m) _Pragma("unroll") for (int k = 0; k < 2; ++k) dst[m][k] = *(const PG8_LAS bf16x8*)(lds + PG8_SA(b, h) + aoff + m * 2048 + k * 1024); } while (0)
; #define PG8_LDB(dst, b, h) do { _Pragma("unroll") for (int n = 0; n < 2; ++n) _Pragma("unroll") for (int k = 0; k < 2; ++k) dst[n][k] = *(const PG8_LAS bf16x8*)(lds + PG8_SB(b, h) + boff + n * 2048 + k * 1024); } while (0)
; #define PG8_SCHED __builtin_amdgcn_sched_barrier(0)
; template <class Epi, class Sched, bool ALIGN_EPI = false, bool SP2 = false>
; __device__ __forceinline__ void gemm_phase(PG8_LAS unsigned char* lds, const Gemm g, const Sched& S, const Epi& E) {
;     ...
;             PG8_LDB(B0, 1, 0); PG8_LDB(B1, 1, 1); PG8_SCHED; PG8_LDA(At, 1, 0); PG8_STAGE(PG8_SA(0, 1), a2 + hstep, voffA);
	ds_read_b128 v[176:179], v207 offset:32768
	ds_read_b128 v[180:183], v207 offset:33792
	ds_read_b128 v[184:187], v207 offset:34816
	ds_read_b128 v[192:195], v207 offset:35840
	ds_read_b128 v[210:213], v207 offset:36864
	ds_read_b128 v[214:217], v207 offset:37888
	ds_read_b128 v[218:221], v207 offset:38912
	ds_read_b128 v[222:225], v207 offset:39936
	global_load_lds_dwordx4 v166, s[54:55]

; #define PG8_MMA(ai, bj, At, Bt) do { __builtin_amdgcn_s_setprio(1); _Pragma("unroll") for (int m = 0; m < 4; ++m) _Pragma("unroll") for (int n = 0; n < 2; ++n) _Pragma("unroll") for (int k = 0; k < 2; ++k) \
;         acc[ai][bj][m][n] = __builtin_amdgcn_mfma_f32_16x16x32_bf16(Bt[n][k], At[m][k], acc[ai][bj][m][n], 0, 0, 0); __builtin_amdgcn_s_setprio(0); } while (0)
; #define PG8_WAIT_V(n) asm volatile("s_waitcnt vmcnt(" #n ")" ::: "memory")
; #define PG8_WAIT_L(n) asm volatile("s_waitcnt lgkmcnt(" #n ")" ::: "memory")
; #define PG8_BAR __builtin_amdgcn_s_barrier()
; #define PG8_SCHED __builtin_amdgcn_sched_barrier(0)
; template <class Epi, class Sched, bool ALIGN_EPI = false, bool SP2 = false>
; __device__ __forceinline__ void gemm_phase(PG8_LAS unsigned char* lds, const Gemm g, const Sched& S, const Epi& E) {
;     ...
;             PG8_WAIT_V(8); PG8_WAIT_L(0); PG8_BAR; PG8_MMA(0, 0, At, B0); PG8_MMA(0, 1, At, B1); PG8_BAR; PG8_SCHED;
	s_mov_b32 m0, s63
	s_nop 0
	global_load_lds_dwordx4 v162, s[54:55]
	s_waitcnt vmcnt(8)
	s_waitcnt lgkmcnt(0)
	s_setprio 1
	s_barrier

; #define PG8_MMA(ai, bj, At, Bt) do { __builtin_amdgcn_s_setprio(1); _Pragma("unroll") for (int m = 0; m < 4; ++m) _Pragma("unroll") for (int n = 0; n < 2; ++n) _Pragma("unroll") for (int k = 0; k < 2; ++k) \
;         acc[ai][bj][m][n] = __builtin_amdgcn_mfma_f32_16x16x32_bf16(Bt[n][k], At[m][k], acc[ai][bj][m][n], 0, 0, 0); __builtin_amdgcn_s_setprio(0); } while (0)
; #define PG8_WAIT_V(n) asm volatile("s_waitcnt vmcnt(" #n ")" ::: "memory")
; #define PG8_WAIT_L(n) asm volatile("s_waitcnt lgkmcnt(" #n ")" ::: "memory")
; #define PG8_BAR __builtin_amdgcn_s_barrier()
; #define PG8_SCHED __builtin_amdgcn_sched_barrier(0)
; template <class Epi, class Sched, bool ALIGN_EPI = false, bool SP2 = false>
; __device__ __forceinline__ void gemm_phase(PG8_LAS unsigned char* lds, const Gemm g, const Sched& S, const Epi& E) {
;     ...
;             PG8_WAIT_V(8); PG8_WAIT_L(0); PG8_BAR; PG8_MMA(0, 0, At, B0); PG8_MMA(0, 1, At, B1); PG8_BAR; PG8_SCHED;
	v_mfma_f32_16x16x32_bf16 v[124:127], v[128:131], v[176:179], v[124:127]
	v_mfma_f32_16x16x32_bf16 v[120:123], v[136:139], v[176:179], v[120:123]
	v_mfma_f32_16x16x32_bf16 v[112:115], v[128:131], v[184:187], v[112:115]
	v_mfma_f32_16x16x32_bf16 v[104:107], v[136:139], v[184:187], v[104:107]
	v_mfma_f32_16x16x32_bf16 v[100:103], v[128:131], v[210:213], v[100:103]
	v_mfma_f32_16x16x32_bf16 v[88:91], v[136:139], v[210:213], v[88:91]
	v_mfma_f32_16x16x32_bf16 v[84:87], v[128:131], v[218:221], v[84:87]
	v_mfma_f32_16x16x32_bf16 v[72:75], v[136:139], v[218:221], v[72:75]
	v_mfma_f32_16x16x32_bf16 v[124:127], v[132:135], v[180:183], v[124:127]
	v_mfma_f32_16x16x32_bf16 v[120:123], v[140:143], v[180:183], v[120:123]
	v_mfma_f32_16x16x32_bf16 v[112:115], v[132:135], v[192:195], v[112:115]
	v_mfma_f32_16x16x32_bf16 v[104:107], v[140:143], v[192:195], v[104:107]
	v_mfma_f32_16x16x32_bf16 v[100:103], v[132:135], v[214:217], v[100:103]
	v_mfma_f32_16x16x32_bf16 v[88:91], v[140:143], v[214:217], v[88:91]
	v_mfma_f32_16x16x32_bf16 v[84:87], v[132:135], v[222:225], v[84:87]
	v_mfma_f32_16x16x32_bf16 v[72:75], v[140:143], v[222:225], v[72:75]


; #define PG8_STAGE(bufoff, gbase, voff) do { _Pragma("unroll") for (int _i = 0; _i < 2; ++_i) \
;         __builtin_amdgcn_global_load_lds((const unsigned*)((const char*)(gbase) + (voff)[_i]), (PG8_LAS unsigned*)(lds + (bufoff) + ldsw + _i * 8192), 16, 0, 0); } while (0)
; #define PG8_LDA(dst, b, h) do { _Pragma("unroll") for (int m = 0; m < 4; ++m) _Pragma("unroll") for (int k = 0; k < 2; ++k) dst[m][k] = *(const PG8_LAS bf16x8*)(lds + PG8_SA(b, h) + aoff + m * 2048 + k * 1024); } while (0)
; #define PG8_MMA(ai, bj, At, Bt) do { __builtin_amdgcn_s_setprio(1); _Pragma("unroll") for (int m = 0; m < 4; ++m) _Pragma("unroll") for (int n = 0; n < 2; ++n) _Pragma("unroll") for (int k = 0; k < 2; ++k) \
;         acc[ai][bj][m][n] = __builtin_amdgcn_mfma_f32_16x16x32_bf16(Bt[n][k], At[m][k], acc[ai][bj][m][n], 0, 0, 0); __builtin_amdgcn_s_setprio(0); } while (0)
; #define PG8_WAIT_V(n) asm volatile("s_waitcnt vmcnt(" #n ")" ::: "memory")
; #define PG8_WAIT_L(n) asm volatile("s_waitcnt lgkmcnt(" #n ")" ::: "memory")
; #define PG8_BAR __builtin_amdgcn_s_barrier()
; #define PG8_SCHED __builtin_amdgcn_sched_barrier(0)
; template <class Epi, class Sched, bool ALIGN_EPI = false, bool SP2 = false>
; __device__ __forceinline__ void gemm_phase(PG8_LAS unsigned char* lds, const Gemm g, const Sched& S, const Epi& E) {
;     ...
;             PG8_WAIT_V(8); PG8_WAIT_L(0); PG8_BAR; PG8_MMA(0, 0, At, B0); PG8_MMA(0, 1, At, B1); PG8_BAR; PG8_SCHED;
;             PG8_LDA(At, 1, 1); PG8_STAGE(PG8_SB(1, 0), b3, voffB); PG8_STAGE(PG8_SB(1, 1), b3 + hstep, voffB); PG8_STAGE(PG8_SA(1, 0), a3, voffA);
	v_mfma_f32_16x16x32_bf16 v[116:119], v[144:147], v[176:179], v[116:119]
	v_mfma_f32_16x16x32_bf16 v[108:111], v[152:155], v[176:179], v[108:111]
	v_mfma_f32_16x16x32_bf16 v[96:99], v[144:147], v[184:187], v[96:99]
	v_mfma_f32_16x16x32_bf16 v[92:95], v[152:155], v[184:187], v[92:95]
	v_mfma_f32_16x16x32_bf16 v[80:83], v[144:147], v[210:213], v[80:83]
	v_mfma_f32_16x16x32_bf16 v[76:79], v[152:155], v[210:213], v[76:79]
	v_mfma_f32_16x16x32_bf16 v[68:71], v[144:147], v[218:221], v[68:71]
	v_mfma_f32_16x16x32_bf16 v[64:67], v[152:155], v[218:221], v[64:67]
	v_mfma_f32_16x16x32_bf16 v[116:119], v[148:151], v[180:183], v[116:119]
	v_mfma_f32_16x16x32_bf16 v[108:111], v[156:159], v[180:183], v[108:111]
	v_mfma_f32_16x16x32_bf16 v[96:99], v[148:151], v[192:195], v[96:99]
	v_mfma_f32_16x16x32_bf16 v[92:95], v[156:159], v[192:195], v[92:95]
	v_mfma_f32_16x16x32_bf16 v[80:83], v[148:151], v[214:217], v[80:83]
	v_mfma_f32_16x16x32_bf16 v[76:79], v[156:159], v[214:217], v[76:79]
	v_mfma_f32_16x16x32_bf16 v[68:71], v[148:151], v[222:225], v[68:71]
	v_mfma_f32_16x16x32_bf16 v[64:67], v[156:159], v[222:225], v[64:67]
	s_setprio 0
	s_barrier
	s_add_i32 s54, s79, s57

; #define PG8_STAGE(bufoff, gbase, voff) do { _Pragma("unroll") for (int _i = 0; _i < 2; ++_i) \
;         __builtin_amdgcn_global_load_lds((const unsigned*)((const char*)(gbase) + (voff)[_i]), (PG8_LAS unsigned*)(lds + (bufoff) + ldsw + _i * 8192), 16, 0, 0); } while (0)
; #define PG8_LDA(dst, b, h) do { _Pragma("unroll") for (int m = 0; m < 4; ++m) _Pragma("unroll") for (int k = 0; k < 2; ++k) dst[m][k] = *(const PG8_LAS bf16x8*)(lds + PG8_SA(b, h) + aoff + m * 2048 + k * 1024); } while (0)
; template <class Epi, class Sched, bool ALIGN_EPI = false, bool SP2 = false>
; __device__ __forceinline__ void gemm_phase(PG8_LAS unsigned char* lds, const Gemm g, const Sched& S, const Epi& E) {
;     ...
;             PG8_LDA(At, 1, 1); PG8_STAGE(PG8_SB(1, 0), b3, voffB); PG8_STAGE(PG8_SB(1, 1), b3 + hstep, voffB); PG8_STAGE(PG8_SA(1, 0), a3, voffA);
	s_mov_b32 m0, s54
	ds_read_b128 v[176:179], v207 offset:49152
	ds_read_b128 v[180:183], v207 offset:50176
	ds_read_b128 v[184:187], v207 offset:51200
	ds_read_b128 v[192:195], v207 offset:52224
	ds_read_b128 v[210:213], v207 offset:53248
	ds_read_b128 v[214:217], v207 offset:54272
	ds_read_b128 v[218:221], v207 offset:55296
	ds_read_b128 v[222:225], v207 offset:56320
	global_load_lds_dwordx4 v250, s[96:97]
	s_add_i32 m0, s54, 0x2000
	s_add_u32 s12, s12, 0x80080

; #define PG8_STAGE(bufoff, gbase, voff) do { _Pragma("unroll") for (int _i = 0; _i < 2; ++_i) \
;         __builtin_amdgcn_global_load_lds((const unsigned*)((const char*)(gbase) + (voff)[_i]), (PG8_LAS unsigned*)(lds + (bufoff) + ldsw + _i * 8192), 16, 0, 0); } while (0)
; #define PG8_LDA(dst, b, h) do { _Pragma("unroll") for (int m = 0; m < 4; ++m) _Pragma("unroll") for (int k = 0; k < 2; ++k) dst[m][k] = *(const PG8_LAS bf16x8*)(lds + PG8_SA(b, h) + aoff + m * 2048 + k * 1024); } while (0)
; template <class Epi, class Sched, bool ALIGN_EPI = false, bool SP2 = false>
; __device__ __forceinline__ void gemm_phase(PG8_LAS unsigned char* lds, const Gemm g, const Sched& S, const Epi& E) {
;     ...
;             PG8_LDA(At, 1, 1); PG8_STAGE(PG8_SB(1, 0), b3, voffB); PG8_STAGE(PG8_SB(1, 1), b3 + hstep, voffB); PG8_STAGE(PG8_SA(1, 0), a3, voffA);
	s_addc_u32 s13, s13, 0
	s_add_i32 s54, s80, s57
	global_load_lds_dwordx4 v251, s[96:97]

; #define PG8_STAGE(bufoff, gbase, voff) do { _Pragma("unroll") for (int _i = 0; _i < 2; ++_i) \
;         __builtin_amdgcn_global_load_lds((const unsigned*)((const char*)(gbase) + (voff)[_i]), (PG8_LAS unsigned*)(lds + (bufoff) + ldsw + _i * 8192), 16, 0, 0); } while (0)
; #define PG8_LDA(dst, b, h) do { _Pragma("unroll") for (int m = 0; m < 4; ++m) _Pragma("unroll") for (int k = 0; k < 2; ++k) dst[m][k] = *(const PG8_LAS bf16x8*)(lds + PG8_SA(b, h) + aoff + m * 2048 + k * 1024); } while (0)
; template <class Epi, class Sched, bool ALIGN_EPI = false, bool SP2 = false>
; __device__ __forceinline__ void gemm_phase(PG8_LAS unsigned char* lds, const Gemm g, const Sched& S, const Epi& E) {
;     ...
;             PG8_LDA(At, 1, 1); PG8_STAGE(PG8_SB(1, 0), b3, voffB); PG8_STAGE(PG8_SB(1, 1), b3 + hstep, voffB); PG8_STAGE(PG8_SA(1, 0), a3, voffA);
	s_mov_b32 m0, s54
	s_nop 0
	global_load_lds_dwordx4 v164, s[12:13]

; #define PG8_STAGE(bufoff, gbase, voff) do { _Pragma("unroll") for (int _i = 0; _i < 2; ++_i) \
;         __builtin_amdgcn_global_load_lds((const unsigned*)((const char*)(gbase) + (voff)[_i]), (PG8_LAS unsigned*)(lds + (bufoff) + ldsw + _i * 8192), 16, 0, 0); } while (0)
; #define PG8_LDA(dst, b, h) do { _Pragma("unroll") for (int m = 0; m < 4; ++m) _Pragma("unroll") for (int k = 0; k < 2; ++k) dst[m][k] = *(const PG8_LAS bf16x8*)(lds + PG8_SA(b, h) + aoff + m * 2048 + k * 1024); } while (0)
; template <class Epi, class Sched, bool ALIGN_EPI = false, bool SP2 = false>
; __device__ __forceinline__ void gemm_phase(PG8_LAS unsigned char* lds, const Gemm g, const Sched& S, const Epi& E) {
;     ...
;             PG8_LDA(At, 1, 1); PG8_STAGE(PG8_SB(1, 0), b3, voffB); PG8_STAGE(PG8_SB(1, 1), b3 + hstep, voffB); PG8_STAGE(PG8_SA(1, 0), a3, voffA);
	s_add_i32 m0, s54, 0x2000
	s_nop 0
	global_load_lds_dwordx4 v160, s[12:13]

; #define PG8_STAGE(bufoff, gbase, voff) do { _Pragma("unroll") for (int _i = 0; _i < 2; ++_i) \
;         __builtin_amdgcn_global_load_lds((const unsigned*)((const char*)(gbase) + (voff)[_i]), (PG8_LAS unsigned*)(lds + (bufoff) + ldsw + _i * 8192), 16, 0, 0); } while (0)
; #define PG8_LDA(dst, b, h) do { _Pragma("unroll") for (int m = 0; m < 4; ++m) _Pragma("unroll") for (int k = 0; k < 2; ++k) dst[m][k] = *(const PG8_LAS bf16x8*)(lds + PG8_SA(b, h) + aoff + m * 2048 + k * 1024); } while (0)
; template <class Epi, class Sched, bool ALIGN_EPI = false, bool SP2 = false>
; __device__ __forceinline__ void gemm_phase(PG8_LAS unsigned char* lds, const Gemm g, const Sched& S, const Epi& E) {
;     ...
;             PG8_LDA(At, 1, 1); PG8_STAGE(PG8_SB(1, 0), b3, voffB); PG8_STAGE(PG8_SB(1, 1), b3 + hstep, voffB); PG8_STAGE(PG8_SA(1, 0), a3, voffA);
	s_mov_b32 m0, s65
	s_nop 0
	global_load_lds_dwordx4 v252, s[98:99]

; #define PG8_MMA(ai, bj, At, Bt) do { __builtin_amdgcn_s_setprio(1); _Pragma("unroll") for (int m = 0; m < 4; ++m) _Pragma("unroll") for (int n = 0; n < 2; ++n) _Pragma("unroll") for (int k = 0; k < 2; ++k) \
;         acc[ai][bj][m][n] = __builtin_amdgcn_mfma_f32_16x16x32_bf16(Bt[n][k], At[m][k], acc[ai][bj][m][n], 0, 0, 0); __builtin_amdgcn_s_setprio(0); } while (0)
; #define PG8_WAIT_V(n) asm volatile("s_waitcnt vmcnt(" #n ")" ::: "memory")
; #define PG8_WAIT_L(n) asm volatile("s_waitcnt lgkmcnt(" #n ")" ::: "memory")
; #define PG8_BAR __builtin_amdgcn_s_barrier()
; #define PG8_SCHED __builtin_amdgcn_sched_barrier(0)
; template <class Epi, class Sched, bool ALIGN_EPI = false, bool SP2 = false>
; __device__ __forceinline__ void gemm_phase(PG8_LAS unsigned char* lds, const Gemm g, const Sched& S, const Epi& E) {
;     ...
;             PG8_WAIT_V(8); PG8_WAIT_L(0); PG8_BAR; PG8_MMA(1, 0, At, B0); PG8_MMA(1, 1, At, B1); PG8_BAR; PG8_SCHED;
	s_mov_b32 m0, s67
	s_nop 0
	global_load_lds_dwordx4 v253, s[98:99]
	s_waitcnt vmcnt(8)
	s_waitcnt lgkmcnt(0)
	s_setprio 1
	s_barrier

; #define PG8_MMA(ai, bj, At, Bt) do { __builtin_amdgcn_s_setprio(1); _Pragma("unroll") for (int m = 0; m < 4; ++m) _Pragma("unroll") for (int n = 0; n < 2; ++n) _Pragma("unroll") for (int k = 0; k < 2; ++k) \
;         acc[ai][bj][m][n] = __builtin_amdgcn_mfma_f32_16x16x32_bf16(Bt[n][k], At[m][k], acc[ai][bj][m][n], 0, 0, 0); __builtin_amdgcn_s_setprio(0); } while (0)
; #define PG8_WAIT_V(n) asm volatile("s_waitcnt vmcnt(" #n ")" ::: "memory")
; #define PG8_WAIT_L(n) asm volatile("s_waitcnt lgkmcnt(" #n ")" ::: "memory")
; #define PG8_BAR __builtin_amdgcn_s_barrier()
; #define PG8_SCHED __builtin_amdgcn_sched_barrier(0)
; template <class Epi, class Sched, bool ALIGN_EPI = false, bool SP2 = false>
; __device__ __forceinline__ void gemm_phase(PG8_LAS unsigned char* lds, const Gemm g, const Sched& S, const Epi& E) {
;     ...
;             PG8_WAIT_V(8); PG8_WAIT_L(0); PG8_BAR; PG8_MMA(1, 0, At, B0); PG8_MMA(1, 1, At, B1); PG8_BAR; PG8_SCHED;
	v_mfma_f32_16x16x32_bf16 v[60:63], v[128:131], v[176:179], v[60:63]
	v_mfma_f32_16x16x32_bf16 v[56:59], v[136:139], v[176:179], v[56:59]
	v_mfma_f32_16x16x32_bf16 v[52:55], v[128:131], v[184:187], v[52:55]
	v_mfma_f32_16x16x32_bf16 v[40:43], v[136:139], v[184:187], v[40:43]
	v_mfma_f32_16x16x32_bf16 v[36:39], v[128:131], v[210:213], v[36:39]
	v_mfma_f32_16x16x32_bf16 v[24:27], v[136:139], v[210:213], v[24:27]
	v_mfma_f32_16x16x32_bf16 v[20:23], v[128:131], v[218:221], v[20:23]
	v_mfma_f32_16x16x32_bf16 v[8:11], v[136:139], v[218:221], v[8:11]
	v_mfma_f32_16x16x32_bf16 v[60:63], v[132:135], v[180:183], v[60:63]
	v_mfma_f32_16x16x32_bf16 v[56:59], v[140:143], v[180:183], v[56:59]
	v_mfma_f32_16x16x32_bf16 v[52:55], v[132:135], v[192:195], v[52:55]
	v_mfma_f32_16x16x32_bf16 v[40:43], v[140:143], v[192:195], v[40:43]
	v_mfma_f32_16x16x32_bf16 v[36:39], v[132:135], v[214:217], v[36:39]
	v_mfma_f32_16x16x32_bf16 v[24:27], v[140:143], v[214:217], v[24:27]
	v_mfma_f32_16x16x32_bf16 v[20:23], v[132:135], v[222:225], v[20:23]
	v_mfma_f32_16x16x32_bf16 v[8:11], v[140:143], v[222:225], v[8:11]


; #define PG8_WAIT_V(n) asm volatile("s_waitcnt vmcnt(" #n ")" ::: "memory")
; template <class Epi, class Sched, bool ALIGN_EPI = false, bool SP2 = false>
; __device__ __forceinline__ void gemm_phase(PG8_LAS unsigned char* lds, const Gemm g, const Sched& S, const Epi& E) {
;     ...
;         for (int t = 0; t < nt; t += 2) {
;             const bool last = (t == nt - 2);
;             const char* a1 = cA + (size_t)(t + 1) * kstep;
;             const char* a2 = last ? nA : cA + (size_t)(t + 2) * kstep; const char* b2 = last ? nB : cB + (size_t)(t + 2) * kstep;
;             const char* a3 = a2 + kstep; const char* b3 = b2 + kstep;
;             if (last && has_next) S.a_ready(nxt);
;             if constexpr (SP2) {
;             PG8_LDB(B0, 0, 0); PG8_LDB(B1, 0, 1); PG8_SCHED; PG8_LDA(At, 0, 0); PG8_STAGE(PG8_SA(1, 1), a1 + hstep, voffA);
;             PG8_WAIT_V(8); PG8_WAIT_L(0); PG8_BAR; PG8_MMA(0, 0, At, B0); PG8_MMA(0, 1, At, B1); PG8_BAR; PG8_SCHED;
;             PG8_LDA(At, 0, 1); PG8_STAGE(PG8_SB(0, 0), b2, voffB); PG8_STAGE(PG8_SB(0, 1), b2 + hstep, voffB); PG8_STAGE(PG8_SA(0, 0), a2, voffA);
;             PG8_WAIT_V(8); PG8_WAIT_L(0); PG8_BAR; PG8_MMA(1, 0, At, B0); PG8_MMA(1, 1, At, B1); PG8_BAR; PG8_SCHED;
;             PG8_LDB(B0, 1, 0); PG8_LDB(B1, 1, 1); PG8_SCHED; PG8_LDA(At, 1, 0); PG8_STAGE(PG8_SA(0, 1), a2 + hstep, voffA);
;             PG8_WAIT_V(8); PG8_WAIT_L(0); PG8_BAR; PG8_MMA(0, 0, At, B0); PG8_MMA(0, 1, At, B1); PG8_BAR; PG8_SCHED;
;             PG8_LDA(At, 1, 1); PG8_STAGE(PG8_SB(1, 0), b3, voffB); PG8_STAGE(PG8_SB(1, 1), b3 + hstep, voffB); PG8_STAGE(PG8_SA(1, 0), a3, voffA);
;             PG8_WAIT_V(8); PG8_WAIT_L(0); PG8_BAR; PG8_MMA(1, 0, At, B0); PG8_MMA(1, 1, At, B1); PG8_BAR; PG8_SCHED;
;             } else {
;             PG8_LDB(B0, 0, 0); PG8_SCHED; PG8_LDA(At, 0, 0); PG8_STAGE(PG8_SA(1, 1), a1 + hstep, voffA);
;             PG8_WAIT_L(8); PG8_BAR; PG8_WAIT_L(0); PG8_MMA(0, 0, At, B0); PG8_BAR; PG8_SCHED;
;             PG8_LDB(B1, 0, 1); PG8_STAGE(PG8_SB(0, 0), b2, voffB);
;             PG8_BAR; PG8_WAIT_L(0); PG8_MMA(0, 1, At, B1); PG8_BAR;
;             PG8_LDA(At, 0, 1); PG8_STAGE(PG8_SA(0, 0), a2, voffA);
;             PG8_BAR; PG8_WAIT_L(0); PG8_MMA(1, 0, At, B0); PG8_BAR; PG8_SCHED;
;             PG8_STAGE(PG8_SB(0, 1), b2 + hstep, voffB);
;             PG8_WAIT_V(6); PG8_BAR; PG8_MMA(1, 1, At, B1); PG8_BAR;
	v_mfma_f32_16x16x32_bf16 v[48:51], v[144:147], v[176:179], v[48:51]
	v_mfma_f32_16x16x32_bf16 v[44:47], v[152:155], v[176:179], v[44:47]
	v_mfma_f32_16x16x32_bf16 v[32:35], v[144:147], v[184:187], v[32:35]
	v_mfma_f32_16x16x32_bf16 v[28:31], v[152:155], v[184:187], v[28:31]
	v_mfma_f32_16x16x32_bf16 v[16:19], v[144:147], v[210:213], v[16:19]
	v_mfma_f32_16x16x32_bf16 v[12:15], v[152:155], v[210:213], v[12:15]
	v_mfma_f32_16x16x32_bf16 v[4:7], v[144:147], v[218:221], v[4:7]
	v_mfma_f32_16x16x32_bf16 v[0:3], v[152:155], v[218:221], v[0:3]
	v_mfma_f32_16x16x32_bf16 v[48:51], v[148:151], v[180:183], v[48:51]
	v_mfma_f32_16x16x32_bf16 v[44:47], v[156:159], v[180:183], v[44:47]
	v_mfma_f32_16x16x32_bf16 v[32:35], v[148:151], v[192:195], v[32:35]
	v_mfma_f32_16x16x32_bf16 v[28:31], v[156:159], v[192:195], v[28:31]
	v_mfma_f32_16x16x32_bf16 v[16:19], v[148:151], v[214:217], v[16:19]
	v_mfma_f32_16x16x32_bf16 v[12:15], v[156:159], v[214:217], v[12:15]
	v_mfma_f32_16x16x32_bf16 v[4:7], v[148:151], v[222:225], v[4:7]
	v_mfma_f32_16x16x32_bf16 v[0:3], v[156:159], v[222:225], v[0:3]
	s_setprio 0
	s_barrier
	s_add_i32 s78, s78, 2
	s_add_u32 s10, s10, 0x100
	s_addc_u32 s11, s11, 0
	s_add_u32 s76, s76, 0x100
	s_addc_u32 s77, s77, 0
	s_cmp_gt_u32 s78, 29
	s_cbranch_scc0 .LBB0_679
	s_and_b64 vcc, exec, s[42:43]
	s_cbranch_vccz .LBB0_682
	s_barrier

; #define PG8_STAGE(bufoff, gbase, voff) do { _Pragma("unroll") for (int _i = 0; _i < 2; ++_i) \
;         __builtin_amdgcn_global_load_lds((const unsigned*)((const char*)(gbase) + (voff)[_i]), (PG8_LAS unsigned*)(lds + (bufoff) + ldsw + _i * 8192), 16, 0, 0); } while (0)
; #define PG8_LDA(dst, b, h) do { _Pragma("unroll") for (int m = 0; m < 4; ++m) _Pragma("unroll") for (int k = 0; k < 2; ++k) dst[m][k] = *(const PG8_LAS bf16x8*)(lds + PG8_SA(b, h) + aoff + m * 2048 + k * 1024); } while (0)
; #define PG8_LDB(dst, b, h) do { _Pragma("unroll") for (int n = 0; n < 2; ++n) _Pragma("unroll") for (int k = 0; k < 2; ++k) dst[n][k] = *(const PG8_LAS bf16x8*)(lds + PG8_SB(b, h) + boff + n * 2048 + k * 1024); } while (0)
; #define PG8_SCHED __builtin_amdgcn_sched_barrier(0)
; template <class Epi, class Sched, bool ALIGN_EPI = false, bool SP2 = false>
; __device__ __forceinline__ void gemm_phase(PG8_LAS unsigned char* lds, const Gemm g, const Sched& S, const Epi& E) {
;     ...
;         for (int t = 0; t < nt; t += 2) {
;             const bool last = (t == nt - 2);
;             const char* a1 = cA + (size_t)(t + 1) * kstep;
;             const char* a2 = last ? nA : cA + (size_t)(t + 2) * kstep; const char* b2 = last ? nB : cB + (size_t)(t + 2) * kstep;
;             const char* a3 = a2 + kstep; const char* b3 = b2 + kstep;
;             if (last && has_next) S.a_ready(nxt);
;             if constexpr (SP2) {
;             PG8_LDB(B0, 0, 0); PG8_LDB(B1, 0, 1); PG8_SCHED; PG8_LDA(At, 0, 0); PG8_STAGE(PG8_SA(1, 1), a1 + hstep, voffA);
.LBB0_939:
	ds_read_b128 v[64:67], v213
	ds_read_b128 v[68:71], v213 offset:1024
	ds_read_b128 v[72:75], v213 offset:2048
	ds_read_b128 v[76:79], v213 offset:3072
	ds_read_b128 v[144:147], v214
	ds_read_b128 v[148:151], v214 offset:1024
	ds_read_b128 v[152:155], v214 offset:2048
	ds_read_b128 v[156:159], v214 offset:3072
	s_add_u32 s60, s58, 0xfff80080
	s_addc_u32 s61, s59, -1
	s_cmp_eq_u32 s81, 28
	s_cselect_b32 s63, s11, s61
	s_cselect_b32 s62, s51, s60
	s_cselect_b32 s61, s49, s80
	s_cselect_b32 s60, s78, s79

; #define PG8_STAGE(bufoff, gbase, voff) do { _Pragma("unroll") for (int _i = 0; _i < 2; ++_i) \
;         __builtin_amdgcn_global_load_lds((const unsigned*)((const char*)(gbase) + (voff)[_i]), (PG8_LAS unsigned*)(lds + (bufoff) + ldsw + _i * 8192), 16, 0, 0); } while (0)
; #define PG8_LDA(dst, b, h) do { _Pragma("unroll") for (int m = 0; m < 4; ++m) _Pragma("unroll") for (int k = 0; k < 2; ++k) dst[m][k] = *(const PG8_LAS bf16x8*)(lds + PG8_SA(b, h) + aoff + m * 2048 + k * 1024); } while (0)
; #define PG8_LDB(dst, b, h) do { _Pragma("unroll") for (int n = 0; n < 2; ++n) _Pragma("unroll") for (int k = 0; k < 2; ++k) dst[n][k] = *(const PG8_LAS bf16x8*)(lds + PG8_SB(b, h) + boff + n * 2048 + k * 1024); } while (0)
; #define PG8_SCHED __builtin_amdgcn_sched_barrier(0)
; template <class Epi, class Sched, bool ALIGN_EPI = false, bool SP2 = false>
; __device__ __forceinline__ void gemm_phase(PG8_LAS unsigned char* lds, const Gemm g, const Sched& S, const Epi& E) {
;     ...
;             PG8_LDB(B0, 0, 0); PG8_LDB(B1, 0, 1); PG8_SCHED; PG8_LDA(At, 0, 0); PG8_STAGE(PG8_SA(1, 1), a1 + hstep, voffA);
	s_add_i32 m0, s57, 0xc000
	ds_read_b128 v[176:179], v215
	ds_read_b128 v[180:183], v215 offset:1024
	ds_read_b128 v[184:187], v215 offset:2048
	ds_read_b128 v[188:191], v215 offset:3072
	ds_read_b128 v[192:195], v215 offset:4096
	ds_read_b128 v[196:199], v215 offset:5120
	ds_read_b128 v[200:203], v215 offset:6144
	ds_read_b128 v[204:207], v215 offset:7168
	global_load_lds_dwordx4 v168, s[58:59]

; #define PG8_MMA(ai, bj, At, Bt) do { __builtin_amdgcn_s_setprio(1); _Pragma("unroll") for (int m = 0; m < 4; ++m) _Pragma("unroll") for (int n = 0; n < 2; ++n) _Pragma("unroll") for (int k = 0; k < 2; ++k) \
;         acc[ai][bj][m][n] = __builtin_amdgcn_mfma_f32_16x16x32_bf16(Bt[n][k], At[m][k], acc[ai][bj][m][n], 0, 0, 0); __builtin_amdgcn_s_setprio(0); } while (0)
; #define PG8_WAIT_V(n) asm volatile("s_waitcnt vmcnt(" #n ")" ::: "memory")
; #define PG8_WAIT_L(n) asm volatile("s_waitcnt lgkmcnt(" #n ")" ::: "memory")
; #define PG8_BAR __builtin_amdgcn_s_barrier()
; #define PG8_SCHED __builtin_amdgcn_sched_barrier(0)
; template <class Epi, class Sched, bool ALIGN_EPI = false, bool SP2 = false>
; __device__ __forceinline__ void gemm_phase(PG8_LAS unsigned char* lds, const Gemm g, const Sched& S, const Epi& E) {
;     ...
;             PG8_WAIT_V(8); PG8_WAIT_L(0); PG8_BAR; PG8_MMA(0, 0, At, B0); PG8_MMA(0, 1, At, B1); PG8_BAR; PG8_SCHED;
	s_add_i32 m0, s57, 0xe000
	s_nop 0
	global_load_lds_dwordx4 v170, s[58:59]
	s_waitcnt vmcnt(8)
	s_waitcnt lgkmcnt(0)
	s_setprio 1
	s_barrier

; #define PG8_MMA(ai, bj, At, Bt) do { __builtin_amdgcn_s_setprio(1); _Pragma("unroll") for (int m = 0; m < 4; ++m) _Pragma("unroll") for (int n = 0; n < 2; ++n) _Pragma("unroll") for (int k = 0; k < 2; ++k) \
;         acc[ai][bj][m][n] = __builtin_amdgcn_mfma_f32_16x16x32_bf16(Bt[n][k], At[m][k], acc[ai][bj][m][n], 0, 0, 0); __builtin_amdgcn_s_setprio(0); } while (0)
; #define PG8_WAIT_V(n) asm volatile("s_waitcnt vmcnt(" #n ")" ::: "memory")
; #define PG8_WAIT_L(n) asm volatile("s_waitcnt lgkmcnt(" #n ")" ::: "memory")
; #define PG8_BAR __builtin_amdgcn_s_barrier()
; #define PG8_SCHED __builtin_amdgcn_sched_barrier(0)
; template <class Epi, class Sched, bool ALIGN_EPI = false, bool SP2 = false>
; __device__ __forceinline__ void gemm_phase(PG8_LAS unsigned char* lds, const Gemm g, const Sched& S, const Epi& E) {
;     ...
;             PG8_WAIT_V(8); PG8_WAIT_L(0); PG8_BAR; PG8_MMA(0, 0, At, B0); PG8_MMA(0, 1, At, B1); PG8_BAR; PG8_SCHED;
	v_mfma_f32_16x16x32_bf16 v[140:143], v[64:67], v[176:179], v[140:143]
	v_mfma_f32_16x16x32_bf16 v[136:139], v[72:75], v[176:179], v[136:139]
	v_mfma_f32_16x16x32_bf16 v[124:127], v[64:67], v[184:187], v[124:127]
	v_mfma_f32_16x16x32_bf16 v[120:123], v[72:75], v[184:187], v[120:123]
	v_mfma_f32_16x16x32_bf16 v[108:111], v[64:67], v[192:195], v[108:111]
	v_mfma_f32_16x16x32_bf16 v[104:107], v[72:75], v[192:195], v[104:107]
	v_mfma_f32_16x16x32_bf16 v[92:95], v[64:67], v[200:203], v[92:95]
	v_mfma_f32_16x16x32_bf16 v[88:91], v[72:75], v[200:203], v[88:91]
	v_mfma_f32_16x16x32_bf16 v[140:143], v[68:71], v[180:183], v[140:143]
	v_mfma_f32_16x16x32_bf16 v[136:139], v[76:79], v[180:183], v[136:139]
	v_mfma_f32_16x16x32_bf16 v[124:127], v[68:71], v[188:191], v[124:127]
	v_mfma_f32_16x16x32_bf16 v[120:123], v[76:79], v[188:191], v[120:123]
	v_mfma_f32_16x16x32_bf16 v[108:111], v[68:71], v[196:199], v[108:111]
	v_mfma_f32_16x16x32_bf16 v[104:107], v[76:79], v[196:199], v[104:107]
	v_mfma_f32_16x16x32_bf16 v[92:95], v[68:71], v[204:207], v[92:95]
	v_mfma_f32_16x16x32_bf16 v[88:91], v[76:79], v[204:207], v[88:91]


; #define PG8_STAGE(bufoff, gbase, voff) do { _Pragma("unroll") for (int _i = 0; _i < 2; ++_i) \
;         __builtin_amdgcn_global_load_lds((const unsigned*)((const char*)(gbase) + (voff)[_i]), (PG8_LAS unsigned*)(lds + (bufoff) + ldsw + _i * 8192), 16, 0, 0); } while (0)
; #define PG8_LDA(dst, b, h) do { _Pragma("unroll") for (int m = 0; m < 4; ++m) _Pragma("unroll") for (int k = 0; k < 2; ++k) dst[m][k] = *(const PG8_LAS bf16x8*)(lds + PG8_SA(b, h) + aoff + m * 2048 + k * 1024); } while (0)
; #define PG8_MMA(ai, bj, At, Bt) do { __builtin_amdgcn_s_setprio(1); _Pragma("unroll") for (int m = 0; m < 4; ++m) _Pragma("unroll") for (int n = 0; n < 2; ++n) _Pragma("unroll") for (int k = 0; k < 2; ++k) \
;         acc[ai][bj][m][n] = __builtin_amdgcn_mfma_f32_16x16x32_bf16(Bt[n][k], At[m][k], acc[ai][bj][m][n], 0, 0, 0); __builtin_amdgcn_s_setprio(0); } while (0)
; #define PG8_WAIT_V(n) asm volatile("s_waitcnt vmcnt(" #n ")" ::: "memory")
; #define PG8_WAIT_L(n) asm volatile("s_waitcnt lgkmcnt(" #n ")" ::: "memory")
; #define PG8_BAR __builtin_amdgcn_s_barrier()
; #define PG8_SCHED __builtin_amdgcn_sched_barrier(0)
; template <class Epi, class Sched, bool ALIGN_EPI = false, bool SP2 = false>
; __device__ __forceinline__ void gemm_phase(PG8_LAS unsigned char* lds, const Gemm g, const Sched& S, const Epi& E) {
;     ...
;             PG8_WAIT_V(8); PG8_WAIT_L(0); PG8_BAR; PG8_MMA(0, 0, At, B0); PG8_MMA(0, 1, At, B1); PG8_BAR; PG8_SCHED;
;             PG8_LDA(At, 0, 1); PG8_STAGE(PG8_SB(0, 0), b2, voffB); PG8_STAGE(PG8_SB(0, 1), b2 + hstep, voffB); PG8_STAGE(PG8_SA(0, 0), a2, voffA);
	v_mfma_f32_16x16x32_bf16 v[132:135], v[144:147], v[176:179], v[132:135]
	v_mfma_f32_16x16x32_bf16 v[128:131], v[152:155], v[176:179], v[128:131]
	v_mfma_f32_16x16x32_bf16 v[116:119], v[144:147], v[184:187], v[116:119]
	v_mfma_f32_16x16x32_bf16 v[112:115], v[152:155], v[184:187], v[112:115]
	v_mfma_f32_16x16x32_bf16 v[100:103], v[144:147], v[192:195], v[100:103]
	v_mfma_f32_16x16x32_bf16 v[96:99], v[152:155], v[192:195], v[96:99]
	v_mfma_f32_16x16x32_bf16 v[84:87], v[144:147], v[200:203], v[84:87]
	v_mfma_f32_16x16x32_bf16 v[80:83], v[152:155], v[200:203], v[80:83]
	v_mfma_f32_16x16x32_bf16 v[132:135], v[148:151], v[180:183], v[132:135]
	v_mfma_f32_16x16x32_bf16 v[128:131], v[156:159], v[180:183], v[128:131]
	v_mfma_f32_16x16x32_bf16 v[116:119], v[148:151], v[188:191], v[116:119]
	v_mfma_f32_16x16x32_bf16 v[112:115], v[156:159], v[188:191], v[112:115]
	v_mfma_f32_16x16x32_bf16 v[100:103], v[148:151], v[196:199], v[100:103]
	v_mfma_f32_16x16x32_bf16 v[96:99], v[156:159], v[196:199], v[96:99]
	v_mfma_f32_16x16x32_bf16 v[84:87], v[148:151], v[204:207], v[84:87]
	v_mfma_f32_16x16x32_bf16 v[80:83], v[156:159], v[204:207], v[80:83]
	s_setprio 0
	s_barrier
	s_add_i32 s82, s75, s64
	s_mov_b64 s[96:97], s[60:61]

; #define PG8_STAGE(bufoff, gbase, voff) do { _Pragma("unroll") for (int _i = 0; _i < 2; ++_i) \
;         __builtin_amdgcn_global_load_lds((const unsigned*)((const char*)(gbase) + (voff)[_i]), (PG8_LAS unsigned*)(lds + (bufoff) + ldsw + _i * 8192), 16, 0, 0); } while (0)
; #define PG8_LDA(dst, b, h) do { _Pragma("unroll") for (int m = 0; m < 4; ++m) _Pragma("unroll") for (int k = 0; k < 2; ++k) dst[m][k] = *(const PG8_LAS bf16x8*)(lds + PG8_SA(b, h) + aoff + m * 2048 + k * 1024); } while (0)
; template <class Epi, class Sched, bool ALIGN_EPI = false, bool SP2 = false>
; __device__ __forceinline__ void gemm_phase(PG8_LAS unsigned char* lds, const Gemm g, const Sched& S, const Epi& E) {
;     ...
;             PG8_LDA(At, 0, 1); PG8_STAGE(PG8_SB(0, 0), b2, voffB); PG8_STAGE(PG8_SB(0, 1), b2 + hstep, voffB); PG8_STAGE(PG8_SA(0, 0), a2, voffA);
	s_mov_b32 m0, s82
	ds_read_b128 v[176:179], v215 offset:16384
	ds_read_b128 v[180:183], v215 offset:17408
	ds_read_b128 v[184:187], v215 offset:18432
	ds_read_b128 v[188:191], v215 offset:19456
	ds_read_b128 v[192:195], v215 offset:20480
	ds_read_b128 v[196:199], v215 offset:21504
	ds_read_b128 v[200:203], v215 offset:22528
	ds_read_b128 v[204:207], v215 offset:23552
	global_load_lds_dwordx4 v162, s[60:61]
	s_add_i32 m0, s82, 0x2000
	s_add_u32 s82, s60, 0x80000

; #define PG8_STAGE(bufoff, gbase, voff) do { _Pragma("unroll") for (int _i = 0; _i < 2; ++_i) \
;         __builtin_amdgcn_global_load_lds((const unsigned*)((const char*)(gbase) + (voff)[_i]), (PG8_LAS unsigned*)(lds + (bufoff) + ldsw + _i * 8192), 16, 0, 0); } while (0)
; #define PG8_LDA(dst, b, h) do { _Pragma("unroll") for (int m = 0; m < 4; ++m) _Pragma("unroll") for (int k = 0; k < 2; ++k) dst[m][k] = *(const PG8_LAS bf16x8*)(lds + PG8_SA(b, h) + aoff + m * 2048 + k * 1024); } while (0)
; template <class Epi, class Sched, bool ALIGN_EPI = false, bool SP2 = false>
; __device__ __forceinline__ void gemm_phase(PG8_LAS unsigned char* lds, const Gemm g, const Sched& S, const Epi& E) {
;     ...
;             PG8_LDA(At, 0, 1); PG8_STAGE(PG8_SB(0, 0), b2, voffB); PG8_STAGE(PG8_SB(0, 1), b2 + hstep, voffB); PG8_STAGE(PG8_SA(0, 0), a2, voffA);
	s_addc_u32 s83, s61, 0
	s_add_i32 s84, s76, s64
	global_load_lds_dwordx4 v166, s[60:61]

; #define PG8_STAGE(bufoff, gbase, voff) do { _Pragma("unroll") for (int _i = 0; _i < 2; ++_i) \
;         __builtin_amdgcn_global_load_lds((const unsigned*)((const char*)(gbase) + (voff)[_i]), (PG8_LAS unsigned*)(lds + (bufoff) + ldsw + _i * 8192), 16, 0, 0); } while (0)
; #define PG8_LDA(dst, b, h) do { _Pragma("unroll") for (int m = 0; m < 4; ++m) _Pragma("unroll") for (int k = 0; k < 2; ++k) dst[m][k] = *(const PG8_LAS bf16x8*)(lds + PG8_SA(b, h) + aoff + m * 2048 + k * 1024); } while (0)
; template <class Epi, class Sched, bool ALIGN_EPI = false, bool SP2 = false>
; __device__ __forceinline__ void gemm_phase(PG8_LAS unsigned char* lds, const Gemm g, const Sched& S, const Epi& E) {
;     ...
;             PG8_LDA(At, 0, 1); PG8_STAGE(PG8_SB(0, 0), b2, voffB); PG8_STAGE(PG8_SB(0, 1), b2 + hstep, voffB); PG8_STAGE(PG8_SA(0, 0), a2, voffA);
	s_mov_b32 m0, s84
	s_nop 0
	global_load_lds_dwordx4 v162, s[82:83]

; #define PG8_STAGE(bufoff, gbase, voff) do { _Pragma("unroll") for (int _i = 0; _i < 2; ++_i) \
;         __builtin_amdgcn_global_load_lds((const unsigned*)((const char*)(gbase) + (voff)[_i]), (PG8_LAS unsigned*)(lds + (bufoff) + ldsw + _i * 8192), 16, 0, 0); } while (0)
; #define PG8_LDA(dst, b, h) do { _Pragma("unroll") for (int m = 0; m < 4; ++m) _Pragma("unroll") for (int k = 0; k < 2; ++k) dst[m][k] = *(const PG8_LAS bf16x8*)(lds + PG8_SA(b, h) + aoff + m * 2048 + k * 1024); } while (0)
; template <class Epi, class Sched, bool ALIGN_EPI = false, bool SP2 = false>
; __device__ __forceinline__ void gemm_phase(PG8_LAS unsigned char* lds, const Gemm g, const Sched& S, const Epi& E) {
;     ...
;             PG8_LDA(At, 0, 1); PG8_STAGE(PG8_SB(0, 0), b2, voffB); PG8_STAGE(PG8_SB(0, 1), b2 + hstep, voffB); PG8_STAGE(PG8_SA(0, 0), a2, voffA);
	s_add_i32 m0, s84, 0x2000
	s_nop 0
	global_load_lds_dwordx4 v166, s[82:83]
	s_mov_b64 s[98:99], s[62:63]

; #define PG8_MMA(ai, bj, At, Bt) do { __builtin_amdgcn_s_setprio(1); _Pragma("unroll") for (int m = 0; m < 4; ++m) _Pragma("unroll") for (int n = 0; n < 2; ++n) _Pragma("unroll") for (int k = 0; k < 2; ++k) \
;         acc[ai][bj][m][n] = __builtin_amdgcn_mfma_f32_16x16x32_bf16(Bt[n][k], At[m][k], acc[ai][bj][m][n], 0, 0, 0); __builtin_amdgcn_s_setprio(0); } while (0)
; #define PG8_WAIT_V(n) asm volatile("s_waitcnt vmcnt(" #n ")" ::: "memory")
; #define PG8_WAIT_L(n) asm volatile("s_waitcnt lgkmcnt(" #n ")" ::: "memory")
; #define PG8_BAR __builtin_amdgcn_s_barrier()
; #define PG8_SCHED __builtin_amdgcn_sched_barrier(0)
; template <class Epi, class Sched, bool ALIGN_EPI = false, bool SP2 = false>
; __device__ __forceinline__ void gemm_phase(PG8_LAS unsigned char* lds, const Gemm g, const Sched& S, const Epi& E) {
;     ...
;             PG8_WAIT_V(8); PG8_WAIT_L(0); PG8_BAR; PG8_MMA(1, 0, At, B0); PG8_MMA(1, 1, At, B1); PG8_BAR; PG8_SCHED;
	s_mov_b32 m0, s57
	s_nop 0
	global_load_lds_dwordx4 v160, s[62:63]
	s_mov_b32 m0, s65
	s_nop 0
	global_load_lds_dwordx4 v164, s[62:63]
	s_waitcnt vmcnt(8)
	s_waitcnt lgkmcnt(0)
	s_setprio 1
	s_barrier

; #define PG8_MMA(ai, bj, At, Bt) do { __builtin_amdgcn_s_setprio(1); _Pragma("unroll") for (int m = 0; m < 4; ++m) _Pragma("unroll") for (int n = 0; n < 2; ++n) _Pragma("unroll") for (int k = 0; k < 2; ++k) \
;         acc[ai][bj][m][n] = __builtin_amdgcn_mfma_f32_16x16x32_bf16(Bt[n][k], At[m][k], acc[ai][bj][m][n], 0, 0, 0); __builtin_amdgcn_s_setprio(0); } while (0)
; #define PG8_WAIT_V(n) asm volatile("s_waitcnt vmcnt(" #n ")" ::: "memory")
; #define PG8_WAIT_L(n) asm volatile("s_waitcnt lgkmcnt(" #n ")" ::: "memory")
; #define PG8_BAR __builtin_amdgcn_s_barrier()
; #define PG8_SCHED __builtin_amdgcn_sched_barrier(0)
; template <class Epi, class Sched, bool ALIGN_EPI = false, bool SP2 = false>
; __device__ __forceinline__ void gemm_phase(PG8_LAS unsigned char* lds, const Gemm g, const Sched& S, const Epi& E) {
;     ...
;             PG8_WAIT_V(8); PG8_WAIT_L(0); PG8_BAR; PG8_MMA(1, 0, At, B0); PG8_MMA(1, 1, At, B1); PG8_BAR; PG8_SCHED;
	v_mfma_f32_16x16x32_bf16 v[60:63], v[64:67], v[176:179], v[60:63]
	v_mfma_f32_16x16x32_bf16 v[56:59], v[72:75], v[176:179], v[56:59]
	v_mfma_f32_16x16x32_bf16 v[44:47], v[64:67], v[184:187], v[44:47]
	v_mfma_f32_16x16x32_bf16 v[40:43], v[72:75], v[184:187], v[40:43]
	v_mfma_f32_16x16x32_bf16 v[28:31], v[64:67], v[192:195], v[28:31]
	v_mfma_f32_16x16x32_bf16 v[24:27], v[72:75], v[192:195], v[24:27]
	v_mfma_f32_16x16x32_bf16 v[12:15], v[64:67], v[200:203], v[12:15]
	v_mfma_f32_16x16x32_bf16 v[8:11], v[72:75], v[200:203], v[8:11]
	v_mfma_f32_16x16x32_bf16 v[60:63], v[68:71], v[180:183], v[60:63]
	v_mfma_f32_16x16x32_bf16 v[56:59], v[76:79], v[180:183], v[56:59]
	v_mfma_f32_16x16x32_bf16 v[44:47], v[68:71], v[188:191], v[44:47]
	v_mfma_f32_16x16x32_bf16 v[40:43], v[76:79], v[188:191], v[40:43]
	v_mfma_f32_16x16x32_bf16 v[28:31], v[68:71], v[196:199], v[28:31]
	v_mfma_f32_16x16x32_bf16 v[24:27], v[76:79], v[196:199], v[24:27]
	v_mfma_f32_16x16x32_bf16 v[12:15], v[68:71], v[204:207], v[12:15]
	v_mfma_f32_16x16x32_bf16 v[8:11], v[76:79], v[204:207], v[8:11]


; #define PG8_STAGE(bufoff, gbase, voff) do { _Pragma("unroll") for (int _i = 0; _i < 2; ++_i) \
;         __builtin_amdgcn_global_load_lds((const unsigned*)((const char*)(gbase) + (voff)[_i]), (PG8_LAS unsigned*)(lds + (bufoff) + ldsw + _i * 8192), 16, 0, 0); } while (0)
; #define PG8_LDA(dst, b, h) do { _Pragma("unroll") for (int m = 0; m < 4; ++m) _Pragma("unroll") for (int k = 0; k < 2; ++k) dst[m][k] = *(const PG8_LAS bf16x8*)(lds + PG8_SA(b, h) + aoff + m * 2048 + k * 1024); } while (0)
; #define PG8_LDB(dst, b, h) do { _Pragma("unroll") for (int n = 0; n < 2; ++n) _Pragma("unroll") for (int k = 0; k < 2; ++k) dst[n][k] = *(const PG8_LAS bf16x8*)(lds + PG8_SB(b, h) + boff + n * 2048 + k * 1024); } while (0)
; #define PG8_MMA(ai, bj, At, Bt) do { __builtin_amdgcn_s_setprio(1); _Pragma("unroll") for (int m = 0; m < 4; ++m) _Pragma("unroll") for (int n = 0; n < 2; ++n) _Pragma("unroll") for (int k = 0; k < 2; ++k) \
;         acc[ai][bj][m][n] = __builtin_amdgcn_mfma_f32_16x16x32_bf16(Bt[n][k], At[m][k], acc[ai][bj][m][n], 0, 0, 0); __builtin_amdgcn_s_setprio(0); } while (0)
; #define PG8_WAIT_V(n) asm volatile("s_waitcnt vmcnt(" #n ")" ::: "memory")
; #define PG8_WAIT_L(n) asm volatile("s_waitcnt lgkmcnt(" #n ")" ::: "memory")
; #define PG8_BAR __builtin_amdgcn_s_barrier()
; #define PG8_SCHED __builtin_amdgcn_sched_barrier(0)
; template <class Epi, class Sched, bool ALIGN_EPI = false, bool SP2 = false>
; __device__ __forceinline__ void gemm_phase(PG8_LAS unsigned char* lds, const Gemm g, const Sched& S, const Epi& E) {
;     ...
;             PG8_WAIT_V(8); PG8_WAIT_L(0); PG8_BAR; PG8_MMA(1, 0, At, B0); PG8_MMA(1, 1, At, B1); PG8_BAR; PG8_SCHED;
;             PG8_LDB(B0, 1, 0); PG8_LDB(B1, 1, 1); PG8_SCHED; PG8_LDA(At, 1, 0); PG8_STAGE(PG8_SA(0, 1), a2 + hstep, voffA);
	v_mfma_f32_16x16x32_bf16 v[52:55], v[144:147], v[176:179], v[52:55]
	v_mfma_f32_16x16x32_bf16 v[48:51], v[152:155], v[176:179], v[48:51]
	v_mfma_f32_16x16x32_bf16 v[36:39], v[144:147], v[184:187], v[36:39]
	v_mfma_f32_16x16x32_bf16 v[32:35], v[152:155], v[184:187], v[32:35]
	v_mfma_f32_16x16x32_bf16 v[20:23], v[144:147], v[192:195], v[20:23]
	v_mfma_f32_16x16x32_bf16 v[16:19], v[152:155], v[192:195], v[16:19]
	v_mfma_f32_16x16x32_bf16 v[4:7], v[144:147], v[200:203], v[4:7]
	v_mfma_f32_16x16x32_bf16 v[0:3], v[152:155], v[200:203], v[0:3]
	v_mfma_f32_16x16x32_bf16 v[52:55], v[148:151], v[180:183], v[52:55]
	v_mfma_f32_16x16x32_bf16 v[48:51], v[156:159], v[180:183], v[48:51]
	v_mfma_f32_16x16x32_bf16 v[36:39], v[148:151], v[188:191], v[36:39]
	v_mfma_f32_16x16x32_bf16 v[32:35], v[156:159], v[188:191], v[32:35]
	v_mfma_f32_16x16x32_bf16 v[20:23], v[148:151], v[196:199], v[20:23]
	v_mfma_f32_16x16x32_bf16 v[16:19], v[156:159], v[196:199], v[16:19]
	v_mfma_f32_16x16x32_bf16 v[4:7], v[148:151], v[204:207], v[4:7]
	v_mfma_f32_16x16x32_bf16 v[0:3], v[156:159], v[204:207], v[0:3]
	s_setprio 0
	s_barrier
	s_add_i32 s82, 0, 0x18000
	s_add_i32 s83, 0, 0x1c000


; #define PG8_STAGE(bufoff, gbase, voff) do { _Pragma("unroll") for (int _i = 0; _i < 2; ++_i) \
;         __builtin_amdgcn_global_load_lds((const unsigned*)((const char*)(gbase) + (voff)[_i]), (PG8_LAS unsigned*)(lds + (bufoff) + ldsw + _i * 8192), 16, 0, 0); } while (0)
; #define PG8_LDA(dst, b, h) do { _Pragma("unroll") for (int m = 0; m < 4; ++m) _Pragma("unroll") for (int k = 0; k < 2; ++k) dst[m][k] = *(const PG8_LAS bf16x8*)(lds + PG8_SA(b, h) + aoff + m * 2048 + k * 1024); } while (0)
; #define PG8_LDB(dst, b, h) do { _Pragma("unroll") for (int n = 0; n < 2; ++n) _Pragma("unroll") for (int k = 0; k < 2; ++k) dst[n][k] = *(const PG8_LAS bf16x8*)(lds + PG8_SB(b, h) + boff + n * 2048 + k * 1024); } while (0)
; #define PG8_SCHED __builtin_amdgcn_sched_barrier(0)
; template <class Epi, class Sched, bool ALIGN_EPI = false, bool SP2 = false>
; __device__ __forceinline__ void gemm_phase(PG8_LAS unsigned char* lds, const Gemm g, const Sched& S, const Epi& E) {
;     ...
;             PG8_LDB(B0, 1, 0); PG8_LDB(B1, 1, 1); PG8_SCHED; PG8_LDA(At, 1, 0); PG8_STAGE(PG8_SA(0, 1), a2 + hstep, voffA);
	ds_read_b128 v[64:67], v254
	ds_read_b128 v[68:71], v254 offset:1024
	ds_read_b128 v[72:75], v254 offset:2048
	ds_read_b128 v[76:79], v254 offset:3072
	ds_read_b128 v[144:147], v255
	ds_read_b128 v[148:151], v255 offset:1024
	ds_read_b128 v[152:155], v255 offset:2048
	ds_read_b128 v[156:159], v255 offset:3072
	s_add_u32 s62, s62, 0x80000
	s_addc_u32 s63, s63, 0
	s_mov_b32 m0, s67

; #define PG8_STAGE(bufoff, gbase, voff) do { _Pragma("unroll") for (int _i = 0; _i < 2; ++_i) \
;         __builtin_amdgcn_global_load_lds((const unsigned*)((const char*)(gbase) + (voff)[_i]), (PG8_LAS unsigned*)(lds + (bufoff) + ldsw + _i * 8192), 16, 0, 0); } while (0)
; #define PG8_LDA(dst, b, h) do { _Pragma("unroll") for (int m = 0; m < 4; ++m) _Pragma("unroll") for (int k = 0; k < 2; ++k) dst[m][k] = *(const PG8_LAS bf16x8*)(lds + PG8_SA(b, h) + aoff + m * 2048 + k * 1024); } while (0)
; #define PG8_LDB(dst, b, h) do { _Pragma("unroll") for (int n = 0; n < 2; ++n) _Pragma("unroll") for (int k = 0; k < 2; ++k) dst[n][k] = *(const PG8_LAS bf16x8*)(lds + PG8_SB(b, h) + boff + n * 2048 + k * 1024); } while (0)
; #define PG8_SCHED __builtin_amdgcn_sched_barrier(0)
; template <class Epi, class Sched, bool ALIGN_EPI = false, bool SP2 = false>
; __device__ __forceinline__ void gemm_phase(PG8_LAS unsigned char* lds, const Gemm g, const Sched& S, const Epi& E) {
;     ...
;             PG8_LDB(B0, 1, 0); PG8_LDB(B1, 1, 1); PG8_SCHED; PG8_LDA(At, 1, 0); PG8_STAGE(PG8_SA(0, 1), a2 + hstep, voffA);
	ds_read_b128 v[176:179], v215 offset:32768
	ds_read_b128 v[180:183], v215 offset:33792
	ds_read_b128 v[184:187], v215 offset:34816
	ds_read_b128 v[188:191], v215 offset:35840
	ds_read_b128 v[192:195], v215 offset:36864
	ds_read_b128 v[196:199], v215 offset:37888
	ds_read_b128 v[200:203], v215 offset:38912
	ds_read_b128 v[204:207], v215 offset:39936
	global_load_lds_dwordx4 v160, s[62:63]

; #define PG8_MMA(ai, bj, At, Bt) do { __builtin_amdgcn_s_setprio(1); _Pragma("unroll") for (int m = 0; m < 4; ++m) _Pragma("unroll") for (int n = 0; n < 2; ++n) _Pragma("unroll") for (int k = 0; k < 2; ++k) \
;         acc[ai][bj][m][n] = __builtin_amdgcn_mfma_f32_16x16x32_bf16(Bt[n][k], At[m][k], acc[ai][bj][m][n], 0, 0, 0); __builtin_amdgcn_s_setprio(0); } while (0)
; #define PG8_WAIT_V(n) asm volatile("s_waitcnt vmcnt(" #n ")" ::: "memory")
; #define PG8_WAIT_L(n) asm volatile("s_waitcnt lgkmcnt(" #n ")" ::: "memory")
; #define PG8_BAR __builtin_amdgcn_s_barrier()
; #define PG8_SCHED __builtin_amdgcn_sched_barrier(0)
; template <class Epi, class Sched, bool ALIGN_EPI = false, bool SP2 = false>
; __device__ __forceinline__ void gemm_phase(PG8_LAS unsigned char* lds, const Gemm g, const Sched& S, const Epi& E) {
;     ...
;             PG8_WAIT_V(8); PG8_WAIT_L(0); PG8_BAR; PG8_MMA(0, 0, At, B0); PG8_MMA(0, 1, At, B1); PG8_BAR; PG8_SCHED;
	s_mov_b32 m0, s68
	s_nop 0
	global_load_lds_dwordx4 v164, s[62:63]
	s_waitcnt vmcnt(8)
	s_waitcnt lgkmcnt(0)
	s_setprio 1
	s_barrier

; #define PG8_MMA(ai, bj, At, Bt) do { __builtin_amdgcn_s_setprio(1); _Pragma("unroll") for (int m = 0; m < 4; ++m) _Pragma("unroll") for (int n = 0; n < 2; ++n) _Pragma("unroll") for (int k = 0; k < 2; ++k) \
;         acc[ai][bj][m][n] = __builtin_amdgcn_mfma_f32_16x16x32_bf16(Bt[n][k], At[m][k], acc[ai][bj][m][n], 0, 0, 0); __builtin_amdgcn_s_setprio(0); } while (0)
; #define PG8_WAIT_V(n) asm volatile("s_waitcnt vmcnt(" #n ")" ::: "memory")
; #define PG8_WAIT_L(n) asm volatile("s_waitcnt lgkmcnt(" #n ")" ::: "memory")
; #define PG8_BAR __builtin_amdgcn_s_barrier()
; #define PG8_SCHED __builtin_amdgcn_sched_barrier(0)
; template <class Epi, class Sched, bool ALIGN_EPI = false, bool SP2 = false>
; __device__ __forceinline__ void gemm_phase(PG8_LAS unsigned char* lds, const Gemm g, const Sched& S, const Epi& E) {
;     ...
;             PG8_WAIT_V(8); PG8_WAIT_L(0); PG8_BAR; PG8_MMA(0, 0, At, B0); PG8_MMA(0, 1, At, B1); PG8_BAR; PG8_SCHED;
	v_mfma_f32_16x16x32_bf16 v[140:143], v[64:67], v[176:179], v[140:143]
	v_mfma_f32_16x16x32_bf16 v[136:139], v[72:75], v[176:179], v[136:139]
	v_mfma_f32_16x16x32_bf16 v[124:127], v[64:67], v[184:187], v[124:127]
	v_mfma_f32_16x16x32_bf16 v[120:123], v[72:75], v[184:187], v[120:123]
	v_mfma_f32_16x16x32_bf16 v[108:111], v[64:67], v[192:195], v[108:111]
	v_mfma_f32_16x16x32_bf16 v[104:107], v[72:75], v[192:195], v[104:107]
	v_mfma_f32_16x16x32_bf16 v[92:95], v[64:67], v[200:203], v[92:95]
	v_mfma_f32_16x16x32_bf16 v[88:91], v[72:75], v[200:203], v[88:91]
	v_mfma_f32_16x16x32_bf16 v[140:143], v[68:71], v[180:183], v[140:143]
	v_mfma_f32_16x16x32_bf16 v[136:139], v[76:79], v[180:183], v[136:139]
	v_mfma_f32_16x16x32_bf16 v[124:127], v[68:71], v[188:191], v[124:127]
	v_mfma_f32_16x16x32_bf16 v[120:123], v[76:79], v[188:191], v[120:123]
	v_mfma_f32_16x16x32_bf16 v[108:111], v[68:71], v[196:199], v[108:111]
	v_mfma_f32_16x16x32_bf16 v[104:107], v[76:79], v[196:199], v[104:107]
	v_mfma_f32_16x16x32_bf16 v[92:95], v[68:71], v[204:207], v[92:95]
	v_mfma_f32_16x16x32_bf16 v[88:91], v[76:79], v[204:207], v[88:91]


; #define PG8_STAGE(bufoff, gbase, voff) do { _Pragma("unroll") for (int _i = 0; _i < 2; ++_i) \
;         __builtin_amdgcn_global_load_lds((const unsigned*)((const char*)(gbase) + (voff)[_i]), (PG8_LAS unsigned*)(lds + (bufoff) + ldsw + _i * 8192), 16, 0, 0); } while (0)
; #define PG8_LDA(dst, b, h) do { _Pragma("unroll") for (int m = 0; m < 4; ++m) _Pragma("unroll") for (int k = 0; k < 2; ++k) dst[m][k] = *(const PG8_LAS bf16x8*)(lds + PG8_SA(b, h) + aoff + m * 2048 + k * 1024); } while (0)
; #define PG8_MMA(ai, bj, At, Bt) do { __builtin_amdgcn_s_setprio(1); _Pragma("unroll") for (int m = 0; m < 4; ++m) _Pragma("unroll") for (int n = 0; n < 2; ++n) _Pragma("unroll") for (int k = 0; k < 2; ++k) \
;         acc[ai][bj][m][n] = __builtin_amdgcn_mfma_f32_16x16x32_bf16(Bt[n][k], At[m][k], acc[ai][bj][m][n], 0, 0, 0); __builtin_amdgcn_s_setprio(0); } while (0)
; #define PG8_WAIT_V(n) asm volatile("s_waitcnt vmcnt(" #n ")" ::: "memory")
; #define PG8_WAIT_L(n) asm volatile("s_waitcnt lgkmcnt(" #n ")" ::: "memory")
; #define PG8_BAR __builtin_amdgcn_s_barrier()
; #define PG8_SCHED __builtin_amdgcn_sched_barrier(0)
; template <class Epi, class Sched, bool ALIGN_EPI = false, bool SP2 = false>
; __device__ __forceinline__ void gemm_phase(PG8_LAS unsigned char* lds, const Gemm g, const Sched& S, const Epi& E) {
;     ...
;             PG8_WAIT_V(8); PG8_WAIT_L(0); PG8_BAR; PG8_MMA(0, 0, At, B0); PG8_MMA(0, 1, At, B1); PG8_BAR; PG8_SCHED;
;             PG8_LDA(At, 1, 1); PG8_STAGE(PG8_SB(1, 0), b3, voffB); PG8_STAGE(PG8_SB(1, 1), b3 + hstep, voffB); PG8_STAGE(PG8_SA(1, 0), a3, voffA);
	v_mfma_f32_16x16x32_bf16 v[132:135], v[144:147], v[176:179], v[132:135]
	v_mfma_f32_16x16x32_bf16 v[128:131], v[152:155], v[176:179], v[128:131]
	v_mfma_f32_16x16x32_bf16 v[116:119], v[144:147], v[184:187], v[116:119]
	v_mfma_f32_16x16x32_bf16 v[112:115], v[152:155], v[184:187], v[112:115]
	v_mfma_f32_16x16x32_bf16 v[100:103], v[144:147], v[192:195], v[100:103]
	v_mfma_f32_16x16x32_bf16 v[96:99], v[152:155], v[192:195], v[96:99]
	v_mfma_f32_16x16x32_bf16 v[84:87], v[144:147], v[200:203], v[84:87]
	v_mfma_f32_16x16x32_bf16 v[80:83], v[152:155], v[200:203], v[80:83]
	v_mfma_f32_16x16x32_bf16 v[132:135], v[148:151], v[180:183], v[132:135]
	v_mfma_f32_16x16x32_bf16 v[128:131], v[156:159], v[180:183], v[128:131]
	v_mfma_f32_16x16x32_bf16 v[116:119], v[148:151], v[188:191], v[116:119]
	v_mfma_f32_16x16x32_bf16 v[112:115], v[156:159], v[188:191], v[112:115]
	v_mfma_f32_16x16x32_bf16 v[100:103], v[148:151], v[196:199], v[100:103]
	v_mfma_f32_16x16x32_bf16 v[96:99], v[156:159], v[196:199], v[96:99]
	v_mfma_f32_16x16x32_bf16 v[84:87], v[148:151], v[204:207], v[84:87]
	v_mfma_f32_16x16x32_bf16 v[80:83], v[156:159], v[204:207], v[80:83]
	s_setprio 0
	s_barrier
	s_add_i32 s62, s82, s64

; #define PG8_STAGE(bufoff, gbase, voff) do { _Pragma("unroll") for (int _i = 0; _i < 2; ++_i) \
;         __builtin_amdgcn_global_load_lds((const unsigned*)((const char*)(gbase) + (voff)[_i]), (PG8_LAS unsigned*)(lds + (bufoff) + ldsw + _i * 8192), 16, 0, 0); } while (0)
; #define PG8_LDA(dst, b, h) do { _Pragma("unroll") for (int m = 0; m < 4; ++m) _Pragma("unroll") for (int k = 0; k < 2; ++k) dst[m][k] = *(const PG8_LAS bf16x8*)(lds + PG8_SA(b, h) + aoff + m * 2048 + k * 1024); } while (0)
; template <class Epi, class Sched, bool ALIGN_EPI = false, bool SP2 = false>
; __device__ __forceinline__ void gemm_phase(PG8_LAS unsigned char* lds, const Gemm g, const Sched& S, const Epi& E) {
;     ...
;             PG8_LDA(At, 1, 1); PG8_STAGE(PG8_SB(1, 0), b3, voffB); PG8_STAGE(PG8_SB(1, 1), b3 + hstep, voffB); PG8_STAGE(PG8_SA(1, 0), a3, voffA);
	s_mov_b32 m0, s62
	ds_read_b128 v[176:179], v215 offset:49152
	ds_read_b128 v[180:183], v215 offset:50176
	ds_read_b128 v[184:187], v215 offset:51200
	ds_read_b128 v[188:191], v215 offset:52224
	ds_read_b128 v[192:195], v215 offset:53248
	ds_read_b128 v[196:199], v215 offset:54272
	ds_read_b128 v[200:203], v215 offset:55296
	ds_read_b128 v[204:207], v215 offset:56320
	global_load_lds_dwordx4 v250, s[96:97]
	s_add_i32 m0, s62, 0x2000
	s_add_u32 s60, s60, 0x80080

; #define PG8_STAGE(bufoff, gbase, voff) do { _Pragma("unroll") for (int _i = 0; _i < 2; ++_i) \
;         __builtin_amdgcn_global_load_lds((const unsigned*)((const char*)(gbase) + (voff)[_i]), (PG8_LAS unsigned*)(lds + (bufoff) + ldsw + _i * 8192), 16, 0, 0); } while (0)
; #define PG8_LDA(dst, b, h) do { _Pragma("unroll") for (int m = 0; m < 4; ++m) _Pragma("unroll") for (int k = 0; k < 2; ++k) dst[m][k] = *(const PG8_LAS bf16x8*)(lds + PG8_SA(b, h) + aoff + m * 2048 + k * 1024); } while (0)
; template <class Epi, class Sched, bool ALIGN_EPI = false, bool SP2 = false>
; __device__ __forceinline__ void gemm_phase(PG8_LAS unsigned char* lds, const Gemm g, const Sched& S, const Epi& E) {
;     ...
;             PG8_LDA(At, 1, 1); PG8_STAGE(PG8_SB(1, 0), b3, voffB); PG8_STAGE(PG8_SB(1, 1), b3 + hstep, voffB); PG8_STAGE(PG8_SA(1, 0), a3, voffA);
	s_addc_u32 s61, s61, 0
	s_add_i32 s62, s83, s64
	global_load_lds_dwordx4 v251, s[96:97]

; #define PG8_STAGE(bufoff, gbase, voff) do { _Pragma("unroll") for (int _i = 0; _i < 2; ++_i) \
;         __builtin_amdgcn_global_load_lds((const unsigned*)((const char*)(gbase) + (voff)[_i]), (PG8_LAS unsigned*)(lds + (bufoff) + ldsw + _i * 8192), 16, 0, 0); } while (0)
; #define PG8_LDA(dst, b, h) do { _Pragma("unroll") for (int m = 0; m < 4; ++m) _Pragma("unroll") for (int k = 0; k < 2; ++k) dst[m][k] = *(const PG8_LAS bf16x8*)(lds + PG8_SA(b, h) + aoff + m * 2048 + k * 1024); } while (0)
; template <class Epi, class Sched, bool ALIGN_EPI = false, bool SP2 = false>
; __device__ __forceinline__ void gemm_phase(PG8_LAS unsigned char* lds, const Gemm g, const Sched& S, const Epi& E) {
;     ...
;             PG8_LDA(At, 1, 1); PG8_STAGE(PG8_SB(1, 0), b3, voffB); PG8_STAGE(PG8_SB(1, 1), b3 + hstep, voffB); PG8_STAGE(PG8_SA(1, 0), a3, voffA);
	s_mov_b32 m0, s62
	s_nop 0
	global_load_lds_dwordx4 v162, s[60:61]

; #define PG8_STAGE(bufoff, gbase, voff) do { _Pragma("unroll") for (int _i = 0; _i < 2; ++_i) \
;         __builtin_amdgcn_global_load_lds((const unsigned*)((const char*)(gbase) + (voff)[_i]), (PG8_LAS unsigned*)(lds + (bufoff) + ldsw + _i * 8192), 16, 0, 0); } while (0)
; #define PG8_LDA(dst, b, h) do { _Pragma("unroll") for (int m = 0; m < 4; ++m) _Pragma("unroll") for (int k = 0; k < 2; ++k) dst[m][k] = *(const PG8_LAS bf16x8*)(lds + PG8_SA(b, h) + aoff + m * 2048 + k * 1024); } while (0)
; template <class Epi, class Sched, bool ALIGN_EPI = false, bool SP2 = false>
; __device__ __forceinline__ void gemm_phase(PG8_LAS unsigned char* lds, const Gemm g, const Sched& S, const Epi& E) {
;     ...
;             PG8_LDA(At, 1, 1); PG8_STAGE(PG8_SB(1, 0), b3, voffB); PG8_STAGE(PG8_SB(1, 1), b3 + hstep, voffB); PG8_STAGE(PG8_SA(1, 0), a3, voffA);
	s_add_i32 m0, s62, 0x2000
	s_nop 0
	global_load_lds_dwordx4 v166, s[60:61]

; #define PG8_STAGE(bufoff, gbase, voff) do { _Pragma("unroll") for (int _i = 0; _i < 2; ++_i) \
;         __builtin_amdgcn_global_load_lds((const unsigned*)((const char*)(gbase) + (voff)[_i]), (PG8_LAS unsigned*)(lds + (bufoff) + ldsw + _i * 8192), 16, 0, 0); } while (0)
; #define PG8_LDA(dst, b, h) do { _Pragma("unroll") for (int m = 0; m < 4; ++m) _Pragma("unroll") for (int k = 0; k < 2; ++k) dst[m][k] = *(const PG8_LAS bf16x8*)(lds + PG8_SA(b, h) + aoff + m * 2048 + k * 1024); } while (0)
; template <class Epi, class Sched, bool ALIGN_EPI = false, bool SP2 = false>
; __device__ __forceinline__ void gemm_phase(PG8_LAS unsigned char* lds, const Gemm g, const Sched& S, const Epi& E) {
;     ...
;             PG8_LDA(At, 1, 1); PG8_STAGE(PG8_SB(1, 0), b3, voffB); PG8_STAGE(PG8_SB(1, 1), b3 + hstep, voffB); PG8_STAGE(PG8_SA(1, 0), a3, voffA);
	s_mov_b32 m0, s70
	s_nop 0
	global_load_lds_dwordx4 v252, s[98:99]

; #define PG8_MMA(ai, bj, At, Bt) do { __builtin_amdgcn_s_setprio(1); _Pragma("unroll") for (int m = 0; m < 4; ++m) _Pragma("unroll") for (int n = 0; n < 2; ++n) _Pragma("unroll") for (int k = 0; k < 2; ++k) \
;         acc[ai][bj][m][n] = __builtin_amdgcn_mfma_f32_16x16x32_bf16(Bt[n][k], At[m][k], acc[ai][bj][m][n], 0, 0, 0); __builtin_amdgcn_s_setprio(0); } while (0)
; #define PG8_WAIT_V(n) asm volatile("s_waitcnt vmcnt(" #n ")" ::: "memory")
; #define PG8_WAIT_L(n) asm volatile("s_waitcnt lgkmcnt(" #n ")" ::: "memory")
; #define PG8_BAR __builtin_amdgcn_s_barrier()
; #define PG8_SCHED __builtin_amdgcn_sched_barrier(0)
; template <class Epi, class Sched, bool ALIGN_EPI = false, bool SP2 = false>
; __device__ __forceinline__ void gemm_phase(PG8_LAS unsigned char* lds, const Gemm g, const Sched& S, const Epi& E) {
;     ...
;             PG8_WAIT_V(8); PG8_WAIT_L(0); PG8_BAR; PG8_MMA(1, 0, At, B0); PG8_MMA(1, 1, At, B1); PG8_BAR; PG8_SCHED;
	s_mov_b32 m0, s71
	s_nop 0
	global_load_lds_dwordx4 v253, s[98:99]
	s_waitcnt vmcnt(8)
	s_waitcnt lgkmcnt(0)
	s_setprio 1
	s_barrier

; #define PG8_MMA(ai, bj, At, Bt) do { __builtin_amdgcn_s_setprio(1); _Pragma("unroll") for (int m = 0; m < 4; ++m) _Pragma("unroll") for (int n = 0; n < 2; ++n) _Pragma("unroll") for (int k = 0; k < 2; ++k) \
;         acc[ai][bj][m][n] = __builtin_amdgcn_mfma_f32_16x16x32_bf16(Bt[n][k], At[m][k], acc[ai][bj][m][n], 0, 0, 0); __builtin_amdgcn_s_setprio(0); } while (0)
; #define PG8_WAIT_V(n) asm volatile("s_waitcnt vmcnt(" #n ")" ::: "memory")
; #define PG8_WAIT_L(n) asm volatile("s_waitcnt lgkmcnt(" #n ")" ::: "memory")
; #define PG8_BAR __builtin_amdgcn_s_barrier()
; #define PG8_SCHED __builtin_amdgcn_sched_barrier(0)
; template <class Epi, class Sched, bool ALIGN_EPI = false, bool SP2 = false>
; __device__ __forceinline__ void gemm_phase(PG8_LAS unsigned char* lds, const Gemm g, const Sched& S, const Epi& E) {
;     ...
;             PG8_WAIT_V(8); PG8_WAIT_L(0); PG8_BAR; PG8_MMA(1, 0, At, B0); PG8_MMA(1, 1, At, B1); PG8_BAR; PG8_SCHED;
	v_mfma_f32_16x16x32_bf16 v[60:63], v[64:67], v[176:179], v[60:63]
	v_mfma_f32_16x16x32_bf16 v[56:59], v[72:75], v[176:179], v[56:59]
	v_mfma_f32_16x16x32_bf16 v[44:47], v[64:67], v[184:187], v[44:47]
	v_mfma_f32_16x16x32_bf16 v[40:43], v[72:75], v[184:187], v[40:43]
	v_mfma_f32_16x16x32_bf16 v[28:31], v[64:67], v[192:195], v[28:31]
	v_mfma_f32_16x16x32_bf16 v[24:27], v[72:75], v[192:195], v[24:27]
	v_mfma_f32_16x16x32_bf16 v[12:15], v[64:67], v[200:203], v[12:15]
	v_mfma_f32_16x16x32_bf16 v[8:11], v[72:75], v[200:203], v[8:11]
	v_mfma_f32_16x16x32_bf16 v[60:63], v[68:71], v[180:183], v[60:63]
	v_mfma_f32_16x16x32_bf16 v[56:59], v[76:79], v[180:183], v[56:59]
	v_mfma_f32_16x16x32_bf16 v[44:47], v[68:71], v[188:191], v[44:47]
	v_mfma_f32_16x16x32_bf16 v[40:43], v[76:79], v[188:191], v[40:43]
	v_mfma_f32_16x16x32_bf16 v[28:31], v[68:71], v[196:199], v[28:31]
	v_mfma_f32_16x16x32_bf16 v[24:27], v[76:79], v[196:199], v[24:27]
	v_mfma_f32_16x16x32_bf16 v[12:15], v[68:71], v[204:207], v[12:15]
	v_mfma_f32_16x16x32_bf16 v[8:11], v[76:79], v[204:207], v[8:11]


; #define PG8_WAIT_V(n) asm volatile("s_waitcnt vmcnt(" #n ")" ::: "memory")
; template <class Epi, class Sched, bool ALIGN_EPI = false, bool SP2 = false>
; __device__ __forceinline__ void gemm_phase(PG8_LAS unsigned char* lds, const Gemm g, const Sched& S, const Epi& E) {
;     ...
;         for (int t = 0; t < nt; t += 2) {
;             const bool last = (t == nt - 2);
;             const char* a1 = cA + (size_t)(t + 1) * kstep;
;             const char* a2 = last ? nA : cA + (size_t)(t + 2) * kstep; const char* b2 = last ? nB : cB + (size_t)(t + 2) * kstep;
;             const char* a3 = a2 + kstep; const char* b3 = b2 + kstep;
;             if (last && has_next) S.a_ready(nxt);
;             if constexpr (SP2) {
;             PG8_LDB(B0, 0, 0); PG8_LDB(B1, 0, 1); PG8_SCHED; PG8_LDA(At, 0, 0); PG8_STAGE(PG8_SA(1, 1), a1 + hstep, voffA);
;             PG8_WAIT_V(8); PG8_WAIT_L(0); PG8_BAR; PG8_MMA(0, 0, At, B0); PG8_MMA(0, 1, At, B1); PG8_BAR; PG8_SCHED;
;             PG8_LDA(At, 0, 1); PG8_STAGE(PG8_SB(0, 0), b2, voffB); PG8_STAGE(PG8_SB(0, 1), b2 + hstep, voffB); PG8_STAGE(PG8_SA(0, 0), a2, voffA);
;             PG8_WAIT_V(8); PG8_WAIT_L(0); PG8_BAR; PG8_MMA(1, 0, At, B0); PG8_MMA(1, 1, At, B1); PG8_BAR; PG8_SCHED;
;             PG8_LDB(B0, 1, 0); PG8_LDB(B1, 1, 1); PG8_SCHED; PG8_LDA(At, 1, 0); PG8_STAGE(PG8_SA(0, 1), a2 + hstep, voffA);
;             PG8_WAIT_V(8); PG8_WAIT_L(0); PG8_BAR; PG8_MMA(0, 0, At, B0); PG8_MMA(0, 1, At, B1); PG8_BAR; PG8_SCHED;
;             PG8_LDA(At, 1, 1); PG8_STAGE(PG8_SB(1, 0), b3, voffB); PG8_STAGE(PG8_SB(1, 1), b3 + hstep, voffB); PG8_STAGE(PG8_SA(1, 0), a3, voffA);
;             PG8_WAIT_V(8); PG8_WAIT_L(0); PG8_BAR; PG8_MMA(1, 0, At, B0); PG8_MMA(1, 1, At, B1); PG8_BAR; PG8_SCHED;
;             } else {
;             PG8_LDB(B0, 0, 0); PG8_SCHED; PG8_LDA(At, 0, 0); PG8_STAGE(PG8_SA(1, 1), a1 + hstep, voffA);
;             PG8_WAIT_L(8); PG8_BAR; PG8_WAIT_L(0); PG8_MMA(0, 0, At, B0); PG8_BAR; PG8_SCHED;
;             PG8_LDB(B1, 0, 1); PG8_STAGE(PG8_SB(0, 0), b2, voffB);
;             PG8_BAR; PG8_WAIT_L(0); PG8_MMA(0, 1, At, B1); PG8_BAR;
;             PG8_LDA(At, 0, 1); PG8_STAGE(PG8_SA(0, 0), a2, voffA);
;             PG8_BAR; PG8_WAIT_L(0); PG8_MMA(1, 0, At, B0); PG8_BAR; PG8_SCHED;
;             PG8_STAGE(PG8_SB(0, 1), b2 + hstep, voffB);
;             PG8_WAIT_V(6); PG8_BAR; PG8_MMA(1, 1, At, B1); PG8_BAR;
	v_mfma_f32_16x16x32_bf16 v[52:55], v[144:147], v[176:179], v[52:55]
	v_mfma_f32_16x16x32_bf16 v[48:51], v[152:155], v[176:179], v[48:51]
	v_mfma_f32_16x16x32_bf16 v[36:39], v[144:147], v[184:187], v[36:39]
	v_mfma_f32_16x16x32_bf16 v[32:35], v[152:155], v[184:187], v[32:35]
	v_mfma_f32_16x16x32_bf16 v[20:23], v[144:147], v[192:195], v[20:23]
	v_mfma_f32_16x16x32_bf16 v[16:19], v[152:155], v[192:195], v[16:19]
	v_mfma_f32_16x16x32_bf16 v[4:7], v[144:147], v[200:203], v[4:7]
	v_mfma_f32_16x16x32_bf16 v[0:3], v[152:155], v[200:203], v[0:3]
	v_mfma_f32_16x16x32_bf16 v[52:55], v[148:151], v[180:183], v[52:55]
	v_mfma_f32_16x16x32_bf16 v[48:51], v[156:159], v[180:183], v[48:51]
	v_mfma_f32_16x16x32_bf16 v[36:39], v[148:151], v[188:191], v[36:39]
	v_mfma_f32_16x16x32_bf16 v[32:35], v[156:159], v[188:191], v[32:35]
	v_mfma_f32_16x16x32_bf16 v[20:23], v[148:151], v[196:199], v[20:23]
	v_mfma_f32_16x16x32_bf16 v[16:19], v[156:159], v[196:199], v[16:19]
	v_mfma_f32_16x16x32_bf16 v[4:7], v[148:151], v[204:207], v[4:7]
	v_mfma_f32_16x16x32_bf16 v[0:3], v[156:159], v[204:207], v[0:3]
	s_setprio 0
	s_barrier
	s_add_i32 s81, s81, 2
	s_add_u32 s58, s58, 0x100
	s_addc_u32 s59, s59, 0
	s_add_u32 s79, s79, 0x100
	s_addc_u32 s80, s80, 0
	s_cmp_gt_u32 s81, 29
	s_cbranch_scc0 .LBB0_939
	s_and_b64 vcc, exec, s[42:43]
	s_cbranch_vccz .LBB0_942
	s_barrier

; #define PG8_STAGE(bufoff, gbase, voff) do { _Pragma("unroll") for (int _i = 0; _i < 2; ++_i) \
;         __builtin_amdgcn_global_load_lds((const unsigned*)((const char*)(gbase) + (voff)[_i]), (PG8_LAS unsigned*)(lds + (bufoff) + ldsw + _i * 8192), 16, 0, 0); } while (0)
; #define PG8_LDA(dst, b, h) do { _Pragma("unroll") for (int m = 0; m < 4; ++m) _Pragma("unroll") for (int k = 0; k < 2; ++k) dst[m][k] = *(const PG8_LAS bf16x8*)(lds + PG8_SA(b, h) + aoff + m * 2048 + k * 1024); } while (0)
; #define PG8_LDB(dst, b, h) do { _Pragma("unroll") for (int n = 0; n < 2; ++n) _Pragma("unroll") for (int k = 0; k < 2; ++k) dst[n][k] = *(const PG8_LAS bf16x8*)(lds + PG8_SB(b, h) + boff + n * 2048 + k * 1024); } while (0)
; #define PG8_SCHED __builtin_amdgcn_sched_barrier(0)
; template <class Epi, class Sched, bool ALIGN_EPI = false, bool SP2 = false>
; __device__ __forceinline__ void gemm_phase(PG8_LAS unsigned char* lds, const Gemm g, const Sched& S, const Epi& E) {
;     ...
;         for (int t = 0; t < nt; t += 2) {
;             const bool last = (t == nt - 2);
;             const char* a1 = cA + (size_t)(t + 1) * kstep;
;             const char* a2 = last ? nA : cA + (size_t)(t + 2) * kstep; const char* b2 = last ? nB : cB + (size_t)(t + 2) * kstep;
;             const char* a3 = a2 + kstep; const char* b3 = b2 + kstep;
;             if (last && has_next) S.a_ready(nxt);
;             if constexpr (SP2) {
;             PG8_LDB(B0, 0, 0); PG8_LDB(B1, 0, 1); PG8_SCHED; PG8_LDA(At, 0, 0); PG8_STAGE(PG8_SA(1, 1), a1 + hstep, voffA);
.LBB0_1034:
	ds_read_b128 v[128:131], v201
	ds_read_b128 v[132:135], v201 offset:1024
	ds_read_b128 v[136:139], v201 offset:2048
	ds_read_b128 v[140:143], v201 offset:3072
	ds_read_b128 v[144:147], v205
	ds_read_b128 v[148:151], v205 offset:1024
	ds_read_b128 v[152:155], v205 offset:2048
	ds_read_b128 v[156:159], v205 offset:3072
	s_add_u32 s12, s10, 0xfff80080
	s_addc_u32 s13, s11, -1
	s_cmp_eq_u32 s83, 28
	s_cselect_b32 s59, s53, s13
	s_cselect_b32 s58, s79, s12
	s_cselect_b32 s13, s51, s82
	s_cselect_b32 s12, s80, s81

; #define PG8_STAGE(bufoff, gbase, voff) do { _Pragma("unroll") for (int _i = 0; _i < 2; ++_i) \
;         __builtin_amdgcn_global_load_lds((const unsigned*)((const char*)(gbase) + (voff)[_i]), (PG8_LAS unsigned*)(lds + (bufoff) + ldsw + _i * 8192), 16, 0, 0); } while (0)
; #define PG8_LDA(dst, b, h) do { _Pragma("unroll") for (int m = 0; m < 4; ++m) _Pragma("unroll") for (int k = 0; k < 2; ++k) dst[m][k] = *(const PG8_LAS bf16x8*)(lds + PG8_SA(b, h) + aoff + m * 2048 + k * 1024); } while (0)
; #define PG8_LDB(dst, b, h) do { _Pragma("unroll") for (int n = 0; n < 2; ++n) _Pragma("unroll") for (int k = 0; k < 2; ++k) dst[n][k] = *(const PG8_LAS bf16x8*)(lds + PG8_SB(b, h) + boff + n * 2048 + k * 1024); } while (0)
; #define PG8_SCHED __builtin_amdgcn_sched_barrier(0)
; template <class Epi, class Sched, bool ALIGN_EPI = false, bool SP2 = false>
; __device__ __forceinline__ void gemm_phase(PG8_LAS unsigned char* lds, const Gemm g, const Sched& S, const Epi& E) {
;     ...
;             PG8_LDB(B0, 0, 0); PG8_LDB(B1, 0, 1); PG8_SCHED; PG8_LDA(At, 0, 0); PG8_STAGE(PG8_SA(1, 1), a1 + hstep, voffA);
	s_add_i32 m0, s63, 0xc000
	ds_read_b128 v[176:179], v207
	ds_read_b128 v[184:187], v207 offset:1024
	ds_read_b128 v[190:193], v207 offset:2048
	ds_read_b128 v[210:213], v207 offset:3072
	ds_read_b128 v[214:217], v207 offset:4096
	ds_read_b128 v[218:221], v207 offset:5120
	ds_read_b128 v[222:225], v207 offset:6144
	ds_read_b128 v[226:229], v207 offset:7168
	global_load_lds_dwordx4 v168, s[10:11]

; #define PG8_MMA(ai, bj, At, Bt) do { __builtin_amdgcn_s_setprio(1); _Pragma("unroll") for (int m = 0; m < 4; ++m) _Pragma("unroll") for (int n = 0; n < 2; ++n) _Pragma("unroll") for (int k = 0; k < 2; ++k) \
;         acc[ai][bj][m][n] = __builtin_amdgcn_mfma_f32_16x16x32_bf16(Bt[n][k], At[m][k], acc[ai][bj][m][n], 0, 0, 0); __builtin_amdgcn_s_setprio(0); } while (0)
; #define PG8_WAIT_V(n) asm volatile("s_waitcnt vmcnt(" #n ")" ::: "memory")
; #define PG8_WAIT_L(n) asm volatile("s_waitcnt lgkmcnt(" #n ")" ::: "memory")
; #define PG8_BAR __builtin_amdgcn_s_barrier()
; #define PG8_SCHED __builtin_amdgcn_sched_barrier(0)
; template <class Epi, class Sched, bool ALIGN_EPI = false, bool SP2 = false>
; __device__ __forceinline__ void gemm_phase(PG8_LAS unsigned char* lds, const Gemm g, const Sched& S, const Epi& E) {
;     ...
;             PG8_WAIT_V(8); PG8_WAIT_L(0); PG8_BAR; PG8_MMA(0, 0, At, B0); PG8_MMA(0, 1, At, B1); PG8_BAR; PG8_SCHED;
	s_add_i32 m0, s63, 0xe000
	s_nop 0
	global_load_lds_dwordx4 v170, s[10:11]
	s_waitcnt vmcnt(8)
	s_waitcnt lgkmcnt(0)
	s_setprio 1
	s_barrier

; #define PG8_MMA(ai, bj, At, Bt) do { __builtin_amdgcn_s_setprio(1); _Pragma("unroll") for (int m = 0; m < 4; ++m) _Pragma("unroll") for (int n = 0; n < 2; ++n) _Pragma("unroll") for (int k = 0; k < 2; ++k) \
;         acc[ai][bj][m][n] = __builtin_amdgcn_mfma_f32_16x16x32_bf16(Bt[n][k], At[m][k], acc[ai][bj][m][n], 0, 0, 0); __builtin_amdgcn_s_setprio(0); } while (0)
; #define PG8_WAIT_V(n) asm volatile("s_waitcnt vmcnt(" #n ")" ::: "memory")
; #define PG8_WAIT_L(n) asm volatile("s_waitcnt lgkmcnt(" #n ")" ::: "memory")
; #define PG8_BAR __builtin_amdgcn_s_barrier()
; #define PG8_SCHED __builtin_amdgcn_sched_barrier(0)
; template <class Epi, class Sched, bool ALIGN_EPI = false, bool SP2 = false>
; __device__ __forceinline__ void gemm_phase(PG8_LAS unsigned char* lds, const Gemm g, const Sched& S, const Epi& E) {
;     ...
;             PG8_WAIT_V(8); PG8_WAIT_L(0); PG8_BAR; PG8_MMA(0, 0, At, B0); PG8_MMA(0, 1, At, B1); PG8_BAR; PG8_SCHED;
	v_mfma_f32_16x16x32_bf16 v[124:127], v[128:131], v[176:179], v[124:127]
	v_mfma_f32_16x16x32_bf16 v[120:123], v[136:139], v[176:179], v[120:123]
	v_mfma_f32_16x16x32_bf16 v[108:111], v[128:131], v[190:193], v[108:111]
	v_mfma_f32_16x16x32_bf16 v[104:107], v[136:139], v[190:193], v[104:107]
	v_mfma_f32_16x16x32_bf16 v[92:95], v[128:131], v[214:217], v[92:95]
	v_mfma_f32_16x16x32_bf16 v[88:91], v[136:139], v[214:217], v[88:91]
	v_mfma_f32_16x16x32_bf16 v[76:79], v[128:131], v[222:225], v[76:79]
	v_mfma_f32_16x16x32_bf16 v[72:75], v[136:139], v[222:225], v[72:75]
	v_mfma_f32_16x16x32_bf16 v[124:127], v[132:135], v[184:187], v[124:127]
	v_mfma_f32_16x16x32_bf16 v[120:123], v[140:143], v[184:187], v[120:123]
	v_mfma_f32_16x16x32_bf16 v[108:111], v[132:135], v[210:213], v[108:111]
	v_mfma_f32_16x16x32_bf16 v[104:107], v[140:143], v[210:213], v[104:107]
	v_mfma_f32_16x16x32_bf16 v[92:95], v[132:135], v[218:221], v[92:95]
	v_mfma_f32_16x16x32_bf16 v[88:91], v[140:143], v[218:221], v[88:91]
	v_mfma_f32_16x16x32_bf16 v[76:79], v[132:135], v[226:229], v[76:79]
	v_mfma_f32_16x16x32_bf16 v[72:75], v[140:143], v[226:229], v[72:75]


; #define PG8_STAGE(bufoff, gbase, voff) do { _Pragma("unroll") for (int _i = 0; _i < 2; ++_i) \
;         __builtin_amdgcn_global_load_lds((const unsigned*)((const char*)(gbase) + (voff)[_i]), (PG8_LAS unsigned*)(lds + (bufoff) + ldsw + _i * 8192), 16, 0, 0); } while (0)
; #define PG8_LDA(dst, b, h) do { _Pragma("unroll") for (int m = 0; m < 4; ++m) _Pragma("unroll") for (int k = 0; k < 2; ++k) dst[m][k] = *(const PG8_LAS bf16x8*)(lds + PG8_SA(b, h) + aoff + m * 2048 + k * 1024); } while (0)
; #define PG8_MMA(ai, bj, At, Bt) do { __builtin_amdgcn_s_setprio(1); _Pragma("unroll") for (int m = 0; m < 4; ++m) _Pragma("unroll") for (int n = 0; n < 2; ++n) _Pragma("unroll") for (int k = 0; k < 2; ++k) \
;         acc[ai][bj][m][n] = __builtin_amdgcn_mfma_f32_16x16x32_bf16(Bt[n][k], At[m][k], acc[ai][bj][m][n], 0, 0, 0); __builtin_amdgcn_s_setprio(0); } while (0)
; #define PG8_WAIT_V(n) asm volatile("s_waitcnt vmcnt(" #n ")" ::: "memory")
; #define PG8_WAIT_L(n) asm volatile("s_waitcnt lgkmcnt(" #n ")" ::: "memory")
; #define PG8_BAR __builtin_amdgcn_s_barrier()
; #define PG8_SCHED __builtin_amdgcn_sched_barrier(0)
; template <class Epi, class Sched, bool ALIGN_EPI = false, bool SP2 = false>
; __device__ __forceinline__ void gemm_phase(PG8_LAS unsigned char* lds, const Gemm g, const Sched& S, const Epi& E) {
;     ...
;             PG8_WAIT_V(8); PG8_WAIT_L(0); PG8_BAR; PG8_MMA(0, 0, At, B0); PG8_MMA(0, 1, At, B1); PG8_BAR; PG8_SCHED;
;             PG8_LDA(At, 0, 1); PG8_STAGE(PG8_SB(0, 0), b2, voffB); PG8_STAGE(PG8_SB(0, 1), b2 + hstep, voffB); PG8_STAGE(PG8_SA(0, 0), a2, voffA);
	v_mfma_f32_16x16x32_bf16 v[116:119], v[144:147], v[176:179], v[116:119]
	v_mfma_f32_16x16x32_bf16 v[112:115], v[152:155], v[176:179], v[112:115]
	v_mfma_f32_16x16x32_bf16 v[100:103], v[144:147], v[190:193], v[100:103]
	v_mfma_f32_16x16x32_bf16 v[96:99], v[152:155], v[190:193], v[96:99]
	v_mfma_f32_16x16x32_bf16 v[84:87], v[144:147], v[214:217], v[84:87]
	v_mfma_f32_16x16x32_bf16 v[80:83], v[152:155], v[214:217], v[80:83]
	v_mfma_f32_16x16x32_bf16 v[68:71], v[144:147], v[222:225], v[68:71]
	v_mfma_f32_16x16x32_bf16 v[64:67], v[152:155], v[222:225], v[64:67]
	v_mfma_f32_16x16x32_bf16 v[116:119], v[148:151], v[184:187], v[116:119]
	v_mfma_f32_16x16x32_bf16 v[112:115], v[156:159], v[184:187], v[112:115]
	v_mfma_f32_16x16x32_bf16 v[100:103], v[148:151], v[210:213], v[100:103]
	v_mfma_f32_16x16x32_bf16 v[96:99], v[156:159], v[210:213], v[96:99]
	v_mfma_f32_16x16x32_bf16 v[84:87], v[148:151], v[218:221], v[84:87]
	v_mfma_f32_16x16x32_bf16 v[80:83], v[156:159], v[218:221], v[80:83]
	v_mfma_f32_16x16x32_bf16 v[68:71], v[148:151], v[226:229], v[68:71]
	v_mfma_f32_16x16x32_bf16 v[64:67], v[156:159], v[226:229], v[64:67]
	s_setprio 0
	s_barrier
	s_add_i32 s84, s73, s62
	s_mov_b64 s[96:97], s[12:13]

; #define PG8_STAGE(bufoff, gbase, voff) do { _Pragma("unroll") for (int _i = 0; _i < 2; ++_i) \
;         __builtin_amdgcn_global_load_lds((const unsigned*)((const char*)(gbase) + (voff)[_i]), (PG8_LAS unsigned*)(lds + (bufoff) + ldsw + _i * 8192), 16, 0, 0); } while (0)
; #define PG8_LDA(dst, b, h) do { _Pragma("unroll") for (int m = 0; m < 4; ++m) _Pragma("unroll") for (int k = 0; k < 2; ++k) dst[m][k] = *(const PG8_LAS bf16x8*)(lds + PG8_SA(b, h) + aoff + m * 2048 + k * 1024); } while (0)
; template <class Epi, class Sched, bool ALIGN_EPI = false, bool SP2 = false>
; __device__ __forceinline__ void gemm_phase(PG8_LAS unsigned char* lds, const Gemm g, const Sched& S, const Epi& E) {
;     ...
;             PG8_LDA(At, 0, 1); PG8_STAGE(PG8_SB(0, 0), b2, voffB); PG8_STAGE(PG8_SB(0, 1), b2 + hstep, voffB); PG8_STAGE(PG8_SA(0, 0), a2, voffA);
	s_mov_b32 m0, s84
	ds_read_b128 v[176:179], v207 offset:16384
	ds_read_b128 v[184:187], v207 offset:17408
	ds_read_b128 v[190:193], v207 offset:18432
	ds_read_b128 v[210:213], v207 offset:19456
	ds_read_b128 v[214:217], v207 offset:20480
	ds_read_b128 v[218:221], v207 offset:21504
	ds_read_b128 v[222:225], v207 offset:22528
	ds_read_b128 v[226:229], v207 offset:23552
	global_load_lds_dwordx4 v162, s[12:13]
	s_add_i32 m0, s84, 0x2000
	s_add_u32 s84, s12, 0x80000

; #define PG8_STAGE(bufoff, gbase, voff) do { _Pragma("unroll") for (int _i = 0; _i < 2; ++_i) \
;         __builtin_amdgcn_global_load_lds((const unsigned*)((const char*)(gbase) + (voff)[_i]), (PG8_LAS unsigned*)(lds + (bufoff) + ldsw + _i * 8192), 16, 0, 0); } while (0)
; #define PG8_LDA(dst, b, h) do { _Pragma("unroll") for (int m = 0; m < 4; ++m) _Pragma("unroll") for (int k = 0; k < 2; ++k) dst[m][k] = *(const PG8_LAS bf16x8*)(lds + PG8_SA(b, h) + aoff + m * 2048 + k * 1024); } while (0)
; template <class Epi, class Sched, bool ALIGN_EPI = false, bool SP2 = false>
; __device__ __forceinline__ void gemm_phase(PG8_LAS unsigned char* lds, const Gemm g, const Sched& S, const Epi& E) {
;     ...
;             PG8_LDA(At, 0, 1); PG8_STAGE(PG8_SB(0, 0), b2, voffB); PG8_STAGE(PG8_SB(0, 1), b2 + hstep, voffB); PG8_STAGE(PG8_SA(0, 0), a2, voffA);
	s_addc_u32 s85, s13, 0
	s_add_i32 s86, s74, s62
	global_load_lds_dwordx4 v166, s[12:13]

; #define PG8_STAGE(bufoff, gbase, voff) do { _Pragma("unroll") for (int _i = 0; _i < 2; ++_i) \
;         __builtin_amdgcn_global_load_lds((const unsigned*)((const char*)(gbase) + (voff)[_i]), (PG8_LAS unsigned*)(lds + (bufoff) + ldsw + _i * 8192), 16, 0, 0); } while (0)
; #define PG8_LDA(dst, b, h) do { _Pragma("unroll") for (int m = 0; m < 4; ++m) _Pragma("unroll") for (int k = 0; k < 2; ++k) dst[m][k] = *(const PG8_LAS bf16x8*)(lds + PG8_SA(b, h) + aoff + m * 2048 + k * 1024); } while (0)
; template <class Epi, class Sched, bool ALIGN_EPI = false, bool SP2 = false>
; __device__ __forceinline__ void gemm_phase(PG8_LAS unsigned char* lds, const Gemm g, const Sched& S, const Epi& E) {
;     ...
;             PG8_LDA(At, 0, 1); PG8_STAGE(PG8_SB(0, 0), b2, voffB); PG8_STAGE(PG8_SB(0, 1), b2 + hstep, voffB); PG8_STAGE(PG8_SA(0, 0), a2, voffA);
	s_mov_b32 m0, s86
	s_nop 0
	global_load_lds_dwordx4 v162, s[84:85]

; #define PG8_STAGE(bufoff, gbase, voff) do { _Pragma("unroll") for (int _i = 0; _i < 2; ++_i) \
;         __builtin_amdgcn_global_load_lds((const unsigned*)((const char*)(gbase) + (voff)[_i]), (PG8_LAS unsigned*)(lds + (bufoff) + ldsw + _i * 8192), 16, 0, 0); } while (0)
; #define PG8_LDA(dst, b, h) do { _Pragma("unroll") for (int m = 0; m < 4; ++m) _Pragma("unroll") for (int k = 0; k < 2; ++k) dst[m][k] = *(const PG8_LAS bf16x8*)(lds + PG8_SA(b, h) + aoff + m * 2048 + k * 1024); } while (0)
; template <class Epi, class Sched, bool ALIGN_EPI = false, bool SP2 = false>
; __device__ __forceinline__ void gemm_phase(PG8_LAS unsigned char* lds, const Gemm g, const Sched& S, const Epi& E) {
;     ...
;             PG8_LDA(At, 0, 1); PG8_STAGE(PG8_SB(0, 0), b2, voffB); PG8_STAGE(PG8_SB(0, 1), b2 + hstep, voffB); PG8_STAGE(PG8_SA(0, 0), a2, voffA);
	s_add_i32 m0, s86, 0x2000
	s_nop 0
	global_load_lds_dwordx4 v166, s[84:85]
	s_mov_b64 s[98:99], s[58:59]

; #define PG8_MMA(ai, bj, At, Bt) do { __builtin_amdgcn_s_setprio(1); _Pragma("unroll") for (int m = 0; m < 4; ++m) _Pragma("unroll") for (int n = 0; n < 2; ++n) _Pragma("unroll") for (int k = 0; k < 2; ++k) \
;         acc[ai][bj][m][n] = __builtin_amdgcn_mfma_f32_16x16x32_bf16(Bt[n][k], At[m][k], acc[ai][bj][m][n], 0, 0, 0); __builtin_amdgcn_s_setprio(0); } while (0)
; #define PG8_WAIT_V(n) asm volatile("s_waitcnt vmcnt(" #n ")" ::: "memory")
; #define PG8_WAIT_L(n) asm volatile("s_waitcnt lgkmcnt(" #n ")" ::: "memory")
; #define PG8_BAR __builtin_amdgcn_s_barrier()
; #define PG8_SCHED __builtin_amdgcn_sched_barrier(0)
; template <class Epi, class Sched, bool ALIGN_EPI = false, bool SP2 = false>
; __device__ __forceinline__ void gemm_phase(PG8_LAS unsigned char* lds, const Gemm g, const Sched& S, const Epi& E) {
;     ...
;             PG8_WAIT_V(8); PG8_WAIT_L(0); PG8_BAR; PG8_MMA(1, 0, At, B0); PG8_MMA(1, 1, At, B1); PG8_BAR; PG8_SCHED;
	s_mov_b32 m0, s63
	s_nop 0
	global_load_lds_dwordx4 v160, s[58:59]
	s_mov_b32 m0, s64
	s_nop 0
	global_load_lds_dwordx4 v164, s[58:59]
	s_waitcnt vmcnt(8)
	s_waitcnt lgkmcnt(0)
	s_setprio 1
	s_barrier

; #define PG8_MMA(ai, bj, At, Bt) do { __builtin_amdgcn_s_setprio(1); _Pragma("unroll") for (int m = 0; m < 4; ++m) _Pragma("unroll") for (int n = 0; n < 2; ++n) _Pragma("unroll") for (int k = 0; k < 2; ++k) \
;         acc[ai][bj][m][n] = __builtin_amdgcn_mfma_f32_16x16x32_bf16(Bt[n][k], At[m][k], acc[ai][bj][m][n], 0, 0, 0); __builtin_amdgcn_s_setprio(0); } while (0)
; #define PG8_WAIT_V(n) asm volatile("s_waitcnt vmcnt(" #n ")" ::: "memory")
; #define PG8_WAIT_L(n) asm volatile("s_waitcnt lgkmcnt(" #n ")" ::: "memory")
; #define PG8_BAR __builtin_amdgcn_s_barrier()
; #define PG8_SCHED __builtin_amdgcn_sched_barrier(0)
; template <class Epi, class Sched, bool ALIGN_EPI = false, bool SP2 = false>
; __device__ __forceinline__ void gemm_phase(PG8_LAS unsigned char* lds, const Gemm g, const Sched& S, const Epi& E) {
;     ...
;             PG8_WAIT_V(8); PG8_WAIT_L(0); PG8_BAR; PG8_MMA(1, 0, At, B0); PG8_MMA(1, 1, At, B1); PG8_BAR; PG8_SCHED;
	v_mfma_f32_16x16x32_bf16 v[60:63], v[128:131], v[176:179], v[60:63]
	v_mfma_f32_16x16x32_bf16 v[56:59], v[136:139], v[176:179], v[56:59]
	v_mfma_f32_16x16x32_bf16 v[44:47], v[128:131], v[190:193], v[44:47]
	v_mfma_f32_16x16x32_bf16 v[40:43], v[136:139], v[190:193], v[40:43]
	v_mfma_f32_16x16x32_bf16 v[28:31], v[128:131], v[214:217], v[28:31]
	v_mfma_f32_16x16x32_bf16 v[24:27], v[136:139], v[214:217], v[24:27]
	v_mfma_f32_16x16x32_bf16 v[12:15], v[128:131], v[222:225], v[12:15]
	v_mfma_f32_16x16x32_bf16 v[8:11], v[136:139], v[222:225], v[8:11]
	v_mfma_f32_16x16x32_bf16 v[60:63], v[132:135], v[184:187], v[60:63]
	v_mfma_f32_16x16x32_bf16 v[56:59], v[140:143], v[184:187], v[56:59]
	v_mfma_f32_16x16x32_bf16 v[44:47], v[132:135], v[210:213], v[44:47]
	v_mfma_f32_16x16x32_bf16 v[40:43], v[140:143], v[210:213], v[40:43]
	v_mfma_f32_16x16x32_bf16 v[28:31], v[132:135], v[218:221], v[28:31]
	v_mfma_f32_16x16x32_bf16 v[24:27], v[140:143], v[218:221], v[24:27]
	v_mfma_f32_16x16x32_bf16 v[12:15], v[132:135], v[226:229], v[12:15]
	v_mfma_f32_16x16x32_bf16 v[8:11], v[140:143], v[226:229], v[8:11]


; #define PG8_STAGE(bufoff, gbase, voff) do { _Pragma("unroll") for (int _i = 0; _i < 2; ++_i) \
;         __builtin_amdgcn_global_load_lds((const unsigned*)((const char*)(gbase) + (voff)[_i]), (PG8_LAS unsigned*)(lds + (bufoff) + ldsw + _i * 8192), 16, 0, 0); } while (0)
; #define PG8_LDA(dst, b, h) do { _Pragma("unroll") for (int m = 0; m < 4; ++m) _Pragma("unroll") for (int k = 0; k < 2; ++k) dst[m][k] = *(const PG8_LAS bf16x8*)(lds + PG8_SA(b, h) + aoff + m * 2048 + k * 1024); } while (0)
; #define PG8_LDB(dst, b, h) do { _Pragma("unroll") for (int n = 0; n < 2; ++n) _Pragma("unroll") for (int k = 0; k < 2; ++k) dst[n][k] = *(const PG8_LAS bf16x8*)(lds + PG8_SB(b, h) + boff + n * 2048 + k * 1024); } while (0)
; #define PG8_MMA(ai, bj, At, Bt) do { __builtin_amdgcn_s_setprio(1); _Pragma("unroll") for (int m = 0; m < 4; ++m) _Pragma("unroll") for (int n = 0; n < 2; ++n) _Pragma("unroll") for (int k = 0; k < 2; ++k) \
;         acc[ai][bj][m][n] = __builtin_amdgcn_mfma_f32_16x16x32_bf16(Bt[n][k], At[m][k], acc[ai][bj][m][n], 0, 0, 0); __builtin_amdgcn_s_setprio(0); } while (0)
; #define PG8_WAIT_V(n) asm volatile("s_waitcnt vmcnt(" #n ")" ::: "memory")
; #define PG8_WAIT_L(n) asm volatile("s_waitcnt lgkmcnt(" #n ")" ::: "memory")
; #define PG8_BAR __builtin_amdgcn_s_barrier()
; #define PG8_SCHED __builtin_amdgcn_sched_barrier(0)
; template <class Epi, class Sched, bool ALIGN_EPI = false, bool SP2 = false>
; __device__ __forceinline__ void gemm_phase(PG8_LAS unsigned char* lds, const Gemm g, const Sched& S, const Epi& E) {
;     ...
;             PG8_WAIT_V(8); PG8_WAIT_L(0); PG8_BAR; PG8_MMA(1, 0, At, B0); PG8_MMA(1, 1, At, B1); PG8_BAR; PG8_SCHED;
;             PG8_LDB(B0, 1, 0); PG8_LDB(B1, 1, 1); PG8_SCHED; PG8_LDA(At, 1, 0); PG8_STAGE(PG8_SA(0, 1), a2 + hstep, voffA);
	v_mfma_f32_16x16x32_bf16 v[52:55], v[144:147], v[176:179], v[52:55]
	v_mfma_f32_16x16x32_bf16 v[48:51], v[152:155], v[176:179], v[48:51]
	v_mfma_f32_16x16x32_bf16 v[36:39], v[144:147], v[190:193], v[36:39]
	v_mfma_f32_16x16x32_bf16 v[32:35], v[152:155], v[190:193], v[32:35]
	v_mfma_f32_16x16x32_bf16 v[20:23], v[144:147], v[214:217], v[20:23]
	v_mfma_f32_16x16x32_bf16 v[16:19], v[152:155], v[214:217], v[16:19]
	v_mfma_f32_16x16x32_bf16 v[4:7], v[144:147], v[222:225], v[4:7]
	v_mfma_f32_16x16x32_bf16 v[0:3], v[152:155], v[222:225], v[0:3]
	v_mfma_f32_16x16x32_bf16 v[52:55], v[148:151], v[184:187], v[52:55]
	v_mfma_f32_16x16x32_bf16 v[48:51], v[156:159], v[184:187], v[48:51]
	v_mfma_f32_16x16x32_bf16 v[36:39], v[148:151], v[210:213], v[36:39]
	v_mfma_f32_16x16x32_bf16 v[32:35], v[156:159], v[210:213], v[32:35]
	v_mfma_f32_16x16x32_bf16 v[20:23], v[148:151], v[218:221], v[20:23]
	v_mfma_f32_16x16x32_bf16 v[16:19], v[156:159], v[218:221], v[16:19]
	v_mfma_f32_16x16x32_bf16 v[4:7], v[148:151], v[226:229], v[4:7]
	v_mfma_f32_16x16x32_bf16 v[0:3], v[156:159], v[226:229], v[0:3]
	s_setprio 0
	s_barrier
	s_add_i32 s84, 0, 0x18000
	s_add_i32 s85, 0, 0x1c000


; #define PG8_STAGE(bufoff, gbase, voff) do { _Pragma("unroll") for (int _i = 0; _i < 2; ++_i) \
;         __builtin_amdgcn_global_load_lds((const unsigned*)((const char*)(gbase) + (voff)[_i]), (PG8_LAS unsigned*)(lds + (bufoff) + ldsw + _i * 8192), 16, 0, 0); } while (0)
; #define PG8_LDA(dst, b, h) do { _Pragma("unroll") for (int m = 0; m < 4; ++m) _Pragma("unroll") for (int k = 0; k < 2; ++k) dst[m][k] = *(const PG8_LAS bf16x8*)(lds + PG8_SA(b, h) + aoff + m * 2048 + k * 1024); } while (0)
; #define PG8_LDB(dst, b, h) do { _Pragma("unroll") for (int n = 0; n < 2; ++n) _Pragma("unroll") for (int k = 0; k < 2; ++k) dst[n][k] = *(const PG8_LAS bf16x8*)(lds + PG8_SB(b, h) + boff + n * 2048 + k * 1024); } while (0)
; #define PG8_SCHED __builtin_amdgcn_sched_barrier(0)
; template <class Epi, class Sched, bool ALIGN_EPI = false, bool SP2 = false>
; __device__ __forceinline__ void gemm_phase(PG8_LAS unsigned char* lds, const Gemm g, const Sched& S, const Epi& E) {
;     ...
;             PG8_LDB(B0, 1, 0); PG8_LDB(B1, 1, 1); PG8_SCHED; PG8_LDA(At, 1, 0); PG8_STAGE(PG8_SA(0, 1), a2 + hstep, voffA);
	ds_read_b128 v[128:131], v254
	ds_read_b128 v[132:135], v254 offset:1024
	ds_read_b128 v[136:139], v254 offset:2048
	ds_read_b128 v[140:143], v254 offset:3072
	ds_read_b128 v[144:147], v255
	ds_read_b128 v[148:151], v255 offset:1024
	ds_read_b128 v[152:155], v255 offset:2048
	ds_read_b128 v[156:159], v255 offset:3072
	s_add_u32 s58, s58, 0x80000
	s_addc_u32 s59, s59, 0
	s_mov_b32 m0, s65

; #define PG8_STAGE(bufoff, gbase, voff) do { _Pragma("unroll") for (int _i = 0; _i < 2; ++_i) \
;         __builtin_amdgcn_global_load_lds((const unsigned*)((const char*)(gbase) + (voff)[_i]), (PG8_LAS unsigned*)(lds + (bufoff) + ldsw + _i * 8192), 16, 0, 0); } while (0)
; #define PG8_LDA(dst, b, h) do { _Pragma("unroll") for (int m = 0; m < 4; ++m) _Pragma("unroll") for (int k = 0; k < 2; ++k) dst[m][k] = *(const PG8_LAS bf16x8*)(lds + PG8_SA(b, h) + aoff + m * 2048 + k * 1024); } while (0)
; #define PG8_LDB(dst, b, h) do { _Pragma("unroll") for (int n = 0; n < 2; ++n) _Pragma("unroll") for (int k = 0; k < 2; ++k) dst[n][k] = *(const PG8_LAS bf16x8*)(lds + PG8_SB(b, h) + boff + n * 2048 + k * 1024); } while (0)
; #define PG8_SCHED __builtin_amdgcn_sched_barrier(0)
; template <class Epi, class Sched, bool ALIGN_EPI = false, bool SP2 = false>
; __device__ __forceinline__ void gemm_phase(PG8_LAS unsigned char* lds, const Gemm g, const Sched& S, const Epi& E) {
;     ...
;             PG8_LDB(B0, 1, 0); PG8_LDB(B1, 1, 1); PG8_SCHED; PG8_LDA(At, 1, 0); PG8_STAGE(PG8_SA(0, 1), a2 + hstep, voffA);
	ds_read_b128 v[176:179], v207 offset:32768
	ds_read_b128 v[184:187], v207 offset:33792
	ds_read_b128 v[190:193], v207 offset:34816
	ds_read_b128 v[210:213], v207 offset:35840
	ds_read_b128 v[214:217], v207 offset:36864
	ds_read_b128 v[218:221], v207 offset:37888
	ds_read_b128 v[222:225], v207 offset:38912
	ds_read_b128 v[226:229], v207 offset:39936
	global_load_lds_dwordx4 v160, s[58:59]

; #define PG8_MMA(ai, bj, At, Bt) do { __builtin_amdgcn_s_setprio(1); _Pragma("unroll") for (int m = 0; m < 4; ++m) _Pragma("unroll") for (int n = 0; n < 2; ++n) _Pragma("unroll") for (int k = 0; k < 2; ++k) \
;         acc[ai][bj][m][n] = __builtin_amdgcn_mfma_f32_16x16x32_bf16(Bt[n][k], At[m][k], acc[ai][bj][m][n], 0, 0, 0); __builtin_amdgcn_s_setprio(0); } while (0)
; #define PG8_WAIT_V(n) asm volatile("s_waitcnt vmcnt(" #n ")" ::: "memory")
; #define PG8_WAIT_L(n) asm volatile("s_waitcnt lgkmcnt(" #n ")" ::: "memory")
; #define PG8_BAR __builtin_amdgcn_s_barrier()
; #define PG8_SCHED __builtin_amdgcn_sched_barrier(0)
; template <class Epi, class Sched, bool ALIGN_EPI = false, bool SP2 = false>
; __device__ __forceinline__ void gemm_phase(PG8_LAS unsigned char* lds, const Gemm g, const Sched& S, const Epi& E) {
;     ...
;             PG8_WAIT_V(8); PG8_WAIT_L(0); PG8_BAR; PG8_MMA(0, 0, At, B0); PG8_MMA(0, 1, At, B1); PG8_BAR; PG8_SCHED;
	s_mov_b32 m0, s67
	s_nop 0
	global_load_lds_dwordx4 v164, s[58:59]
	s_waitcnt vmcnt(8)
	s_waitcnt lgkmcnt(0)
	s_setprio 1
	s_barrier

; #define PG8_MMA(ai, bj, At, Bt) do { __builtin_amdgcn_s_setprio(1); _Pragma("unroll") for (int m = 0; m < 4; ++m) _Pragma("unroll") for (int n = 0; n < 2; ++n) _Pragma("unroll") for (int k = 0; k < 2; ++k) \
;         acc[ai][bj][m][n] = __builtin_amdgcn_mfma_f32_16x16x32_bf16(Bt[n][k], At[m][k], acc[ai][bj][m][n], 0, 0, 0); __builtin_amdgcn_s_setprio(0); } while (0)
; #define PG8_WAIT_V(n) asm volatile("s_waitcnt vmcnt(" #n ")" ::: "memory")
; #define PG8_WAIT_L(n) asm volatile("s_waitcnt lgkmcnt(" #n ")" ::: "memory")
; #define PG8_BAR __builtin_amdgcn_s_barrier()
; #define PG8_SCHED __builtin_amdgcn_sched_barrier(0)
; template <class Epi, class Sched, bool ALIGN_EPI = false, bool SP2 = false>
; __device__ __forceinline__ void gemm_phase(PG8_LAS unsigned char* lds, const Gemm g, const Sched& S, const Epi& E) {
;     ...
;             PG8_WAIT_V(8); PG8_WAIT_L(0); PG8_BAR; PG8_MMA(0, 0, At, B0); PG8_MMA(0, 1, At, B1); PG8_BAR; PG8_SCHED;
	v_mfma_f32_16x16x32_bf16 v[124:127], v[128:131], v[176:179], v[124:127]
	v_mfma_f32_16x16x32_bf16 v[120:123], v[136:139], v[176:179], v[120:123]
	v_mfma_f32_16x16x32_bf16 v[108:111], v[128:131], v[190:193], v[108:111]
	v_mfma_f32_16x16x32_bf16 v[104:107], v[136:139], v[190:193], v[104:107]
	v_mfma_f32_16x16x32_bf16 v[92:95], v[128:131], v[214:217], v[92:95]
	v_mfma_f32_16x16x32_bf16 v[88:91], v[136:139], v[214:217], v[88:91]
	v_mfma_f32_16x16x32_bf16 v[76:79], v[128:131], v[222:225], v[76:79]
	v_mfma_f32_16x16x32_bf16 v[72:75], v[136:139], v[222:225], v[72:75]
	v_mfma_f32_16x16x32_bf16 v[124:127], v[132:135], v[184:187], v[124:127]
	v_mfma_f32_16x16x32_bf16 v[120:123], v[140:143], v[184:187], v[120:123]
	v_mfma_f32_16x16x32_bf16 v[108:111], v[132:135], v[210:213], v[108:111]
	v_mfma_f32_16x16x32_bf16 v[104:107], v[140:143], v[210:213], v[104:107]
	v_mfma_f32_16x16x32_bf16 v[92:95], v[132:135], v[218:221], v[92:95]
	v_mfma_f32_16x16x32_bf16 v[88:91], v[140:143], v[218:221], v[88:91]
	v_mfma_f32_16x16x32_bf16 v[76:79], v[132:135], v[226:229], v[76:79]
	v_mfma_f32_16x16x32_bf16 v[72:75], v[140:143], v[226:229], v[72:75]


; #define PG8_STAGE(bufoff, gbase, voff) do { _Pragma("unroll") for (int _i = 0; _i < 2; ++_i) \
;         __builtin_amdgcn_global_load_lds((const unsigned*)((const char*)(gbase) + (voff)[_i]), (PG8_LAS unsigned*)(lds + (bufoff) + ldsw + _i * 8192), 16, 0, 0); } while (0)
; #define PG8_LDA(dst, b, h) do { _Pragma("unroll") for (int m = 0; m < 4; ++m) _Pragma("unroll") for (int k = 0; k < 2; ++k) dst[m][k] = *(const PG8_LAS bf16x8*)(lds + PG8_SA(b, h) + aoff + m * 2048 + k * 1024); } while (0)
; #define PG8_MMA(ai, bj, At, Bt) do { __builtin_amdgcn_s_setprio(1); _Pragma("unroll") for (int m = 0; m < 4; ++m) _Pragma("unroll") for (int n = 0; n < 2; ++n) _Pragma("unroll") for (int k = 0; k < 2; ++k) \
;         acc[ai][bj][m][n] = __builtin_amdgcn_mfma_f32_16x16x32_bf16(Bt[n][k], At[m][k], acc[ai][bj][m][n], 0, 0, 0); __builtin_amdgcn_s_setprio(0); } while (0)
; #define PG8_WAIT_V(n) asm volatile("s_waitcnt vmcnt(" #n ")" ::: "memory")
; #define PG8_WAIT_L(n) asm volatile("s_waitcnt lgkmcnt(" #n ")" ::: "memory")
; #define PG8_BAR __builtin_amdgcn_s_barrier()
; #define PG8_SCHED __builtin_amdgcn_sched_barrier(0)
; template <class Epi, class Sched, bool ALIGN_EPI = false, bool SP2 = false>
; __device__ __forceinline__ void gemm_phase(PG8_LAS unsigned char* lds, const Gemm g, const Sched& S, const Epi& E) {
;     ...
;             PG8_WAIT_V(8); PG8_WAIT_L(0); PG8_BAR; PG8_MMA(0, 0, At, B0); PG8_MMA(0, 1, At, B1); PG8_BAR; PG8_SCHED;
;             PG8_LDA(At, 1, 1); PG8_STAGE(PG8_SB(1, 0), b3, voffB); PG8_STAGE(PG8_SB(1, 1), b3 + hstep, voffB); PG8_STAGE(PG8_SA(1, 0), a3, voffA);
	v_mfma_f32_16x16x32_bf16 v[116:119], v[144:147], v[176:179], v[116:119]
	v_mfma_f32_16x16x32_bf16 v[112:115], v[152:155], v[176:179], v[112:115]
	v_mfma_f32_16x16x32_bf16 v[100:103], v[144:147], v[190:193], v[100:103]
	v_mfma_f32_16x16x32_bf16 v[96:99], v[152:155], v[190:193], v[96:99]
	v_mfma_f32_16x16x32_bf16 v[84:87], v[144:147], v[214:217], v[84:87]
	v_mfma_f32_16x16x32_bf16 v[80:83], v[152:155], v[214:217], v[80:83]
	v_mfma_f32_16x16x32_bf16 v[68:71], v[144:147], v[222:225], v[68:71]
	v_mfma_f32_16x16x32_bf16 v[64:67], v[152:155], v[222:225], v[64:67]
	v_mfma_f32_16x16x32_bf16 v[116:119], v[148:151], v[184:187], v[116:119]
	v_mfma_f32_16x16x32_bf16 v[112:115], v[156:159], v[184:187], v[112:115]
	v_mfma_f32_16x16x32_bf16 v[100:103], v[148:151], v[210:213], v[100:103]
	v_mfma_f32_16x16x32_bf16 v[96:99], v[156:159], v[210:213], v[96:99]
	v_mfma_f32_16x16x32_bf16 v[84:87], v[148:151], v[218:221], v[84:87]
	v_mfma_f32_16x16x32_bf16 v[80:83], v[156:159], v[218:221], v[80:83]
	v_mfma_f32_16x16x32_bf16 v[68:71], v[148:151], v[226:229], v[68:71]
	v_mfma_f32_16x16x32_bf16 v[64:67], v[156:159], v[226:229], v[64:67]
	s_setprio 0
	s_barrier
	s_add_i32 s58, s84, s62

; #define PG8_STAGE(bufoff, gbase, voff) do { _Pragma("unroll") for (int _i = 0; _i < 2; ++_i) \
;         __builtin_amdgcn_global_load_lds((const unsigned*)((const char*)(gbase) + (voff)[_i]), (PG8_LAS unsigned*)(lds + (bufoff) + ldsw + _i * 8192), 16, 0, 0); } while (0)
; #define PG8_LDA(dst, b, h) do { _Pragma("unroll") for (int m = 0; m < 4; ++m) _Pragma("unroll") for (int k = 0; k < 2; ++k) dst[m][k] = *(const PG8_LAS bf16x8*)(lds + PG8_SA(b, h) + aoff + m * 2048 + k * 1024); } while (0)
; template <class Epi, class Sched, bool ALIGN_EPI = false, bool SP2 = false>
; __device__ __forceinline__ void gemm_phase(PG8_LAS unsigned char* lds, const Gemm g, const Sched& S, const Epi& E) {
;     ...
;             PG8_LDA(At, 1, 1); PG8_STAGE(PG8_SB(1, 0), b3, voffB); PG8_STAGE(PG8_SB(1, 1), b3 + hstep, voffB); PG8_STAGE(PG8_SA(1, 0), a3, voffA);
	s_mov_b32 m0, s58
	ds_read_b128 v[176:179], v207 offset:49152
	ds_read_b128 v[184:187], v207 offset:50176
	ds_read_b128 v[190:193], v207 offset:51200
	ds_read_b128 v[210:213], v207 offset:52224
	ds_read_b128 v[214:217], v207 offset:53248
	ds_read_b128 v[218:221], v207 offset:54272
	ds_read_b128 v[222:225], v207 offset:55296
	ds_read_b128 v[226:229], v207 offset:56320
	global_load_lds_dwordx4 v250, s[96:97]
	s_add_i32 m0, s58, 0x2000
	s_add_u32 s12, s12, 0x80080

; #define PG8_STAGE(bufoff, gbase, voff) do { _Pragma("unroll") for (int _i = 0; _i < 2; ++_i) \
;         __builtin_amdgcn_global_load_lds((const unsigned*)((const char*)(gbase) + (voff)[_i]), (PG8_LAS unsigned*)(lds + (bufoff) + ldsw + _i * 8192), 16, 0, 0); } while (0)
; #define PG8_LDA(dst, b, h) do { _Pragma("unroll") for (int m = 0; m < 4; ++m) _Pragma("unroll") for (int k = 0; k < 2; ++k) dst[m][k] = *(const PG8_LAS bf16x8*)(lds + PG8_SA(b, h) + aoff + m * 2048 + k * 1024); } while (0)
; template <class Epi, class Sched, bool ALIGN_EPI = false, bool SP2 = false>
; __device__ __forceinline__ void gemm_phase(PG8_LAS unsigned char* lds, const Gemm g, const Sched& S, const Epi& E) {
;     ...
;             PG8_LDA(At, 1, 1); PG8_STAGE(PG8_SB(1, 0), b3, voffB); PG8_STAGE(PG8_SB(1, 1), b3 + hstep, voffB); PG8_STAGE(PG8_SA(1, 0), a3, voffA);
	s_addc_u32 s13, s13, 0
	s_add_i32 s58, s85, s62
	global_load_lds_dwordx4 v251, s[96:97]

; #define PG8_STAGE(bufoff, gbase, voff) do { _Pragma("unroll") for (int _i = 0; _i < 2; ++_i) \
;         __builtin_amdgcn_global_load_lds((const unsigned*)((const char*)(gbase) + (voff)[_i]), (PG8_LAS unsigned*)(lds + (bufoff) + ldsw + _i * 8192), 16, 0, 0); } while (0)
; #define PG8_LDA(dst, b, h) do { _Pragma("unroll") for (int m = 0; m < 4; ++m) _Pragma("unroll") for (int k = 0; k < 2; ++k) dst[m][k] = *(const PG8_LAS bf16x8*)(lds + PG8_SA(b, h) + aoff + m * 2048 + k * 1024); } while (0)
; template <class Epi, class Sched, bool ALIGN_EPI = false, bool SP2 = false>
; __device__ __forceinline__ void gemm_phase(PG8_LAS unsigned char* lds, const Gemm g, const Sched& S, const Epi& E) {
;     ...
;             PG8_LDA(At, 1, 1); PG8_STAGE(PG8_SB(1, 0), b3, voffB); PG8_STAGE(PG8_SB(1, 1), b3 + hstep, voffB); PG8_STAGE(PG8_SA(1, 0), a3, voffA);
	s_mov_b32 m0, s58
	s_nop 0
	global_load_lds_dwordx4 v162, s[12:13]

; #define PG8_STAGE(bufoff, gbase, voff) do { _Pragma("unroll") for (int _i = 0; _i < 2; ++_i) \
;         __builtin_amdgcn_global_load_lds((const unsigned*)((const char*)(gbase) + (voff)[_i]), (PG8_LAS unsigned*)(lds + (bufoff) + ldsw + _i * 8192), 16, 0, 0); } while (0)
; #define PG8_LDA(dst, b, h) do { _Pragma("unroll") for (int m = 0; m < 4; ++m) _Pragma("unroll") for (int k = 0; k < 2; ++k) dst[m][k] = *(const PG8_LAS bf16x8*)(lds + PG8_SA(b, h) + aoff + m * 2048 + k * 1024); } while (0)
; template <class Epi, class Sched, bool ALIGN_EPI = false, bool SP2 = false>
; __device__ __forceinline__ void gemm_phase(PG8_LAS unsigned char* lds, const Gemm g, const Sched& S, const Epi& E) {
;     ...
;             PG8_LDA(At, 1, 1); PG8_STAGE(PG8_SB(1, 0), b3, voffB); PG8_STAGE(PG8_SB(1, 1), b3 + hstep, voffB); PG8_STAGE(PG8_SA(1, 0), a3, voffA);
	s_add_i32 m0, s58, 0x2000
	s_nop 0
	global_load_lds_dwordx4 v166, s[12:13]

; #define PG8_STAGE(bufoff, gbase, voff) do { _Pragma("unroll") for (int _i = 0; _i < 2; ++_i) \
;         __builtin_amdgcn_global_load_lds((const unsigned*)((const char*)(gbase) + (voff)[_i]), (PG8_LAS unsigned*)(lds + (bufoff) + ldsw + _i * 8192), 16, 0, 0); } while (0)
; #define PG8_LDA(dst, b, h) do { _Pragma("unroll") for (int m = 0; m < 4; ++m) _Pragma("unroll") for (int k = 0; k < 2; ++k) dst[m][k] = *(const PG8_LAS bf16x8*)(lds + PG8_SA(b, h) + aoff + m * 2048 + k * 1024); } while (0)
; template <class Epi, class Sched, bool ALIGN_EPI = false, bool SP2 = false>
; __device__ __forceinline__ void gemm_phase(PG8_LAS unsigned char* lds, const Gemm g, const Sched& S, const Epi& E) {
;     ...
;             PG8_LDA(At, 1, 1); PG8_STAGE(PG8_SB(1, 0), b3, voffB); PG8_STAGE(PG8_SB(1, 1), b3 + hstep, voffB); PG8_STAGE(PG8_SA(1, 0), a3, voffA);
	s_mov_b32 m0, s69
	s_nop 0
	global_load_lds_dwordx4 v252, s[98:99]

; #define PG8_STAGE(bufoff, gbase, voff) do { _Pragma("unroll") for (int _i = 0; _i < 2; ++_i) \
;         __builtin_amdgcn_global_load_lds((const unsigned*)((const char*)(gbase) + (voff)[_i]), (PG8_LAS unsigned*)(lds + (bufoff) + ldsw + _i * 8192), 16, 0, 0); } while (0)
; #define PG8_LDA(dst, b, h) do { _Pragma("unroll") for (int m = 0; m < 4; ++m) _Pragma("unroll") for (int k = 0; k < 2; ++k) dst[m][k] = *(const PG8_LAS bf16x8*)(lds + PG8_SA(b, h) + aoff + m * 2048 + k * 1024); } while (0)
; #define PG8_MMA(ai, bj, At, Bt) do { __builtin_amdgcn_s_setprio(1); _Pragma("unroll") for (int m = 0; m < 4; ++m) _Pragma("unroll") for (int n = 0; n < 2; ++n) _Pragma("unroll") for (int k = 0; k < 2; ++k) \
;         acc[ai][bj][m][n] = __builtin_amdgcn_mfma_f32_16x16x32_bf16(Bt[n][k], At[m][k], acc[ai][bj][m][n], 0, 0, 0); __builtin_amdgcn_s_setprio(0); } while (0)
; #define PG8_WAIT_V(n) asm volatile("s_waitcnt vmcnt(" #n ")" ::: "memory")
; #define PG8_WAIT_L(n) asm volatile("s_waitcnt lgkmcnt(" #n ")" ::: "memory")
; #define PG8_BAR __builtin_amdgcn_s_barrier()
; #define PG8_SCHED __builtin_amdgcn_sched_barrier(0)
; template <class Epi, class Sched, bool ALIGN_EPI = false, bool SP2 = false>
; __device__ __forceinline__ void gemm_phase(PG8_LAS unsigned char* lds, const Gemm g, const Sched& S, const Epi& E) {
;     ...
;             PG8_LDA(At, 1, 1); PG8_STAGE(PG8_SB(1, 0), b3, voffB); PG8_STAGE(PG8_SB(1, 1), b3 + hstep, voffB); PG8_STAGE(PG8_SA(1, 0), a3, voffA);
;             PG8_WAIT_V(8); PG8_WAIT_L(0); PG8_BAR; PG8_MMA(1, 0, At, B0); PG8_MMA(1, 1, At, B1); PG8_BAR; PG8_SCHED;
	s_mov_b32 m0, s70
	s_nop 0
	global_load_lds_dwordx4 v253, s[98:99]
	s_waitcnt vmcnt(8)
	s_waitcnt lgkmcnt(0)
	s_setprio 1
	s_barrier

; #define PG8_MMA(ai, bj, At, Bt) do { __builtin_amdgcn_s_setprio(1); _Pragma("unroll") for (int m = 0; m < 4; ++m) _Pragma("unroll") for (int n = 0; n < 2; ++n) _Pragma("unroll") for (int k = 0; k < 2; ++k) \
;         acc[ai][bj][m][n] = __builtin_amdgcn_mfma_f32_16x16x32_bf16(Bt[n][k], At[m][k], acc[ai][bj][m][n], 0, 0, 0); __builtin_amdgcn_s_setprio(0); } while (0)
; #define PG8_WAIT_V(n) asm volatile("s_waitcnt vmcnt(" #n ")" ::: "memory")
; #define PG8_WAIT_L(n) asm volatile("s_waitcnt lgkmcnt(" #n ")" ::: "memory")
; #define PG8_BAR __builtin_amdgcn_s_barrier()
; #define PG8_SCHED __builtin_amdgcn_sched_barrier(0)
; template <class Epi, class Sched, bool ALIGN_EPI = false, bool SP2 = false>
; __device__ __forceinline__ void gemm_phase(PG8_LAS unsigned char* lds, const Gemm g, const Sched& S, const Epi& E) {
;     ...
;             PG8_WAIT_V(8); PG8_WAIT_L(0); PG8_BAR; PG8_MMA(1, 0, At, B0); PG8_MMA(1, 1, At, B1); PG8_BAR; PG8_SCHED;
	v_mfma_f32_16x16x32_bf16 v[60:63], v[128:131], v[176:179], v[60:63]
	v_mfma_f32_16x16x32_bf16 v[56:59], v[136:139], v[176:179], v[56:59]
	v_mfma_f32_16x16x32_bf16 v[44:47], v[128:131], v[190:193], v[44:47]
	v_mfma_f32_16x16x32_bf16 v[40:43], v[136:139], v[190:193], v[40:43]
	v_mfma_f32_16x16x32_bf16 v[28:31], v[128:131], v[214:217], v[28:31]
	v_mfma_f32_16x16x32_bf16 v[24:27], v[136:139], v[214:217], v[24:27]
	v_mfma_f32_16x16x32_bf16 v[12:15], v[128:131], v[222:225], v[12:15]
	v_mfma_f32_16x16x32_bf16 v[8:11], v[136:139], v[222:225], v[8:11]
	v_mfma_f32_16x16x32_bf16 v[60:63], v[132:135], v[184:187], v[60:63]
	v_mfma_f32_16x16x32_bf16 v[56:59], v[140:143], v[184:187], v[56:59]
	v_mfma_f32_16x16x32_bf16 v[44:47], v[132:135], v[210:213], v[44:47]
	v_mfma_f32_16x16x32_bf16 v[40:43], v[140:143], v[210:213], v[40:43]
	v_mfma_f32_16x16x32_bf16 v[28:31], v[132:135], v[218:221], v[28:31]
	v_mfma_f32_16x16x32_bf16 v[24:27], v[140:143], v[218:221], v[24:27]
	v_mfma_f32_16x16x32_bf16 v[12:15], v[132:135], v[226:229], v[12:15]
	v_mfma_f32_16x16x32_bf16 v[8:11], v[140:143], v[226:229], v[8:11]


; #define PG8_MMA(ai, bj, At, Bt) do { __builtin_amdgcn_s_setprio(1); _Pragma("unroll") for (int m = 0; m < 4; ++m) _Pragma("unroll") for (int n = 0; n < 2; ++n) _Pragma("unroll") for (int k = 0; k < 2; ++k) \
;         acc[ai][bj][m][n] = __builtin_amdgcn_mfma_f32_16x16x32_bf16(Bt[n][k], At[m][k], acc[ai][bj][m][n], 0, 0, 0); __builtin_amdgcn_s_setprio(0); } while (0)
; #define PG8_WAIT_V(n) asm volatile("s_waitcnt vmcnt(" #n ")" ::: "memory")
; #define PG8_WAIT_L(n) asm volatile("s_waitcnt lgkmcnt(" #n ")" ::: "memory")
; #define PG8_BAR __builtin_amdgcn_s_barrier()
; #define PG8_SCHED __builtin_amdgcn_sched_barrier(0)
; template <class Epi, class Sched, bool ALIGN_EPI = false, bool SP2 = false>
; __device__ __forceinline__ void gemm_phase(PG8_LAS unsigned char* lds, const Gemm g, const Sched& S, const Epi& E) {
;     ...
;             PG8_WAIT_V(8); PG8_WAIT_L(0); PG8_BAR; PG8_MMA(1, 0, At, B0); PG8_MMA(1, 1, At, B1); PG8_BAR; PG8_SCHED;
;     ...
;         if constexpr (ALIGN_EPI) { if (wr == 0) PG8_BAR; }
	v_mfma_f32_16x16x32_bf16 v[52:55], v[144:147], v[176:179], v[52:55]
	v_mfma_f32_16x16x32_bf16 v[48:51], v[152:155], v[176:179], v[48:51]
	v_mfma_f32_16x16x32_bf16 v[36:39], v[144:147], v[190:193], v[36:39]
	v_mfma_f32_16x16x32_bf16 v[32:35], v[152:155], v[190:193], v[32:35]
	v_mfma_f32_16x16x32_bf16 v[20:23], v[144:147], v[214:217], v[20:23]
	v_mfma_f32_16x16x32_bf16 v[16:19], v[152:155], v[214:217], v[16:19]
	v_mfma_f32_16x16x32_bf16 v[4:7], v[144:147], v[222:225], v[4:7]
	v_mfma_f32_16x16x32_bf16 v[0:3], v[152:155], v[222:225], v[0:3]
	v_mfma_f32_16x16x32_bf16 v[52:55], v[148:151], v[184:187], v[52:55]
	v_mfma_f32_16x16x32_bf16 v[48:51], v[156:159], v[184:187], v[48:51]
	v_mfma_f32_16x16x32_bf16 v[36:39], v[148:151], v[210:213], v[36:39]
	v_mfma_f32_16x16x32_bf16 v[32:35], v[156:159], v[210:213], v[32:35]
	v_mfma_f32_16x16x32_bf16 v[20:23], v[148:151], v[218:221], v[20:23]
	v_mfma_f32_16x16x32_bf16 v[16:19], v[156:159], v[218:221], v[16:19]
	v_mfma_f32_16x16x32_bf16 v[4:7], v[148:151], v[226:229], v[4:7]
	v_mfma_f32_16x16x32_bf16 v[0:3], v[156:159], v[226:229], v[0:3]
	s_setprio 0
	s_barrier
	s_add_i32 s83, s83, 2
	s_add_u32 s10, s10, 0x100
	s_addc_u32 s11, s11, 0
	s_add_u32 s81, s81, 0x100
	s_addc_u32 s82, s82, 0
	s_cmp_gt_u32 s83, 29
	s_cbranch_scc0 .LBB0_1034
	s_and_b64 vcc, exec, s[40:41]
	s_cbranch_vccz .LBB0_1037
	s_barrier

; #define PG8_STAGE(bufoff, gbase, voff) do { _Pragma("unroll") for (int _i = 0; _i < 2; ++_i) \
;         __builtin_amdgcn_global_load_lds((const unsigned*)((const char*)(gbase) + (voff)[_i]), (PG8_LAS unsigned*)(lds + (bufoff) + ldsw + _i * 8192), 16, 0, 0); } while (0)
; #define PG8_LDA(dst, b, h) do { _Pragma("unroll") for (int m = 0; m < 4; ++m) _Pragma("unroll") for (int k = 0; k < 2; ++k) dst[m][k] = *(const PG8_LAS bf16x8*)(lds + PG8_SA(b, h) + aoff + m * 2048 + k * 1024); } while (0)
; #define PG8_LDB(dst, b, h) do { _Pragma("unroll") for (int n = 0; n < 2; ++n) _Pragma("unroll") for (int k = 0; k < 2; ++k) dst[n][k] = *(const PG8_LAS bf16x8*)(lds + PG8_SB(b, h) + boff + n * 2048 + k * 1024); } while (0)
; #define PG8_SCHED __builtin_amdgcn_sched_barrier(0)
; template <class Epi, class Sched, bool ALIGN_EPI = false, bool SP2 = false>
; __device__ __forceinline__ void gemm_phase(PG8_LAS unsigned char* lds, const Gemm g, const Sched& S, const Epi& E) {
;     ...
;             const bool last = (t == nt - 2);
;             const char* a1 = cA + (size_t)(t + 1) * kstep;
;             const char* a2 = last ? nA : cA + (size_t)(t + 2) * kstep; const char* b2 = last ? nB : cB + (size_t)(t + 2) * kstep;
;             const char* a3 = a2 + kstep; const char* b3 = b2 + kstep;
;             if (last && has_next) S.a_ready(nxt);
;             if constexpr (SP2) {
;             PG8_LDB(B0, 0, 0); PG8_LDB(B1, 0, 1); PG8_SCHED; PG8_LDA(At, 0, 0); PG8_STAGE(PG8_SA(1, 1), a1 + hstep, voffA);
.LBB0_1114:
	ds_read_b128 v[96:99], v197
	ds_read_b128 v[100:103], v197 offset:1024
	ds_read_b128 v[104:107], v197 offset:2048
	ds_read_b128 v[112:115], v197 offset:3072
	ds_read_b128 v[144:147], v198
	ds_read_b128 v[148:151], v198 offset:1024
	ds_read_b128 v[152:155], v198 offset:2048
	ds_read_b128 v[172:175], v198 offset:3072
	s_add_u32 s50, s48, 0xffe00080
	s_addc_u32 s51, s49, -1
	s_cmpk_eq_i32 s73, 0x7c
	s_cselect_b32 s53, s43, s51
	s_cselect_b32 s52, s69, s50
	s_cselect_b32 s51, s41, s72
	s_cselect_b32 s50, s70, s71

; #define PG8_STAGE(bufoff, gbase, voff) do { _Pragma("unroll") for (int _i = 0; _i < 2; ++_i) \
;         __builtin_amdgcn_global_load_lds((const unsigned*)((const char*)(gbase) + (voff)[_i]), (PG8_LAS unsigned*)(lds + (bufoff) + ldsw + _i * 8192), 16, 0, 0); } while (0)
; #define PG8_LDA(dst, b, h) do { _Pragma("unroll") for (int m = 0; m < 4; ++m) _Pragma("unroll") for (int k = 0; k < 2; ++k) dst[m][k] = *(const PG8_LAS bf16x8*)(lds + PG8_SA(b, h) + aoff + m * 2048 + k * 1024); } while (0)
; #define PG8_LDB(dst, b, h) do { _Pragma("unroll") for (int n = 0; n < 2; ++n) _Pragma("unroll") for (int k = 0; k < 2; ++k) dst[n][k] = *(const PG8_LAS bf16x8*)(lds + PG8_SB(b, h) + boff + n * 2048 + k * 1024); } while (0)
; #define PG8_SCHED __builtin_amdgcn_sched_barrier(0)
; template <class Epi, class Sched, bool ALIGN_EPI = false, bool SP2 = false>
; __device__ __forceinline__ void gemm_phase(PG8_LAS unsigned char* lds, const Gemm g, const Sched& S, const Epi& E) {
;     ...
;             PG8_LDB(B0, 0, 0); PG8_LDB(B1, 0, 1); PG8_SCHED; PG8_LDA(At, 0, 0); PG8_STAGE(PG8_SA(1, 1), a1 + hstep, voffA);
	s_add_i32 m0, s56, 0xc000
	ds_read_b128 v[176:179], v199
	ds_read_b128 v[180:183], v199 offset:1024
	ds_read_b128 v[184:187], v199 offset:2048
	ds_read_b128 v[188:191], v199 offset:3072
	ds_read_b128 v[202:205], v199 offset:4096
	ds_read_b128 v[206:209], v199 offset:5120
	ds_read_b128 v[210:213], v199 offset:6144
	ds_read_b128 v[214:217], v199 offset:7168
	global_load_lds_dwordx4 v164, s[48:49]

; #define PG8_STAGE(bufoff, gbase, voff) do { _Pragma("unroll") for (int _i = 0; _i < 2; ++_i) \
;         __builtin_amdgcn_global_load_lds((const unsigned*)((const char*)(gbase) + (voff)[_i]), (PG8_LAS unsigned*)(lds + (bufoff) + ldsw + _i * 8192), 16, 0, 0); } while (0)
; #define PG8_LDA(dst, b, h) do { _Pragma("unroll") for (int m = 0; m < 4; ++m) _Pragma("unroll") for (int k = 0; k < 2; ++k) dst[m][k] = *(const PG8_LAS bf16x8*)(lds + PG8_SA(b, h) + aoff + m * 2048 + k * 1024); } while (0)
; #define PG8_LDB(dst, b, h) do { _Pragma("unroll") for (int n = 0; n < 2; ++n) _Pragma("unroll") for (int k = 0; k < 2; ++k) dst[n][k] = *(const PG8_LAS bf16x8*)(lds + PG8_SB(b, h) + boff + n * 2048 + k * 1024); } while (0)
; #define PG8_MMA(ai, bj, At, Bt) do { __builtin_amdgcn_s_setprio(1); _Pragma("unroll") for (int m = 0; m < 4; ++m) _Pragma("unroll") for (int n = 0; n < 2; ++n) _Pragma("unroll") for (int k = 0; k < 2; ++k) \
;         acc[ai][bj][m][n] = __builtin_amdgcn_mfma_f32_16x16x32_bf16(Bt[n][k], At[m][k], acc[ai][bj][m][n], 0, 0, 0); __builtin_amdgcn_s_setprio(0); } while (0)
; #define PG8_WAIT_V(n) asm volatile("s_waitcnt vmcnt(" #n ")" ::: "memory")
; #define PG8_WAIT_L(n) asm volatile("s_waitcnt lgkmcnt(" #n ")" ::: "memory")
; #define PG8_BAR __builtin_amdgcn_s_barrier()
; #define PG8_SCHED __builtin_amdgcn_sched_barrier(0)
; template <class Epi, class Sched, bool ALIGN_EPI = false, bool SP2 = false>
; __device__ __forceinline__ void gemm_phase(PG8_LAS unsigned char* lds, const Gemm g, const Sched& S, const Epi& E) {
;     ...
;             PG8_LDB(B0, 0, 0); PG8_LDB(B1, 0, 1); PG8_SCHED; PG8_LDA(At, 0, 0); PG8_STAGE(PG8_SA(1, 1), a1 + hstep, voffA);
;             PG8_WAIT_V(8); PG8_WAIT_L(0); PG8_BAR; PG8_MMA(0, 0, At, B0); PG8_MMA(0, 1, At, B1); PG8_BAR; PG8_SCHED;
	s_add_i32 m0, s56, 0xe000
	s_nop 0
	global_load_lds_dwordx4 v166, s[48:49]
	s_waitcnt vmcnt(8)
	s_waitcnt lgkmcnt(0)
	s_setprio 1
	s_barrier

; #define PG8_MMA(ai, bj, At, Bt) do { __builtin_amdgcn_s_setprio(1); _Pragma("unroll") for (int m = 0; m < 4; ++m) _Pragma("unroll") for (int n = 0; n < 2; ++n) _Pragma("unroll") for (int k = 0; k < 2; ++k) \
;         acc[ai][bj][m][n] = __builtin_amdgcn_mfma_f32_16x16x32_bf16(Bt[n][k], At[m][k], acc[ai][bj][m][n], 0, 0, 0); __builtin_amdgcn_s_setprio(0); } while (0)
; #define PG8_WAIT_V(n) asm volatile("s_waitcnt vmcnt(" #n ")" ::: "memory")
; #define PG8_WAIT_L(n) asm volatile("s_waitcnt lgkmcnt(" #n ")" ::: "memory")
; #define PG8_BAR __builtin_amdgcn_s_barrier()
; #define PG8_SCHED __builtin_amdgcn_sched_barrier(0)
; template <class Epi, class Sched, bool ALIGN_EPI = false, bool SP2 = false>
; __device__ __forceinline__ void gemm_phase(PG8_LAS unsigned char* lds, const Gemm g, const Sched& S, const Epi& E) {
;     ...
;             PG8_WAIT_V(8); PG8_WAIT_L(0); PG8_BAR; PG8_MMA(0, 0, At, B0); PG8_MMA(0, 1, At, B1); PG8_BAR; PG8_SCHED;
	v_mfma_f32_16x16x32_bf16 v[140:143], v[96:99], v[176:179], v[140:143]
	v_mfma_f32_16x16x32_bf16 v[136:139], v[104:107], v[176:179], v[136:139]
	v_mfma_f32_16x16x32_bf16 v[124:127], v[96:99], v[184:187], v[124:127]
	v_mfma_f32_16x16x32_bf16 v[120:123], v[104:107], v[184:187], v[120:123]
	v_mfma_f32_16x16x32_bf16 v[92:95], v[96:99], v[202:205], v[92:95]
	v_mfma_f32_16x16x32_bf16 v[88:91], v[104:107], v[202:205], v[88:91]
	v_mfma_f32_16x16x32_bf16 v[76:79], v[96:99], v[210:213], v[76:79]
	v_mfma_f32_16x16x32_bf16 v[72:75], v[104:107], v[210:213], v[72:75]
	v_mfma_f32_16x16x32_bf16 v[140:143], v[100:103], v[180:183], v[140:143]
	v_mfma_f32_16x16x32_bf16 v[136:139], v[112:115], v[180:183], v[136:139]
	v_mfma_f32_16x16x32_bf16 v[124:127], v[100:103], v[188:191], v[124:127]
	v_mfma_f32_16x16x32_bf16 v[120:123], v[112:115], v[188:191], v[120:123]
	v_mfma_f32_16x16x32_bf16 v[92:95], v[100:103], v[206:209], v[92:95]
	v_mfma_f32_16x16x32_bf16 v[88:91], v[112:115], v[206:209], v[88:91]
	v_mfma_f32_16x16x32_bf16 v[76:79], v[100:103], v[214:217], v[76:79]
	v_mfma_f32_16x16x32_bf16 v[72:75], v[112:115], v[214:217], v[72:75]


; #define PG8_MMA(ai, bj, At, Bt) do { __builtin_amdgcn_s_setprio(1); _Pragma("unroll") for (int m = 0; m < 4; ++m) _Pragma("unroll") for (int n = 0; n < 2; ++n) _Pragma("unroll") for (int k = 0; k < 2; ++k) \
;         acc[ai][bj][m][n] = __builtin_amdgcn_mfma_f32_16x16x32_bf16(Bt[n][k], At[m][k], acc[ai][bj][m][n], 0, 0, 0); __builtin_amdgcn_s_setprio(0); } while (0)
; #define PG8_WAIT_V(n) asm volatile("s_waitcnt vmcnt(" #n ")" ::: "memory")
; #define PG8_WAIT_L(n) asm volatile("s_waitcnt lgkmcnt(" #n ")" ::: "memory")
; #define PG8_BAR __builtin_amdgcn_s_barrier()
; #define PG8_SCHED __builtin_amdgcn_sched_barrier(0)
; template <class Epi, class Sched, bool ALIGN_EPI = false, bool SP2 = false>
; __device__ __forceinline__ void gemm_phase(PG8_LAS unsigned char* lds, const Gemm g, const Sched& S, const Epi& E) {
;     ...
;             PG8_WAIT_V(8); PG8_WAIT_L(0); PG8_BAR; PG8_MMA(0, 0, At, B0); PG8_MMA(0, 1, At, B1); PG8_BAR; PG8_SCHED;
	v_mfma_f32_16x16x32_bf16 v[132:135], v[144:147], v[176:179], v[132:135]
	v_mfma_f32_16x16x32_bf16 v[128:131], v[152:155], v[176:179], v[128:131]
	v_mfma_f32_16x16x32_bf16 v[116:119], v[144:147], v[184:187], v[116:119]
	v_mfma_f32_16x16x32_bf16 v[108:111], v[152:155], v[184:187], v[108:111]
	v_mfma_f32_16x16x32_bf16 v[84:87], v[144:147], v[202:205], v[84:87]
	v_mfma_f32_16x16x32_bf16 v[80:83], v[152:155], v[202:205], v[80:83]
	v_mfma_f32_16x16x32_bf16 v[68:71], v[144:147], v[210:213], v[68:71]
	v_mfma_f32_16x16x32_bf16 v[64:67], v[152:155], v[210:213], v[64:67]
	v_mfma_f32_16x16x32_bf16 v[132:135], v[148:151], v[180:183], v[132:135]
	v_mfma_f32_16x16x32_bf16 v[128:131], v[172:175], v[180:183], v[128:131]
	v_mfma_f32_16x16x32_bf16 v[116:119], v[148:151], v[188:191], v[116:119]
	v_mfma_f32_16x16x32_bf16 v[108:111], v[172:175], v[188:191], v[108:111]
	v_mfma_f32_16x16x32_bf16 v[84:87], v[148:151], v[206:209], v[84:87]
	v_mfma_f32_16x16x32_bf16 v[80:83], v[172:175], v[206:209], v[80:83]
	v_mfma_f32_16x16x32_bf16 v[68:71], v[148:151], v[214:217], v[68:71]
	v_mfma_f32_16x16x32_bf16 v[64:67], v[172:175], v[214:217], v[64:67]
	s_setprio 0
	s_barrier
	s_add_i32 s74, s65, s55
	s_mov_b64 s[96:97], s[50:51]

; #define PG8_STAGE(bufoff, gbase, voff) do { _Pragma("unroll") for (int _i = 0; _i < 2; ++_i) \
;         __builtin_amdgcn_global_load_lds((const unsigned*)((const char*)(gbase) + (voff)[_i]), (PG8_LAS unsigned*)(lds + (bufoff) + ldsw + _i * 8192), 16, 0, 0); } while (0)
; #define PG8_LDA(dst, b, h) do { _Pragma("unroll") for (int m = 0; m < 4; ++m) _Pragma("unroll") for (int k = 0; k < 2; ++k) dst[m][k] = *(const PG8_LAS bf16x8*)(lds + PG8_SA(b, h) + aoff + m * 2048 + k * 1024); } while (0)
; template <class Epi, class Sched, bool ALIGN_EPI = false, bool SP2 = false>
; __device__ __forceinline__ void gemm_phase(PG8_LAS unsigned char* lds, const Gemm g, const Sched& S, const Epi& E) {
;     ...
;             PG8_LDA(At, 0, 1); PG8_STAGE(PG8_SB(0, 0), b2, voffB); PG8_STAGE(PG8_SB(0, 1), b2 + hstep, voffB); PG8_STAGE(PG8_SA(0, 0), a2, voffA);
	s_mov_b32 m0, s74
	ds_read_b128 v[176:179], v199 offset:16384
	ds_read_b128 v[180:183], v199 offset:17408
	ds_read_b128 v[184:187], v199 offset:18432
	ds_read_b128 v[188:191], v199 offset:19456
	ds_read_b128 v[202:205], v199 offset:20480
	ds_read_b128 v[206:209], v199 offset:21504
	ds_read_b128 v[210:213], v199 offset:22528
	ds_read_b128 v[214:217], v199 offset:23552
	global_load_lds_dwordx4 v158, s[50:51]
	s_add_i32 m0, s74, 0x2000
	s_add_u32 s74, s50, 0x200000

; #define PG8_STAGE(bufoff, gbase, voff) do { _Pragma("unroll") for (int _i = 0; _i < 2; ++_i) \
;         __builtin_amdgcn_global_load_lds((const unsigned*)((const char*)(gbase) + (voff)[_i]), (PG8_LAS unsigned*)(lds + (bufoff) + ldsw + _i * 8192), 16, 0, 0); } while (0)
; #define PG8_LDA(dst, b, h) do { _Pragma("unroll") for (int m = 0; m < 4; ++m) _Pragma("unroll") for (int k = 0; k < 2; ++k) dst[m][k] = *(const PG8_LAS bf16x8*)(lds + PG8_SA(b, h) + aoff + m * 2048 + k * 1024); } while (0)
; template <class Epi, class Sched, bool ALIGN_EPI = false, bool SP2 = false>
; __device__ __forceinline__ void gemm_phase(PG8_LAS unsigned char* lds, const Gemm g, const Sched& S, const Epi& E) {
;     ...
;             PG8_LDA(At, 0, 1); PG8_STAGE(PG8_SB(0, 0), b2, voffB); PG8_STAGE(PG8_SB(0, 1), b2 + hstep, voffB); PG8_STAGE(PG8_SA(0, 0), a2, voffA);
	s_addc_u32 s75, s51, 0
	s_add_i32 s76, s67, s55
	global_load_lds_dwordx4 v162, s[50:51]

; #define PG8_STAGE(bufoff, gbase, voff) do { _Pragma("unroll") for (int _i = 0; _i < 2; ++_i) \
;         __builtin_amdgcn_global_load_lds((const unsigned*)((const char*)(gbase) + (voff)[_i]), (PG8_LAS unsigned*)(lds + (bufoff) + ldsw + _i * 8192), 16, 0, 0); } while (0)
; #define PG8_LDA(dst, b, h) do { _Pragma("unroll") for (int m = 0; m < 4; ++m) _Pragma("unroll") for (int k = 0; k < 2; ++k) dst[m][k] = *(const PG8_LAS bf16x8*)(lds + PG8_SA(b, h) + aoff + m * 2048 + k * 1024); } while (0)
; template <class Epi, class Sched, bool ALIGN_EPI = false, bool SP2 = false>
; __device__ __forceinline__ void gemm_phase(PG8_LAS unsigned char* lds, const Gemm g, const Sched& S, const Epi& E) {
;     ...
;             PG8_LDA(At, 0, 1); PG8_STAGE(PG8_SB(0, 0), b2, voffB); PG8_STAGE(PG8_SB(0, 1), b2 + hstep, voffB); PG8_STAGE(PG8_SA(0, 0), a2, voffA);
	s_mov_b32 m0, s76
	s_nop 0
	global_load_lds_dwordx4 v158, s[74:75]

; #define PG8_STAGE(bufoff, gbase, voff) do { _Pragma("unroll") for (int _i = 0; _i < 2; ++_i) \
;         __builtin_amdgcn_global_load_lds((const unsigned*)((const char*)(gbase) + (voff)[_i]), (PG8_LAS unsigned*)(lds + (bufoff) + ldsw + _i * 8192), 16, 0, 0); } while (0)
; #define PG8_LDA(dst, b, h) do { _Pragma("unroll") for (int m = 0; m < 4; ++m) _Pragma("unroll") for (int k = 0; k < 2; ++k) dst[m][k] = *(const PG8_LAS bf16x8*)(lds + PG8_SA(b, h) + aoff + m * 2048 + k * 1024); } while (0)
; template <class Epi, class Sched, bool ALIGN_EPI = false, bool SP2 = false>
; __device__ __forceinline__ void gemm_phase(PG8_LAS unsigned char* lds, const Gemm g, const Sched& S, const Epi& E) {
;     ...
;             PG8_LDA(At, 0, 1); PG8_STAGE(PG8_SB(0, 0), b2, voffB); PG8_STAGE(PG8_SB(0, 1), b2 + hstep, voffB); PG8_STAGE(PG8_SA(0, 0), a2, voffA);
	s_add_i32 m0, s76, 0x2000
	s_nop 0
	global_load_lds_dwordx4 v162, s[74:75]
	s_mov_b64 s[98:99], s[52:53]

; #define PG8_STAGE(bufoff, gbase, voff) do { _Pragma("unroll") for (int _i = 0; _i < 2; ++_i) \
;         __builtin_amdgcn_global_load_lds((const unsigned*)((const char*)(gbase) + (voff)[_i]), (PG8_LAS unsigned*)(lds + (bufoff) + ldsw + _i * 8192), 16, 0, 0); } while (0)
; #define PG8_LDA(dst, b, h) do { _Pragma("unroll") for (int m = 0; m < 4; ++m) _Pragma("unroll") for (int k = 0; k < 2; ++k) dst[m][k] = *(const PG8_LAS bf16x8*)(lds + PG8_SA(b, h) + aoff + m * 2048 + k * 1024); } while (0)
; #define PG8_MMA(ai, bj, At, Bt) do { __builtin_amdgcn_s_setprio(1); _Pragma("unroll") for (int m = 0; m < 4; ++m) _Pragma("unroll") for (int n = 0; n < 2; ++n) _Pragma("unroll") for (int k = 0; k < 2; ++k) \
;         acc[ai][bj][m][n] = __builtin_amdgcn_mfma_f32_16x16x32_bf16(Bt[n][k], At[m][k], acc[ai][bj][m][n], 0, 0, 0); __builtin_amdgcn_s_setprio(0); } while (0)
; #define PG8_WAIT_V(n) asm volatile("s_waitcnt vmcnt(" #n ")" ::: "memory")
; #define PG8_WAIT_L(n) asm volatile("s_waitcnt lgkmcnt(" #n ")" ::: "memory")
; #define PG8_BAR __builtin_amdgcn_s_barrier()
; #define PG8_SCHED __builtin_amdgcn_sched_barrier(0)
; template <class Epi, class Sched, bool ALIGN_EPI = false, bool SP2 = false>
; __device__ __forceinline__ void gemm_phase(PG8_LAS unsigned char* lds, const Gemm g, const Sched& S, const Epi& E) {
;     ...
;             PG8_LDA(At, 0, 1); PG8_STAGE(PG8_SB(0, 0), b2, voffB); PG8_STAGE(PG8_SB(0, 1), b2 + hstep, voffB); PG8_STAGE(PG8_SA(0, 0), a2, voffA);
;             PG8_WAIT_V(8); PG8_WAIT_L(0); PG8_BAR; PG8_MMA(1, 0, At, B0); PG8_MMA(1, 1, At, B1); PG8_BAR; PG8_SCHED;
	s_mov_b32 m0, s56
	s_nop 0
	global_load_lds_dwordx4 v156, s[52:53]
	s_mov_b32 m0, s57
	s_nop 0
	global_load_lds_dwordx4 v160, s[52:53]
	s_waitcnt vmcnt(8)
	s_waitcnt lgkmcnt(0)
	s_setprio 1
	s_barrier

; #define PG8_MMA(ai, bj, At, Bt) do { __builtin_amdgcn_s_setprio(1); _Pragma("unroll") for (int m = 0; m < 4; ++m) _Pragma("unroll") for (int n = 0; n < 2; ++n) _Pragma("unroll") for (int k = 0; k < 2; ++k) \
;         acc[ai][bj][m][n] = __builtin_amdgcn_mfma_f32_16x16x32_bf16(Bt[n][k], At[m][k], acc[ai][bj][m][n], 0, 0, 0); __builtin_amdgcn_s_setprio(0); } while (0)
; #define PG8_WAIT_V(n) asm volatile("s_waitcnt vmcnt(" #n ")" ::: "memory")
; #define PG8_WAIT_L(n) asm volatile("s_waitcnt lgkmcnt(" #n ")" ::: "memory")
; #define PG8_BAR __builtin_amdgcn_s_barrier()
; #define PG8_SCHED __builtin_amdgcn_sched_barrier(0)
; template <class Epi, class Sched, bool ALIGN_EPI = false, bool SP2 = false>
; __device__ __forceinline__ void gemm_phase(PG8_LAS unsigned char* lds, const Gemm g, const Sched& S, const Epi& E) {
;     ...
;             PG8_WAIT_V(8); PG8_WAIT_L(0); PG8_BAR; PG8_MMA(1, 0, At, B0); PG8_MMA(1, 1, At, B1); PG8_BAR; PG8_SCHED;
	v_mfma_f32_16x16x32_bf16 v[60:63], v[96:99], v[176:179], v[60:63]
	v_mfma_f32_16x16x32_bf16 v[56:59], v[104:107], v[176:179], v[56:59]
	v_mfma_f32_16x16x32_bf16 v[44:47], v[96:99], v[184:187], v[44:47]
	v_mfma_f32_16x16x32_bf16 v[40:43], v[104:107], v[184:187], v[40:43]
	v_mfma_f32_16x16x32_bf16 v[28:31], v[96:99], v[202:205], v[28:31]
	v_mfma_f32_16x16x32_bf16 v[24:27], v[104:107], v[202:205], v[24:27]
	v_mfma_f32_16x16x32_bf16 v[12:15], v[96:99], v[210:213], v[12:15]
	v_mfma_f32_16x16x32_bf16 v[8:11], v[104:107], v[210:213], v[8:11]
	v_mfma_f32_16x16x32_bf16 v[60:63], v[100:103], v[180:183], v[60:63]
	v_mfma_f32_16x16x32_bf16 v[56:59], v[112:115], v[180:183], v[56:59]
	v_mfma_f32_16x16x32_bf16 v[44:47], v[100:103], v[188:191], v[44:47]
	v_mfma_f32_16x16x32_bf16 v[40:43], v[112:115], v[188:191], v[40:43]
	v_mfma_f32_16x16x32_bf16 v[28:31], v[100:103], v[206:209], v[28:31]
	v_mfma_f32_16x16x32_bf16 v[24:27], v[112:115], v[206:209], v[24:27]
	v_mfma_f32_16x16x32_bf16 v[12:15], v[100:103], v[214:217], v[12:15]
	v_mfma_f32_16x16x32_bf16 v[8:11], v[112:115], v[214:217], v[8:11]


; #define PG8_STAGE(bufoff, gbase, voff) do { _Pragma("unroll") for (int _i = 0; _i < 2; ++_i) \
;         __builtin_amdgcn_global_load_lds((const unsigned*)((const char*)(gbase) + (voff)[_i]), (PG8_LAS unsigned*)(lds + (bufoff) + ldsw + _i * 8192), 16, 0, 0); } while (0)
; #define PG8_LDA(dst, b, h) do { _Pragma("unroll") for (int m = 0; m < 4; ++m) _Pragma("unroll") for (int k = 0; k < 2; ++k) dst[m][k] = *(const PG8_LAS bf16x8*)(lds + PG8_SA(b, h) + aoff + m * 2048 + k * 1024); } while (0)
; #define PG8_LDB(dst, b, h) do { _Pragma("unroll") for (int n = 0; n < 2; ++n) _Pragma("unroll") for (int k = 0; k < 2; ++k) dst[n][k] = *(const PG8_LAS bf16x8*)(lds + PG8_SB(b, h) + boff + n * 2048 + k * 1024); } while (0)
; #define PG8_MMA(ai, bj, At, Bt) do { __builtin_amdgcn_s_setprio(1); _Pragma("unroll") for (int m = 0; m < 4; ++m) _Pragma("unroll") for (int n = 0; n < 2; ++n) _Pragma("unroll") for (int k = 0; k < 2; ++k) \
;         acc[ai][bj][m][n] = __builtin_amdgcn_mfma_f32_16x16x32_bf16(Bt[n][k], At[m][k], acc[ai][bj][m][n], 0, 0, 0); __builtin_amdgcn_s_setprio(0); } while (0)
; #define PG8_WAIT_V(n) asm volatile("s_waitcnt vmcnt(" #n ")" ::: "memory")
; #define PG8_WAIT_L(n) asm volatile("s_waitcnt lgkmcnt(" #n ")" ::: "memory")
; #define PG8_BAR __builtin_amdgcn_s_barrier()
; #define PG8_SCHED __builtin_amdgcn_sched_barrier(0)
; template <class Epi, class Sched, bool ALIGN_EPI = false, bool SP2 = false>
; __device__ __forceinline__ void gemm_phase(PG8_LAS unsigned char* lds, const Gemm g, const Sched& S, const Epi& E) {
;     ...
;             PG8_WAIT_V(8); PG8_WAIT_L(0); PG8_BAR; PG8_MMA(1, 0, At, B0); PG8_MMA(1, 1, At, B1); PG8_BAR; PG8_SCHED;
;             PG8_LDB(B0, 1, 0); PG8_LDB(B1, 1, 1); PG8_SCHED; PG8_LDA(At, 1, 0); PG8_STAGE(PG8_SA(0, 1), a2 + hstep, voffA);
	v_mfma_f32_16x16x32_bf16 v[52:55], v[144:147], v[176:179], v[52:55]
	v_mfma_f32_16x16x32_bf16 v[48:51], v[152:155], v[176:179], v[48:51]
	v_mfma_f32_16x16x32_bf16 v[36:39], v[144:147], v[184:187], v[36:39]
	v_mfma_f32_16x16x32_bf16 v[32:35], v[152:155], v[184:187], v[32:35]
	v_mfma_f32_16x16x32_bf16 v[20:23], v[144:147], v[202:205], v[20:23]
	v_mfma_f32_16x16x32_bf16 v[16:19], v[152:155], v[202:205], v[16:19]
	v_mfma_f32_16x16x32_bf16 v[4:7], v[144:147], v[210:213], v[4:7]
	v_mfma_f32_16x16x32_bf16 v[0:3], v[152:155], v[210:213], v[0:3]
	v_mfma_f32_16x16x32_bf16 v[52:55], v[148:151], v[180:183], v[52:55]
	v_mfma_f32_16x16x32_bf16 v[48:51], v[172:175], v[180:183], v[48:51]
	v_mfma_f32_16x16x32_bf16 v[36:39], v[148:151], v[188:191], v[36:39]
	v_mfma_f32_16x16x32_bf16 v[32:35], v[172:175], v[188:191], v[32:35]
	v_mfma_f32_16x16x32_bf16 v[20:23], v[148:151], v[206:209], v[20:23]
	v_mfma_f32_16x16x32_bf16 v[16:19], v[172:175], v[206:209], v[16:19]
	v_mfma_f32_16x16x32_bf16 v[4:7], v[148:151], v[214:217], v[4:7]
	v_mfma_f32_16x16x32_bf16 v[0:3], v[172:175], v[214:217], v[0:3]
	s_setprio 0
	s_barrier
	s_add_i32 s74, 0, 0x18000
	s_add_i32 s75, 0, 0x1c000


; #define PG8_STAGE(bufoff, gbase, voff) do { _Pragma("unroll") for (int _i = 0; _i < 2; ++_i) \
;         __builtin_amdgcn_global_load_lds((const unsigned*)((const char*)(gbase) + (voff)[_i]), (PG8_LAS unsigned*)(lds + (bufoff) + ldsw + _i * 8192), 16, 0, 0); } while (0)
; #define PG8_LDA(dst, b, h) do { _Pragma("unroll") for (int m = 0; m < 4; ++m) _Pragma("unroll") for (int k = 0; k < 2; ++k) dst[m][k] = *(const PG8_LAS bf16x8*)(lds + PG8_SA(b, h) + aoff + m * 2048 + k * 1024); } while (0)
; #define PG8_LDB(dst, b, h) do { _Pragma("unroll") for (int n = 0; n < 2; ++n) _Pragma("unroll") for (int k = 0; k < 2; ++k) dst[n][k] = *(const PG8_LAS bf16x8*)(lds + PG8_SB(b, h) + boff + n * 2048 + k * 1024); } while (0)
; #define PG8_SCHED __builtin_amdgcn_sched_barrier(0)
; template <class Epi, class Sched, bool ALIGN_EPI = false, bool SP2 = false>
; __device__ __forceinline__ void gemm_phase(PG8_LAS unsigned char* lds, const Gemm g, const Sched& S, const Epi& E) {
;     ...
;             PG8_LDB(B0, 1, 0); PG8_LDB(B1, 1, 1); PG8_SCHED; PG8_LDA(At, 1, 0); PG8_STAGE(PG8_SA(0, 1), a2 + hstep, voffA);
	ds_read_b128 v[96:99], v254
	ds_read_b128 v[100:103], v254 offset:1024
	ds_read_b128 v[104:107], v254 offset:2048
	ds_read_b128 v[112:115], v254 offset:3072
	ds_read_b128 v[144:147], v255
	ds_read_b128 v[148:151], v255 offset:1024
	ds_read_b128 v[152:155], v255 offset:2048
	ds_read_b128 v[172:175], v255 offset:3072
	s_add_u32 s52, s52, 0x200000
	s_addc_u32 s53, s53, 0
	s_mov_b32 m0, s58

; #define PG8_STAGE(bufoff, gbase, voff) do { _Pragma("unroll") for (int _i = 0; _i < 2; ++_i) \
;         __builtin_amdgcn_global_load_lds((const unsigned*)((const char*)(gbase) + (voff)[_i]), (PG8_LAS unsigned*)(lds + (bufoff) + ldsw + _i * 8192), 16, 0, 0); } while (0)
; #define PG8_LDA(dst, b, h) do { _Pragma("unroll") for (int m = 0; m < 4; ++m) _Pragma("unroll") for (int k = 0; k < 2; ++k) dst[m][k] = *(const PG8_LAS bf16x8*)(lds + PG8_SA(b, h) + aoff + m * 2048 + k * 1024); } while (0)
; #define PG8_LDB(dst, b, h) do { _Pragma("unroll") for (int n = 0; n < 2; ++n) _Pragma("unroll") for (int k = 0; k < 2; ++k) dst[n][k] = *(const PG8_LAS bf16x8*)(lds + PG8_SB(b, h) + boff + n * 2048 + k * 1024); } while (0)
; #define PG8_SCHED __builtin_amdgcn_sched_barrier(0)
; template <class Epi, class Sched, bool ALIGN_EPI = false, bool SP2 = false>
; __device__ __forceinline__ void gemm_phase(PG8_LAS unsigned char* lds, const Gemm g, const Sched& S, const Epi& E) {
;     ...
;             PG8_LDB(B0, 1, 0); PG8_LDB(B1, 1, 1); PG8_SCHED; PG8_LDA(At, 1, 0); PG8_STAGE(PG8_SA(0, 1), a2 + hstep, voffA);
	ds_read_b128 v[176:179], v199 offset:32768
	ds_read_b128 v[180:183], v199 offset:33792
	ds_read_b128 v[184:187], v199 offset:34816
	ds_read_b128 v[188:191], v199 offset:35840
	ds_read_b128 v[202:205], v199 offset:36864
	ds_read_b128 v[206:209], v199 offset:37888
	ds_read_b128 v[210:213], v199 offset:38912
	ds_read_b128 v[214:217], v199 offset:39936
	global_load_lds_dwordx4 v156, s[52:53]

; #define PG8_STAGE(bufoff, gbase, voff) do { _Pragma("unroll") for (int _i = 0; _i < 2; ++_i) \
;         __builtin_amdgcn_global_load_lds((const unsigned*)((const char*)(gbase) + (voff)[_i]), (PG8_LAS unsigned*)(lds + (bufoff) + ldsw + _i * 8192), 16, 0, 0); } while (0)
; #define PG8_LDA(dst, b, h) do { _Pragma("unroll") for (int m = 0; m < 4; ++m) _Pragma("unroll") for (int k = 0; k < 2; ++k) dst[m][k] = *(const PG8_LAS bf16x8*)(lds + PG8_SA(b, h) + aoff + m * 2048 + k * 1024); } while (0)
; #define PG8_LDB(dst, b, h) do { _Pragma("unroll") for (int n = 0; n < 2; ++n) _Pragma("unroll") for (int k = 0; k < 2; ++k) dst[n][k] = *(const PG8_LAS bf16x8*)(lds + PG8_SB(b, h) + boff + n * 2048 + k * 1024); } while (0)
; #define PG8_MMA(ai, bj, At, Bt) do { __builtin_amdgcn_s_setprio(1); _Pragma("unroll") for (int m = 0; m < 4; ++m) _Pragma("unroll") for (int n = 0; n < 2; ++n) _Pragma("unroll") for (int k = 0; k < 2; ++k) \
;         acc[ai][bj][m][n] = __builtin_amdgcn_mfma_f32_16x16x32_bf16(Bt[n][k], At[m][k], acc[ai][bj][m][n], 0, 0, 0); __builtin_amdgcn_s_setprio(0); } while (0)
; #define PG8_WAIT_V(n) asm volatile("s_waitcnt vmcnt(" #n ")" ::: "memory")
; #define PG8_WAIT_L(n) asm volatile("s_waitcnt lgkmcnt(" #n ")" ::: "memory")
; #define PG8_BAR __builtin_amdgcn_s_barrier()
; #define PG8_SCHED __builtin_amdgcn_sched_barrier(0)
; template <class Epi, class Sched, bool ALIGN_EPI = false, bool SP2 = false>
; __device__ __forceinline__ void gemm_phase(PG8_LAS unsigned char* lds, const Gemm g, const Sched& S, const Epi& E) {
;     ...
;             PG8_LDB(B0, 1, 0); PG8_LDB(B1, 1, 1); PG8_SCHED; PG8_LDA(At, 1, 0); PG8_STAGE(PG8_SA(0, 1), a2 + hstep, voffA);
;             PG8_WAIT_V(8); PG8_WAIT_L(0); PG8_BAR; PG8_MMA(0, 0, At, B0); PG8_MMA(0, 1, At, B1); PG8_BAR; PG8_SCHED;
	s_mov_b32 m0, s59
	s_nop 0
	global_load_lds_dwordx4 v160, s[52:53]
	s_waitcnt vmcnt(8)
	s_waitcnt lgkmcnt(0)
	s_setprio 1
	s_barrier

; #define PG8_MMA(ai, bj, At, Bt) do { __builtin_amdgcn_s_setprio(1); _Pragma("unroll") for (int m = 0; m < 4; ++m) _Pragma("unroll") for (int n = 0; n < 2; ++n) _Pragma("unroll") for (int k = 0; k < 2; ++k) \
;         acc[ai][bj][m][n] = __builtin_amdgcn_mfma_f32_16x16x32_bf16(Bt[n][k], At[m][k], acc[ai][bj][m][n], 0, 0, 0); __builtin_amdgcn_s_setprio(0); } while (0)
; #define PG8_WAIT_V(n) asm volatile("s_waitcnt vmcnt(" #n ")" ::: "memory")
; #define PG8_WAIT_L(n) asm volatile("s_waitcnt lgkmcnt(" #n ")" ::: "memory")
; #define PG8_BAR __builtin_amdgcn_s_barrier()
; #define PG8_SCHED __builtin_amdgcn_sched_barrier(0)
; template <class Epi, class Sched, bool ALIGN_EPI = false, bool SP2 = false>
; __device__ __forceinline__ void gemm_phase(PG8_LAS unsigned char* lds, const Gemm g, const Sched& S, const Epi& E) {
;     ...
;             PG8_WAIT_V(8); PG8_WAIT_L(0); PG8_BAR; PG8_MMA(0, 0, At, B0); PG8_MMA(0, 1, At, B1); PG8_BAR; PG8_SCHED;
	v_mfma_f32_16x16x32_bf16 v[140:143], v[96:99], v[176:179], v[140:143]
	v_mfma_f32_16x16x32_bf16 v[136:139], v[104:107], v[176:179], v[136:139]
	v_mfma_f32_16x16x32_bf16 v[124:127], v[96:99], v[184:187], v[124:127]
	v_mfma_f32_16x16x32_bf16 v[120:123], v[104:107], v[184:187], v[120:123]
	v_mfma_f32_16x16x32_bf16 v[92:95], v[96:99], v[202:205], v[92:95]
	v_mfma_f32_16x16x32_bf16 v[88:91], v[104:107], v[202:205], v[88:91]
	v_mfma_f32_16x16x32_bf16 v[76:79], v[96:99], v[210:213], v[76:79]
	v_mfma_f32_16x16x32_bf16 v[72:75], v[104:107], v[210:213], v[72:75]
	v_mfma_f32_16x16x32_bf16 v[140:143], v[100:103], v[180:183], v[140:143]
	v_mfma_f32_16x16x32_bf16 v[136:139], v[112:115], v[180:183], v[136:139]
	v_mfma_f32_16x16x32_bf16 v[124:127], v[100:103], v[188:191], v[124:127]
	v_mfma_f32_16x16x32_bf16 v[120:123], v[112:115], v[188:191], v[120:123]
	v_mfma_f32_16x16x32_bf16 v[92:95], v[100:103], v[206:209], v[92:95]
	v_mfma_f32_16x16x32_bf16 v[88:91], v[112:115], v[206:209], v[88:91]
	v_mfma_f32_16x16x32_bf16 v[76:79], v[100:103], v[214:217], v[76:79]
	v_mfma_f32_16x16x32_bf16 v[72:75], v[112:115], v[214:217], v[72:75]


; #define PG8_STAGE(bufoff, gbase, voff) do { _Pragma("unroll") for (int _i = 0; _i < 2; ++_i) \
;         __builtin_amdgcn_global_load_lds((const unsigned*)((const char*)(gbase) + (voff)[_i]), (PG8_LAS unsigned*)(lds + (bufoff) + ldsw + _i * 8192), 16, 0, 0); } while (0)
; #define PG8_LDA(dst, b, h) do { _Pragma("unroll") for (int m = 0; m < 4; ++m) _Pragma("unroll") for (int k = 0; k < 2; ++k) dst[m][k] = *(const PG8_LAS bf16x8*)(lds + PG8_SA(b, h) + aoff + m * 2048 + k * 1024); } while (0)
; #define PG8_MMA(ai, bj, At, Bt) do { __builtin_amdgcn_s_setprio(1); _Pragma("unroll") for (int m = 0; m < 4; ++m) _Pragma("unroll") for (int n = 0; n < 2; ++n) _Pragma("unroll") for (int k = 0; k < 2; ++k) \
;         acc[ai][bj][m][n] = __builtin_amdgcn_mfma_f32_16x16x32_bf16(Bt[n][k], At[m][k], acc[ai][bj][m][n], 0, 0, 0); __builtin_amdgcn_s_setprio(0); } while (0)
; #define PG8_WAIT_V(n) asm volatile("s_waitcnt vmcnt(" #n ")" ::: "memory")
; #define PG8_WAIT_L(n) asm volatile("s_waitcnt lgkmcnt(" #n ")" ::: "memory")
; #define PG8_BAR __builtin_amdgcn_s_barrier()
; #define PG8_SCHED __builtin_amdgcn_sched_barrier(0)
; template <class Epi, class Sched, bool ALIGN_EPI = false, bool SP2 = false>
; __device__ __forceinline__ void gemm_phase(PG8_LAS unsigned char* lds, const Gemm g, const Sched& S, const Epi& E) {
;     ...
;             PG8_WAIT_V(8); PG8_WAIT_L(0); PG8_BAR; PG8_MMA(0, 0, At, B0); PG8_MMA(0, 1, At, B1); PG8_BAR; PG8_SCHED;
;             PG8_LDA(At, 1, 1); PG8_STAGE(PG8_SB(1, 0), b3, voffB); PG8_STAGE(PG8_SB(1, 1), b3 + hstep, voffB); PG8_STAGE(PG8_SA(1, 0), a3, voffA);
	v_mfma_f32_16x16x32_bf16 v[132:135], v[144:147], v[176:179], v[132:135]
	v_mfma_f32_16x16x32_bf16 v[128:131], v[152:155], v[176:179], v[128:131]
	v_mfma_f32_16x16x32_bf16 v[116:119], v[144:147], v[184:187], v[116:119]
	v_mfma_f32_16x16x32_bf16 v[108:111], v[152:155], v[184:187], v[108:111]
	v_mfma_f32_16x16x32_bf16 v[84:87], v[144:147], v[202:205], v[84:87]
	v_mfma_f32_16x16x32_bf16 v[80:83], v[152:155], v[202:205], v[80:83]
	v_mfma_f32_16x16x32_bf16 v[68:71], v[144:147], v[210:213], v[68:71]
	v_mfma_f32_16x16x32_bf16 v[64:67], v[152:155], v[210:213], v[64:67]
	v_mfma_f32_16x16x32_bf16 v[132:135], v[148:151], v[180:183], v[132:135]
	v_mfma_f32_16x16x32_bf16 v[128:131], v[172:175], v[180:183], v[128:131]
	v_mfma_f32_16x16x32_bf16 v[116:119], v[148:151], v[188:191], v[116:119]
	v_mfma_f32_16x16x32_bf16 v[108:111], v[172:175], v[188:191], v[108:111]
	v_mfma_f32_16x16x32_bf16 v[84:87], v[148:151], v[206:209], v[84:87]
	v_mfma_f32_16x16x32_bf16 v[80:83], v[172:175], v[206:209], v[80:83]
	v_mfma_f32_16x16x32_bf16 v[68:71], v[148:151], v[214:217], v[68:71]
	v_mfma_f32_16x16x32_bf16 v[64:67], v[172:175], v[214:217], v[64:67]
	s_setprio 0
	s_barrier
	s_add_i32 s52, s74, s55

; #define PG8_STAGE(bufoff, gbase, voff) do { _Pragma("unroll") for (int _i = 0; _i < 2; ++_i) \
;         __builtin_amdgcn_global_load_lds((const unsigned*)((const char*)(gbase) + (voff)[_i]), (PG8_LAS unsigned*)(lds + (bufoff) + ldsw + _i * 8192), 16, 0, 0); } while (0)
; #define PG8_LDA(dst, b, h) do { _Pragma("unroll") for (int m = 0; m < 4; ++m) _Pragma("unroll") for (int k = 0; k < 2; ++k) dst[m][k] = *(const PG8_LAS bf16x8*)(lds + PG8_SA(b, h) + aoff + m * 2048 + k * 1024); } while (0)
; template <class Epi, class Sched, bool ALIGN_EPI = false, bool SP2 = false>
; __device__ __forceinline__ void gemm_phase(PG8_LAS unsigned char* lds, const Gemm g, const Sched& S, const Epi& E) {
;     ...
;             PG8_LDA(At, 1, 1); PG8_STAGE(PG8_SB(1, 0), b3, voffB); PG8_STAGE(PG8_SB(1, 1), b3 + hstep, voffB); PG8_STAGE(PG8_SA(1, 0), a3, voffA);
	s_mov_b32 m0, s52
	ds_read_b128 v[176:179], v199 offset:49152
	ds_read_b128 v[180:183], v199 offset:50176
	ds_read_b128 v[184:187], v199 offset:51200
	ds_read_b128 v[188:191], v199 offset:52224
	ds_read_b128 v[202:205], v199 offset:53248
	ds_read_b128 v[206:209], v199 offset:54272
	ds_read_b128 v[210:213], v199 offset:55296
	ds_read_b128 v[214:217], v199 offset:56320
	global_load_lds_dwordx4 v250, s[96:97]
	s_add_i32 m0, s52, 0x2000
	s_add_u32 s50, s50, 0x200080

; #define PG8_STAGE(bufoff, gbase, voff) do { _Pragma("unroll") for (int _i = 0; _i < 2; ++_i) \
;         __builtin_amdgcn_global_load_lds((const unsigned*)((const char*)(gbase) + (voff)[_i]), (PG8_LAS unsigned*)(lds + (bufoff) + ldsw + _i * 8192), 16, 0, 0); } while (0)
; #define PG8_LDA(dst, b, h) do { _Pragma("unroll") for (int m = 0; m < 4; ++m) _Pragma("unroll") for (int k = 0; k < 2; ++k) dst[m][k] = *(const PG8_LAS bf16x8*)(lds + PG8_SA(b, h) + aoff + m * 2048 + k * 1024); } while (0)
; template <class Epi, class Sched, bool ALIGN_EPI = false, bool SP2 = false>
; __device__ __forceinline__ void gemm_phase(PG8_LAS unsigned char* lds, const Gemm g, const Sched& S, const Epi& E) {
;     ...
;             PG8_LDA(At, 1, 1); PG8_STAGE(PG8_SB(1, 0), b3, voffB); PG8_STAGE(PG8_SB(1, 1), b3 + hstep, voffB); PG8_STAGE(PG8_SA(1, 0), a3, voffA);
	s_addc_u32 s51, s51, 0
	s_add_i32 s52, s75, s55
	global_load_lds_dwordx4 v251, s[96:97]

; #define PG8_STAGE(bufoff, gbase, voff) do { _Pragma("unroll") for (int _i = 0; _i < 2; ++_i) \
;         __builtin_amdgcn_global_load_lds((const unsigned*)((const char*)(gbase) + (voff)[_i]), (PG8_LAS unsigned*)(lds + (bufoff) + ldsw + _i * 8192), 16, 0, 0); } while (0)
; #define PG8_LDA(dst, b, h) do { _Pragma("unroll") for (int m = 0; m < 4; ++m) _Pragma("unroll") for (int k = 0; k < 2; ++k) dst[m][k] = *(const PG8_LAS bf16x8*)(lds + PG8_SA(b, h) + aoff + m * 2048 + k * 1024); } while (0)
; template <class Epi, class Sched, bool ALIGN_EPI = false, bool SP2 = false>
; __device__ __forceinline__ void gemm_phase(PG8_LAS unsigned char* lds, const Gemm g, const Sched& S, const Epi& E) {
;     ...
;             PG8_LDA(At, 1, 1); PG8_STAGE(PG8_SB(1, 0), b3, voffB); PG8_STAGE(PG8_SB(1, 1), b3 + hstep, voffB); PG8_STAGE(PG8_SA(1, 0), a3, voffA);
	s_mov_b32 m0, s52
	s_nop 0
	global_load_lds_dwordx4 v158, s[50:51]

; #define PG8_STAGE(bufoff, gbase, voff) do { _Pragma("unroll") for (int _i = 0; _i < 2; ++_i) \
;         __builtin_amdgcn_global_load_lds((const unsigned*)((const char*)(gbase) + (voff)[_i]), (PG8_LAS unsigned*)(lds + (bufoff) + ldsw + _i * 8192), 16, 0, 0); } while (0)
; #define PG8_LDA(dst, b, h) do { _Pragma("unroll") for (int m = 0; m < 4; ++m) _Pragma("unroll") for (int k = 0; k < 2; ++k) dst[m][k] = *(const PG8_LAS bf16x8*)(lds + PG8_SA(b, h) + aoff + m * 2048 + k * 1024); } while (0)
; template <class Epi, class Sched, bool ALIGN_EPI = false, bool SP2 = false>
; __device__ __forceinline__ void gemm_phase(PG8_LAS unsigned char* lds, const Gemm g, const Sched& S, const Epi& E) {
;     ...
;             PG8_LDA(At, 1, 1); PG8_STAGE(PG8_SB(1, 0), b3, voffB); PG8_STAGE(PG8_SB(1, 1), b3 + hstep, voffB); PG8_STAGE(PG8_SA(1, 0), a3, voffA);
	s_add_i32 m0, s52, 0x2000
	s_nop 0
	global_load_lds_dwordx4 v162, s[50:51]

; #define PG8_STAGE(bufoff, gbase, voff) do { _Pragma("unroll") for (int _i = 0; _i < 2; ++_i) \
;         __builtin_amdgcn_global_load_lds((const unsigned*)((const char*)(gbase) + (voff)[_i]), (PG8_LAS unsigned*)(lds + (bufoff) + ldsw + _i * 8192), 16, 0, 0); } while (0)
; #define PG8_LDA(dst, b, h) do { _Pragma("unroll") for (int m = 0; m < 4; ++m) _Pragma("unroll") for (int k = 0; k < 2; ++k) dst[m][k] = *(const PG8_LAS bf16x8*)(lds + PG8_SA(b, h) + aoff + m * 2048 + k * 1024); } while (0)
; template <class Epi, class Sched, bool ALIGN_EPI = false, bool SP2 = false>
; __device__ __forceinline__ void gemm_phase(PG8_LAS unsigned char* lds, const Gemm g, const Sched& S, const Epi& E) {
;     ...
;             PG8_LDA(At, 1, 1); PG8_STAGE(PG8_SB(1, 0), b3, voffB); PG8_STAGE(PG8_SB(1, 1), b3 + hstep, voffB); PG8_STAGE(PG8_SA(1, 0), a3, voffA);
	s_mov_b32 m0, s61
	s_nop 0
	global_load_lds_dwordx4 v252, s[98:99]

; #define PG8_STAGE(bufoff, gbase, voff) do { _Pragma("unroll") for (int _i = 0; _i < 2; ++_i) \
;         __builtin_amdgcn_global_load_lds((const unsigned*)((const char*)(gbase) + (voff)[_i]), (PG8_LAS unsigned*)(lds + (bufoff) + ldsw + _i * 8192), 16, 0, 0); } while (0)
; #define PG8_LDA(dst, b, h) do { _Pragma("unroll") for (int m = 0; m < 4; ++m) _Pragma("unroll") for (int k = 0; k < 2; ++k) dst[m][k] = *(const PG8_LAS bf16x8*)(lds + PG8_SA(b, h) + aoff + m * 2048 + k * 1024); } while (0)
; #define PG8_MMA(ai, bj, At, Bt) do { __builtin_amdgcn_s_setprio(1); _Pragma("unroll") for (int m = 0; m < 4; ++m) _Pragma("unroll") for (int n = 0; n < 2; ++n) _Pragma("unroll") for (int k = 0; k < 2; ++k) \
;         acc[ai][bj][m][n] = __builtin_amdgcn_mfma_f32_16x16x32_bf16(Bt[n][k], At[m][k], acc[ai][bj][m][n], 0, 0, 0); __builtin_amdgcn_s_setprio(0); } while (0)
; #define PG8_WAIT_V(n) asm volatile("s_waitcnt vmcnt(" #n ")" ::: "memory")
; #define PG8_WAIT_L(n) asm volatile("s_waitcnt lgkmcnt(" #n ")" ::: "memory")
; #define PG8_BAR __builtin_amdgcn_s_barrier()
; #define PG8_SCHED __builtin_amdgcn_sched_barrier(0)
; template <class Epi, class Sched, bool ALIGN_EPI = false, bool SP2 = false>
; __device__ __forceinline__ void gemm_phase(PG8_LAS unsigned char* lds, const Gemm g, const Sched& S, const Epi& E) {
;     ...
;             PG8_LDA(At, 1, 1); PG8_STAGE(PG8_SB(1, 0), b3, voffB); PG8_STAGE(PG8_SB(1, 1), b3 + hstep, voffB); PG8_STAGE(PG8_SA(1, 0), a3, voffA);
;             PG8_WAIT_V(8); PG8_WAIT_L(0); PG8_BAR; PG8_MMA(1, 0, At, B0); PG8_MMA(1, 1, At, B1); PG8_BAR; PG8_SCHED;
	s_mov_b32 m0, s62
	s_nop 0
	global_load_lds_dwordx4 v253, s[98:99]
	s_waitcnt vmcnt(8)
	s_waitcnt lgkmcnt(0)
	s_setprio 1
	s_barrier

; #define PG8_MMA(ai, bj, At, Bt) do { __builtin_amdgcn_s_setprio(1); _Pragma("unroll") for (int m = 0; m < 4; ++m) _Pragma("unroll") for (int n = 0; n < 2; ++n) _Pragma("unroll") for (int k = 0; k < 2; ++k) \
;         acc[ai][bj][m][n] = __builtin_amdgcn_mfma_f32_16x16x32_bf16(Bt[n][k], At[m][k], acc[ai][bj][m][n], 0, 0, 0); __builtin_amdgcn_s_setprio(0); } while (0)
; #define PG8_WAIT_V(n) asm volatile("s_waitcnt vmcnt(" #n ")" ::: "memory")
; #define PG8_WAIT_L(n) asm volatile("s_waitcnt lgkmcnt(" #n ")" ::: "memory")
; #define PG8_BAR __builtin_amdgcn_s_barrier()
; #define PG8_SCHED __builtin_amdgcn_sched_barrier(0)
; template <class Epi, class Sched, bool ALIGN_EPI = false, bool SP2 = false>
; __device__ __forceinline__ void gemm_phase(PG8_LAS unsigned char* lds, const Gemm g, const Sched& S, const Epi& E) {
;     ...
;             PG8_WAIT_V(8); PG8_WAIT_L(0); PG8_BAR; PG8_MMA(1, 0, At, B0); PG8_MMA(1, 1, At, B1); PG8_BAR; PG8_SCHED;
	v_mfma_f32_16x16x32_bf16 v[60:63], v[96:99], v[176:179], v[60:63]
	v_mfma_f32_16x16x32_bf16 v[56:59], v[104:107], v[176:179], v[56:59]
	v_mfma_f32_16x16x32_bf16 v[44:47], v[96:99], v[184:187], v[44:47]
	v_mfma_f32_16x16x32_bf16 v[40:43], v[104:107], v[184:187], v[40:43]
	v_mfma_f32_16x16x32_bf16 v[28:31], v[96:99], v[202:205], v[28:31]
	v_mfma_f32_16x16x32_bf16 v[24:27], v[104:107], v[202:205], v[24:27]
	v_mfma_f32_16x16x32_bf16 v[12:15], v[96:99], v[210:213], v[12:15]
	v_mfma_f32_16x16x32_bf16 v[8:11], v[104:107], v[210:213], v[8:11]
	v_mfma_f32_16x16x32_bf16 v[60:63], v[100:103], v[180:183], v[60:63]
	v_mfma_f32_16x16x32_bf16 v[56:59], v[112:115], v[180:183], v[56:59]
	v_mfma_f32_16x16x32_bf16 v[44:47], v[100:103], v[188:191], v[44:47]
	v_mfma_f32_16x16x32_bf16 v[40:43], v[112:115], v[188:191], v[40:43]
	v_mfma_f32_16x16x32_bf16 v[28:31], v[100:103], v[206:209], v[28:31]
	v_mfma_f32_16x16x32_bf16 v[24:27], v[112:115], v[206:209], v[24:27]
	v_mfma_f32_16x16x32_bf16 v[12:15], v[100:103], v[214:217], v[12:15]
	v_mfma_f32_16x16x32_bf16 v[8:11], v[112:115], v[214:217], v[8:11]


; #define PG8_MMA(ai, bj, At, Bt) do { __builtin_amdgcn_s_setprio(1); _Pragma("unroll") for (int m = 0; m < 4; ++m) _Pragma("unroll") for (int n = 0; n < 2; ++n) _Pragma("unroll") for (int k = 0; k < 2; ++k) \
;         acc[ai][bj][m][n] = __builtin_amdgcn_mfma_f32_16x16x32_bf16(Bt[n][k], At[m][k], acc[ai][bj][m][n], 0, 0, 0); __builtin_amdgcn_s_setprio(0); } while (0)
; #define PG8_WAIT_V(n) asm volatile("s_waitcnt vmcnt(" #n ")" ::: "memory")
; #define PG8_WAIT_L(n) asm volatile("s_waitcnt lgkmcnt(" #n ")" ::: "memory")
; #define PG8_BAR __builtin_amdgcn_s_barrier()
; #define PG8_SCHED __builtin_amdgcn_sched_barrier(0)
; template <class Epi, class Sched, bool ALIGN_EPI = false, bool SP2 = false>
; __device__ __forceinline__ void gemm_phase(PG8_LAS unsigned char* lds, const Gemm g, const Sched& S, const Epi& E) {
;     ...
;             PG8_WAIT_V(8); PG8_WAIT_L(0); PG8_BAR; PG8_MMA(1, 0, At, B0); PG8_MMA(1, 1, At, B1); PG8_BAR; PG8_SCHED;
;     ...
;         if constexpr (ALIGN_EPI) { if (wr == 0) PG8_BAR; }
	v_mfma_f32_16x16x32_bf16 v[52:55], v[144:147], v[176:179], v[52:55]
	v_mfma_f32_16x16x32_bf16 v[48:51], v[152:155], v[176:179], v[48:51]
	v_mfma_f32_16x16x32_bf16 v[36:39], v[144:147], v[184:187], v[36:39]
	v_mfma_f32_16x16x32_bf16 v[32:35], v[152:155], v[184:187], v[32:35]
	v_mfma_f32_16x16x32_bf16 v[20:23], v[144:147], v[202:205], v[20:23]
	v_mfma_f32_16x16x32_bf16 v[16:19], v[152:155], v[202:205], v[16:19]
	v_mfma_f32_16x16x32_bf16 v[4:7], v[144:147], v[210:213], v[4:7]
	v_mfma_f32_16x16x32_bf16 v[0:3], v[152:155], v[210:213], v[0:3]
	v_mfma_f32_16x16x32_bf16 v[52:55], v[148:151], v[180:183], v[52:55]
	v_mfma_f32_16x16x32_bf16 v[48:51], v[172:175], v[180:183], v[48:51]
	v_mfma_f32_16x16x32_bf16 v[36:39], v[148:151], v[188:191], v[36:39]
	v_mfma_f32_16x16x32_bf16 v[32:35], v[172:175], v[188:191], v[32:35]
	v_mfma_f32_16x16x32_bf16 v[20:23], v[148:151], v[206:209], v[20:23]
	v_mfma_f32_16x16x32_bf16 v[16:19], v[172:175], v[206:209], v[16:19]
	v_mfma_f32_16x16x32_bf16 v[4:7], v[148:151], v[214:217], v[4:7]
	v_mfma_f32_16x16x32_bf16 v[0:3], v[172:175], v[214:217], v[0:3]
	s_setprio 0
	s_barrier
	s_add_i32 s73, s73, 2
	s_add_u32 s48, s48, 0x100
	s_addc_u32 s49, s49, 0
	s_add_u32 s71, s71, 0x100
	s_addc_u32 s72, s72, 0
	s_cmpk_gt_u32 s73, 0x7d
	s_cbranch_scc0 .LBB0_1114
	s_and_b64 vcc, exec, s[34:35]
	s_cbranch_vccz .LBB0_1117
	s_barrier
